# v10 + GEMM K-loop LDS-read rebalancing: B0 fragment reads moved from phases 1/5 into the read-free phases 8/4 (extra counted vmcnt(10) one phase earlier), so no data-return wait before the phase-1/5 b
# speedup vs baseline: 1.0224x; 1.0095x over previous
.LBB0_116:
	s_ashr_i32 s9, s8, 31
	s_lshl_b64 s[12:13], s[8:9], 18
	s_add_u32 s12, s24, s12
	s_addc_u32 s13, s25, s13
	s_and_b64 s[14:15], s[22:23], exec
	s_cselect_b32 s9, s13, s19
	s_cselect_b32 s41, s12, s18
	s_ashr_i32 s7, s6, 31
	s_lshl_b64 s[14:15], s[6:7], 18
	s_add_u32 s14, s28, s14
	s_addc_u32 s15, s29, s15
	s_and_b64 s[22:23], s[22:23], exec
	s_cselect_b32 s7, s15, s21
	s_cselect_b32 s42, s14, s20
	s_add_u32 s18, s18, 0x20080
	s_addc_u32 s19, s19, 0
	s_add_u32 s43, s20, 0x100
	v_mov_b32_e32 v0, 0
	s_addc_u32 s44, s21, 0
	s_mov_b32 s45, -2
	v_mov_b32_e32 v1, v0
	v_mov_b32_e32 v2, v0
	v_mov_b32_e32 v3, v0
	v_mov_b32_e32 v4, v0
	v_mov_b32_e32 v5, v0
	v_mov_b32_e32 v6, v0
	v_mov_b32_e32 v7, v0
	v_mov_b32_e32 v16, v0
	v_mov_b32_e32 v17, v0
	v_mov_b32_e32 v18, v0
	v_mov_b32_e32 v19, v0
	v_mov_b32_e32 v20, v0
	v_mov_b32_e32 v21, v0
	v_mov_b32_e32 v22, v0
	v_mov_b32_e32 v23, v0
	v_mov_b32_e32 v32, v0
	v_mov_b32_e32 v33, v0
	v_mov_b32_e32 v34, v0
	v_mov_b32_e32 v35, v0
	v_mov_b32_e32 v36, v0
	v_mov_b32_e32 v37, v0
	v_mov_b32_e32 v38, v0
	v_mov_b32_e32 v39, v0
	v_mov_b32_e32 v48, v0
	v_mov_b32_e32 v49, v0
	v_mov_b32_e32 v50, v0
	v_mov_b32_e32 v51, v0
	v_mov_b32_e32 v52, v0
	v_mov_b32_e32 v53, v0
	v_mov_b32_e32 v54, v0
	v_mov_b32_e32 v55, v0
	v_mov_b32_e32 v8, v0
	v_mov_b32_e32 v9, v0
	v_mov_b32_e32 v10, v0
	v_mov_b32_e32 v11, v0
	v_mov_b32_e32 v12, v0
	v_mov_b32_e32 v13, v0
	v_mov_b32_e32 v14, v0
	v_mov_b32_e32 v15, v0
	v_mov_b32_e32 v24, v0
	v_mov_b32_e32 v25, v0
	v_mov_b32_e32 v26, v0
	v_mov_b32_e32 v27, v0
	v_mov_b32_e32 v28, v0
	v_mov_b32_e32 v29, v0
	v_mov_b32_e32 v30, v0
	v_mov_b32_e32 v31, v0
	v_mov_b32_e32 v40, v0
	v_mov_b32_e32 v41, v0
	v_mov_b32_e32 v42, v0
	v_mov_b32_e32 v43, v0
	v_mov_b32_e32 v44, v0
	v_mov_b32_e32 v45, v0
	v_mov_b32_e32 v46, v0
	v_mov_b32_e32 v47, v0
	v_mov_b32_e32 v56, v0
	v_mov_b32_e32 v57, v0
	v_mov_b32_e32 v58, v0
	v_mov_b32_e32 v59, v0
	v_mov_b32_e32 v60, v0
	v_mov_b32_e32 v61, v0
	v_mov_b32_e32 v62, v0
	v_mov_b32_e32 v63, v0
	v_mov_b32_e32 v64, v0
	v_mov_b32_e32 v65, v0
	v_mov_b32_e32 v66, v0
	v_mov_b32_e32 v67, v0
	v_mov_b32_e32 v68, v0
	v_mov_b32_e32 v69, v0
	v_mov_b32_e32 v70, v0
	v_mov_b32_e32 v71, v0
	v_mov_b32_e32 v80, v0
	v_mov_b32_e32 v81, v0
	v_mov_b32_e32 v82, v0
	v_mov_b32_e32 v83, v0
	v_mov_b32_e32 v84, v0
	v_mov_b32_e32 v85, v0
	v_mov_b32_e32 v86, v0
	v_mov_b32_e32 v87, v0
	v_mov_b32_e32 v96, v0
	v_mov_b32_e32 v97, v0
	v_mov_b32_e32 v98, v0
	v_mov_b32_e32 v99, v0
	v_mov_b32_e32 v100, v0
	v_mov_b32_e32 v101, v0
	v_mov_b32_e32 v102, v0
	v_mov_b32_e32 v103, v0
	v_mov_b32_e32 v112, v0
	v_mov_b32_e32 v113, v0
	v_mov_b32_e32 v114, v0
	v_mov_b32_e32 v115, v0
	v_mov_b32_e32 v116, v0
	v_mov_b32_e32 v117, v0
	v_mov_b32_e32 v118, v0
	v_mov_b32_e32 v119, v0
	v_mov_b32_e32 v72, v0
	v_mov_b32_e32 v73, v0
	v_mov_b32_e32 v74, v0
	v_mov_b32_e32 v75, v0
	v_mov_b32_e32 v76, v0
	v_mov_b32_e32 v77, v0
	v_mov_b32_e32 v78, v0
	v_mov_b32_e32 v79, v0
	v_mov_b32_e32 v88, v0
	v_mov_b32_e32 v89, v0
	v_mov_b32_e32 v90, v0
	v_mov_b32_e32 v91, v0
	v_mov_b32_e32 v92, v0
	v_mov_b32_e32 v93, v0
	v_mov_b32_e32 v94, v0
	v_mov_b32_e32 v95, v0
	v_mov_b32_e32 v104, v0
	v_mov_b32_e32 v105, v0
	v_mov_b32_e32 v106, v0
	v_mov_b32_e32 v107, v0
	v_mov_b32_e32 v108, v0
	v_mov_b32_e32 v109, v0
	v_mov_b32_e32 v110, v0
	v_mov_b32_e32 v111, v0
	v_mov_b32_e32 v120, v0
	v_mov_b32_e32 v121, v0
	v_mov_b32_e32 v122, v0
	v_mov_b32_e32 v123, v0
	v_mov_b32_e32 v124, v0
	v_mov_b32_e32 v125, v0
	v_mov_b32_e32 v126, v0
	v_mov_b32_e32 v127, v0
	s_mov_b64 s[50:51], 0x80
	v_add_u32_e32 v156, 0x10000, v142
	ds_read_b128 v[144:147], v156
	ds_read_b128 v[148:151], v156 offset:1024
	ds_read_b128 v[152:155], v156 offset:2048
	ds_read_b128 v[156:159], v156 offset:3072
.LBB0_117:
	s_add_u32 s20, s18, 0xfffe0080
	s_addc_u32 s21, s19, -1
	s_add_i32 s46, 0, 0x10000
	v_add_u32_e32 v138, s46, v142
	s_cmp_eq_u32 s45, 4
	s_cselect_b32 s23, s9, s21
	s_cselect_b32 s22, s41, s20
	s_cselect_b32 s21, s7, s44
	s_cselect_b32 s20, s42, s43
	v_lshl_add_u64 v[138:139], s[18:19], 0, v[134:135]
	s_add_i32 m0, s17, 0xc000
	ds_read_b128 v[160:163], v143
	ds_read_b128 v[164:167], v143 offset:1024
	ds_read_b128 v[168:171], v143 offset:2048
	ds_read_b128 v[172:175], v143 offset:3072
	ds_read_b128 v[176:179], v143 offset:4096
	ds_read_b128 v[180:183], v143 offset:5120
	ds_read_b128 v[188:191], v143 offset:6144
	ds_read_b128 v[192:195], v143 offset:7168
	global_load_lds_dwordx4 v[138:139], off
	v_lshl_add_u64 v[138:139], s[18:19], 0, v[136:137]
	s_add_i32 m0, s17, 0xe000
	s_nop 0
	global_load_lds_dwordx4 v[138:139], off
	s_waitcnt lgkmcnt(8)
	s_setprio 1
	s_barrier
	s_waitcnt lgkmcnt(0)
	v_mfma_f32_16x16x32_bf16 v[124:127], v[144:147], v[160:163], v[124:127]
	v_mfma_f32_16x16x32_bf16 v[120:123], v[152:155], v[160:163], v[120:123]
	v_mfma_f32_16x16x32_bf16 v[108:111], v[144:147], v[168:171], v[108:111]
	v_mfma_f32_16x16x32_bf16 v[104:107], v[152:155], v[168:171], v[104:107]
	v_mfma_f32_16x16x32_bf16 v[92:95], v[144:147], v[176:179], v[92:95]
	v_mfma_f32_16x16x32_bf16 v[88:91], v[152:155], v[176:179], v[88:91]
	v_mfma_f32_16x16x32_bf16 v[76:79], v[144:147], v[188:191], v[76:79]
	v_mfma_f32_16x16x32_bf16 v[72:75], v[152:155], v[188:191], v[72:75]
	v_mfma_f32_16x16x32_bf16 v[124:127], v[148:151], v[164:167], v[124:127]
	v_mfma_f32_16x16x32_bf16 v[120:123], v[156:159], v[164:167], v[120:123]
	v_mfma_f32_16x16x32_bf16 v[108:111], v[148:151], v[172:175], v[108:111]
	v_mfma_f32_16x16x32_bf16 v[104:107], v[156:159], v[172:175], v[104:107]
	v_mfma_f32_16x16x32_bf16 v[92:95], v[148:151], v[180:183], v[92:95]
	v_mfma_f32_16x16x32_bf16 v[88:91], v[156:159], v[180:183], v[88:91]
	v_mfma_f32_16x16x32_bf16 v[76:79], v[148:151], v[192:195], v[76:79]
	v_mfma_f32_16x16x32_bf16 v[72:75], v[156:159], v[192:195], v[72:75]
	s_barrier
	s_setprio 0
	s_add_i32 s48, 0, 0x14000
	v_add_u32_e32 v138, s48, v142
	s_add_i32 s46, s46, s30
	ds_read_b128 v[202:205], v138
	ds_read_b128 v[206:209], v138 offset:1024
	ds_read_b128 v[210:213], v138 offset:2048
	ds_read_b128 v[214:217], v138 offset:3072
	v_lshl_add_u64 v[138:139], s[20:21], 0, v[184:185]
	s_mov_b32 m0, s46
	v_lshl_add_u64 v[196:197], s[20:21], 0, v[128:129]
	global_load_lds_dwordx4 v[138:139], off
	s_add_i32 m0, s46, 0x2000
	s_nop 0
	global_load_lds_dwordx4 v[196:197], off
	s_setprio 1
	s_barrier
	s_waitcnt lgkmcnt(0)
	v_mfma_f32_16x16x32_bf16 v[116:119], v[202:205], v[160:163], v[116:119]
	v_mfma_f32_16x16x32_bf16 v[112:115], v[210:213], v[160:163], v[112:115]
	v_mfma_f32_16x16x32_bf16 v[100:103], v[202:205], v[168:171], v[100:103]
	v_mfma_f32_16x16x32_bf16 v[96:99], v[210:213], v[168:171], v[96:99]
	v_mfma_f32_16x16x32_bf16 v[84:87], v[202:205], v[176:179], v[84:87]
	v_mfma_f32_16x16x32_bf16 v[80:83], v[210:213], v[176:179], v[80:83]
	v_mfma_f32_16x16x32_bf16 v[68:71], v[202:205], v[188:191], v[68:71]
	v_mfma_f32_16x16x32_bf16 v[64:67], v[210:213], v[188:191], v[64:67]
	v_mfma_f32_16x16x32_bf16 v[116:119], v[206:209], v[164:167], v[116:119]
	v_mfma_f32_16x16x32_bf16 v[112:115], v[214:217], v[164:167], v[112:115]
	v_mfma_f32_16x16x32_bf16 v[100:103], v[206:209], v[172:175], v[100:103]
	v_mfma_f32_16x16x32_bf16 v[96:99], v[214:217], v[172:175], v[96:99]
	v_mfma_f32_16x16x32_bf16 v[84:87], v[206:209], v[180:183], v[84:87]
	v_mfma_f32_16x16x32_bf16 v[80:83], v[214:217], v[180:183], v[80:83]
	v_mfma_f32_16x16x32_bf16 v[68:71], v[206:209], v[192:195], v[68:71]
	v_mfma_f32_16x16x32_bf16 v[64:67], v[214:217], v[192:195], v[64:67]
	s_barrier
	s_setprio 0
	s_mov_b32 m0, s17
	v_lshl_add_u64 v[218:219], s[22:23], 0, v[132:133]
	ds_read_b128 v[160:163], v143 offset:16384
	ds_read_b128 v[164:167], v143 offset:17408
	ds_read_b128 v[168:171], v143 offset:18432
	ds_read_b128 v[172:175], v143 offset:19456
	ds_read_b128 v[176:179], v143 offset:20480
	ds_read_b128 v[180:183], v143 offset:21504
	ds_read_b128 v[188:191], v143 offset:22528
	ds_read_b128 v[192:195], v143 offset:23552
	global_load_lds_dwordx4 v[218:219], off
	v_lshl_add_u64 v[220:221], s[22:23], 0, v[130:131]
	s_mov_b32 m0, s31
	s_nop 0
	global_load_lds_dwordx4 v[220:221], off
	s_setprio 1
	s_waitcnt vmcnt(10)
	s_barrier
	s_waitcnt lgkmcnt(0)
	v_mfma_f32_16x16x32_bf16 v[60:63], v[144:147], v[160:163], v[60:63]
	v_mfma_f32_16x16x32_bf16 v[56:59], v[152:155], v[160:163], v[56:59]
	v_mfma_f32_16x16x32_bf16 v[44:47], v[144:147], v[168:171], v[44:47]
	v_mfma_f32_16x16x32_bf16 v[40:43], v[152:155], v[168:171], v[40:43]
	v_mfma_f32_16x16x32_bf16 v[28:31], v[144:147], v[176:179], v[28:31]
	v_mfma_f32_16x16x32_bf16 v[24:27], v[152:155], v[176:179], v[24:27]
	v_mfma_f32_16x16x32_bf16 v[12:15], v[144:147], v[188:191], v[12:15]
	v_mfma_f32_16x16x32_bf16 v[8:11], v[152:155], v[188:191], v[8:11]
	v_mfma_f32_16x16x32_bf16 v[60:63], v[148:151], v[164:167], v[60:63]
	v_mfma_f32_16x16x32_bf16 v[56:59], v[156:159], v[164:167], v[56:59]
	v_mfma_f32_16x16x32_bf16 v[44:47], v[148:151], v[172:175], v[44:47]
	v_mfma_f32_16x16x32_bf16 v[40:43], v[156:159], v[172:175], v[40:43]
	v_mfma_f32_16x16x32_bf16 v[28:31], v[148:151], v[180:183], v[28:31]
	v_mfma_f32_16x16x32_bf16 v[24:27], v[156:159], v[180:183], v[24:27]
	v_mfma_f32_16x16x32_bf16 v[12:15], v[148:151], v[192:195], v[12:15]
	v_mfma_f32_16x16x32_bf16 v[8:11], v[156:159], v[192:195], v[8:11]
	s_barrier
	s_setprio 0
	v_add_u32_e32 v156, 0x18000, v142
	ds_read_b128 v[144:147], v156
	ds_read_b128 v[148:151], v156 offset:1024
	ds_read_b128 v[152:155], v156 offset:2048
	ds_read_b128 v[156:159], v156 offset:3072
	s_add_u32 s46, s20, 0x20000
	s_addc_u32 s47, s21, 0
	s_add_i32 s48, s48, s30
	v_lshl_add_u64 v[246:247], s[46:47], 0, v[184:185]
	s_mov_b32 m0, s48
	s_nop 0
	global_load_lds_dwordx4 v[246:247], off
	v_lshl_add_u64 v[248:249], s[46:47], 0, v[128:129]
	s_add_i32 m0, s48, 0x2000
	s_nop 0
	global_load_lds_dwordx4 v[248:249], off
	s_waitcnt vmcnt(6)
	s_setprio 1
	s_barrier
	v_mfma_f32_16x16x32_bf16 v[52:55], v[202:205], v[160:163], v[52:55]
	v_mfma_f32_16x16x32_bf16 v[48:51], v[210:213], v[160:163], v[48:51]
	v_mfma_f32_16x16x32_bf16 v[36:39], v[202:205], v[168:171], v[36:39]
	v_mfma_f32_16x16x32_bf16 v[32:35], v[210:213], v[168:171], v[32:35]
	v_mfma_f32_16x16x32_bf16 v[20:23], v[202:205], v[176:179], v[20:23]
	v_mfma_f32_16x16x32_bf16 v[16:19], v[210:213], v[176:179], v[16:19]
	v_mfma_f32_16x16x32_bf16 v[4:7], v[202:205], v[188:191], v[4:7]
	v_mfma_f32_16x16x32_bf16 v[0:3], v[210:213], v[188:191], v[0:3]
	v_mfma_f32_16x16x32_bf16 v[52:55], v[206:209], v[164:167], v[52:55]
	v_mfma_f32_16x16x32_bf16 v[48:51], v[214:217], v[164:167], v[48:51]
	v_mfma_f32_16x16x32_bf16 v[36:39], v[206:209], v[172:175], v[36:39]
	v_mfma_f32_16x16x32_bf16 v[32:35], v[214:217], v[172:175], v[32:35]
	v_mfma_f32_16x16x32_bf16 v[20:23], v[206:209], v[180:183], v[20:23]
	v_mfma_f32_16x16x32_bf16 v[16:19], v[214:217], v[180:183], v[16:19]
	v_mfma_f32_16x16x32_bf16 v[4:7], v[206:209], v[192:195], v[4:7]
	v_mfma_f32_16x16x32_bf16 v[0:3], v[214:217], v[192:195], v[0:3]
	s_barrier
	s_setprio 0
	s_add_i32 s46, 0, 0x18000
	s_add_u32 s22, s22, 0x20000
	s_addc_u32 s23, s23, 0
	s_mov_b32 m0, s33
	v_lshl_add_u64 v[202:203], s[22:23], 0, v[132:133]
	ds_read_b128 v[160:163], v143 offset:32768
	ds_read_b128 v[164:167], v143 offset:33792
	ds_read_b128 v[168:171], v143 offset:34816
	ds_read_b128 v[172:175], v143 offset:35840
	ds_read_b128 v[176:179], v143 offset:36864
	ds_read_b128 v[180:183], v143 offset:37888
	ds_read_b128 v[188:191], v143 offset:38912
	ds_read_b128 v[192:195], v143 offset:39936
	global_load_lds_dwordx4 v[202:203], off
	v_lshl_add_u64 v[202:203], s[22:23], 0, v[130:131]
	s_mov_b32 m0, s34
	s_nop 0
	global_load_lds_dwordx4 v[202:203], off
	s_waitcnt lgkmcnt(8)
	s_setprio 1
	s_barrier
	s_waitcnt lgkmcnt(0)
	v_mfma_f32_16x16x32_bf16 v[124:127], v[144:147], v[160:163], v[124:127]
	v_mfma_f32_16x16x32_bf16 v[120:123], v[152:155], v[160:163], v[120:123]
	v_mfma_f32_16x16x32_bf16 v[108:111], v[144:147], v[168:171], v[108:111]
	v_mfma_f32_16x16x32_bf16 v[104:107], v[152:155], v[168:171], v[104:107]
	v_mfma_f32_16x16x32_bf16 v[92:95], v[144:147], v[176:179], v[92:95]
	v_mfma_f32_16x16x32_bf16 v[88:91], v[152:155], v[176:179], v[88:91]
	v_mfma_f32_16x16x32_bf16 v[76:79], v[144:147], v[188:191], v[76:79]
	v_mfma_f32_16x16x32_bf16 v[72:75], v[152:155], v[188:191], v[72:75]
	v_mfma_f32_16x16x32_bf16 v[124:127], v[148:151], v[164:167], v[124:127]
	v_mfma_f32_16x16x32_bf16 v[120:123], v[156:159], v[164:167], v[120:123]
	v_mfma_f32_16x16x32_bf16 v[108:111], v[148:151], v[172:175], v[108:111]
	v_mfma_f32_16x16x32_bf16 v[104:107], v[156:159], v[172:175], v[104:107]
	v_mfma_f32_16x16x32_bf16 v[92:95], v[148:151], v[180:183], v[92:95]
	v_mfma_f32_16x16x32_bf16 v[88:91], v[156:159], v[180:183], v[88:91]
	v_mfma_f32_16x16x32_bf16 v[76:79], v[148:151], v[192:195], v[76:79]
	v_mfma_f32_16x16x32_bf16 v[72:75], v[156:159], v[192:195], v[72:75]
	s_barrier
	s_setprio 0
	s_add_i32 s22, 0, 0x1c000
	s_add_i32 s23, s46, s30
	v_add_u32_e32 v187, s22, v142
	v_lshl_add_u64 v[138:139], v[138:139], 0, s[50:51]
	s_mov_b32 m0, s23
	ds_read_b128 v[202:205], v187
	ds_read_b128 v[206:209], v187 offset:1024
	ds_read_b128 v[210:213], v187 offset:2048
	ds_read_b128 v[214:217], v187 offset:3072
	global_load_lds_dwordx4 v[138:139], off
	v_lshl_add_u64 v[138:139], v[196:197], 0, s[50:51]
	s_add_i32 m0, s23, 0x2000
	s_nop 0
	global_load_lds_dwordx4 v[138:139], off
	s_setprio 1
	s_barrier
	s_waitcnt lgkmcnt(0)
	v_mfma_f32_16x16x32_bf16 v[116:119], v[202:205], v[160:163], v[116:119]
	v_mfma_f32_16x16x32_bf16 v[112:115], v[210:213], v[160:163], v[112:115]
	v_mfma_f32_16x16x32_bf16 v[100:103], v[202:205], v[168:171], v[100:103]
	v_mfma_f32_16x16x32_bf16 v[96:99], v[210:213], v[168:171], v[96:99]
	v_mfma_f32_16x16x32_bf16 v[84:87], v[202:205], v[176:179], v[84:87]
	v_mfma_f32_16x16x32_bf16 v[80:83], v[210:213], v[176:179], v[80:83]
	v_mfma_f32_16x16x32_bf16 v[68:71], v[202:205], v[188:191], v[68:71]
	v_mfma_f32_16x16x32_bf16 v[64:67], v[210:213], v[188:191], v[64:67]
	v_mfma_f32_16x16x32_bf16 v[116:119], v[206:209], v[164:167], v[116:119]
	v_mfma_f32_16x16x32_bf16 v[112:115], v[214:217], v[164:167], v[112:115]
	v_mfma_f32_16x16x32_bf16 v[100:103], v[206:209], v[172:175], v[100:103]
	v_mfma_f32_16x16x32_bf16 v[96:99], v[214:217], v[172:175], v[96:99]
	v_mfma_f32_16x16x32_bf16 v[84:87], v[206:209], v[180:183], v[84:87]
	v_mfma_f32_16x16x32_bf16 v[80:83], v[214:217], v[180:183], v[80:83]
	v_mfma_f32_16x16x32_bf16 v[68:71], v[206:209], v[192:195], v[68:71]
	v_mfma_f32_16x16x32_bf16 v[64:67], v[214:217], v[192:195], v[64:67]
	s_barrier
	s_setprio 0
	s_mov_b32 m0, s37
	v_lshl_add_u64 v[138:139], v[218:219], 0, s[50:51]
	ds_read_b128 v[160:163], v143 offset:49152
	ds_read_b128 v[164:167], v143 offset:50176
	ds_read_b128 v[168:171], v143 offset:51200
	ds_read_b128 v[172:175], v143 offset:52224
	ds_read_b128 v[176:179], v143 offset:53248
	ds_read_b128 v[180:183], v143 offset:54272
	ds_read_b128 v[188:191], v143 offset:55296
	ds_read_b128 v[192:195], v143 offset:56320
	global_load_lds_dwordx4 v[138:139], off
	v_lshl_add_u64 v[138:139], v[220:221], 0, s[50:51]
	s_mov_b32 m0, s38
	s_nop 0
	global_load_lds_dwordx4 v[138:139], off
	s_setprio 1
	s_waitcnt vmcnt(10)
	s_barrier
	s_waitcnt lgkmcnt(0)
	v_mfma_f32_16x16x32_bf16 v[60:63], v[144:147], v[160:163], v[60:63]
	v_mfma_f32_16x16x32_bf16 v[56:59], v[152:155], v[160:163], v[56:59]
	v_mfma_f32_16x16x32_bf16 v[44:47], v[144:147], v[168:171], v[44:47]
	v_mfma_f32_16x16x32_bf16 v[40:43], v[152:155], v[168:171], v[40:43]
	v_mfma_f32_16x16x32_bf16 v[28:31], v[144:147], v[176:179], v[28:31]
	v_mfma_f32_16x16x32_bf16 v[24:27], v[152:155], v[176:179], v[24:27]
	v_mfma_f32_16x16x32_bf16 v[12:15], v[144:147], v[188:191], v[12:15]
	v_mfma_f32_16x16x32_bf16 v[8:11], v[152:155], v[188:191], v[8:11]
	v_mfma_f32_16x16x32_bf16 v[60:63], v[148:151], v[164:167], v[60:63]
	v_mfma_f32_16x16x32_bf16 v[56:59], v[156:159], v[164:167], v[56:59]
	v_mfma_f32_16x16x32_bf16 v[44:47], v[148:151], v[172:175], v[44:47]
	v_mfma_f32_16x16x32_bf16 v[40:43], v[156:159], v[172:175], v[40:43]
	v_mfma_f32_16x16x32_bf16 v[28:31], v[148:151], v[180:183], v[28:31]
	v_mfma_f32_16x16x32_bf16 v[24:27], v[156:159], v[180:183], v[24:27]
	v_mfma_f32_16x16x32_bf16 v[12:15], v[148:151], v[192:195], v[12:15]
	v_mfma_f32_16x16x32_bf16 v[8:11], v[156:159], v[192:195], v[8:11]
	s_barrier
	s_setprio 0
	v_add_u32_e32 v156, 0x10000, v142
	ds_read_b128 v[144:147], v156
	ds_read_b128 v[148:151], v156 offset:1024
	ds_read_b128 v[152:155], v156 offset:2048
	ds_read_b128 v[156:159], v156 offset:3072
	s_add_u32 s20, s20, 0x20080
	s_addc_u32 s21, s21, 0
	s_add_i32 s22, s22, s30
	v_lshl_add_u64 v[138:139], s[20:21], 0, v[184:185]
	s_mov_b32 m0, s22
	s_nop 0
	global_load_lds_dwordx4 v[138:139], off
	v_lshl_add_u64 v[138:139], s[20:21], 0, v[128:129]
	s_add_i32 m0, s22, 0x2000
	s_nop 0
	global_load_lds_dwordx4 v[138:139], off
	s_waitcnt vmcnt(6)
	s_setprio 1
	s_barrier
	v_mfma_f32_16x16x32_bf16 v[52:55], v[202:205], v[160:163], v[52:55]
	v_mfma_f32_16x16x32_bf16 v[48:51], v[210:213], v[160:163], v[48:51]
	v_mfma_f32_16x16x32_bf16 v[36:39], v[202:205], v[168:171], v[36:39]
	v_mfma_f32_16x16x32_bf16 v[32:35], v[210:213], v[168:171], v[32:35]
	v_mfma_f32_16x16x32_bf16 v[20:23], v[202:205], v[176:179], v[20:23]
	v_mfma_f32_16x16x32_bf16 v[16:19], v[210:213], v[176:179], v[16:19]
	v_mfma_f32_16x16x32_bf16 v[4:7], v[202:205], v[188:191], v[4:7]
	v_mfma_f32_16x16x32_bf16 v[0:3], v[210:213], v[188:191], v[0:3]
	v_mfma_f32_16x16x32_bf16 v[52:55], v[206:209], v[164:167], v[52:55]
	v_mfma_f32_16x16x32_bf16 v[48:51], v[214:217], v[164:167], v[48:51]
	v_mfma_f32_16x16x32_bf16 v[36:39], v[206:209], v[172:175], v[36:39]
	v_mfma_f32_16x16x32_bf16 v[32:35], v[214:217], v[172:175], v[32:35]
	v_mfma_f32_16x16x32_bf16 v[20:23], v[206:209], v[180:183], v[20:23]
	v_mfma_f32_16x16x32_bf16 v[16:19], v[214:217], v[180:183], v[16:19]
	v_mfma_f32_16x16x32_bf16 v[4:7], v[206:209], v[192:195], v[4:7]
	v_mfma_f32_16x16x32_bf16 v[0:3], v[214:217], v[192:195], v[0:3]
	s_barrier
	s_setprio 0
	s_add_i32 s45, s45, 2
	s_add_u32 s18, s18, 0x100
	s_addc_u32 s19, s19, 0
	s_add_u32 s43, s43, 0x100
	s_addc_u32 s44, s44, 0
	s_cmp_gt_u32 s45, 5
	s_cbranch_scc0 .LBB0_117
	s_waitcnt lgkmcnt(0)
	v_mov_b32_e32 v138, v140
	v_mov_b32_e32 v139, v141
	s_lshl_b32 s7, s16, 8
	s_add_i32 s7, s7, s35
	v_add_u32_e32 v138, s7, v138
	s_lshl_b32 s7, s40, 8
	s_or_b32 s7, s7, s36
	v_lshl_add_u32 v152, v139, 3, s7
	v_ashrrev_i32_e32 v139, 31, v138
	v_lshlrev_b64 v[144:145], 5, v[138:139]
	v_lshl_add_u64 v[148:149], s[4:5], 0, v[144:145]
	global_load_dwordx4 v[144:147], v[148:149], off offset:16
	s_nop 0
	global_load_dwordx4 v[148:151], v[148:149], off
	v_ashrrev_i32_e32 v153, 31, v152
	s_mov_b32 s40, s6
	s_mov_b32 s16, s8
	s_mov_b64 s[20:21], s[14:15]
	s_mov_b64 s[18:19], s[12:13]
	s_waitcnt vmcnt(0)
	v_add_f32_e32 v148, v148, v149
	v_add_f32_e32 v148, v150, v148
	v_add_f32_e32 v148, v151, v148
	v_add_f32_e32 v144, v144, v148
	v_add_f32_e32 v144, v145, v144
	v_add_f32_e32 v144, v146, v144
	v_add_f32_e32 v144, v147, v144
	v_add_f32_e32 v144, 0x3a0637bd, v144
	v_mul_f32_e32 v144, 0x3b000000, v144
	v_cmp_gt_f32_e32 vcc, s67, v144
	v_mul_f32_e32 v145, 0x4b800000, v144
	s_nop 0
	v_cndmask_b32_e32 v144, v144, v145, vcc
	v_rsq_f32_e32 v144, v144
	s_nop 0
	v_mul_f32_e32 v145, 0x45800000, v144
	v_cndmask_b32_e32 v144, v144, v145, vcc
	v_mul_f32_e32 v124, v124, v144
	v_mul_f32_e32 v120, v120, v144
	v_mul_f32_e32 v121, v121, v144
	v_mul_f32_e32 v125, v125, v144
	v_mul_f32_e32 v126, v126, v144
	v_mul_f32_e32 v127, v127, v144
	v_mul_f32_e32 v145, v122, v144
	v_mul_f32_e32 v146, v123, v144
	v_cvt_pk_bf16_f32 v122, v124, v125
	v_cvt_pk_bf16_f32 v123, v126, v127
	v_cvt_pk_bf16_f32 v124, v120, v121
	v_lshlrev_b64 v[120:121], 12, v[138:139]
	v_lshl_add_u64 v[126:127], s[2:3], 0, v[120:121]
	v_lshlrev_b64 v[120:121], 1, v[152:153]
	v_lshl_add_u64 v[126:127], v[126:127], 0, v[120:121]
	v_cvt_pk_bf16_f32 v125, v145, v146
	global_store_dwordx4 v[126:127], v[122:125], off
	v_mul_f32_e32 v116, v116, v144
	v_mul_f32_e32 v117, v117, v144
	v_mul_f32_e32 v122, v112, v144
	v_mul_f32_e32 v118, v118, v144
	v_mul_f32_e32 v119, v119, v144
	v_mul_f32_e32 v123, v113, v144
	v_mul_f32_e32 v124, v114, v144
	v_cvt_pk_bf16_f32 v112, v116, v117
	v_cvt_pk_bf16_f32 v113, v118, v119
	v_cvt_pk_bf16_f32 v114, v122, v123
	v_add_u32_e32 v122, 16, v138
	v_mul_f32_e32 v115, v115, v144
	v_ashrrev_i32_e32 v123, 31, v122
	v_cvt_pk_bf16_f32 v115, v124, v115
	global_store_dwordx4 v[126:127], v[112:115], off offset:256
	s_nop 1
	v_lshlrev_b64 v[112:113], 5, v[122:123]
	v_lshl_add_u64 v[116:117], s[4:5], 0, v[112:113]
	global_load_dwordx4 v[112:115], v[116:117], off offset:16
	s_nop 0
	global_load_dwordx4 v[116:119], v[116:117], off
	s_waitcnt vmcnt(0)
	v_add_f32_e32 v116, v116, v117
	v_add_f32_e32 v116, v118, v116
	v_add_f32_e32 v116, v119, v116
	v_add_f32_e32 v112, v112, v116
	v_add_f32_e32 v112, v113, v112
	v_add_f32_e32 v112, v114, v112
	v_add_f32_e32 v112, v115, v112
	v_add_f32_e32 v112, 0x3a0637bd, v112
	v_mul_f32_e32 v112, 0x3b000000, v112
	v_cmp_gt_f32_e32 vcc, s67, v112
	v_mul_f32_e32 v113, 0x4b800000, v112
	s_nop 0
	v_cndmask_b32_e32 v112, v112, v113, vcc
	v_rsq_f32_e32 v112, v112
	s_nop 0
	v_mul_f32_e32 v113, 0x45800000, v112
	v_cndmask_b32_e32 v112, v112, v113, vcc
	v_mul_f32_e32 v108, v108, v112
	v_mul_f32_e32 v109, v109, v112
	v_mul_f32_e32 v113, v104, v112
	v_cvt_pk_bf16_f32 v104, v108, v109
	v_lshlrev_b64 v[108:109], 12, v[122:123]
	v_lshl_add_u64 v[108:109], s[2:3], 0, v[108:109]
	v_mul_f32_e32 v107, v107, v112
	v_lshl_add_u64 v[108:109], v[108:109], 0, v[120:121]
	v_mul_f32_e32 v110, v110, v112
	v_mul_f32_e32 v111, v111, v112
	v_mul_f32_e32 v114, v105, v112
	v_mul_f32_e32 v115, v106, v112
	v_cvt_pk_bf16_f32 v105, v110, v111
	v_cvt_pk_bf16_f32 v106, v113, v114
	v_cvt_pk_bf16_f32 v107, v115, v107
	global_store_dwordx4 v[108:109], v[104:107], off
	v_mul_f32_e32 v100, v100, v112
	v_mul_f32_e32 v101, v101, v112
	v_mul_f32_e32 v104, v96, v112
	v_mul_f32_e32 v102, v102, v112
	v_mul_f32_e32 v103, v103, v112
	v_mul_f32_e32 v105, v97, v112
	v_mul_f32_e32 v106, v98, v112
	v_cvt_pk_bf16_f32 v96, v100, v101
	v_cvt_pk_bf16_f32 v97, v102, v103
	v_cvt_pk_bf16_f32 v98, v104, v105
	v_add_u32_e32 v104, 32, v138
	v_mul_f32_e32 v99, v99, v112
	v_ashrrev_i32_e32 v105, 31, v104
	v_cvt_pk_bf16_f32 v99, v106, v99
	global_store_dwordx4 v[108:109], v[96:99], off offset:256
	s_nop 1
	v_lshlrev_b64 v[96:97], 5, v[104:105]
	v_lshl_add_u64 v[100:101], s[4:5], 0, v[96:97]
	global_load_dwordx4 v[96:99], v[100:101], off offset:16
	s_nop 0
	global_load_dwordx4 v[100:103], v[100:101], off
	s_waitcnt vmcnt(0)
	v_add_f32_e32 v100, v100, v101
	v_add_f32_e32 v100, v102, v100
	v_add_f32_e32 v100, v103, v100
	v_add_f32_e32 v96, v96, v100
	v_add_f32_e32 v96, v97, v96
	v_add_f32_e32 v96, v98, v96
	v_add_f32_e32 v96, v99, v96
	v_add_f32_e32 v96, 0x3a0637bd, v96
	v_mul_f32_e32 v96, 0x3b000000, v96
	v_cmp_gt_f32_e32 vcc, s67, v96
	v_mul_f32_e32 v97, 0x4b800000, v96
	s_nop 0
	v_cndmask_b32_e32 v96, v96, v97, vcc
	v_rsq_f32_e32 v96, v96
	s_nop 0
	v_mul_f32_e32 v97, 0x45800000, v96
	v_cndmask_b32_e32 v96, v96, v97, vcc
	v_mul_f32_e32 v92, v92, v96
	v_mul_f32_e32 v93, v93, v96
	v_mul_f32_e32 v97, v88, v96
	v_cvt_pk_bf16_f32 v88, v92, v93
	v_lshlrev_b64 v[92:93], 12, v[104:105]
	v_lshl_add_u64 v[92:93], s[2:3], 0, v[92:93]
	v_mul_f32_e32 v91, v91, v96
	v_lshl_add_u64 v[92:93], v[92:93], 0, v[120:121]
	v_mul_f32_e32 v94, v94, v96
	v_mul_f32_e32 v95, v95, v96
	v_mul_f32_e32 v98, v89, v96
	v_mul_f32_e32 v99, v90, v96
	v_cvt_pk_bf16_f32 v89, v94, v95
	v_cvt_pk_bf16_f32 v90, v97, v98
	v_cvt_pk_bf16_f32 v91, v99, v91
	global_store_dwordx4 v[92:93], v[88:91], off
	v_mul_f32_e32 v84, v84, v96
	v_mul_f32_e32 v85, v85, v96
	v_mul_f32_e32 v88, v80, v96
	v_mul_f32_e32 v86, v86, v96
	v_mul_f32_e32 v87, v87, v96
	v_mul_f32_e32 v89, v81, v96
	v_mul_f32_e32 v90, v82, v96
	v_cvt_pk_bf16_f32 v80, v84, v85
	v_cvt_pk_bf16_f32 v81, v86, v87
	v_cvt_pk_bf16_f32 v82, v88, v89
	v_add_u32_e32 v88, 48, v138
	v_mul_f32_e32 v83, v83, v96
	v_ashrrev_i32_e32 v89, 31, v88
	v_cvt_pk_bf16_f32 v83, v90, v83
	global_store_dwordx4 v[92:93], v[80:83], off offset:256
	s_nop 1
	v_lshlrev_b64 v[80:81], 5, v[88:89]
	v_lshl_add_u64 v[84:85], s[4:5], 0, v[80:81]
	global_load_dwordx4 v[80:83], v[84:85], off offset:16
	s_nop 0
	global_load_dwordx4 v[84:87], v[84:85], off
	s_waitcnt vmcnt(0)
	v_add_f32_e32 v84, v84, v85
	v_add_f32_e32 v84, v86, v84
	v_add_f32_e32 v84, v87, v84
	v_add_f32_e32 v80, v80, v84
	v_add_f32_e32 v80, v81, v80
	v_add_f32_e32 v80, v82, v80
	v_add_f32_e32 v80, v83, v80
	v_add_f32_e32 v80, 0x3a0637bd, v80
	v_mul_f32_e32 v80, 0x3b000000, v80
	v_cmp_gt_f32_e32 vcc, s67, v80
	v_mul_f32_e32 v81, 0x4b800000, v80
	s_nop 0
	v_cndmask_b32_e32 v80, v80, v81, vcc
	v_rsq_f32_e32 v80, v80
	s_nop 0
	v_mul_f32_e32 v81, 0x45800000, v80
	v_cndmask_b32_e32 v80, v80, v81, vcc
	v_mul_f32_e32 v76, v76, v80
	v_mul_f32_e32 v77, v77, v80
	v_mul_f32_e32 v81, v72, v80
	v_cvt_pk_bf16_f32 v72, v76, v77
	v_lshlrev_b64 v[76:77], 12, v[88:89]
	v_lshl_add_u64 v[76:77], s[2:3], 0, v[76:77]
	v_mul_f32_e32 v75, v75, v80
	v_lshl_add_u64 v[76:77], v[76:77], 0, v[120:121]
	v_mul_f32_e32 v78, v78, v80
	v_mul_f32_e32 v79, v79, v80
	v_mul_f32_e32 v82, v73, v80
	v_mul_f32_e32 v83, v74, v80
	v_cvt_pk_bf16_f32 v73, v78, v79
	v_cvt_pk_bf16_f32 v74, v81, v82
	v_cvt_pk_bf16_f32 v75, v83, v75
	global_store_dwordx4 v[76:77], v[72:75], off
	v_mul_f32_e32 v68, v68, v80
	v_mul_f32_e32 v69, v69, v80
	v_mul_f32_e32 v72, v64, v80
	v_mul_f32_e32 v70, v70, v80
	v_mul_f32_e32 v71, v71, v80
	v_mul_f32_e32 v73, v65, v80
	v_mul_f32_e32 v74, v66, v80
	v_cvt_pk_bf16_f32 v64, v68, v69
	v_cvt_pk_bf16_f32 v65, v70, v71
	v_cvt_pk_bf16_f32 v66, v72, v73
	v_add_u32_e32 v72, 0x80, v138
	v_mul_f32_e32 v67, v67, v80
	v_ashrrev_i32_e32 v73, 31, v72
	v_cvt_pk_bf16_f32 v67, v74, v67
	global_store_dwordx4 v[76:77], v[64:67], off offset:256
	s_nop 1
	v_lshlrev_b64 v[64:65], 5, v[72:73]
	v_lshl_add_u64 v[68:69], s[4:5], 0, v[64:65]
	global_load_dwordx4 v[64:67], v[68:69], off offset:16
	s_nop 0
	global_load_dwordx4 v[68:71], v[68:69], off
	s_waitcnt vmcnt(0)
	v_add_f32_e32 v68, v68, v69
	v_add_f32_e32 v68, v70, v68
	v_add_f32_e32 v68, v71, v68
	v_add_f32_e32 v64, v64, v68
	v_add_f32_e32 v64, v65, v64
	v_add_f32_e32 v64, v66, v64
	v_add_f32_e32 v64, v67, v64
	v_add_f32_e32 v64, 0x3a0637bd, v64
	v_mul_f32_e32 v64, 0x3b000000, v64
	v_cmp_gt_f32_e32 vcc, s67, v64
	v_mul_f32_e32 v65, 0x4b800000, v64
	s_nop 0
	v_cndmask_b32_e32 v64, v64, v65, vcc
	v_rsq_f32_e32 v64, v64
	s_nop 0
	v_mul_f32_e32 v65, 0x45800000, v64
	v_cndmask_b32_e32 v64, v64, v65, vcc
	v_mul_f32_e32 v60, v60, v64
	v_mul_f32_e32 v61, v61, v64
	v_mul_f32_e32 v65, v56, v64
	v_cvt_pk_bf16_f32 v56, v60, v61
	v_lshlrev_b64 v[60:61], 12, v[72:73]
	v_lshl_add_u64 v[60:61], s[2:3], 0, v[60:61]
	v_mul_f32_e32 v59, v59, v64
	v_lshl_add_u64 v[60:61], v[60:61], 0, v[120:121]
	v_mul_f32_e32 v62, v62, v64
	v_mul_f32_e32 v63, v63, v64
	v_mul_f32_e32 v66, v57, v64
	v_mul_f32_e32 v67, v58, v64
	v_cvt_pk_bf16_f32 v57, v62, v63
	v_cvt_pk_bf16_f32 v58, v65, v66
	v_cvt_pk_bf16_f32 v59, v67, v59
	global_store_dwordx4 v[60:61], v[56:59], off
	v_mul_f32_e32 v52, v52, v64
	v_mul_f32_e32 v53, v53, v64
	v_mul_f32_e32 v56, v48, v64
	v_mul_f32_e32 v54, v54, v64
	v_mul_f32_e32 v55, v55, v64
	v_mul_f32_e32 v57, v49, v64
	v_mul_f32_e32 v58, v50, v64
	v_cvt_pk_bf16_f32 v48, v52, v53
	v_cvt_pk_bf16_f32 v49, v54, v55
	v_cvt_pk_bf16_f32 v50, v56, v57
	v_add_u32_e32 v56, 0x90, v138
	v_mul_f32_e32 v51, v51, v64
	v_ashrrev_i32_e32 v57, 31, v56
	v_cvt_pk_bf16_f32 v51, v58, v51
	global_store_dwordx4 v[60:61], v[48:51], off offset:256
	s_nop 1
	v_lshlrev_b64 v[48:49], 5, v[56:57]
	v_lshl_add_u64 v[52:53], s[4:5], 0, v[48:49]
	global_load_dwordx4 v[48:51], v[52:53], off offset:16
	s_nop 0
	global_load_dwordx4 v[52:55], v[52:53], off
	s_waitcnt vmcnt(0)
	v_add_f32_e32 v52, v52, v53
	v_add_f32_e32 v52, v54, v52
	v_add_f32_e32 v52, v55, v52
	v_add_f32_e32 v48, v48, v52
	v_add_f32_e32 v48, v49, v48
	v_add_f32_e32 v48, v50, v48
	v_add_f32_e32 v48, v51, v48
	v_add_f32_e32 v48, 0x3a0637bd, v48
	v_mul_f32_e32 v48, 0x3b000000, v48
	v_cmp_gt_f32_e32 vcc, s67, v48
	v_mul_f32_e32 v49, 0x4b800000, v48
	s_nop 0
	v_cndmask_b32_e32 v48, v48, v49, vcc
	v_rsq_f32_e32 v48, v48
	s_nop 0
	v_mul_f32_e32 v49, 0x45800000, v48
	v_cndmask_b32_e32 v48, v48, v49, vcc
	v_mul_f32_e32 v44, v44, v48
	v_mul_f32_e32 v45, v45, v48
	v_mul_f32_e32 v49, v40, v48
	v_cvt_pk_bf16_f32 v40, v44, v45
	v_lshlrev_b64 v[44:45], 12, v[56:57]
	v_lshl_add_u64 v[44:45], s[2:3], 0, v[44:45]
	v_mul_f32_e32 v43, v43, v48
	v_lshl_add_u64 v[44:45], v[44:45], 0, v[120:121]
	v_mul_f32_e32 v46, v46, v48
	v_mul_f32_e32 v47, v47, v48
	v_mul_f32_e32 v50, v41, v48
	v_mul_f32_e32 v51, v42, v48
	v_cvt_pk_bf16_f32 v41, v46, v47
	v_cvt_pk_bf16_f32 v42, v49, v50
	v_cvt_pk_bf16_f32 v43, v51, v43
	global_store_dwordx4 v[44:45], v[40:43], off
	v_mul_f32_e32 v36, v36, v48
	v_mul_f32_e32 v37, v37, v48
	v_mul_f32_e32 v40, v32, v48
	v_mul_f32_e32 v38, v38, v48
	v_mul_f32_e32 v39, v39, v48
	v_mul_f32_e32 v41, v33, v48
	v_mul_f32_e32 v42, v34, v48
	v_cvt_pk_bf16_f32 v32, v36, v37
	v_cvt_pk_bf16_f32 v33, v38, v39
	v_cvt_pk_bf16_f32 v34, v40, v41
	v_add_u32_e32 v40, 0xa0, v138
	v_mul_f32_e32 v35, v35, v48
	v_ashrrev_i32_e32 v41, 31, v40
	v_cvt_pk_bf16_f32 v35, v42, v35
	global_store_dwordx4 v[44:45], v[32:35], off offset:256
	s_nop 1
	v_lshlrev_b64 v[32:33], 5, v[40:41]
	v_lshl_add_u64 v[36:37], s[4:5], 0, v[32:33]
	global_load_dwordx4 v[32:35], v[36:37], off offset:16
	s_nop 0
	global_load_dwordx4 v[36:39], v[36:37], off
	s_waitcnt vmcnt(0)
	v_add_f32_e32 v36, v36, v37
	v_add_f32_e32 v36, v38, v36
	v_add_f32_e32 v36, v39, v36
	v_add_f32_e32 v32, v32, v36
	v_add_f32_e32 v32, v33, v32
	v_add_f32_e32 v32, v34, v32
	v_add_f32_e32 v32, v35, v32
	v_add_f32_e32 v32, 0x3a0637bd, v32
	v_mul_f32_e32 v32, 0x3b000000, v32
	v_cmp_gt_f32_e32 vcc, s67, v32
	v_mul_f32_e32 v33, 0x4b800000, v32
	s_nop 0
	v_cndmask_b32_e32 v32, v32, v33, vcc
	v_rsq_f32_e32 v32, v32
	s_nop 0
	v_mul_f32_e32 v33, 0x45800000, v32
	v_cndmask_b32_e32 v32, v32, v33, vcc
	v_mul_f32_e32 v28, v28, v32
	v_mul_f32_e32 v29, v29, v32
	v_mul_f32_e32 v33, v24, v32
	v_cvt_pk_bf16_f32 v24, v28, v29
	v_lshlrev_b64 v[28:29], 12, v[40:41]
	v_lshl_add_u64 v[28:29], s[2:3], 0, v[28:29]
	v_mul_f32_e32 v27, v27, v32
	v_lshl_add_u64 v[28:29], v[28:29], 0, v[120:121]
	v_mul_f32_e32 v30, v30, v32
	v_mul_f32_e32 v31, v31, v32
	v_mul_f32_e32 v34, v25, v32
	v_mul_f32_e32 v35, v26, v32
	v_cvt_pk_bf16_f32 v25, v30, v31
	v_cvt_pk_bf16_f32 v26, v33, v34
	v_cvt_pk_bf16_f32 v27, v35, v27
	global_store_dwordx4 v[28:29], v[24:27], off
	v_mul_f32_e32 v20, v20, v32
	v_mul_f32_e32 v21, v21, v32
	v_mul_f32_e32 v24, v16, v32
	v_mul_f32_e32 v22, v22, v32
	v_mul_f32_e32 v23, v23, v32
	v_mul_f32_e32 v25, v17, v32
	v_mul_f32_e32 v26, v18, v32
	v_cvt_pk_bf16_f32 v16, v20, v21
	v_cvt_pk_bf16_f32 v17, v22, v23
	v_cvt_pk_bf16_f32 v18, v24, v25
	v_add_u32_e32 v24, 0xb0, v138
	v_mul_f32_e32 v19, v19, v32
	v_ashrrev_i32_e32 v25, 31, v24
	v_cvt_pk_bf16_f32 v19, v26, v19
	global_store_dwordx4 v[28:29], v[16:19], off offset:256
	s_nop 1
	v_lshlrev_b64 v[16:17], 5, v[24:25]
	v_lshl_add_u64 v[20:21], s[4:5], 0, v[16:17]
	global_load_dwordx4 v[16:19], v[20:21], off offset:16
	s_nop 0
	global_load_dwordx4 v[20:23], v[20:21], off
	s_waitcnt vmcnt(0)
	v_add_f32_e32 v20, v20, v21
	v_add_f32_e32 v20, v22, v20
	v_add_f32_e32 v20, v23, v20
	v_add_f32_e32 v16, v16, v20
	v_add_f32_e32 v16, v17, v16
	v_add_f32_e32 v16, v18, v16
	v_add_f32_e32 v16, v19, v16
	v_add_f32_e32 v16, 0x3a0637bd, v16
	v_mul_f32_e32 v16, 0x3b000000, v16
	v_cmp_gt_f32_e32 vcc, s67, v16
	v_mul_f32_e32 v17, 0x4b800000, v16
	s_nop 0
	v_cndmask_b32_e32 v16, v16, v17, vcc
	v_rsq_f32_e32 v16, v16
	s_nop 0
	v_mul_f32_e32 v17, 0x45800000, v16
	v_cndmask_b32_e32 v16, v16, v17, vcc
	v_mul_f32_e32 v12, v12, v16
	v_mul_f32_e32 v13, v13, v16
	v_mul_f32_e32 v17, v8, v16
	v_cvt_pk_bf16_f32 v8, v12, v13
	v_lshlrev_b64 v[12:13], 12, v[24:25]
	v_lshl_add_u64 v[12:13], s[2:3], 0, v[12:13]
	v_mul_f32_e32 v14, v14, v16
	v_mul_f32_e32 v15, v15, v16
	v_mul_f32_e32 v18, v9, v16
	v_mul_f32_e32 v19, v10, v16
	v_mul_f32_e32 v11, v11, v16
	v_cvt_pk_bf16_f32 v9, v14, v15
	v_cvt_pk_bf16_f32 v10, v17, v18
	v_lshl_add_u64 v[12:13], v[12:13], 0, v[120:121]
	v_mul_f32_e32 v3, v3, v16
	s_and_b64 vcc, exec, s[10:11]
	v_cvt_pk_bf16_f32 v11, v19, v11
	global_store_dwordx4 v[12:13], v[8:11], off
	v_mul_f32_e32 v4, v4, v16
	v_mul_f32_e32 v5, v5, v16
	v_mul_f32_e32 v6, v6, v16
	v_mul_f32_e32 v7, v7, v16
	v_mul_f32_e32 v8, v0, v16
	v_mul_f32_e32 v9, v1, v16
	v_mul_f32_e32 v10, v2, v16
	v_cvt_pk_bf16_f32 v0, v4, v5
	v_cvt_pk_bf16_f32 v1, v6, v7
	v_cvt_pk_bf16_f32 v2, v8, v9
	v_cvt_pk_bf16_f32 v3, v10, v3
	global_store_dwordx4 v[12:13], v[0:3], off offset:256
	s_cbranch_vccz .LBB0_114
	s_waitcnt vmcnt(0)
	v_readlane_b32 s40, v244, 49
	s_cmpk_gt_u32 s27, 0xff
	v_readlane_b32 s41, v244, 50
	v_readlane_b32 s46, v244, 55
	v_readlane_b32 s47, v244, 56
	v_readlane_b32 s48, v244, 57
	v_readlane_b32 s49, v244, 58
	v_readlane_b32 s50, v244, 59
	v_readlane_b32 s51, v244, 60
	v_readlane_b32 s42, v244, 51
	v_readlane_b32 s43, v244, 52
	v_readlane_b32 s44, v244, 53
	v_readlane_b32 s45, v244, 54
	v_readlane_b32 s52, v244, 61
	v_readlane_b32 s53, v244, 62
	v_readlane_b32 s54, v244, 63
	v_readlane_b32 s55, v243, 0
	s_cbranch_scc1 .LBB0_121
	s_barrier

.LBB0_136:
	s_ashr_i32 s9, s8, 31
	s_lshl_b64 s[12:13], s[8:9], 18
	s_add_u32 s12, s23, s12
	s_addc_u32 s13, s27, s13
	s_and_b64 s[14:15], s[20:21], exec
	s_cselect_b32 s9, s13, s17
	s_cselect_b32 s39, s12, s16
	s_ashr_i32 s11, s10, 31
	s_lshl_b64 s[14:15], s[10:11], 18
	s_add_u32 s14, s24, s14
	s_addc_u32 s15, s25, s15
	s_and_b64 s[20:21], s[20:21], exec
	s_cselect_b32 s11, s15, s19
	s_cselect_b32 s40, s14, s18
	s_add_u32 s16, s16, 0x20080
	s_addc_u32 s17, s17, 0
	s_add_u32 s41, s18, 0x100
	v_mov_b32_e32 v0, 0
	s_addc_u32 s42, s19, 0
	s_mov_b32 s43, -2
	v_mov_b32_e32 v1, v0
	v_mov_b32_e32 v2, v0
	v_mov_b32_e32 v3, v0
	v_mov_b32_e32 v32, v0
	v_mov_b32_e32 v33, v0
	v_mov_b32_e32 v34, v0
	v_mov_b32_e32 v35, v0
	v_mov_b32_e32 v4, v0
	v_mov_b32_e32 v5, v0
	v_mov_b32_e32 v6, v0
	v_mov_b32_e32 v7, v0
	v_mov_b32_e32 v36, v0
	v_mov_b32_e32 v37, v0
	v_mov_b32_e32 v38, v0
	v_mov_b32_e32 v39, v0
	v_mov_b32_e32 v8, v0
	v_mov_b32_e32 v9, v0
	v_mov_b32_e32 v10, v0
	v_mov_b32_e32 v11, v0
	v_mov_b32_e32 v40, v0
	v_mov_b32_e32 v41, v0
	v_mov_b32_e32 v42, v0
	v_mov_b32_e32 v43, v0
	v_mov_b32_e32 v12, v0
	v_mov_b32_e32 v13, v0
	v_mov_b32_e32 v14, v0
	v_mov_b32_e32 v15, v0
	v_mov_b32_e32 v44, v0
	v_mov_b32_e32 v45, v0
	v_mov_b32_e32 v46, v0
	v_mov_b32_e32 v47, v0
	v_mov_b32_e32 v64, v0
	v_mov_b32_e32 v65, v0
	v_mov_b32_e32 v66, v0
	v_mov_b32_e32 v67, v0
	v_mov_b32_e32 v96, v0
	v_mov_b32_e32 v97, v0
	v_mov_b32_e32 v98, v0
	v_mov_b32_e32 v99, v0
	v_mov_b32_e32 v68, v0
	v_mov_b32_e32 v69, v0
	v_mov_b32_e32 v70, v0
	v_mov_b32_e32 v71, v0
	v_mov_b32_e32 v100, v0
	v_mov_b32_e32 v101, v0
	v_mov_b32_e32 v102, v0
	v_mov_b32_e32 v103, v0
	v_mov_b32_e32 v72, v0
	v_mov_b32_e32 v73, v0
	v_mov_b32_e32 v74, v0
	v_mov_b32_e32 v75, v0
	v_mov_b32_e32 v104, v0
	v_mov_b32_e32 v105, v0
	v_mov_b32_e32 v106, v0
	v_mov_b32_e32 v107, v0
	v_mov_b32_e32 v76, v0
	v_mov_b32_e32 v77, v0
	v_mov_b32_e32 v78, v0
	v_mov_b32_e32 v79, v0
	v_mov_b32_e32 v108, v0
	v_mov_b32_e32 v109, v0
	v_mov_b32_e32 v110, v0
	v_mov_b32_e32 v111, v0
	v_mov_b32_e32 v16, v0
	v_mov_b32_e32 v17, v0
	v_mov_b32_e32 v18, v0
	v_mov_b32_e32 v19, v0
	v_mov_b32_e32 v48, v0
	v_mov_b32_e32 v49, v0
	v_mov_b32_e32 v50, v0
	v_mov_b32_e32 v51, v0
	v_mov_b32_e32 v20, v0
	v_mov_b32_e32 v21, v0
	v_mov_b32_e32 v22, v0
	v_mov_b32_e32 v23, v0
	v_mov_b32_e32 v52, v0
	v_mov_b32_e32 v53, v0
	v_mov_b32_e32 v54, v0
	v_mov_b32_e32 v55, v0
	v_mov_b32_e32 v24, v0
	v_mov_b32_e32 v25, v0
	v_mov_b32_e32 v26, v0
	v_mov_b32_e32 v27, v0
	v_mov_b32_e32 v56, v0
	v_mov_b32_e32 v57, v0
	v_mov_b32_e32 v58, v0
	v_mov_b32_e32 v59, v0
	v_mov_b32_e32 v28, v0
	v_mov_b32_e32 v29, v0
	v_mov_b32_e32 v30, v0
	v_mov_b32_e32 v31, v0
	v_mov_b32_e32 v60, v0
	v_mov_b32_e32 v61, v0
	v_mov_b32_e32 v62, v0
	v_mov_b32_e32 v63, v0
	v_mov_b32_e32 v80, v0
	v_mov_b32_e32 v81, v0
	v_mov_b32_e32 v82, v0
	v_mov_b32_e32 v83, v0
	v_mov_b32_e32 v112, v0
	v_mov_b32_e32 v113, v0
	v_mov_b32_e32 v114, v0
	v_mov_b32_e32 v115, v0
	v_mov_b32_e32 v84, v0
	v_mov_b32_e32 v85, v0
	v_mov_b32_e32 v86, v0
	v_mov_b32_e32 v87, v0
	v_mov_b32_e32 v116, v0
	v_mov_b32_e32 v117, v0
	v_mov_b32_e32 v118, v0
	v_mov_b32_e32 v119, v0
	v_mov_b32_e32 v88, v0
	v_mov_b32_e32 v89, v0
	v_mov_b32_e32 v90, v0
	v_mov_b32_e32 v91, v0
	v_mov_b32_e32 v120, v0
	v_mov_b32_e32 v121, v0
	v_mov_b32_e32 v122, v0
	v_mov_b32_e32 v123, v0
	v_mov_b32_e32 v92, v0
	v_mov_b32_e32 v93, v0
	v_mov_b32_e32 v94, v0
	v_mov_b32_e32 v95, v0
	v_mov_b32_e32 v124, v0
	v_mov_b32_e32 v125, v0
	v_mov_b32_e32 v126, v0
	v_mov_b32_e32 v127, v0
	s_mov_b64 s[48:49], 0x80
	v_add_u32_e32 v152, 0x10000, v146
	ds_read_b128 v[134:137], v152
	ds_read_b128 v[138:141], v152 offset:1024
	ds_read_b128 v[148:151], v152 offset:2048
	ds_read_b128 v[152:155], v152 offset:3072
.LBB0_137:
	s_add_u32 s18, s16, 0xfffe0080
	s_addc_u32 s19, s17, -1
	s_add_i32 s44, 0, 0x10000
	v_add_u32_e32 v142, s44, v146
	s_cmp_eq_u32 s43, 4
	s_cselect_b32 s21, s9, s19
	s_cselect_b32 s20, s39, s18
	s_cselect_b32 s19, s11, s42
	s_cselect_b32 s18, s40, s41
	v_lshl_add_u64 v[142:143], s[16:17], 0, v[130:131]
	s_add_i32 m0, s29, 0xc000
	ds_read_b128 v[156:159], v147
	ds_read_b128 v[160:163], v147 offset:1024
	ds_read_b128 v[164:167], v147 offset:2048
	ds_read_b128 v[168:171], v147 offset:3072
	ds_read_b128 v[172:175], v147 offset:4096
	ds_read_b128 v[176:179], v147 offset:5120
	ds_read_b128 v[180:183], v147 offset:6144
	ds_read_b128 v[188:191], v147 offset:7168
	global_load_lds_dwordx4 v[142:143], off
	v_lshl_add_u64 v[142:143], s[16:17], 0, v[132:133]
	s_add_i32 m0, s29, 0xe000
	s_nop 0
	global_load_lds_dwordx4 v[142:143], off
	s_waitcnt lgkmcnt(8)
	s_setprio 1
	s_barrier
	s_waitcnt lgkmcnt(0)
	v_mfma_f32_16x16x32_bf16 v[124:127], v[134:137], v[156:159], v[124:127]
	v_mfma_f32_16x16x32_bf16 v[92:95], v[148:151], v[156:159], v[92:95]
	v_mfma_f32_16x16x32_bf16 v[120:123], v[134:137], v[164:167], v[120:123]
	v_mfma_f32_16x16x32_bf16 v[88:91], v[148:151], v[164:167], v[88:91]
	v_mfma_f32_16x16x32_bf16 v[116:119], v[134:137], v[172:175], v[116:119]
	v_mfma_f32_16x16x32_bf16 v[84:87], v[148:151], v[172:175], v[84:87]
	v_mfma_f32_16x16x32_bf16 v[112:115], v[134:137], v[180:183], v[112:115]
	v_mfma_f32_16x16x32_bf16 v[80:83], v[148:151], v[180:183], v[80:83]
	v_mfma_f32_16x16x32_bf16 v[124:127], v[138:141], v[160:163], v[124:127]
	v_mfma_f32_16x16x32_bf16 v[92:95], v[152:155], v[160:163], v[92:95]
	v_mfma_f32_16x16x32_bf16 v[120:123], v[138:141], v[168:171], v[120:123]
	v_mfma_f32_16x16x32_bf16 v[88:91], v[152:155], v[168:171], v[88:91]
	v_mfma_f32_16x16x32_bf16 v[116:119], v[138:141], v[176:179], v[116:119]
	v_mfma_f32_16x16x32_bf16 v[84:87], v[152:155], v[176:179], v[84:87]
	v_mfma_f32_16x16x32_bf16 v[112:115], v[138:141], v[188:191], v[112:115]
	v_mfma_f32_16x16x32_bf16 v[80:83], v[152:155], v[188:191], v[80:83]
	s_barrier
	s_setprio 0
	s_add_i32 s46, 0, 0x14000
	v_add_u32_e32 v142, s46, v146
	s_add_i32 s44, s44, s28
	ds_read_b128 v[192:195], v142
	ds_read_b128 v[202:205], v142 offset:1024
	ds_read_b128 v[206:209], v142 offset:2048
	ds_read_b128 v[210:213], v142 offset:3072
	v_lshl_add_u64 v[142:143], s[18:19], 0, v[184:185]
	s_mov_b32 m0, s44
	v_lshl_add_u64 v[196:197], s[18:19], 0, v[128:129]
	global_load_lds_dwordx4 v[142:143], off
	s_add_i32 m0, s44, 0x2000
	s_nop 0
	global_load_lds_dwordx4 v[196:197], off
	s_setprio 1
	s_barrier
	s_waitcnt lgkmcnt(0)
	v_mfma_f32_16x16x32_bf16 v[60:63], v[192:195], v[156:159], v[60:63]
	v_mfma_f32_16x16x32_bf16 v[28:31], v[206:209], v[156:159], v[28:31]
	v_mfma_f32_16x16x32_bf16 v[56:59], v[192:195], v[164:167], v[56:59]
	v_mfma_f32_16x16x32_bf16 v[24:27], v[206:209], v[164:167], v[24:27]
	v_mfma_f32_16x16x32_bf16 v[52:55], v[192:195], v[172:175], v[52:55]
	v_mfma_f32_16x16x32_bf16 v[20:23], v[206:209], v[172:175], v[20:23]
	v_mfma_f32_16x16x32_bf16 v[48:51], v[192:195], v[180:183], v[48:51]
	v_mfma_f32_16x16x32_bf16 v[16:19], v[206:209], v[180:183], v[16:19]
	v_mfma_f32_16x16x32_bf16 v[60:63], v[202:205], v[160:163], v[60:63]
	v_mfma_f32_16x16x32_bf16 v[28:31], v[210:213], v[160:163], v[28:31]
	v_mfma_f32_16x16x32_bf16 v[56:59], v[202:205], v[168:171], v[56:59]
	v_mfma_f32_16x16x32_bf16 v[24:27], v[210:213], v[168:171], v[24:27]
	v_mfma_f32_16x16x32_bf16 v[52:55], v[202:205], v[176:179], v[52:55]
	v_mfma_f32_16x16x32_bf16 v[20:23], v[210:213], v[176:179], v[20:23]
	v_mfma_f32_16x16x32_bf16 v[48:51], v[202:205], v[188:191], v[48:51]
	v_mfma_f32_16x16x32_bf16 v[16:19], v[210:213], v[188:191], v[16:19]
	s_barrier
	s_setprio 0
	s_mov_b32 m0, s29
	v_lshl_add_u64 v[214:215], s[20:21], 0, v[184:185]
	ds_read_b128 v[156:159], v147 offset:16384
	ds_read_b128 v[160:163], v147 offset:17408
	ds_read_b128 v[164:167], v147 offset:18432
	ds_read_b128 v[168:171], v147 offset:19456
	ds_read_b128 v[172:175], v147 offset:20480
	ds_read_b128 v[176:179], v147 offset:21504
	ds_read_b128 v[180:183], v147 offset:22528
	ds_read_b128 v[188:191], v147 offset:23552
	global_load_lds_dwordx4 v[214:215], off
	v_lshl_add_u64 v[216:217], s[20:21], 0, v[128:129]
	s_mov_b32 m0, s30
	s_nop 0
	global_load_lds_dwordx4 v[216:217], off
	s_setprio 1
	s_waitcnt vmcnt(10)
	s_barrier
	s_waitcnt lgkmcnt(0)
	v_mfma_f32_16x16x32_bf16 v[108:111], v[134:137], v[156:159], v[108:111]
	v_mfma_f32_16x16x32_bf16 v[76:79], v[148:151], v[156:159], v[76:79]
	v_mfma_f32_16x16x32_bf16 v[104:107], v[134:137], v[164:167], v[104:107]
	v_mfma_f32_16x16x32_bf16 v[72:75], v[148:151], v[164:167], v[72:75]
	v_mfma_f32_16x16x32_bf16 v[100:103], v[134:137], v[172:175], v[100:103]
	v_mfma_f32_16x16x32_bf16 v[68:71], v[148:151], v[172:175], v[68:71]
	v_mfma_f32_16x16x32_bf16 v[96:99], v[134:137], v[180:183], v[96:99]
	v_mfma_f32_16x16x32_bf16 v[64:67], v[148:151], v[180:183], v[64:67]
	v_mfma_f32_16x16x32_bf16 v[108:111], v[138:141], v[160:163], v[108:111]
	v_mfma_f32_16x16x32_bf16 v[76:79], v[152:155], v[160:163], v[76:79]
	v_mfma_f32_16x16x32_bf16 v[104:107], v[138:141], v[168:171], v[104:107]
	v_mfma_f32_16x16x32_bf16 v[72:75], v[152:155], v[168:171], v[72:75]
	v_mfma_f32_16x16x32_bf16 v[100:103], v[138:141], v[176:179], v[100:103]
	v_mfma_f32_16x16x32_bf16 v[68:71], v[152:155], v[176:179], v[68:71]
	v_mfma_f32_16x16x32_bf16 v[96:99], v[138:141], v[188:191], v[96:99]
	v_mfma_f32_16x16x32_bf16 v[64:67], v[152:155], v[188:191], v[64:67]
	s_barrier
	s_setprio 0
	v_add_u32_e32 v152, 0x18000, v146
	ds_read_b128 v[134:137], v152
	ds_read_b128 v[138:141], v152 offset:1024
	ds_read_b128 v[148:151], v152 offset:2048
	ds_read_b128 v[152:155], v152 offset:3072
	s_add_u32 s44, s18, 0x20000
	s_addc_u32 s45, s19, 0
	s_add_i32 s46, s46, s28
	v_lshl_add_u64 v[246:247], s[44:45], 0, v[184:185]
	s_mov_b32 m0, s46
	s_nop 0
	global_load_lds_dwordx4 v[246:247], off
	v_lshl_add_u64 v[248:249], s[44:45], 0, v[128:129]
	s_add_i32 m0, s46, 0x2000
	s_nop 0
	global_load_lds_dwordx4 v[248:249], off
	s_waitcnt vmcnt(6)
	s_setprio 1
	s_barrier
	v_mfma_f32_16x16x32_bf16 v[44:47], v[192:195], v[156:159], v[44:47]
	v_mfma_f32_16x16x32_bf16 v[12:15], v[206:209], v[156:159], v[12:15]
	v_mfma_f32_16x16x32_bf16 v[40:43], v[192:195], v[164:167], v[40:43]
	v_mfma_f32_16x16x32_bf16 v[8:11], v[206:209], v[164:167], v[8:11]
	v_mfma_f32_16x16x32_bf16 v[36:39], v[192:195], v[172:175], v[36:39]
	v_mfma_f32_16x16x32_bf16 v[4:7], v[206:209], v[172:175], v[4:7]
	v_mfma_f32_16x16x32_bf16 v[32:35], v[192:195], v[180:183], v[32:35]
	v_mfma_f32_16x16x32_bf16 v[0:3], v[206:209], v[180:183], v[0:3]
	v_mfma_f32_16x16x32_bf16 v[44:47], v[202:205], v[160:163], v[44:47]
	v_mfma_f32_16x16x32_bf16 v[12:15], v[210:213], v[160:163], v[12:15]
	v_mfma_f32_16x16x32_bf16 v[40:43], v[202:205], v[168:171], v[40:43]
	v_mfma_f32_16x16x32_bf16 v[8:11], v[210:213], v[168:171], v[8:11]
	v_mfma_f32_16x16x32_bf16 v[36:39], v[202:205], v[176:179], v[36:39]
	v_mfma_f32_16x16x32_bf16 v[4:7], v[210:213], v[176:179], v[4:7]
	v_mfma_f32_16x16x32_bf16 v[32:35], v[202:205], v[188:191], v[32:35]
	v_mfma_f32_16x16x32_bf16 v[0:3], v[210:213], v[188:191], v[0:3]
	s_barrier
	s_setprio 0
	s_add_i32 s44, 0, 0x18000
	s_add_u32 s20, s20, 0x20000
	s_addc_u32 s21, s21, 0
	s_mov_b32 m0, s31
	v_lshl_add_u64 v[192:193], s[20:21], 0, v[184:185]
	ds_read_b128 v[156:159], v147 offset:32768
	ds_read_b128 v[160:163], v147 offset:33792
	ds_read_b128 v[164:167], v147 offset:34816
	ds_read_b128 v[168:171], v147 offset:35840
	ds_read_b128 v[172:175], v147 offset:36864
	ds_read_b128 v[176:179], v147 offset:37888
	ds_read_b128 v[180:183], v147 offset:38912
	ds_read_b128 v[188:191], v147 offset:39936
	global_load_lds_dwordx4 v[192:193], off
	v_lshl_add_u64 v[192:193], s[20:21], 0, v[128:129]
	s_mov_b32 m0, s33
	s_nop 0
	global_load_lds_dwordx4 v[192:193], off
	s_waitcnt lgkmcnt(8)
	s_setprio 1
	s_barrier
	s_waitcnt lgkmcnt(0)
	v_mfma_f32_16x16x32_bf16 v[124:127], v[134:137], v[156:159], v[124:127]
	v_mfma_f32_16x16x32_bf16 v[92:95], v[148:151], v[156:159], v[92:95]
	v_mfma_f32_16x16x32_bf16 v[120:123], v[134:137], v[164:167], v[120:123]
	v_mfma_f32_16x16x32_bf16 v[88:91], v[148:151], v[164:167], v[88:91]
	v_mfma_f32_16x16x32_bf16 v[116:119], v[134:137], v[172:175], v[116:119]
	v_mfma_f32_16x16x32_bf16 v[84:87], v[148:151], v[172:175], v[84:87]
	v_mfma_f32_16x16x32_bf16 v[112:115], v[134:137], v[180:183], v[112:115]
	v_mfma_f32_16x16x32_bf16 v[80:83], v[148:151], v[180:183], v[80:83]
	v_mfma_f32_16x16x32_bf16 v[124:127], v[138:141], v[160:163], v[124:127]
	v_mfma_f32_16x16x32_bf16 v[92:95], v[152:155], v[160:163], v[92:95]
	v_mfma_f32_16x16x32_bf16 v[120:123], v[138:141], v[168:171], v[120:123]
	v_mfma_f32_16x16x32_bf16 v[88:91], v[152:155], v[168:171], v[88:91]
	v_mfma_f32_16x16x32_bf16 v[116:119], v[138:141], v[176:179], v[116:119]
	v_mfma_f32_16x16x32_bf16 v[84:87], v[152:155], v[176:179], v[84:87]
	v_mfma_f32_16x16x32_bf16 v[112:115], v[138:141], v[188:191], v[112:115]
	v_mfma_f32_16x16x32_bf16 v[80:83], v[152:155], v[188:191], v[80:83]
	s_barrier
	s_setprio 0
	s_add_i32 s20, 0, 0x1c000
	s_add_i32 s21, s44, s28
	v_add_u32_e32 v187, s20, v146
	v_lshl_add_u64 v[142:143], v[142:143], 0, s[48:49]
	s_mov_b32 m0, s21
	ds_read_b128 v[192:195], v187
	ds_read_b128 v[202:205], v187 offset:1024
	ds_read_b128 v[206:209], v187 offset:2048
	ds_read_b128 v[210:213], v187 offset:3072
	global_load_lds_dwordx4 v[142:143], off
	v_lshl_add_u64 v[142:143], v[196:197], 0, s[48:49]
	s_add_i32 m0, s21, 0x2000
	s_nop 0
	global_load_lds_dwordx4 v[142:143], off
	s_setprio 1
	s_barrier
	s_waitcnt lgkmcnt(0)
	v_mfma_f32_16x16x32_bf16 v[60:63], v[192:195], v[156:159], v[60:63]
	v_mfma_f32_16x16x32_bf16 v[28:31], v[206:209], v[156:159], v[28:31]
	v_mfma_f32_16x16x32_bf16 v[56:59], v[192:195], v[164:167], v[56:59]
	v_mfma_f32_16x16x32_bf16 v[24:27], v[206:209], v[164:167], v[24:27]
	v_mfma_f32_16x16x32_bf16 v[52:55], v[192:195], v[172:175], v[52:55]
	v_mfma_f32_16x16x32_bf16 v[20:23], v[206:209], v[172:175], v[20:23]
	v_mfma_f32_16x16x32_bf16 v[48:51], v[192:195], v[180:183], v[48:51]
	v_mfma_f32_16x16x32_bf16 v[16:19], v[206:209], v[180:183], v[16:19]
	v_mfma_f32_16x16x32_bf16 v[60:63], v[202:205], v[160:163], v[60:63]
	v_mfma_f32_16x16x32_bf16 v[28:31], v[210:213], v[160:163], v[28:31]
	v_mfma_f32_16x16x32_bf16 v[56:59], v[202:205], v[168:171], v[56:59]
	v_mfma_f32_16x16x32_bf16 v[24:27], v[210:213], v[168:171], v[24:27]
	v_mfma_f32_16x16x32_bf16 v[52:55], v[202:205], v[176:179], v[52:55]
	v_mfma_f32_16x16x32_bf16 v[20:23], v[210:213], v[176:179], v[20:23]
	v_mfma_f32_16x16x32_bf16 v[48:51], v[202:205], v[188:191], v[48:51]
	v_mfma_f32_16x16x32_bf16 v[16:19], v[210:213], v[188:191], v[16:19]
	s_barrier
	s_setprio 0
	s_mov_b32 m0, s36
	v_lshl_add_u64 v[142:143], v[214:215], 0, s[48:49]
	ds_read_b128 v[156:159], v147 offset:49152
	ds_read_b128 v[160:163], v147 offset:50176
	ds_read_b128 v[164:167], v147 offset:51200
	ds_read_b128 v[168:171], v147 offset:52224
	ds_read_b128 v[172:175], v147 offset:53248
	ds_read_b128 v[176:179], v147 offset:54272
	ds_read_b128 v[180:183], v147 offset:55296
	ds_read_b128 v[188:191], v147 offset:56320
	global_load_lds_dwordx4 v[142:143], off
	v_lshl_add_u64 v[142:143], v[216:217], 0, s[48:49]
	s_mov_b32 m0, s37
	s_nop 0
	global_load_lds_dwordx4 v[142:143], off
	s_setprio 1
	s_waitcnt vmcnt(10)
	s_barrier
	s_waitcnt lgkmcnt(0)
	v_mfma_f32_16x16x32_bf16 v[108:111], v[134:137], v[156:159], v[108:111]
	v_mfma_f32_16x16x32_bf16 v[76:79], v[148:151], v[156:159], v[76:79]
	v_mfma_f32_16x16x32_bf16 v[104:107], v[134:137], v[164:167], v[104:107]
	v_mfma_f32_16x16x32_bf16 v[72:75], v[148:151], v[164:167], v[72:75]
	v_mfma_f32_16x16x32_bf16 v[100:103], v[134:137], v[172:175], v[100:103]
	v_mfma_f32_16x16x32_bf16 v[68:71], v[148:151], v[172:175], v[68:71]
	v_mfma_f32_16x16x32_bf16 v[96:99], v[134:137], v[180:183], v[96:99]
	v_mfma_f32_16x16x32_bf16 v[64:67], v[148:151], v[180:183], v[64:67]
	v_mfma_f32_16x16x32_bf16 v[108:111], v[138:141], v[160:163], v[108:111]
	v_mfma_f32_16x16x32_bf16 v[76:79], v[152:155], v[160:163], v[76:79]
	v_mfma_f32_16x16x32_bf16 v[104:107], v[138:141], v[168:171], v[104:107]
	v_mfma_f32_16x16x32_bf16 v[72:75], v[152:155], v[168:171], v[72:75]
	v_mfma_f32_16x16x32_bf16 v[100:103], v[138:141], v[176:179], v[100:103]
	v_mfma_f32_16x16x32_bf16 v[68:71], v[152:155], v[176:179], v[68:71]
	v_mfma_f32_16x16x32_bf16 v[96:99], v[138:141], v[188:191], v[96:99]
	v_mfma_f32_16x16x32_bf16 v[64:67], v[152:155], v[188:191], v[64:67]
	s_barrier
	s_setprio 0
	v_add_u32_e32 v152, 0x10000, v146
	ds_read_b128 v[134:137], v152
	ds_read_b128 v[138:141], v152 offset:1024
	ds_read_b128 v[148:151], v152 offset:2048
	ds_read_b128 v[152:155], v152 offset:3072
	s_add_u32 s18, s18, 0x20080
	s_addc_u32 s19, s19, 0
	s_add_i32 s20, s20, s28
	v_lshl_add_u64 v[250:251], s[18:19], 0, v[184:185]
	s_mov_b32 m0, s20
	s_nop 0
	global_load_lds_dwordx4 v[250:251], off
	v_lshl_add_u64 v[252:253], s[18:19], 0, v[128:129]
	s_add_i32 m0, s20, 0x2000
	s_nop 0
	global_load_lds_dwordx4 v[252:253], off
	s_waitcnt vmcnt(6)
	s_setprio 1
	s_barrier
	v_mfma_f32_16x16x32_bf16 v[44:47], v[192:195], v[156:159], v[44:47]
	v_mfma_f32_16x16x32_bf16 v[12:15], v[206:209], v[156:159], v[12:15]
	v_mfma_f32_16x16x32_bf16 v[40:43], v[192:195], v[164:167], v[40:43]
	v_mfma_f32_16x16x32_bf16 v[8:11], v[206:209], v[164:167], v[8:11]
	v_mfma_f32_16x16x32_bf16 v[36:39], v[192:195], v[172:175], v[36:39]
	v_mfma_f32_16x16x32_bf16 v[4:7], v[206:209], v[172:175], v[4:7]
	v_mfma_f32_16x16x32_bf16 v[32:35], v[192:195], v[180:183], v[32:35]
	v_mfma_f32_16x16x32_bf16 v[0:3], v[206:209], v[180:183], v[0:3]
	v_mfma_f32_16x16x32_bf16 v[44:47], v[202:205], v[160:163], v[44:47]
	v_mfma_f32_16x16x32_bf16 v[12:15], v[210:213], v[160:163], v[12:15]
	v_mfma_f32_16x16x32_bf16 v[40:43], v[202:205], v[168:171], v[40:43]
	v_mfma_f32_16x16x32_bf16 v[8:11], v[210:213], v[168:171], v[8:11]
	v_mfma_f32_16x16x32_bf16 v[36:39], v[202:205], v[176:179], v[36:39]
	v_mfma_f32_16x16x32_bf16 v[4:7], v[210:213], v[176:179], v[4:7]
	v_mfma_f32_16x16x32_bf16 v[32:35], v[202:205], v[188:191], v[32:35]
	v_mfma_f32_16x16x32_bf16 v[0:3], v[210:213], v[188:191], v[0:3]
	s_barrier
	s_setprio 0
	s_add_i32 s43, s43, 2
	s_add_u32 s16, s16, 0x100
	s_addc_u32 s17, s17, 0
	s_add_u32 s41, s41, 0x100
	s_addc_u32 s42, s42, 0
	s_cmp_gt_u32 s43, 5
	s_cbranch_scc0 .LBB0_137
	s_waitcnt lgkmcnt(0)
	s_lshl_b32 s0, s0, 8
	v_mov_b32_e32 v134, v145
	v_mov_b32_e32 v135, v144
	s_add_i32 s0, s0, s34
	s_mov_b32 s20, 0x3a0637bd
	v_add_u32_e32 v142, s0, v135
	s_lshl_b32 s0, s1, 8
	v_lshlrev_b32_e32 v135, 1, v134
	v_lshrrev_b32_e32 v136, 1, v134
	s_or_b32 s16, s0, s35
	v_and_or_b32 v135, v135, 2, v136
	v_lshl_add_u32 v134, v134, 2, s16
	v_lshlrev_b32_e32 v136, 2, v135
	v_ashrrev_i32_e32 v135, 31, v134
	v_lshlrev_b64 v[138:139], 5, v[134:135]
	v_lshl_add_u64 v[156:157], s[4:5], 0, v[138:139]
	global_load_dwordx4 v[138:141], v[156:157], off offset:16
	global_load_dwordx4 v[148:151], v[156:157], off offset:48
	global_load_dwordx4 v[152:155], v[156:157], off
	s_nop 0
	global_load_dwordx4 v[156:159], v[156:157], off offset:32
	s_mov_b32 s40, 0x3b000000
	s_mov_b32 s18, 0x45800000
	v_ashrrev_i32_e32 v143, 31, v142
	v_ashrrev_i32_e32 v137, 31, v136
	s_ashr_i32 s17, s16, 31
	s_waitcnt vmcnt(0)
	v_mov_b32_e32 v160, v152
	v_mov_b32_e32 v161, v156
	v_mov_b32_e32 v156, v153
	v_pk_add_f32 v[152:153], v[160:161], v[156:157]
	v_mov_b32_e32 v156, v154
	v_mov_b32_e32 v157, v158
	v_pk_add_f32 v[152:153], v[156:157], v[152:153]
	v_mov_b32_e32 v158, v155
	v_pk_add_f32 v[152:153], v[158:159], v[152:153]
	v_mov_b32_e32 v154, v138
	v_mov_b32_e32 v155, v148
	v_pk_add_f32 v[152:153], v[154:155], v[152:153]
	v_mov_b32_e32 v148, v139
	v_pk_add_f32 v[138:139], v[148:149], v[152:153]
	v_mov_b32_e32 v148, v140
	v_mov_b32_e32 v149, v150
	v_pk_add_f32 v[138:139], v[148:149], v[138:139]
	v_mov_b32_e32 v150, v141
	v_pk_add_f32 v[138:139], v[150:151], v[138:139]
	s_nop 0
	v_pk_add_f32 v[138:139], v[138:139], s[20:21] op_sel_hi:[1,0]
	s_nop 0
	v_pk_mul_f32 v[138:139], v[138:139], s[40:41] op_sel_hi:[1,0]
	s_nop 0
	v_mul_f32_e32 v135, 0x4b800000, v138
	v_cmp_gt_f32_e64 s[0:1], s67, v138
	v_cmp_gt_f32_e32 vcc, s67, v139
	s_nop 0
	v_cndmask_b32_e64 v135, v138, v135, s[0:1]
	v_rsq_f32_e32 v138, v135
	v_mul_f32_e32 v135, 0x4b800000, v139
	v_cndmask_b32_e32 v135, v139, v135, vcc
	v_rsq_f32_e32 v139, v135
	s_nop 0
	v_pk_mul_f32 v[140:141], v[138:139], s[18:19] op_sel_hi:[1,0]
	s_nop 0
	v_cndmask_b32_e64 v138, v138, v140, s[0:1]
	v_or_b32_e32 v140, 2, v134
	v_cndmask_b32_e32 v139, v139, v141, vcc
	v_ashrrev_i32_e32 v141, 31, v140
	v_lshlrev_b64 v[140:141], 5, v[140:141]
	v_lshl_add_u64 v[140:141], s[4:5], 0, v[140:141]
	global_load_dwordx4 v[148:151], v[140:141], off offset:16
	global_load_dwordx4 v[152:155], v[140:141], off offset:48
	global_load_dwordx4 v[156:159], v[140:141], off
	global_load_dwordx4 v[160:163], v[140:141], off offset:32
	v_pk_mul_f32 v[124:125], v[124:125], v[138:139]
	v_pk_mul_f32 v[120:121], v[120:121], v[138:139]
	v_pk_mul_f32 v[116:117], v[116:117], v[138:139]
	v_pk_mul_f32 v[112:113], v[112:113], v[138:139]
	v_pk_mul_f32 v[108:109], v[108:109], v[138:139]
	v_pk_mul_f32 v[104:105], v[104:105], v[138:139]
	v_pk_mul_f32 v[100:101], v[100:101], v[138:139]
	v_pk_mul_f32 v[96:97], v[96:97], v[138:139]
	s_waitcnt vmcnt(0)
	v_mov_b32_e32 v140, v156
	v_mov_b32_e32 v141, v160
	v_mov_b32_e32 v160, v157
	v_pk_add_f32 v[140:141], v[140:141], v[160:161]
	v_mov_b32_e32 v156, v158
	v_mov_b32_e32 v157, v162
	v_pk_add_f32 v[140:141], v[156:157], v[140:141]
	v_mov_b32_e32 v162, v159
	v_pk_add_f32 v[140:141], v[162:163], v[140:141]
	v_mov_b32_e32 v156, v148
	v_mov_b32_e32 v157, v152
	v_pk_add_f32 v[140:141], v[156:157], v[140:141]
	v_mov_b32_e32 v152, v149
	v_pk_add_f32 v[140:141], v[152:153], v[140:141]
	v_mov_b32_e32 v148, v150
	v_mov_b32_e32 v149, v154
	v_pk_add_f32 v[140:141], v[148:149], v[140:141]
	v_mov_b32_e32 v154, v151
	v_pk_add_f32 v[140:141], v[154:155], v[140:141]
	v_cvt_pk_bf16_f32 v150, v124, v125
	v_lshlrev_b64 v[124:125], 16, v[142:143]
	v_pk_add_f32 v[140:141], v[140:141], s[20:21] op_sel_hi:[1,0]
	v_lshl_add_u64 v[124:125], s[2:3], 0, v[124:125]
	v_pk_mul_f32 v[140:141], v[140:141], s[40:41] op_sel_hi:[1,0]
	s_nop 0
	v_mul_f32_e32 v135, 0x4b800000, v140
	v_cmp_gt_f32_e64 s[0:1], s67, v140
	v_cmp_gt_f32_e32 vcc, s67, v141
	s_nop 0
	v_cndmask_b32_e64 v135, v140, v135, s[0:1]
	v_rsq_f32_e32 v140, v135
	v_mul_f32_e32 v135, 0x4b800000, v141
	v_cndmask_b32_e32 v135, v141, v135, vcc
	v_rsq_f32_e32 v141, v135
	s_nop 0
	v_pk_mul_f32 v[148:149], v[140:141], s[18:19] op_sel_hi:[1,0]
	s_nop 0
	v_cndmask_b32_e32 v141, v141, v149, vcc
	v_cndmask_b32_e64 v140, v140, v148, s[0:1]
	v_add_u32_e32 v148, s16, v136
	v_ashrrev_i32_e32 v149, 31, v148
	v_pk_mul_f32 v[126:127], v[126:127], v[140:141]
	s_mov_b64 s[0:1], 0x100000
	v_cvt_pk_bf16_f32 v151, v126, v127
	v_lshlrev_b64 v[126:127], 1, v[148:149]
	v_lshl_add_u64 v[142:143], v[124:125], 0, v[126:127]
	global_store_dwordx2 v[142:143], v[150:151], off
	v_pk_mul_f32 v[122:123], v[122:123], v[140:141]
	v_cvt_pk_bf16_f32 v142, v120, v121
	v_lshl_add_u64 v[120:121], v[124:125], 0, s[0:1]
	v_cvt_pk_bf16_f32 v143, v122, v123
	v_lshl_add_u64 v[122:123], v[120:121], 0, v[126:127]
	s_mov_b64 s[0:1], 0x200000
	global_store_dwordx2 v[122:123], v[142:143], off
	v_pk_mul_f32 v[118:119], v[118:119], v[140:141]
	v_cvt_pk_bf16_f32 v122, v116, v117
	v_lshl_add_u64 v[116:117], v[124:125], 0, s[0:1]
	v_cvt_pk_bf16_f32 v123, v118, v119
	v_lshl_add_u64 v[118:119], v[116:117], 0, v[126:127]
	s_mov_b64 s[0:1], 0x300000
	global_store_dwordx2 v[118:119], v[122:123], off
	v_pk_mul_f32 v[114:115], v[114:115], v[140:141]
	v_cvt_pk_bf16_f32 v118, v112, v113
	v_lshl_add_u64 v[112:113], v[124:125], 0, s[0:1]
	v_cvt_pk_bf16_f32 v119, v114, v115
	v_lshl_add_u64 v[114:115], v[112:113], 0, v[126:127]
	s_mov_b64 s[0:1], 0x800000
	global_store_dwordx2 v[114:115], v[118:119], off
	v_pk_mul_f32 v[110:111], v[110:111], v[140:141]
	v_cvt_pk_bf16_f32 v114, v108, v109
	v_lshl_add_u64 v[108:109], v[124:125], 0, s[0:1]
	v_cvt_pk_bf16_f32 v115, v110, v111
	v_lshl_add_u64 v[110:111], v[108:109], 0, v[126:127]
	s_mov_b64 s[0:1], 0x900000
	global_store_dwordx2 v[110:111], v[114:115], off
	v_pk_mul_f32 v[106:107], v[106:107], v[140:141]
	v_cvt_pk_bf16_f32 v110, v104, v105
	v_lshl_add_u64 v[104:105], v[124:125], 0, s[0:1]
	v_cvt_pk_bf16_f32 v111, v106, v107
	v_lshl_add_u64 v[106:107], v[104:105], 0, v[126:127]
	s_mov_b64 s[0:1], 0xa00000
	global_store_dwordx2 v[106:107], v[110:111], off
	v_pk_mul_f32 v[102:103], v[102:103], v[140:141]
	v_cvt_pk_bf16_f32 v106, v100, v101
	v_lshl_add_u64 v[100:101], v[124:125], 0, s[0:1]
	v_cvt_pk_bf16_f32 v107, v102, v103
	v_lshl_add_u64 v[102:103], v[100:101], 0, v[126:127]
	s_mov_b64 s[0:1], 0xb00000
	global_store_dwordx2 v[102:103], v[106:107], off
	v_pk_mul_f32 v[98:99], v[98:99], v[140:141]
	v_cvt_pk_bf16_f32 v102, v96, v97
	v_lshl_add_u64 v[96:97], v[124:125], 0, s[0:1]
	v_cvt_pk_bf16_f32 v103, v98, v99
	v_lshl_add_u64 v[98:99], v[96:97], 0, v[126:127]
	global_store_dwordx2 v[98:99], v[102:103], off
	v_add_u32_e32 v98, 16, v134
	v_ashrrev_i32_e32 v99, 31, v98
	v_lshlrev_b64 v[98:99], 5, v[98:99]
	v_lshl_add_u64 v[98:99], s[4:5], 0, v[98:99]
	global_load_dwordx4 v[138:141], v[98:99], off offset:16
	global_load_dwordx4 v[148:151], v[98:99], off offset:48
	global_load_dwordx4 v[152:155], v[98:99], off
	global_load_dwordx4 v[156:159], v[98:99], off offset:32
	s_waitcnt vmcnt(0)
	v_mov_b32_e32 v98, v152
	v_mov_b32_e32 v99, v156
	v_mov_b32_e32 v156, v153
	v_pk_add_f32 v[98:99], v[98:99], v[156:157]
	v_mov_b32_e32 v102, v154
	v_mov_b32_e32 v103, v158
	v_pk_add_f32 v[98:99], v[102:103], v[98:99]
	v_mov_b32_e32 v158, v155
	v_pk_add_f32 v[98:99], v[158:159], v[98:99]
	v_mov_b32_e32 v102, v138
	v_mov_b32_e32 v103, v148
	v_pk_add_f32 v[98:99], v[102:103], v[98:99]
	v_mov_b32_e32 v148, v139
	v_pk_add_f32 v[98:99], v[148:149], v[98:99]
	v_mov_b32_e32 v102, v140
	v_mov_b32_e32 v103, v150
	v_pk_add_f32 v[98:99], v[102:103], v[98:99]
	v_mov_b32_e32 v150, v141
	v_pk_add_f32 v[98:99], v[150:151], v[98:99]
	s_nop 0
	v_pk_add_f32 v[98:99], v[98:99], s[20:21] op_sel_hi:[1,0]
	s_nop 0
	v_pk_mul_f32 v[98:99], v[98:99], s[40:41] op_sel_hi:[1,0]
	s_nop 0
	v_mul_f32_e32 v102, 0x4b800000, v98
	v_cmp_gt_f32_e64 s[0:1], s67, v98
	v_cmp_gt_f32_e32 vcc, s67, v99
	s_nop 0
	v_cndmask_b32_e64 v98, v98, v102, s[0:1]
	v_mul_f32_e32 v102, 0x4b800000, v99
	v_cndmask_b32_e32 v99, v99, v102, vcc
	v_rsq_f32_e32 v98, v98
	v_rsq_f32_e32 v99, v99
	s_nop 0
	v_pk_mul_f32 v[102:103], v[98:99], s[18:19] op_sel_hi:[1,0]
	s_nop 0
	v_cndmask_b32_e64 v98, v98, v102, s[0:1]
	v_add_u32_e32 v102, 18, v134
	v_cndmask_b32_e32 v99, v99, v103, vcc
	v_ashrrev_i32_e32 v103, 31, v102
	v_lshlrev_b64 v[102:103], 5, v[102:103]
	v_lshl_add_u64 v[102:103], s[4:5], 0, v[102:103]
	global_load_dwordx4 v[138:141], v[102:103], off offset:16
	global_load_dwordx4 v[148:151], v[102:103], off offset:48
	global_load_dwordx4 v[152:155], v[102:103], off
	global_load_dwordx4 v[156:159], v[102:103], off offset:32
	v_pk_mul_f32 v[92:93], v[92:93], v[98:99]
	v_pk_mul_f32 v[88:89], v[88:89], v[98:99]
	v_pk_mul_f32 v[84:85], v[84:85], v[98:99]
	v_pk_mul_f32 v[80:81], v[80:81], v[98:99]
	v_pk_mul_f32 v[76:77], v[76:77], v[98:99]
	v_pk_mul_f32 v[72:73], v[72:73], v[98:99]
	v_pk_mul_f32 v[68:69], v[68:69], v[98:99]
	v_pk_mul_f32 v[64:65], v[64:65], v[98:99]
	s_waitcnt vmcnt(0)
	v_mov_b32_e32 v102, v152
	v_mov_b32_e32 v103, v156
	v_mov_b32_e32 v156, v153
	v_pk_add_f32 v[102:103], v[102:103], v[156:157]
	v_mov_b32_e32 v106, v154
	v_mov_b32_e32 v107, v158
	v_pk_add_f32 v[102:103], v[106:107], v[102:103]
	v_mov_b32_e32 v158, v155
	v_pk_add_f32 v[102:103], v[158:159], v[102:103]
	v_mov_b32_e32 v106, v138
	v_mov_b32_e32 v107, v148
	v_pk_add_f32 v[102:103], v[106:107], v[102:103]
	v_mov_b32_e32 v148, v139
	v_pk_add_f32 v[102:103], v[148:149], v[102:103]
	v_mov_b32_e32 v106, v140
	v_mov_b32_e32 v107, v150
	v_pk_add_f32 v[102:103], v[106:107], v[102:103]
	v_mov_b32_e32 v150, v141
	v_pk_add_f32 v[102:103], v[150:151], v[102:103]
	s_nop 0
	v_pk_add_f32 v[102:103], v[102:103], s[20:21] op_sel_hi:[1,0]
	s_nop 0
	v_pk_mul_f32 v[102:103], v[102:103], s[40:41] op_sel_hi:[1,0]
	s_nop 0
	v_mul_f32_e32 v106, 0x4b800000, v102
	v_cmp_gt_f32_e64 s[0:1], s67, v102
	v_cmp_gt_f32_e32 vcc, s67, v103
	s_nop 0
	v_cndmask_b32_e64 v102, v102, v106, s[0:1]
	v_mul_f32_e32 v106, 0x4b800000, v103
	v_cndmask_b32_e32 v103, v103, v106, vcc
	v_rsq_f32_e32 v102, v102
	v_rsq_f32_e32 v103, v103
	s_nop 0
	v_pk_mul_f32 v[106:107], v[102:103], s[18:19] op_sel_hi:[1,0]
	s_nop 0
	v_cndmask_b32_e32 v103, v103, v107, vcc
	v_cndmask_b32_e64 v102, v102, v106, s[0:1]
	v_pk_mul_f32 v[94:95], v[94:95], v[102:103]
	v_cvt_pk_bf16_f32 v106, v92, v93
	v_lshl_add_u64 v[92:93], v[136:137], 0, s[16:17]
	v_cvt_pk_bf16_f32 v107, v94, v95
	v_lshlrev_b64 v[94:95], 1, v[92:93]
	v_lshl_add_u64 v[92:93], v[124:125], 0, v[94:95]
	global_store_dwordx2 v[92:93], v[106:107], off offset:32
	v_pk_mul_f32 v[90:91], v[90:91], v[102:103]
	v_cvt_pk_bf16_f32 v106, v88, v89
	v_lshl_add_u64 v[88:89], v[120:121], 0, v[94:95]
	v_cvt_pk_bf16_f32 v107, v90, v91
	global_store_dwordx2 v[88:89], v[106:107], off offset:32
	v_pk_mul_f32 v[86:87], v[86:87], v[102:103]
	v_cvt_pk_bf16_f32 v90, v84, v85
	v_lshl_add_u64 v[84:85], v[116:117], 0, v[94:95]
	v_cvt_pk_bf16_f32 v91, v86, v87
	global_store_dwordx2 v[84:85], v[90:91], off offset:32
	v_pk_mul_f32 v[82:83], v[82:83], v[102:103]
	v_cvt_pk_bf16_f32 v86, v80, v81
	v_lshl_add_u64 v[80:81], v[112:113], 0, v[94:95]
	v_cvt_pk_bf16_f32 v87, v82, v83
	global_store_dwordx2 v[80:81], v[86:87], off offset:32
	v_pk_mul_f32 v[78:79], v[78:79], v[102:103]
	v_cvt_pk_bf16_f32 v82, v76, v77
	v_lshl_add_u64 v[76:77], v[108:109], 0, v[94:95]
	v_cvt_pk_bf16_f32 v83, v78, v79
	global_store_dwordx2 v[76:77], v[82:83], off offset:32
	v_pk_mul_f32 v[74:75], v[74:75], v[102:103]
	v_cvt_pk_bf16_f32 v78, v72, v73
	v_lshl_add_u64 v[72:73], v[104:105], 0, v[94:95]
	v_cvt_pk_bf16_f32 v79, v74, v75
	global_store_dwordx2 v[72:73], v[78:79], off offset:32
	v_pk_mul_f32 v[70:71], v[70:71], v[102:103]
	v_cvt_pk_bf16_f32 v74, v68, v69
	v_lshl_add_u64 v[68:69], v[100:101], 0, v[94:95]
	v_pk_mul_f32 v[66:67], v[66:67], v[102:103]
	v_cvt_pk_bf16_f32 v75, v70, v71
	global_store_dwordx2 v[68:69], v[74:75], off offset:32
	v_cvt_pk_bf16_f32 v70, v64, v65
	v_cvt_pk_bf16_f32 v71, v66, v67
	v_add_u32_e32 v66, 0x80, v134
	v_ashrrev_i32_e32 v67, 31, v66
	v_lshl_add_u64 v[64:65], v[96:97], 0, v[94:95]
	v_lshlrev_b64 v[66:67], 5, v[66:67]
	global_store_dwordx2 v[64:65], v[70:71], off offset:32
	v_lshl_add_u64 v[66:67], s[4:5], 0, v[66:67]
	global_load_dwordx4 v[94:97], v[66:67], off offset:16
	global_load_dwordx4 v[98:101], v[66:67], off offset:48
	global_load_dwordx4 v[102:105], v[66:67], off
	global_load_dwordx4 v[106:109], v[66:67], off offset:32
	s_mov_b64 s[16:17], s[12:13]
	s_waitcnt vmcnt(0)
	v_mov_b32_e32 v66, v102
	v_mov_b32_e32 v67, v106
	v_mov_b32_e32 v106, v103
	v_pk_add_f32 v[66:67], v[66:67], v[106:107]
	v_mov_b32_e32 v70, v104
	v_mov_b32_e32 v71, v108
	v_pk_add_f32 v[66:67], v[70:71], v[66:67]
	v_mov_b32_e32 v108, v105
	v_pk_add_f32 v[66:67], v[108:109], v[66:67]
	v_mov_b32_e32 v70, v94
	v_mov_b32_e32 v71, v98
	v_pk_add_f32 v[66:67], v[70:71], v[66:67]
	v_mov_b32_e32 v98, v95
	v_pk_add_f32 v[66:67], v[98:99], v[66:67]
	v_mov_b32_e32 v70, v96
	v_mov_b32_e32 v71, v100
	v_pk_add_f32 v[66:67], v[70:71], v[66:67]
	v_mov_b32_e32 v100, v97
	v_pk_add_f32 v[66:67], v[100:101], v[66:67]
	s_nop 0
	v_pk_add_f32 v[66:67], v[66:67], s[20:21] op_sel_hi:[1,0]
	s_nop 0
	v_pk_mul_f32 v[66:67], v[66:67], s[40:41] op_sel_hi:[1,0]
	s_nop 0
	v_mul_f32_e32 v70, 0x4b800000, v66
	v_cmp_gt_f32_e64 s[0:1], s67, v66
	v_cmp_gt_f32_e32 vcc, s67, v67
	s_nop 0
	v_cndmask_b32_e64 v66, v66, v70, s[0:1]
	v_mul_f32_e32 v70, 0x4b800000, v67
	v_cndmask_b32_e32 v67, v67, v70, vcc
	v_rsq_f32_e32 v66, v66
	v_rsq_f32_e32 v67, v67
	s_nop 0
	v_pk_mul_f32 v[70:71], v[66:67], s[18:19] op_sel_hi:[1,0]
	s_nop 0
	v_cndmask_b32_e64 v66, v66, v70, s[0:1]
	v_add_u32_e32 v70, 0x82, v134
	v_cndmask_b32_e32 v67, v67, v71, vcc
	v_ashrrev_i32_e32 v71, 31, v70
	v_lshlrev_b64 v[70:71], 5, v[70:71]
	v_lshl_add_u64 v[70:71], s[4:5], 0, v[70:71]
	global_load_dwordx4 v[94:97], v[70:71], off offset:16
	global_load_dwordx4 v[98:101], v[70:71], off offset:48
	global_load_dwordx4 v[102:105], v[70:71], off
	global_load_dwordx4 v[106:109], v[70:71], off offset:32
	v_pk_mul_f32 v[60:61], v[60:61], v[66:67]
	v_pk_mul_f32 v[56:57], v[56:57], v[66:67]
	v_pk_mul_f32 v[52:53], v[52:53], v[66:67]
	v_pk_mul_f32 v[48:49], v[48:49], v[66:67]
	v_pk_mul_f32 v[44:45], v[44:45], v[66:67]
	v_pk_mul_f32 v[40:41], v[40:41], v[66:67]
	v_pk_mul_f32 v[36:37], v[36:37], v[66:67]
	v_pk_mul_f32 v[32:33], v[32:33], v[66:67]
	v_cvt_pk_bf16_f32 v60, v60, v61
	s_waitcnt vmcnt(0)
	v_mov_b32_e32 v70, v102
	v_mov_b32_e32 v71, v106
	v_mov_b32_e32 v106, v103
	v_pk_add_f32 v[70:71], v[70:71], v[106:107]
	v_mov_b32_e32 v74, v104
	v_mov_b32_e32 v75, v108
	v_pk_add_f32 v[70:71], v[74:75], v[70:71]
	v_mov_b32_e32 v108, v105
	v_pk_add_f32 v[70:71], v[108:109], v[70:71]
	v_mov_b32_e32 v74, v94
	v_mov_b32_e32 v75, v98
	v_pk_add_f32 v[70:71], v[74:75], v[70:71]
	v_mov_b32_e32 v98, v95
	v_pk_add_f32 v[70:71], v[98:99], v[70:71]
	v_mov_b32_e32 v74, v96
	v_mov_b32_e32 v75, v100
	v_pk_add_f32 v[70:71], v[74:75], v[70:71]
	v_mov_b32_e32 v100, v97
	v_pk_add_f32 v[70:71], v[100:101], v[70:71]
	s_nop 0
	v_pk_add_f32 v[70:71], v[70:71], s[20:21] op_sel_hi:[1,0]
	s_nop 0
	v_pk_mul_f32 v[70:71], v[70:71], s[40:41] op_sel_hi:[1,0]
	s_nop 0
	v_mul_f32_e32 v74, 0x4b800000, v70
	v_cmp_gt_f32_e64 s[0:1], s67, v70
	v_cmp_gt_f32_e32 vcc, s67, v71
	s_nop 0
	v_cndmask_b32_e64 v70, v70, v74, s[0:1]
	v_mul_f32_e32 v74, 0x4b800000, v71
	v_cndmask_b32_e32 v71, v71, v74, vcc
	v_rsq_f32_e32 v70, v70
	v_rsq_f32_e32 v71, v71
	s_nop 0
	v_pk_mul_f32 v[74:75], v[70:71], s[18:19] op_sel_hi:[1,0]
	s_nop 0
	v_cndmask_b32_e32 v71, v71, v75, vcc
	v_cndmask_b32_e64 v70, v70, v74, s[0:1]
	v_pk_mul_f32 v[62:63], v[62:63], v[70:71]
	v_pk_mul_f32 v[58:59], v[58:59], v[70:71]
	v_cvt_pk_bf16_f32 v61, v62, v63
	global_store_dwordx2 v[92:93], v[60:61], off offset:256
	v_cvt_pk_bf16_f32 v56, v56, v57
	v_cvt_pk_bf16_f32 v57, v58, v59
	global_store_dwordx2 v[88:89], v[56:57], off offset:256
	v_pk_mul_f32 v[54:55], v[54:55], v[70:71]
	v_cvt_pk_bf16_f32 v52, v52, v53
	v_pk_mul_f32 v[50:51], v[50:51], v[70:71]
	v_cvt_pk_bf16_f32 v53, v54, v55
	global_store_dwordx2 v[84:85], v[52:53], off offset:256
	v_cvt_pk_bf16_f32 v48, v48, v49
	v_cvt_pk_bf16_f32 v49, v50, v51
	global_store_dwordx2 v[80:81], v[48:49], off offset:256
	v_pk_mul_f32 v[46:47], v[46:47], v[70:71]
	v_cvt_pk_bf16_f32 v44, v44, v45
	v_pk_mul_f32 v[42:43], v[42:43], v[70:71]
	v_cvt_pk_bf16_f32 v45, v46, v47
	global_store_dwordx2 v[76:77], v[44:45], off offset:256
	v_cvt_pk_bf16_f32 v40, v40, v41
	v_cvt_pk_bf16_f32 v41, v42, v43
	global_store_dwordx2 v[72:73], v[40:41], off offset:256
	v_pk_mul_f32 v[38:39], v[38:39], v[70:71]
	v_cvt_pk_bf16_f32 v36, v36, v37
	v_pk_mul_f32 v[34:35], v[34:35], v[70:71]
	v_cvt_pk_bf16_f32 v37, v38, v39
	global_store_dwordx2 v[68:69], v[36:37], off offset:256
	v_cvt_pk_bf16_f32 v32, v32, v33
	v_cvt_pk_bf16_f32 v33, v34, v35
	global_store_dwordx2 v[64:65], v[32:33], off offset:256
	v_add_u32_e32 v32, 0x90, v134
	v_ashrrev_i32_e32 v33, 31, v32
	v_lshlrev_b64 v[32:33], 5, v[32:33]
	v_lshl_add_u64 v[44:45], s[4:5], 0, v[32:33]
	global_load_dwordx4 v[32:35], v[44:45], off offset:16
	global_load_dwordx4 v[36:39], v[44:45], off offset:48
	global_load_dwordx4 v[40:43], v[44:45], off
	s_nop 0
	global_load_dwordx4 v[44:47], v[44:45], off offset:32
	s_waitcnt vmcnt(0)
	v_mov_b32_e32 v48, v40
	v_mov_b32_e32 v49, v44
	v_mov_b32_e32 v44, v41
	v_pk_add_f32 v[40:41], v[48:49], v[44:45]
	v_mov_b32_e32 v44, v42
	v_mov_b32_e32 v45, v46
	v_pk_add_f32 v[40:41], v[44:45], v[40:41]
	v_mov_b32_e32 v46, v43
	v_pk_add_f32 v[40:41], v[46:47], v[40:41]
	v_mov_b32_e32 v42, v32
	v_mov_b32_e32 v43, v36
	v_pk_add_f32 v[40:41], v[42:43], v[40:41]
	v_mov_b32_e32 v36, v33
	v_pk_add_f32 v[32:33], v[36:37], v[40:41]
	v_mov_b32_e32 v36, v34
	v_mov_b32_e32 v37, v38
	v_pk_add_f32 v[32:33], v[36:37], v[32:33]
	v_mov_b32_e32 v38, v35
	v_pk_add_f32 v[32:33], v[38:39], v[32:33]
	s_nop 0
	v_pk_add_f32 v[32:33], v[32:33], s[20:21] op_sel_hi:[1,0]
	s_nop 0
	v_pk_mul_f32 v[32:33], v[32:33], s[40:41] op_sel_hi:[1,0]
	s_nop 0
	v_mul_f32_e32 v34, 0x4b800000, v32
	v_cmp_gt_f32_e64 s[0:1], s67, v32
	v_cmp_gt_f32_e32 vcc, s67, v33
	s_nop 0
	v_cndmask_b32_e64 v32, v32, v34, s[0:1]
	v_mul_f32_e32 v34, 0x4b800000, v33
	v_cndmask_b32_e32 v33, v33, v34, vcc
	v_rsq_f32_e32 v32, v32
	v_rsq_f32_e32 v33, v33
	s_nop 0
	v_pk_mul_f32 v[34:35], v[32:33], s[18:19] op_sel_hi:[1,0]
	s_nop 0
	v_cndmask_b32_e64 v32, v32, v34, s[0:1]
	v_add_u32_e32 v34, 0x92, v134
	v_cndmask_b32_e32 v33, v33, v35, vcc
	v_ashrrev_i32_e32 v35, 31, v34
	v_lshlrev_b64 v[34:35], 5, v[34:35]
	v_lshl_add_u64 v[46:47], s[4:5], 0, v[34:35]
	global_load_dwordx4 v[34:37], v[46:47], off offset:16
	global_load_dwordx4 v[38:41], v[46:47], off offset:48
	global_load_dwordx4 v[42:45], v[46:47], off
	s_nop 0
	global_load_dwordx4 v[46:49], v[46:47], off offset:32
	v_pk_mul_f32 v[28:29], v[28:29], v[32:33]
	v_pk_mul_f32 v[24:25], v[24:25], v[32:33]
	v_pk_mul_f32 v[20:21], v[20:21], v[32:33]
	v_pk_mul_f32 v[16:17], v[16:17], v[32:33]
	v_pk_mul_f32 v[12:13], v[12:13], v[32:33]
	v_pk_mul_f32 v[8:9], v[8:9], v[32:33]
	v_pk_mul_f32 v[4:5], v[4:5], v[32:33]
	v_pk_mul_f32 v[0:1], v[0:1], v[32:33]
	v_cvt_pk_bf16_f32 v28, v28, v29
	s_waitcnt vmcnt(0)
	v_mov_b32_e32 v50, v42
	v_mov_b32_e32 v51, v46
	v_mov_b32_e32 v46, v43
	v_pk_add_f32 v[42:43], v[50:51], v[46:47]
	v_mov_b32_e32 v46, v44
	v_mov_b32_e32 v47, v48
	v_pk_add_f32 v[42:43], v[46:47], v[42:43]
	v_mov_b32_e32 v48, v45
	v_pk_add_f32 v[42:43], v[48:49], v[42:43]
	v_mov_b32_e32 v44, v34
	v_mov_b32_e32 v45, v38
	v_pk_add_f32 v[42:43], v[44:45], v[42:43]
	v_mov_b32_e32 v38, v35
	v_pk_add_f32 v[34:35], v[38:39], v[42:43]
	v_mov_b32_e32 v38, v36
	v_mov_b32_e32 v39, v40
	v_pk_add_f32 v[34:35], v[38:39], v[34:35]
	v_mov_b32_e32 v40, v37
	v_pk_add_f32 v[34:35], v[40:41], v[34:35]
	s_nop 0
	v_pk_add_f32 v[34:35], v[34:35], s[20:21] op_sel_hi:[1,0]
	s_nop 0
	v_pk_mul_f32 v[34:35], v[34:35], s[40:41] op_sel_hi:[1,0]
	v_readlane_b32 s40, v244, 49
	v_mul_f32_e32 v36, 0x4b800000, v34
	v_cmp_gt_f32_e64 s[0:1], s67, v34
	v_cmp_gt_f32_e32 vcc, s67, v35
	v_readlane_b32 s41, v244, 50
	v_cndmask_b32_e64 v34, v34, v36, s[0:1]
	v_mul_f32_e32 v36, 0x4b800000, v35
	v_cndmask_b32_e32 v35, v35, v36, vcc
	v_rsq_f32_e32 v34, v34
	v_rsq_f32_e32 v35, v35
	v_readlane_b32 s46, v244, 55
	v_readlane_b32 s47, v244, 56
	v_readlane_b32 s48, v244, 57
	v_pk_mul_f32 v[36:37], v[34:35], s[18:19] op_sel_hi:[1,0]
	s_mov_b64 s[18:19], s[14:15]
	v_cndmask_b32_e32 v35, v35, v37, vcc
	v_cndmask_b32_e64 v34, v34, v36, s[0:1]
	s_and_b64 vcc, exec, s[6:7]
	s_mov_b32 s1, s10
	s_mov_b32 s0, s8
	v_readlane_b32 s49, v244, 58
	v_readlane_b32 s50, v244, 59
	v_readlane_b32 s51, v244, 60
	v_pk_mul_f32 v[30:31], v[30:31], v[34:35]
	v_pk_mul_f32 v[26:27], v[26:27], v[34:35]
	v_cvt_pk_bf16_f32 v29, v30, v31
	global_store_dwordx2 v[92:93], v[28:29], off offset:288
	v_cvt_pk_bf16_f32 v24, v24, v25
	v_cvt_pk_bf16_f32 v25, v26, v27
	global_store_dwordx2 v[88:89], v[24:25], off offset:288
	v_pk_mul_f32 v[22:23], v[22:23], v[34:35]
	v_cvt_pk_bf16_f32 v20, v20, v21
	v_pk_mul_f32 v[18:19], v[18:19], v[34:35]
	v_cvt_pk_bf16_f32 v21, v22, v23
	global_store_dwordx2 v[84:85], v[20:21], off offset:288
	v_cvt_pk_bf16_f32 v16, v16, v17
	v_cvt_pk_bf16_f32 v17, v18, v19
	global_store_dwordx2 v[80:81], v[16:17], off offset:288
	v_pk_mul_f32 v[14:15], v[14:15], v[34:35]
	v_cvt_pk_bf16_f32 v12, v12, v13
	v_pk_mul_f32 v[10:11], v[10:11], v[34:35]
	v_cvt_pk_bf16_f32 v13, v14, v15
	global_store_dwordx2 v[76:77], v[12:13], off offset:288
	v_cvt_pk_bf16_f32 v8, v8, v9
	v_cvt_pk_bf16_f32 v9, v10, v11
	global_store_dwordx2 v[72:73], v[8:9], off offset:288
	v_pk_mul_f32 v[6:7], v[6:7], v[34:35]
	v_cvt_pk_bf16_f32 v4, v4, v5
	v_pk_mul_f32 v[2:3], v[2:3], v[34:35]
	v_cvt_pk_bf16_f32 v5, v6, v7
	global_store_dwordx2 v[68:69], v[4:5], off offset:288
	v_cvt_pk_bf16_f32 v0, v0, v1
	v_cvt_pk_bf16_f32 v1, v2, v3
	global_store_dwordx2 v[64:65], v[0:1], off offset:288
	v_readlane_b32 s42, v244, 51
	v_readlane_b32 s43, v244, 52
	v_readlane_b32 s44, v244, 53
	v_readlane_b32 s45, v244, 54
	v_readlane_b32 s52, v244, 61
	v_readlane_b32 s53, v244, 62
	v_readlane_b32 s54, v244, 63
	v_readlane_b32 s55, v243, 0
	s_cbranch_vccz .LBB0_130
	s_waitcnt vmcnt(0)
	s_cmpk_gt_u32 s22, 0xff
	s_cbranch_scc1 .LBB0_141
	s_barrier

.LBB0_151:
	s_ashr_i32 s9, s8, 31
	s_lshl_b64 s[12:13], s[8:9], 18
	s_add_u32 s12, s25, s12
	s_addc_u32 s13, s26, s13
	s_and_b64 s[14:15], s[22:23], exec
	s_cselect_b32 s9, s13, s19
	s_cselect_b32 s40, s12, s18
	s_ashr_i32 s7, s6, 31
	s_lshl_b64 s[14:15], s[6:7], 18
	s_add_u32 s14, s27, s14
	s_addc_u32 s15, s28, s15
	s_and_b64 s[22:23], s[22:23], exec
	s_cselect_b32 s7, s15, s21
	s_cselect_b32 s41, s14, s20
	s_add_u32 s18, s18, 0x20080
	s_addc_u32 s19, s19, 0
	s_add_u32 s42, s20, 0x100
	v_mov_b32_e32 v0, 0
	s_addc_u32 s43, s21, 0
	s_mov_b32 s44, -2
	v_mov_b32_e32 v1, v0
	v_mov_b32_e32 v2, v0
	v_mov_b32_e32 v3, v0
	v_mov_b32_e32 v4, v0
	v_mov_b32_e32 v5, v0
	v_mov_b32_e32 v6, v0
	v_mov_b32_e32 v7, v0
	v_mov_b32_e32 v16, v0
	v_mov_b32_e32 v17, v0
	v_mov_b32_e32 v18, v0
	v_mov_b32_e32 v19, v0
	v_mov_b32_e32 v20, v0
	v_mov_b32_e32 v21, v0
	v_mov_b32_e32 v22, v0
	v_mov_b32_e32 v23, v0
	v_mov_b32_e32 v32, v0
	v_mov_b32_e32 v33, v0
	v_mov_b32_e32 v34, v0
	v_mov_b32_e32 v35, v0
	v_mov_b32_e32 v36, v0
	v_mov_b32_e32 v37, v0
	v_mov_b32_e32 v38, v0
	v_mov_b32_e32 v39, v0
	v_mov_b32_e32 v48, v0
	v_mov_b32_e32 v49, v0
	v_mov_b32_e32 v50, v0
	v_mov_b32_e32 v51, v0
	v_mov_b32_e32 v52, v0
	v_mov_b32_e32 v53, v0
	v_mov_b32_e32 v54, v0
	v_mov_b32_e32 v55, v0
	v_mov_b32_e32 v8, v0
	v_mov_b32_e32 v9, v0
	v_mov_b32_e32 v10, v0
	v_mov_b32_e32 v11, v0
	v_mov_b32_e32 v12, v0
	v_mov_b32_e32 v13, v0
	v_mov_b32_e32 v14, v0
	v_mov_b32_e32 v15, v0
	v_mov_b32_e32 v24, v0
	v_mov_b32_e32 v25, v0
	v_mov_b32_e32 v26, v0
	v_mov_b32_e32 v27, v0
	v_mov_b32_e32 v28, v0
	v_mov_b32_e32 v29, v0
	v_mov_b32_e32 v30, v0
	v_mov_b32_e32 v31, v0
	v_mov_b32_e32 v40, v0
	v_mov_b32_e32 v41, v0
	v_mov_b32_e32 v42, v0
	v_mov_b32_e32 v43, v0
	v_mov_b32_e32 v44, v0
	v_mov_b32_e32 v45, v0
	v_mov_b32_e32 v46, v0
	v_mov_b32_e32 v47, v0
	v_mov_b32_e32 v56, v0
	v_mov_b32_e32 v57, v0
	v_mov_b32_e32 v58, v0
	v_mov_b32_e32 v59, v0
	v_mov_b32_e32 v60, v0
	v_mov_b32_e32 v61, v0
	v_mov_b32_e32 v62, v0
	v_mov_b32_e32 v63, v0
	v_mov_b32_e32 v64, v0
	v_mov_b32_e32 v65, v0
	v_mov_b32_e32 v66, v0
	v_mov_b32_e32 v67, v0
	v_mov_b32_e32 v68, v0
	v_mov_b32_e32 v69, v0
	v_mov_b32_e32 v70, v0
	v_mov_b32_e32 v71, v0
	v_mov_b32_e32 v80, v0
	v_mov_b32_e32 v81, v0
	v_mov_b32_e32 v82, v0
	v_mov_b32_e32 v83, v0
	v_mov_b32_e32 v84, v0
	v_mov_b32_e32 v85, v0
	v_mov_b32_e32 v86, v0
	v_mov_b32_e32 v87, v0
	v_mov_b32_e32 v96, v0
	v_mov_b32_e32 v97, v0
	v_mov_b32_e32 v98, v0
	v_mov_b32_e32 v99, v0
	v_mov_b32_e32 v100, v0
	v_mov_b32_e32 v101, v0
	v_mov_b32_e32 v102, v0
	v_mov_b32_e32 v103, v0
	v_mov_b32_e32 v112, v0
	v_mov_b32_e32 v113, v0
	v_mov_b32_e32 v114, v0
	v_mov_b32_e32 v115, v0
	v_mov_b32_e32 v116, v0
	v_mov_b32_e32 v117, v0
	v_mov_b32_e32 v118, v0
	v_mov_b32_e32 v119, v0
	v_mov_b32_e32 v72, v0
	v_mov_b32_e32 v73, v0
	v_mov_b32_e32 v74, v0
	v_mov_b32_e32 v75, v0
	v_mov_b32_e32 v76, v0
	v_mov_b32_e32 v77, v0
	v_mov_b32_e32 v78, v0
	v_mov_b32_e32 v79, v0
	v_mov_b32_e32 v88, v0
	v_mov_b32_e32 v89, v0
	v_mov_b32_e32 v90, v0
	v_mov_b32_e32 v91, v0
	v_mov_b32_e32 v92, v0
	v_mov_b32_e32 v93, v0
	v_mov_b32_e32 v94, v0
	v_mov_b32_e32 v95, v0
	v_mov_b32_e32 v104, v0
	v_mov_b32_e32 v105, v0
	v_mov_b32_e32 v106, v0
	v_mov_b32_e32 v107, v0
	v_mov_b32_e32 v108, v0
	v_mov_b32_e32 v109, v0
	v_mov_b32_e32 v110, v0
	v_mov_b32_e32 v111, v0
	v_mov_b32_e32 v120, v0
	v_mov_b32_e32 v121, v0
	v_mov_b32_e32 v122, v0
	v_mov_b32_e32 v123, v0
	v_mov_b32_e32 v124, v0
	v_mov_b32_e32 v125, v0
	v_mov_b32_e32 v126, v0
	v_mov_b32_e32 v127, v0
	s_mov_b64 s[50:51], 0x80
	v_add_u32_e32 v156, 0x10000, v142
	ds_read_b128 v[144:147], v156
	ds_read_b128 v[148:151], v156 offset:1024
	ds_read_b128 v[152:155], v156 offset:2048
	ds_read_b128 v[156:159], v156 offset:3072
.LBB0_152:
	s_add_u32 s20, s18, 0xfffe0080
	s_addc_u32 s21, s19, -1
	s_add_i32 s45, 0, 0x10000
	v_add_u32_e32 v138, s45, v142
	s_cmp_eq_u32 s44, 4
	s_cselect_b32 s23, s9, s21
	s_cselect_b32 s22, s40, s20
	s_cselect_b32 s21, s7, s43
	s_cselect_b32 s20, s41, s42
	v_lshl_add_u64 v[138:139], s[18:19], 0, v[134:135]
	s_add_i32 m0, s17, 0xc000
	ds_read_b128 v[160:163], v143
	ds_read_b128 v[164:167], v143 offset:1024
	ds_read_b128 v[168:171], v143 offset:2048
	ds_read_b128 v[172:175], v143 offset:3072
	ds_read_b128 v[176:179], v143 offset:4096
	ds_read_b128 v[180:183], v143 offset:5120
	ds_read_b128 v[188:191], v143 offset:6144
	ds_read_b128 v[192:195], v143 offset:7168
	global_load_lds_dwordx4 v[138:139], off
	v_lshl_add_u64 v[138:139], s[18:19], 0, v[136:137]
	s_add_i32 m0, s17, 0xe000
	s_nop 0
	global_load_lds_dwordx4 v[138:139], off
	s_waitcnt lgkmcnt(8)
	s_setprio 1
	s_barrier
	s_waitcnt lgkmcnt(0)
	v_mfma_f32_16x16x32_bf16 v[124:127], v[144:147], v[160:163], v[124:127]
	v_mfma_f32_16x16x32_bf16 v[120:123], v[152:155], v[160:163], v[120:123]
	v_mfma_f32_16x16x32_bf16 v[108:111], v[144:147], v[168:171], v[108:111]
	v_mfma_f32_16x16x32_bf16 v[104:107], v[152:155], v[168:171], v[104:107]
	v_mfma_f32_16x16x32_bf16 v[92:95], v[144:147], v[176:179], v[92:95]
	v_mfma_f32_16x16x32_bf16 v[88:91], v[152:155], v[176:179], v[88:91]
	v_mfma_f32_16x16x32_bf16 v[76:79], v[144:147], v[188:191], v[76:79]
	v_mfma_f32_16x16x32_bf16 v[72:75], v[152:155], v[188:191], v[72:75]
	v_mfma_f32_16x16x32_bf16 v[124:127], v[148:151], v[164:167], v[124:127]
	v_mfma_f32_16x16x32_bf16 v[120:123], v[156:159], v[164:167], v[120:123]
	v_mfma_f32_16x16x32_bf16 v[108:111], v[148:151], v[172:175], v[108:111]
	v_mfma_f32_16x16x32_bf16 v[104:107], v[156:159], v[172:175], v[104:107]
	v_mfma_f32_16x16x32_bf16 v[92:95], v[148:151], v[180:183], v[92:95]
	v_mfma_f32_16x16x32_bf16 v[88:91], v[156:159], v[180:183], v[88:91]
	v_mfma_f32_16x16x32_bf16 v[76:79], v[148:151], v[192:195], v[76:79]
	v_mfma_f32_16x16x32_bf16 v[72:75], v[156:159], v[192:195], v[72:75]
	s_barrier
	s_setprio 0
	s_add_i32 s48, 0, 0x14000
	v_add_u32_e32 v138, s48, v142
	s_add_i32 s45, s45, s29
	ds_read_b128 v[202:205], v138
	ds_read_b128 v[206:209], v138 offset:1024
	ds_read_b128 v[210:213], v138 offset:2048
	ds_read_b128 v[214:217], v138 offset:3072
	v_lshl_add_u64 v[138:139], s[20:21], 0, v[184:185]
	s_mov_b32 m0, s45
	v_lshl_add_u64 v[196:197], s[20:21], 0, v[128:129]
	global_load_lds_dwordx4 v[138:139], off
	s_add_i32 m0, s45, 0x2000
	s_nop 0
	global_load_lds_dwordx4 v[196:197], off
	s_setprio 1
	s_barrier
	s_waitcnt lgkmcnt(0)
	v_mfma_f32_16x16x32_bf16 v[116:119], v[202:205], v[160:163], v[116:119]
	v_mfma_f32_16x16x32_bf16 v[112:115], v[210:213], v[160:163], v[112:115]
	v_mfma_f32_16x16x32_bf16 v[100:103], v[202:205], v[168:171], v[100:103]
	v_mfma_f32_16x16x32_bf16 v[96:99], v[210:213], v[168:171], v[96:99]
	v_mfma_f32_16x16x32_bf16 v[84:87], v[202:205], v[176:179], v[84:87]
	v_mfma_f32_16x16x32_bf16 v[80:83], v[210:213], v[176:179], v[80:83]
	v_mfma_f32_16x16x32_bf16 v[68:71], v[202:205], v[188:191], v[68:71]
	v_mfma_f32_16x16x32_bf16 v[64:67], v[210:213], v[188:191], v[64:67]
	v_mfma_f32_16x16x32_bf16 v[116:119], v[206:209], v[164:167], v[116:119]
	v_mfma_f32_16x16x32_bf16 v[112:115], v[214:217], v[164:167], v[112:115]
	v_mfma_f32_16x16x32_bf16 v[100:103], v[206:209], v[172:175], v[100:103]
	v_mfma_f32_16x16x32_bf16 v[96:99], v[214:217], v[172:175], v[96:99]
	v_mfma_f32_16x16x32_bf16 v[84:87], v[206:209], v[180:183], v[84:87]
	v_mfma_f32_16x16x32_bf16 v[80:83], v[214:217], v[180:183], v[80:83]
	v_mfma_f32_16x16x32_bf16 v[68:71], v[206:209], v[192:195], v[68:71]
	v_mfma_f32_16x16x32_bf16 v[64:67], v[214:217], v[192:195], v[64:67]
	s_barrier
	s_setprio 0
	s_mov_b32 m0, s17
	v_lshl_add_u64 v[218:219], s[22:23], 0, v[132:133]
	ds_read_b128 v[160:163], v143 offset:16384
	ds_read_b128 v[164:167], v143 offset:17408
	ds_read_b128 v[168:171], v143 offset:18432
	ds_read_b128 v[172:175], v143 offset:19456
	ds_read_b128 v[176:179], v143 offset:20480
	ds_read_b128 v[180:183], v143 offset:21504
	ds_read_b128 v[188:191], v143 offset:22528
	ds_read_b128 v[192:195], v143 offset:23552
	global_load_lds_dwordx4 v[218:219], off
	v_lshl_add_u64 v[220:221], s[22:23], 0, v[130:131]
	s_mov_b32 m0, s30
	s_nop 0
	global_load_lds_dwordx4 v[220:221], off
	s_setprio 1
	s_waitcnt vmcnt(10)
	s_barrier
	s_waitcnt lgkmcnt(0)
	v_mfma_f32_16x16x32_bf16 v[60:63], v[144:147], v[160:163], v[60:63]
	v_mfma_f32_16x16x32_bf16 v[56:59], v[152:155], v[160:163], v[56:59]
	v_mfma_f32_16x16x32_bf16 v[44:47], v[144:147], v[168:171], v[44:47]
	v_mfma_f32_16x16x32_bf16 v[40:43], v[152:155], v[168:171], v[40:43]
	v_mfma_f32_16x16x32_bf16 v[28:31], v[144:147], v[176:179], v[28:31]
	v_mfma_f32_16x16x32_bf16 v[24:27], v[152:155], v[176:179], v[24:27]
	v_mfma_f32_16x16x32_bf16 v[12:15], v[144:147], v[188:191], v[12:15]
	v_mfma_f32_16x16x32_bf16 v[8:11], v[152:155], v[188:191], v[8:11]
	v_mfma_f32_16x16x32_bf16 v[60:63], v[148:151], v[164:167], v[60:63]
	v_mfma_f32_16x16x32_bf16 v[56:59], v[156:159], v[164:167], v[56:59]
	v_mfma_f32_16x16x32_bf16 v[44:47], v[148:151], v[172:175], v[44:47]
	v_mfma_f32_16x16x32_bf16 v[40:43], v[156:159], v[172:175], v[40:43]
	v_mfma_f32_16x16x32_bf16 v[28:31], v[148:151], v[180:183], v[28:31]
	v_mfma_f32_16x16x32_bf16 v[24:27], v[156:159], v[180:183], v[24:27]
	v_mfma_f32_16x16x32_bf16 v[12:15], v[148:151], v[192:195], v[12:15]
	v_mfma_f32_16x16x32_bf16 v[8:11], v[156:159], v[192:195], v[8:11]
	s_barrier
	s_setprio 0
	v_add_u32_e32 v156, 0x18000, v142
	ds_read_b128 v[144:147], v156
	ds_read_b128 v[148:151], v156 offset:1024
	ds_read_b128 v[152:155], v156 offset:2048
	ds_read_b128 v[156:159], v156 offset:3072
	s_add_u32 s46, s20, 0x20000
	s_addc_u32 s47, s21, 0
	s_add_i32 s45, s48, s29
	v_lshl_add_u64 v[246:247], s[46:47], 0, v[184:185]
	s_mov_b32 m0, s45
	s_nop 0
	global_load_lds_dwordx4 v[246:247], off
	v_lshl_add_u64 v[248:249], s[46:47], 0, v[128:129]
	s_add_i32 m0, s45, 0x2000
	s_nop 0
	global_load_lds_dwordx4 v[248:249], off
	s_waitcnt vmcnt(6)
	s_setprio 1
	s_barrier
	v_mfma_f32_16x16x32_bf16 v[52:55], v[202:205], v[160:163], v[52:55]
	v_mfma_f32_16x16x32_bf16 v[48:51], v[210:213], v[160:163], v[48:51]
	v_mfma_f32_16x16x32_bf16 v[36:39], v[202:205], v[168:171], v[36:39]
	v_mfma_f32_16x16x32_bf16 v[32:35], v[210:213], v[168:171], v[32:35]
	v_mfma_f32_16x16x32_bf16 v[20:23], v[202:205], v[176:179], v[20:23]
	v_mfma_f32_16x16x32_bf16 v[16:19], v[210:213], v[176:179], v[16:19]
	v_mfma_f32_16x16x32_bf16 v[4:7], v[202:205], v[188:191], v[4:7]
	v_mfma_f32_16x16x32_bf16 v[0:3], v[210:213], v[188:191], v[0:3]
	v_mfma_f32_16x16x32_bf16 v[52:55], v[206:209], v[164:167], v[52:55]
	v_mfma_f32_16x16x32_bf16 v[48:51], v[214:217], v[164:167], v[48:51]
	v_mfma_f32_16x16x32_bf16 v[36:39], v[206:209], v[172:175], v[36:39]
	v_mfma_f32_16x16x32_bf16 v[32:35], v[214:217], v[172:175], v[32:35]
	v_mfma_f32_16x16x32_bf16 v[20:23], v[206:209], v[180:183], v[20:23]
	v_mfma_f32_16x16x32_bf16 v[16:19], v[214:217], v[180:183], v[16:19]
	v_mfma_f32_16x16x32_bf16 v[4:7], v[206:209], v[192:195], v[4:7]
	v_mfma_f32_16x16x32_bf16 v[0:3], v[214:217], v[192:195], v[0:3]
	s_barrier
	s_setprio 0
	s_add_i32 s45, 0, 0x18000
	s_add_u32 s22, s22, 0x20000
	s_addc_u32 s23, s23, 0
	s_mov_b32 m0, s31
	v_lshl_add_u64 v[202:203], s[22:23], 0, v[132:133]
	ds_read_b128 v[160:163], v143 offset:32768
	ds_read_b128 v[164:167], v143 offset:33792
	ds_read_b128 v[168:171], v143 offset:34816
	ds_read_b128 v[172:175], v143 offset:35840
	ds_read_b128 v[176:179], v143 offset:36864
	ds_read_b128 v[180:183], v143 offset:37888
	ds_read_b128 v[188:191], v143 offset:38912
	ds_read_b128 v[192:195], v143 offset:39936
	global_load_lds_dwordx4 v[202:203], off
	v_lshl_add_u64 v[202:203], s[22:23], 0, v[130:131]
	s_mov_b32 m0, s33
	s_nop 0
	global_load_lds_dwordx4 v[202:203], off
	s_waitcnt lgkmcnt(8)
	s_setprio 1
	s_barrier
	s_waitcnt lgkmcnt(0)
	v_mfma_f32_16x16x32_bf16 v[124:127], v[144:147], v[160:163], v[124:127]
	v_mfma_f32_16x16x32_bf16 v[120:123], v[152:155], v[160:163], v[120:123]
	v_mfma_f32_16x16x32_bf16 v[108:111], v[144:147], v[168:171], v[108:111]
	v_mfma_f32_16x16x32_bf16 v[104:107], v[152:155], v[168:171], v[104:107]
	v_mfma_f32_16x16x32_bf16 v[92:95], v[144:147], v[176:179], v[92:95]
	v_mfma_f32_16x16x32_bf16 v[88:91], v[152:155], v[176:179], v[88:91]
	v_mfma_f32_16x16x32_bf16 v[76:79], v[144:147], v[188:191], v[76:79]
	v_mfma_f32_16x16x32_bf16 v[72:75], v[152:155], v[188:191], v[72:75]
	v_mfma_f32_16x16x32_bf16 v[124:127], v[148:151], v[164:167], v[124:127]
	v_mfma_f32_16x16x32_bf16 v[120:123], v[156:159], v[164:167], v[120:123]
	v_mfma_f32_16x16x32_bf16 v[108:111], v[148:151], v[172:175], v[108:111]
	v_mfma_f32_16x16x32_bf16 v[104:107], v[156:159], v[172:175], v[104:107]
	v_mfma_f32_16x16x32_bf16 v[92:95], v[148:151], v[180:183], v[92:95]
	v_mfma_f32_16x16x32_bf16 v[88:91], v[156:159], v[180:183], v[88:91]
	v_mfma_f32_16x16x32_bf16 v[76:79], v[148:151], v[192:195], v[76:79]
	v_mfma_f32_16x16x32_bf16 v[72:75], v[156:159], v[192:195], v[72:75]
	s_barrier
	s_setprio 0
	s_add_i32 s22, 0, 0x1c000
	s_add_i32 s23, s45, s29
	v_add_u32_e32 v187, s22, v142
	v_lshl_add_u64 v[138:139], v[138:139], 0, s[50:51]
	s_mov_b32 m0, s23
	ds_read_b128 v[202:205], v187
	ds_read_b128 v[206:209], v187 offset:1024
	ds_read_b128 v[210:213], v187 offset:2048
	ds_read_b128 v[214:217], v187 offset:3072
	global_load_lds_dwordx4 v[138:139], off
	v_lshl_add_u64 v[138:139], v[196:197], 0, s[50:51]
	s_add_i32 m0, s23, 0x2000
	s_nop 0
	global_load_lds_dwordx4 v[138:139], off
	s_setprio 1
	s_barrier
	s_waitcnt lgkmcnt(0)
	v_mfma_f32_16x16x32_bf16 v[116:119], v[202:205], v[160:163], v[116:119]
	v_mfma_f32_16x16x32_bf16 v[112:115], v[210:213], v[160:163], v[112:115]
	v_mfma_f32_16x16x32_bf16 v[100:103], v[202:205], v[168:171], v[100:103]
	v_mfma_f32_16x16x32_bf16 v[96:99], v[210:213], v[168:171], v[96:99]
	v_mfma_f32_16x16x32_bf16 v[84:87], v[202:205], v[176:179], v[84:87]
	v_mfma_f32_16x16x32_bf16 v[80:83], v[210:213], v[176:179], v[80:83]
	v_mfma_f32_16x16x32_bf16 v[68:71], v[202:205], v[188:191], v[68:71]
	v_mfma_f32_16x16x32_bf16 v[64:67], v[210:213], v[188:191], v[64:67]
	v_mfma_f32_16x16x32_bf16 v[116:119], v[206:209], v[164:167], v[116:119]
	v_mfma_f32_16x16x32_bf16 v[112:115], v[214:217], v[164:167], v[112:115]
	v_mfma_f32_16x16x32_bf16 v[100:103], v[206:209], v[172:175], v[100:103]
	v_mfma_f32_16x16x32_bf16 v[96:99], v[214:217], v[172:175], v[96:99]
	v_mfma_f32_16x16x32_bf16 v[84:87], v[206:209], v[180:183], v[84:87]
	v_mfma_f32_16x16x32_bf16 v[80:83], v[214:217], v[180:183], v[80:83]
	v_mfma_f32_16x16x32_bf16 v[68:71], v[206:209], v[192:195], v[68:71]
	v_mfma_f32_16x16x32_bf16 v[64:67], v[214:217], v[192:195], v[64:67]
	s_barrier
	s_setprio 0
	s_mov_b32 m0, s36
	v_lshl_add_u64 v[138:139], v[218:219], 0, s[50:51]
	ds_read_b128 v[160:163], v143 offset:49152
	ds_read_b128 v[164:167], v143 offset:50176
	ds_read_b128 v[168:171], v143 offset:51200
	ds_read_b128 v[172:175], v143 offset:52224
	ds_read_b128 v[176:179], v143 offset:53248
	ds_read_b128 v[180:183], v143 offset:54272
	ds_read_b128 v[188:191], v143 offset:55296
	ds_read_b128 v[192:195], v143 offset:56320
	global_load_lds_dwordx4 v[138:139], off
	v_lshl_add_u64 v[138:139], v[220:221], 0, s[50:51]
	s_mov_b32 m0, s37
	s_nop 0
	global_load_lds_dwordx4 v[138:139], off
	s_setprio 1
	s_waitcnt vmcnt(10)
	s_barrier
	s_waitcnt lgkmcnt(0)
	v_mfma_f32_16x16x32_bf16 v[60:63], v[144:147], v[160:163], v[60:63]
	v_mfma_f32_16x16x32_bf16 v[56:59], v[152:155], v[160:163], v[56:59]
	v_mfma_f32_16x16x32_bf16 v[44:47], v[144:147], v[168:171], v[44:47]
	v_mfma_f32_16x16x32_bf16 v[40:43], v[152:155], v[168:171], v[40:43]
	v_mfma_f32_16x16x32_bf16 v[28:31], v[144:147], v[176:179], v[28:31]
	v_mfma_f32_16x16x32_bf16 v[24:27], v[152:155], v[176:179], v[24:27]
	v_mfma_f32_16x16x32_bf16 v[12:15], v[144:147], v[188:191], v[12:15]
	v_mfma_f32_16x16x32_bf16 v[8:11], v[152:155], v[188:191], v[8:11]
	v_mfma_f32_16x16x32_bf16 v[60:63], v[148:151], v[164:167], v[60:63]
	v_mfma_f32_16x16x32_bf16 v[56:59], v[156:159], v[164:167], v[56:59]
	v_mfma_f32_16x16x32_bf16 v[44:47], v[148:151], v[172:175], v[44:47]
	v_mfma_f32_16x16x32_bf16 v[40:43], v[156:159], v[172:175], v[40:43]
	v_mfma_f32_16x16x32_bf16 v[28:31], v[148:151], v[180:183], v[28:31]
	v_mfma_f32_16x16x32_bf16 v[24:27], v[156:159], v[180:183], v[24:27]
	v_mfma_f32_16x16x32_bf16 v[12:15], v[148:151], v[192:195], v[12:15]
	v_mfma_f32_16x16x32_bf16 v[8:11], v[156:159], v[192:195], v[8:11]
	s_barrier
	s_setprio 0
	v_add_u32_e32 v156, 0x10000, v142
	ds_read_b128 v[144:147], v156
	ds_read_b128 v[148:151], v156 offset:1024
	ds_read_b128 v[152:155], v156 offset:2048
	ds_read_b128 v[156:159], v156 offset:3072
	s_add_u32 s20, s20, 0x20080
	s_addc_u32 s21, s21, 0
	s_add_i32 s22, s22, s29
	v_lshl_add_u64 v[138:139], s[20:21], 0, v[184:185]
	s_mov_b32 m0, s22
	s_nop 0
	global_load_lds_dwordx4 v[138:139], off
	v_lshl_add_u64 v[138:139], s[20:21], 0, v[128:129]
	s_add_i32 m0, s22, 0x2000
	s_nop 0
	global_load_lds_dwordx4 v[138:139], off
	s_waitcnt vmcnt(6)
	s_setprio 1
	s_barrier
	v_mfma_f32_16x16x32_bf16 v[52:55], v[202:205], v[160:163], v[52:55]
	v_mfma_f32_16x16x32_bf16 v[48:51], v[210:213], v[160:163], v[48:51]
	v_mfma_f32_16x16x32_bf16 v[36:39], v[202:205], v[168:171], v[36:39]
	v_mfma_f32_16x16x32_bf16 v[32:35], v[210:213], v[168:171], v[32:35]
	v_mfma_f32_16x16x32_bf16 v[20:23], v[202:205], v[176:179], v[20:23]
	v_mfma_f32_16x16x32_bf16 v[16:19], v[210:213], v[176:179], v[16:19]
	v_mfma_f32_16x16x32_bf16 v[4:7], v[202:205], v[188:191], v[4:7]
	v_mfma_f32_16x16x32_bf16 v[0:3], v[210:213], v[188:191], v[0:3]
	v_mfma_f32_16x16x32_bf16 v[52:55], v[206:209], v[164:167], v[52:55]
	v_mfma_f32_16x16x32_bf16 v[48:51], v[214:217], v[164:167], v[48:51]
	v_mfma_f32_16x16x32_bf16 v[36:39], v[206:209], v[172:175], v[36:39]
	v_mfma_f32_16x16x32_bf16 v[32:35], v[214:217], v[172:175], v[32:35]
	v_mfma_f32_16x16x32_bf16 v[20:23], v[206:209], v[180:183], v[20:23]
	v_mfma_f32_16x16x32_bf16 v[16:19], v[214:217], v[180:183], v[16:19]
	v_mfma_f32_16x16x32_bf16 v[4:7], v[206:209], v[192:195], v[4:7]
	v_mfma_f32_16x16x32_bf16 v[0:3], v[214:217], v[192:195], v[0:3]
	s_barrier
	s_setprio 0
	s_add_i32 s44, s44, 2
	s_add_u32 s18, s18, 0x100
	s_addc_u32 s19, s19, 0
	s_add_u32 s42, s42, 0x100
	s_addc_u32 s43, s43, 0
	s_cmp_gt_u32 s44, 5
	s_cbranch_scc0 .LBB0_152
	s_waitcnt lgkmcnt(0)
	v_mov_b32_e32 v139, v141
	v_mov_b32_e32 v138, v140
	s_lshl_b32 s7, s16, 8
	s_add_i32 s7, s7, s34
	v_add_u32_e32 v138, s7, v138
	s_lshl_b32 s7, s39, 8
	s_or_b32 s7, s7, s35
	v_lshl_add_u32 v152, v139, 3, s7
	v_ashrrev_i32_e32 v139, 31, v138
	v_lshlrev_b64 v[144:145], 5, v[138:139]
	v_lshl_add_u64 v[148:149], s[4:5], 0, v[144:145]
	global_load_dwordx4 v[144:147], v[148:149], off offset:16
	s_nop 0
	global_load_dwordx4 v[148:151], v[148:149], off
	s_movk_i32 s7, 0x1800
	v_ashrrev_i32_e32 v153, 31, v152
	s_mov_b32 s39, s6
	s_mov_b32 s16, s8
	s_mov_b64 s[20:21], s[14:15]
	s_waitcnt vmcnt(0)
	v_add_f32_e32 v139, v148, v149
	v_add_f32_e32 v139, v150, v139
	v_add_f32_e32 v139, v151, v139
	v_add_f32_e32 v139, v144, v139
	v_add_f32_e32 v139, v145, v139
	v_add_f32_e32 v139, v146, v139
	v_add_f32_e32 v139, v147, v139
	v_add_f32_e32 v139, 0x3a0637bd, v139
	v_mul_f32_e32 v139, 0x3b000000, v139
	v_cmp_gt_f32_e32 vcc, s67, v139
	v_mul_f32_e32 v144, 0x4b800000, v139
	s_nop 0
	v_cndmask_b32_e32 v139, v139, v144, vcc
	v_rsq_f32_e32 v139, v139
	s_nop 0
	v_mul_f32_e32 v144, 0x45800000, v139
	v_cndmask_b32_e32 v139, v139, v144, vcc
	v_mul_f32_e32 v124, v124, v139
	v_mul_f32_e32 v125, v125, v139
	v_mul_f32_e32 v126, v126, v139
	v_mul_f32_e32 v120, v120, v139
	v_mul_f32_e32 v121, v121, v139
	v_mul_f32_e32 v127, v127, v139
	v_mul_f32_e32 v122, v122, v139
	v_mul_f32_e32 v123, v123, v139
	v_cvt_pk_bf16_f32 v124, v124, v125
	v_cvt_pk_bf16_f32 v125, v126, v127
	v_cvt_pk_bf16_f32 v126, v120, v121
	v_mov_b64_e32 v[120:121], s[2:3]
	v_cvt_pk_bf16_f32 v127, v122, v123
	v_mad_i64_i32 v[144:145], s[18:19], v138, s7, v[120:121]
	v_lshlrev_b64 v[122:123], 1, v[152:153]
	v_lshl_add_u64 v[144:145], v[144:145], 0, v[122:123]
	global_store_dwordx4 v[144:145], v[124:127], off
	v_mul_f32_e32 v116, v116, v139
	v_mul_f32_e32 v117, v117, v139
	v_mul_f32_e32 v124, v112, v139
	v_mul_f32_e32 v118, v118, v139
	v_mul_f32_e32 v119, v119, v139
	v_mul_f32_e32 v125, v113, v139
	v_mul_f32_e32 v126, v114, v139
	v_cvt_pk_bf16_f32 v112, v116, v117
	v_cvt_pk_bf16_f32 v113, v118, v119
	v_cvt_pk_bf16_f32 v114, v124, v125
	v_add_u32_e32 v124, 16, v138
	v_mul_f32_e32 v115, v115, v139
	v_ashrrev_i32_e32 v125, 31, v124
	v_cvt_pk_bf16_f32 v115, v126, v115
	global_store_dwordx4 v[144:145], v[112:115], off offset:256
	s_nop 1
	v_lshlrev_b64 v[112:113], 5, v[124:125]
	v_lshl_add_u64 v[116:117], s[4:5], 0, v[112:113]
	global_load_dwordx4 v[112:115], v[116:117], off offset:16
	s_nop 0
	global_load_dwordx4 v[116:119], v[116:117], off
	s_waitcnt vmcnt(0)
	v_add_f32_e32 v116, v116, v117
	v_add_f32_e32 v116, v118, v116
	v_add_f32_e32 v116, v119, v116
	v_add_f32_e32 v112, v112, v116
	v_add_f32_e32 v112, v113, v112
	v_add_f32_e32 v112, v114, v112
	v_add_f32_e32 v112, v115, v112
	v_add_f32_e32 v112, 0x3a0637bd, v112
	v_mul_f32_e32 v112, 0x3b000000, v112
	v_cmp_gt_f32_e32 vcc, s67, v112
	v_mul_f32_e32 v113, 0x4b800000, v112
	s_nop 0
	v_cndmask_b32_e32 v112, v112, v113, vcc
	v_rsq_f32_e32 v112, v112
	s_nop 0
	v_mul_f32_e32 v113, 0x45800000, v112
	v_cndmask_b32_e32 v112, v112, v113, vcc
	v_mul_f32_e32 v108, v108, v112
	v_mul_f32_e32 v109, v109, v112
	v_mul_f32_e32 v113, v104, v112
	v_cvt_pk_bf16_f32 v104, v108, v109
	v_mad_i64_i32 v[108:109], s[18:19], v124, s7, v[120:121]
	v_mul_f32_e32 v107, v107, v112
	v_lshl_add_u64 v[108:109], v[108:109], 0, v[122:123]
	v_mul_f32_e32 v110, v110, v112
	v_mul_f32_e32 v111, v111, v112
	v_mul_f32_e32 v114, v105, v112
	v_mul_f32_e32 v115, v106, v112
	v_cvt_pk_bf16_f32 v105, v110, v111
	v_cvt_pk_bf16_f32 v106, v113, v114
	v_cvt_pk_bf16_f32 v107, v115, v107
	global_store_dwordx4 v[108:109], v[104:107], off
	v_mul_f32_e32 v100, v100, v112
	v_mul_f32_e32 v101, v101, v112
	v_mul_f32_e32 v104, v96, v112
	v_mul_f32_e32 v102, v102, v112
	v_mul_f32_e32 v103, v103, v112
	v_mul_f32_e32 v105, v97, v112
	v_mul_f32_e32 v106, v98, v112
	v_cvt_pk_bf16_f32 v96, v100, v101
	v_cvt_pk_bf16_f32 v97, v102, v103
	v_cvt_pk_bf16_f32 v98, v104, v105
	v_add_u32_e32 v104, 32, v138
	v_mul_f32_e32 v99, v99, v112
	v_ashrrev_i32_e32 v105, 31, v104
	v_cvt_pk_bf16_f32 v99, v106, v99
	global_store_dwordx4 v[108:109], v[96:99], off offset:256
	s_nop 1
	v_lshlrev_b64 v[96:97], 5, v[104:105]
	v_lshl_add_u64 v[100:101], s[4:5], 0, v[96:97]
	global_load_dwordx4 v[96:99], v[100:101], off offset:16
	s_nop 0
	global_load_dwordx4 v[100:103], v[100:101], off
	s_waitcnt vmcnt(0)
	v_add_f32_e32 v100, v100, v101
	v_add_f32_e32 v100, v102, v100
	v_add_f32_e32 v100, v103, v100
	v_add_f32_e32 v96, v96, v100
	v_add_f32_e32 v96, v97, v96
	v_add_f32_e32 v96, v98, v96
	v_add_f32_e32 v96, v99, v96
	v_add_f32_e32 v96, 0x3a0637bd, v96
	v_mul_f32_e32 v96, 0x3b000000, v96
	v_cmp_gt_f32_e32 vcc, s67, v96
	v_mul_f32_e32 v97, 0x4b800000, v96
	s_nop 0
	v_cndmask_b32_e32 v96, v96, v97, vcc
	v_rsq_f32_e32 v96, v96
	s_nop 0
	v_mul_f32_e32 v97, 0x45800000, v96
	v_cndmask_b32_e32 v96, v96, v97, vcc
	v_mul_f32_e32 v92, v92, v96
	v_mul_f32_e32 v93, v93, v96
	v_mul_f32_e32 v97, v88, v96
	v_cvt_pk_bf16_f32 v88, v92, v93
	v_mad_i64_i32 v[92:93], s[18:19], v104, s7, v[120:121]
	v_mul_f32_e32 v91, v91, v96
	v_lshl_add_u64 v[92:93], v[92:93], 0, v[122:123]
	v_mul_f32_e32 v94, v94, v96
	v_mul_f32_e32 v95, v95, v96
	v_mul_f32_e32 v98, v89, v96
	v_mul_f32_e32 v99, v90, v96
	v_cvt_pk_bf16_f32 v89, v94, v95
	v_cvt_pk_bf16_f32 v90, v97, v98
	v_cvt_pk_bf16_f32 v91, v99, v91
	global_store_dwordx4 v[92:93], v[88:91], off
	v_mul_f32_e32 v84, v84, v96
	v_mul_f32_e32 v85, v85, v96
	v_mul_f32_e32 v88, v80, v96
	v_mul_f32_e32 v86, v86, v96
	v_mul_f32_e32 v87, v87, v96
	v_mul_f32_e32 v89, v81, v96
	v_mul_f32_e32 v90, v82, v96
	v_cvt_pk_bf16_f32 v80, v84, v85
	v_cvt_pk_bf16_f32 v81, v86, v87
	v_cvt_pk_bf16_f32 v82, v88, v89
	v_add_u32_e32 v88, 48, v138
	v_mul_f32_e32 v83, v83, v96
	v_ashrrev_i32_e32 v89, 31, v88
	v_cvt_pk_bf16_f32 v83, v90, v83
	global_store_dwordx4 v[92:93], v[80:83], off offset:256
	s_nop 1
	v_lshlrev_b64 v[80:81], 5, v[88:89]
	v_lshl_add_u64 v[84:85], s[4:5], 0, v[80:81]
	global_load_dwordx4 v[80:83], v[84:85], off offset:16
	s_nop 0
	global_load_dwordx4 v[84:87], v[84:85], off
	s_waitcnt vmcnt(0)
	v_add_f32_e32 v84, v84, v85
	v_add_f32_e32 v84, v86, v84
	v_add_f32_e32 v84, v87, v84
	v_add_f32_e32 v80, v80, v84
	v_add_f32_e32 v80, v81, v80
	v_add_f32_e32 v80, v82, v80
	v_add_f32_e32 v80, v83, v80
	v_add_f32_e32 v80, 0x3a0637bd, v80
	v_mul_f32_e32 v80, 0x3b000000, v80
	v_cmp_gt_f32_e32 vcc, s67, v80
	v_mul_f32_e32 v81, 0x4b800000, v80
	s_nop 0
	v_cndmask_b32_e32 v80, v80, v81, vcc
	v_rsq_f32_e32 v80, v80
	s_nop 0
	v_mul_f32_e32 v81, 0x45800000, v80
	v_cndmask_b32_e32 v80, v80, v81, vcc
	v_mul_f32_e32 v76, v76, v80
	v_mul_f32_e32 v77, v77, v80
	v_mul_f32_e32 v81, v72, v80
	v_cvt_pk_bf16_f32 v72, v76, v77
	v_mad_i64_i32 v[76:77], s[18:19], v88, s7, v[120:121]
	v_mul_f32_e32 v75, v75, v80
	v_lshl_add_u64 v[76:77], v[76:77], 0, v[122:123]
	v_mul_f32_e32 v78, v78, v80
	v_mul_f32_e32 v79, v79, v80
	v_mul_f32_e32 v82, v73, v80
	v_mul_f32_e32 v83, v74, v80
	v_cvt_pk_bf16_f32 v73, v78, v79
	v_cvt_pk_bf16_f32 v74, v81, v82
	v_cvt_pk_bf16_f32 v75, v83, v75
	global_store_dwordx4 v[76:77], v[72:75], off
	v_mul_f32_e32 v68, v68, v80
	v_mul_f32_e32 v69, v69, v80
	v_mul_f32_e32 v72, v64, v80
	v_mul_f32_e32 v70, v70, v80
	v_mul_f32_e32 v71, v71, v80
	v_mul_f32_e32 v73, v65, v80
	v_mul_f32_e32 v74, v66, v80
	v_cvt_pk_bf16_f32 v64, v68, v69
	v_cvt_pk_bf16_f32 v65, v70, v71
	v_cvt_pk_bf16_f32 v66, v72, v73
	v_add_u32_e32 v72, 0x80, v138
	v_mul_f32_e32 v67, v67, v80
	v_ashrrev_i32_e32 v73, 31, v72
	v_cvt_pk_bf16_f32 v67, v74, v67
	global_store_dwordx4 v[76:77], v[64:67], off offset:256
	s_nop 1
	v_lshlrev_b64 v[64:65], 5, v[72:73]
	v_lshl_add_u64 v[68:69], s[4:5], 0, v[64:65]
	global_load_dwordx4 v[64:67], v[68:69], off offset:16
	s_nop 0
	global_load_dwordx4 v[68:71], v[68:69], off
	s_waitcnt vmcnt(0)
	v_add_f32_e32 v68, v68, v69
	v_add_f32_e32 v68, v70, v68
	v_add_f32_e32 v68, v71, v68
	v_add_f32_e32 v64, v64, v68
	v_add_f32_e32 v64, v65, v64
	v_add_f32_e32 v64, v66, v64
	v_add_f32_e32 v64, v67, v64
	v_add_f32_e32 v64, 0x3a0637bd, v64
	v_mul_f32_e32 v64, 0x3b000000, v64
	v_cmp_gt_f32_e32 vcc, s67, v64
	v_mul_f32_e32 v65, 0x4b800000, v64
	s_nop 0
	v_cndmask_b32_e32 v64, v64, v65, vcc
	v_rsq_f32_e32 v64, v64
	s_nop 0
	v_mul_f32_e32 v65, 0x45800000, v64
	v_cndmask_b32_e32 v64, v64, v65, vcc
	v_mul_f32_e32 v60, v60, v64
	v_mul_f32_e32 v61, v61, v64
	v_mul_f32_e32 v65, v56, v64
	v_cvt_pk_bf16_f32 v56, v60, v61
	v_mad_i64_i32 v[60:61], s[18:19], v72, s7, v[120:121]
	v_mul_f32_e32 v59, v59, v64
	v_lshl_add_u64 v[60:61], v[60:61], 0, v[122:123]
	v_mul_f32_e32 v62, v62, v64
	v_mul_f32_e32 v63, v63, v64
	v_mul_f32_e32 v66, v57, v64
	v_mul_f32_e32 v67, v58, v64
	v_cvt_pk_bf16_f32 v57, v62, v63
	v_cvt_pk_bf16_f32 v58, v65, v66
	v_cvt_pk_bf16_f32 v59, v67, v59
	global_store_dwordx4 v[60:61], v[56:59], off
	v_mul_f32_e32 v52, v52, v64
	v_mul_f32_e32 v53, v53, v64
	v_mul_f32_e32 v56, v48, v64
	v_mul_f32_e32 v54, v54, v64
	v_mul_f32_e32 v55, v55, v64
	v_mul_f32_e32 v57, v49, v64
	v_mul_f32_e32 v58, v50, v64
	v_cvt_pk_bf16_f32 v48, v52, v53
	v_cvt_pk_bf16_f32 v49, v54, v55
	v_cvt_pk_bf16_f32 v50, v56, v57
	v_add_u32_e32 v56, 0x90, v138
	v_mul_f32_e32 v51, v51, v64
	v_ashrrev_i32_e32 v57, 31, v56
	v_cvt_pk_bf16_f32 v51, v58, v51
	global_store_dwordx4 v[60:61], v[48:51], off offset:256
	s_nop 1
	v_lshlrev_b64 v[48:49], 5, v[56:57]
	v_lshl_add_u64 v[52:53], s[4:5], 0, v[48:49]
	global_load_dwordx4 v[48:51], v[52:53], off offset:16
	s_nop 0
	global_load_dwordx4 v[52:55], v[52:53], off
	s_waitcnt vmcnt(0)
	v_add_f32_e32 v52, v52, v53
	v_add_f32_e32 v52, v54, v52
	v_add_f32_e32 v52, v55, v52
	v_add_f32_e32 v48, v48, v52
	v_add_f32_e32 v48, v49, v48
	v_add_f32_e32 v48, v50, v48
	v_add_f32_e32 v48, v51, v48
	v_add_f32_e32 v48, 0x3a0637bd, v48
	v_mul_f32_e32 v48, 0x3b000000, v48
	v_cmp_gt_f32_e32 vcc, s67, v48
	v_mul_f32_e32 v49, 0x4b800000, v48
	s_nop 0
	v_cndmask_b32_e32 v48, v48, v49, vcc
	v_rsq_f32_e32 v48, v48
	s_nop 0
	v_mul_f32_e32 v49, 0x45800000, v48
	v_cndmask_b32_e32 v48, v48, v49, vcc
	v_mul_f32_e32 v44, v44, v48
	v_mul_f32_e32 v45, v45, v48
	v_mul_f32_e32 v49, v40, v48
	v_cvt_pk_bf16_f32 v40, v44, v45
	v_mad_i64_i32 v[44:45], s[18:19], v56, s7, v[120:121]
	v_mul_f32_e32 v43, v43, v48
	v_lshl_add_u64 v[44:45], v[44:45], 0, v[122:123]
	v_mul_f32_e32 v46, v46, v48
	v_mul_f32_e32 v47, v47, v48
	v_mul_f32_e32 v50, v41, v48
	v_mul_f32_e32 v51, v42, v48
	v_cvt_pk_bf16_f32 v41, v46, v47
	v_cvt_pk_bf16_f32 v42, v49, v50
	v_cvt_pk_bf16_f32 v43, v51, v43
	global_store_dwordx4 v[44:45], v[40:43], off
	v_mul_f32_e32 v36, v36, v48
	v_mul_f32_e32 v37, v37, v48
	v_mul_f32_e32 v40, v32, v48
	v_mul_f32_e32 v38, v38, v48
	v_mul_f32_e32 v39, v39, v48
	v_mul_f32_e32 v41, v33, v48
	v_mul_f32_e32 v42, v34, v48
	v_cvt_pk_bf16_f32 v32, v36, v37
	v_cvt_pk_bf16_f32 v33, v38, v39
	v_cvt_pk_bf16_f32 v34, v40, v41
	v_add_u32_e32 v40, 0xa0, v138
	v_mul_f32_e32 v35, v35, v48
	v_ashrrev_i32_e32 v41, 31, v40
	v_cvt_pk_bf16_f32 v35, v42, v35
	global_store_dwordx4 v[44:45], v[32:35], off offset:256
	s_nop 1
	v_lshlrev_b64 v[32:33], 5, v[40:41]
	v_lshl_add_u64 v[36:37], s[4:5], 0, v[32:33]
	global_load_dwordx4 v[32:35], v[36:37], off offset:16
	s_nop 0
	global_load_dwordx4 v[36:39], v[36:37], off
	s_waitcnt vmcnt(0)
	v_add_f32_e32 v36, v36, v37
	v_add_f32_e32 v36, v38, v36
	v_add_f32_e32 v36, v39, v36
	v_add_f32_e32 v32, v32, v36
	v_add_f32_e32 v32, v33, v32
	v_add_f32_e32 v32, v34, v32
	v_add_f32_e32 v32, v35, v32
	v_add_f32_e32 v32, 0x3a0637bd, v32
	v_mul_f32_e32 v32, 0x3b000000, v32
	v_cmp_gt_f32_e32 vcc, s67, v32
	v_mul_f32_e32 v33, 0x4b800000, v32
	s_nop 0
	v_cndmask_b32_e32 v32, v32, v33, vcc
	v_rsq_f32_e32 v32, v32
	s_nop 0
	v_mul_f32_e32 v33, 0x45800000, v32
	v_cndmask_b32_e32 v32, v32, v33, vcc
	v_mul_f32_e32 v28, v28, v32
	v_mul_f32_e32 v29, v29, v32
	v_mul_f32_e32 v33, v24, v32
	v_cvt_pk_bf16_f32 v24, v28, v29
	v_mad_i64_i32 v[28:29], s[18:19], v40, s7, v[120:121]
	v_mul_f32_e32 v27, v27, v32
	v_lshl_add_u64 v[28:29], v[28:29], 0, v[122:123]
	v_mul_f32_e32 v30, v30, v32
	v_mul_f32_e32 v31, v31, v32
	v_mul_f32_e32 v34, v25, v32
	v_mul_f32_e32 v35, v26, v32
	v_cvt_pk_bf16_f32 v25, v30, v31
	v_cvt_pk_bf16_f32 v26, v33, v34
	v_cvt_pk_bf16_f32 v27, v35, v27
	global_store_dwordx4 v[28:29], v[24:27], off
	v_mul_f32_e32 v20, v20, v32
	v_mul_f32_e32 v21, v21, v32
	v_mul_f32_e32 v24, v16, v32
	v_mul_f32_e32 v22, v22, v32
	v_mul_f32_e32 v23, v23, v32
	v_mul_f32_e32 v25, v17, v32
	v_mul_f32_e32 v26, v18, v32
	v_cvt_pk_bf16_f32 v16, v20, v21
	v_cvt_pk_bf16_f32 v17, v22, v23
	v_cvt_pk_bf16_f32 v18, v24, v25
	v_add_u32_e32 v24, 0xb0, v138
	v_mul_f32_e32 v19, v19, v32
	v_ashrrev_i32_e32 v25, 31, v24
	v_cvt_pk_bf16_f32 v19, v26, v19
	global_store_dwordx4 v[28:29], v[16:19], off offset:256
	s_nop 1
	v_lshlrev_b64 v[16:17], 5, v[24:25]
	v_lshl_add_u64 v[20:21], s[4:5], 0, v[16:17]
	global_load_dwordx4 v[16:19], v[20:21], off offset:16
	s_nop 0
	global_load_dwordx4 v[20:23], v[20:21], off
	s_waitcnt vmcnt(0)
	v_add_f32_e32 v20, v20, v21
	v_add_f32_e32 v20, v22, v20
	v_add_f32_e32 v20, v23, v20
	v_add_f32_e32 v16, v16, v20
	v_add_f32_e32 v16, v17, v16
	v_add_f32_e32 v16, v18, v16
	v_add_f32_e32 v16, v19, v16
	v_add_f32_e32 v16, 0x3a0637bd, v16
	v_mul_f32_e32 v16, 0x3b000000, v16
	v_cmp_gt_f32_e32 vcc, s67, v16
	v_mul_f32_e32 v17, 0x4b800000, v16
	s_nop 0
	v_cndmask_b32_e32 v16, v16, v17, vcc
	v_rsq_f32_e32 v16, v16
	s_nop 0
	v_mul_f32_e32 v17, 0x45800000, v16
	v_cndmask_b32_e32 v16, v16, v17, vcc
	v_mul_f32_e32 v12, v12, v16
	v_mul_f32_e32 v13, v13, v16
	v_mul_f32_e32 v17, v8, v16
	v_cvt_pk_bf16_f32 v8, v12, v13
	v_mad_i64_i32 v[12:13], s[18:19], v24, s7, v[120:121]
	v_mul_f32_e32 v14, v14, v16
	v_mul_f32_e32 v15, v15, v16
	v_mul_f32_e32 v18, v9, v16
	v_mul_f32_e32 v19, v10, v16
	v_mul_f32_e32 v11, v11, v16
	v_cvt_pk_bf16_f32 v9, v14, v15
	v_cvt_pk_bf16_f32 v10, v17, v18
	v_lshl_add_u64 v[12:13], v[12:13], 0, v[122:123]
	v_mul_f32_e32 v3, v3, v16
	s_and_b64 vcc, exec, s[10:11]
	s_mov_b64 s[18:19], s[12:13]
	v_cvt_pk_bf16_f32 v11, v19, v11
	global_store_dwordx4 v[12:13], v[8:11], off
	v_mul_f32_e32 v4, v4, v16
	v_mul_f32_e32 v5, v5, v16
	v_mul_f32_e32 v6, v6, v16
	v_mul_f32_e32 v7, v7, v16
	v_mul_f32_e32 v8, v0, v16
	v_mul_f32_e32 v9, v1, v16
	v_mul_f32_e32 v10, v2, v16
	v_cvt_pk_bf16_f32 v0, v4, v5
	v_cvt_pk_bf16_f32 v1, v6, v7
	v_cvt_pk_bf16_f32 v2, v8, v9
	v_cvt_pk_bf16_f32 v3, v10, v3
	global_store_dwordx4 v[12:13], v[0:3], off offset:256
	s_cbranch_vccz .LBB0_149
	s_waitcnt vmcnt(0)
	s_cmpk_gt_u32 s24, 0xff
	s_cbranch_scc1 .LBB0_156
	s_barrier

.LBB0_168:
	s_ashr_i32 s11, s10, 31
	s_lshl_b64 s[16:17], s[10:11], 20
	s_add_u32 s16, s29, s16
	s_addc_u32 s17, s30, s17
	s_and_b64 s[18:19], s[26:27], exec
	s_cselect_b32 s1, s17, s23
	s_cselect_b32 s11, s16, s22
	s_ashr_i32 s13, s12, 31
	s_lshl_b64 s[18:19], s[12:13], 20
	s_add_u32 s18, s31, s18
	s_addc_u32 s19, s33, s19
	s_and_b64 s[26:27], s[26:27], exec
	s_cselect_b32 s13, s19, s25
	s_cselect_b32 s21, s18, s24
	s_add_u32 s22, s22, 0x80080
	s_addc_u32 s23, s23, 0
	s_add_u32 s45, s24, 0x100
	v_mov_b32_e32 v0, 0
	s_addc_u32 s46, s25, 0
	s_mov_b32 s47, -2
	v_mov_b32_e32 v1, v0
	v_mov_b32_e32 v2, v0
	v_mov_b32_e32 v3, v0
	v_mov_b32_e32 v4, v0
	v_mov_b32_e32 v5, v0
	v_mov_b32_e32 v6, v0
	v_mov_b32_e32 v7, v0
	v_mov_b32_e32 v16, v0
	v_mov_b32_e32 v17, v0
	v_mov_b32_e32 v18, v0
	v_mov_b32_e32 v19, v0
	v_mov_b32_e32 v20, v0
	v_mov_b32_e32 v21, v0
	v_mov_b32_e32 v22, v0
	v_mov_b32_e32 v23, v0
	v_mov_b32_e32 v32, v0
	v_mov_b32_e32 v33, v0
	v_mov_b32_e32 v34, v0
	v_mov_b32_e32 v35, v0
	v_mov_b32_e32 v36, v0
	v_mov_b32_e32 v37, v0
	v_mov_b32_e32 v38, v0
	v_mov_b32_e32 v39, v0
	v_mov_b32_e32 v48, v0
	v_mov_b32_e32 v49, v0
	v_mov_b32_e32 v50, v0
	v_mov_b32_e32 v51, v0
	v_mov_b32_e32 v52, v0
	v_mov_b32_e32 v53, v0
	v_mov_b32_e32 v54, v0
	v_mov_b32_e32 v55, v0
	v_mov_b32_e32 v8, v0
	v_mov_b32_e32 v9, v0
	v_mov_b32_e32 v10, v0
	v_mov_b32_e32 v11, v0
	v_mov_b32_e32 v12, v0
	v_mov_b32_e32 v13, v0
	v_mov_b32_e32 v14, v0
	v_mov_b32_e32 v15, v0
	v_mov_b32_e32 v24, v0
	v_mov_b32_e32 v25, v0
	v_mov_b32_e32 v26, v0
	v_mov_b32_e32 v27, v0
	v_mov_b32_e32 v28, v0
	v_mov_b32_e32 v29, v0
	v_mov_b32_e32 v30, v0
	v_mov_b32_e32 v31, v0
	v_mov_b32_e32 v40, v0
	v_mov_b32_e32 v41, v0
	v_mov_b32_e32 v42, v0
	v_mov_b32_e32 v43, v0
	v_mov_b32_e32 v44, v0
	v_mov_b32_e32 v45, v0
	v_mov_b32_e32 v46, v0
	v_mov_b32_e32 v47, v0
	v_mov_b32_e32 v56, v0
	v_mov_b32_e32 v57, v0
	v_mov_b32_e32 v58, v0
	v_mov_b32_e32 v59, v0
	v_mov_b32_e32 v60, v0
	v_mov_b32_e32 v61, v0
	v_mov_b32_e32 v62, v0
	v_mov_b32_e32 v63, v0
	v_mov_b32_e32 v64, v0
	v_mov_b32_e32 v65, v0
	v_mov_b32_e32 v66, v0
	v_mov_b32_e32 v67, v0
	v_mov_b32_e32 v68, v0
	v_mov_b32_e32 v69, v0
	v_mov_b32_e32 v70, v0
	v_mov_b32_e32 v71, v0
	v_mov_b32_e32 v80, v0
	v_mov_b32_e32 v81, v0
	v_mov_b32_e32 v82, v0
	v_mov_b32_e32 v83, v0
	v_mov_b32_e32 v84, v0
	v_mov_b32_e32 v85, v0
	v_mov_b32_e32 v86, v0
	v_mov_b32_e32 v87, v0
	v_mov_b32_e32 v96, v0
	v_mov_b32_e32 v97, v0
	v_mov_b32_e32 v98, v0
	v_mov_b32_e32 v99, v0
	v_mov_b32_e32 v100, v0
	v_mov_b32_e32 v101, v0
	v_mov_b32_e32 v102, v0
	v_mov_b32_e32 v103, v0
	v_mov_b32_e32 v112, v0
	v_mov_b32_e32 v113, v0
	v_mov_b32_e32 v114, v0
	v_mov_b32_e32 v115, v0
	v_mov_b32_e32 v116, v0
	v_mov_b32_e32 v117, v0
	v_mov_b32_e32 v118, v0
	v_mov_b32_e32 v119, v0
	v_mov_b32_e32 v72, v0
	v_mov_b32_e32 v73, v0
	v_mov_b32_e32 v74, v0
	v_mov_b32_e32 v75, v0
	v_mov_b32_e32 v76, v0
	v_mov_b32_e32 v77, v0
	v_mov_b32_e32 v78, v0
	v_mov_b32_e32 v79, v0
	v_mov_b32_e32 v88, v0
	v_mov_b32_e32 v89, v0
	v_mov_b32_e32 v90, v0
	v_mov_b32_e32 v91, v0
	v_mov_b32_e32 v92, v0
	v_mov_b32_e32 v93, v0
	v_mov_b32_e32 v94, v0
	v_mov_b32_e32 v95, v0
	v_mov_b32_e32 v104, v0
	v_mov_b32_e32 v105, v0
	v_mov_b32_e32 v106, v0
	v_mov_b32_e32 v107, v0
	v_mov_b32_e32 v108, v0
	v_mov_b32_e32 v109, v0
	v_mov_b32_e32 v110, v0
	v_mov_b32_e32 v111, v0
	v_mov_b32_e32 v120, v0
	v_mov_b32_e32 v121, v0
	v_mov_b32_e32 v122, v0
	v_mov_b32_e32 v123, v0
	v_mov_b32_e32 v124, v0
	v_mov_b32_e32 v125, v0
	v_mov_b32_e32 v126, v0
	v_mov_b32_e32 v127, v0
	s_mov_b64 s[52:53], 0x80
	v_add_u32_e32 v154, 0x10000, v144
	ds_read_b128 v[138:141], v154
	ds_read_b128 v[146:149], v154 offset:1024
	ds_read_b128 v[150:153], v154 offset:2048
	ds_read_b128 v[154:157], v154 offset:3072
.LBB0_169:
	s_add_u32 s24, s22, 0xfff80080
	s_addc_u32 s25, s23, -1
	s_add_i32 s48, 0, 0x10000
	s_cmp_eq_u32 s47, 28
	s_cselect_b32 s27, s1, s25
	s_cselect_b32 s26, s11, s24
	s_cselect_b32 s25, s13, s46
	s_cselect_b32 s24, s21, s45
	v_lshl_add_u64 v[182:183], s[22:23], 0, v[134:135]
	s_add_i32 m0, s35, 0xc000
	ds_read_b128 v[158:161], v145
	ds_read_b128 v[162:165], v145 offset:1024
	ds_read_b128 v[166:169], v145 offset:2048
	ds_read_b128 v[170:173], v145 offset:3072
	ds_read_b128 v[174:177], v145 offset:4096
	ds_read_b128 v[178:181], v145 offset:5120
	ds_read_b128 v[188:191], v145 offset:6144
	ds_read_b128 v[192:195], v145 offset:7168
	global_load_lds_dwordx4 v[182:183], off
	v_lshl_add_u64 v[182:183], s[22:23], 0, v[136:137]
	s_add_i32 m0, s35, 0xe000
	s_nop 0
	global_load_lds_dwordx4 v[182:183], off
	s_waitcnt lgkmcnt(8)
	s_setprio 1
	s_barrier
	s_waitcnt lgkmcnt(0)
	v_mfma_f32_16x16x32_bf16 v[124:127], v[138:141], v[158:161], v[124:127]
	v_mfma_f32_16x16x32_bf16 v[120:123], v[150:153], v[158:161], v[120:123]
	v_mfma_f32_16x16x32_bf16 v[108:111], v[138:141], v[166:169], v[108:111]
	v_mfma_f32_16x16x32_bf16 v[104:107], v[150:153], v[166:169], v[104:107]
	v_mfma_f32_16x16x32_bf16 v[92:95], v[138:141], v[174:177], v[92:95]
	v_mfma_f32_16x16x32_bf16 v[88:91], v[150:153], v[174:177], v[88:91]
	v_mfma_f32_16x16x32_bf16 v[76:79], v[138:141], v[188:191], v[76:79]
	v_mfma_f32_16x16x32_bf16 v[72:75], v[150:153], v[188:191], v[72:75]
	v_mfma_f32_16x16x32_bf16 v[124:127], v[146:149], v[162:165], v[124:127]
	v_mfma_f32_16x16x32_bf16 v[120:123], v[154:157], v[162:165], v[120:123]
	v_mfma_f32_16x16x32_bf16 v[108:111], v[146:149], v[170:173], v[108:111]
	v_mfma_f32_16x16x32_bf16 v[104:107], v[154:157], v[170:173], v[104:107]
	v_mfma_f32_16x16x32_bf16 v[92:95], v[146:149], v[178:181], v[92:95]
	v_mfma_f32_16x16x32_bf16 v[88:91], v[154:157], v[178:181], v[88:91]
	v_mfma_f32_16x16x32_bf16 v[76:79], v[146:149], v[192:195], v[76:79]
	v_mfma_f32_16x16x32_bf16 v[72:75], v[154:157], v[192:195], v[72:75]
	s_barrier
	s_setprio 0
	s_add_i32 s50, 0, 0x14000
	v_add_u32_e32 v182, s50, v144
	s_add_i32 s48, s48, s34
	ds_read_b128 v[202:205], v182
	ds_read_b128 v[206:209], v182 offset:1024
	ds_read_b128 v[210:213], v182 offset:2048
	ds_read_b128 v[214:217], v182 offset:3072
	v_lshl_add_u64 v[182:183], s[24:25], 0, v[184:185]
	s_mov_b32 m0, s48
	v_lshl_add_u64 v[196:197], s[24:25], 0, v[132:133]
	global_load_lds_dwordx4 v[182:183], off
	s_add_i32 m0, s48, 0x2000
	s_nop 0
	global_load_lds_dwordx4 v[196:197], off
	s_setprio 1
	s_barrier
	s_waitcnt lgkmcnt(0)
	v_mfma_f32_16x16x32_bf16 v[116:119], v[202:205], v[158:161], v[116:119]
	v_mfma_f32_16x16x32_bf16 v[112:115], v[210:213], v[158:161], v[112:115]
	v_mfma_f32_16x16x32_bf16 v[100:103], v[202:205], v[166:169], v[100:103]
	v_mfma_f32_16x16x32_bf16 v[96:99], v[210:213], v[166:169], v[96:99]
	v_mfma_f32_16x16x32_bf16 v[84:87], v[202:205], v[174:177], v[84:87]
	v_mfma_f32_16x16x32_bf16 v[80:83], v[210:213], v[174:177], v[80:83]
	v_mfma_f32_16x16x32_bf16 v[68:71], v[202:205], v[188:191], v[68:71]
	v_mfma_f32_16x16x32_bf16 v[64:67], v[210:213], v[188:191], v[64:67]
	v_mfma_f32_16x16x32_bf16 v[116:119], v[206:209], v[162:165], v[116:119]
	v_mfma_f32_16x16x32_bf16 v[112:115], v[214:217], v[162:165], v[112:115]
	v_mfma_f32_16x16x32_bf16 v[100:103], v[206:209], v[170:173], v[100:103]
	v_mfma_f32_16x16x32_bf16 v[96:99], v[214:217], v[170:173], v[96:99]
	v_mfma_f32_16x16x32_bf16 v[84:87], v[206:209], v[178:181], v[84:87]
	v_mfma_f32_16x16x32_bf16 v[80:83], v[214:217], v[178:181], v[80:83]
	v_mfma_f32_16x16x32_bf16 v[68:71], v[206:209], v[192:195], v[68:71]
	v_mfma_f32_16x16x32_bf16 v[64:67], v[214:217], v[192:195], v[64:67]
	s_barrier
	s_setprio 0
	s_mov_b32 m0, s35
	v_lshl_add_u64 v[218:219], s[26:27], 0, v[128:129]
	ds_read_b128 v[158:161], v145 offset:16384
	ds_read_b128 v[162:165], v145 offset:17408
	ds_read_b128 v[166:169], v145 offset:18432
	ds_read_b128 v[170:173], v145 offset:19456
	ds_read_b128 v[174:177], v145 offset:20480
	ds_read_b128 v[178:181], v145 offset:21504
	ds_read_b128 v[188:191], v145 offset:22528
	ds_read_b128 v[192:195], v145 offset:23552
	global_load_lds_dwordx4 v[218:219], off
	v_lshl_add_u64 v[220:221], s[26:27], 0, v[130:131]
	s_mov_b32 m0, s36
	s_nop 0
	global_load_lds_dwordx4 v[220:221], off
	s_setprio 1
	s_waitcnt vmcnt(10)
	s_barrier
	s_waitcnt lgkmcnt(0)
	v_mfma_f32_16x16x32_bf16 v[60:63], v[138:141], v[158:161], v[60:63]
	v_mfma_f32_16x16x32_bf16 v[56:59], v[150:153], v[158:161], v[56:59]
	v_mfma_f32_16x16x32_bf16 v[44:47], v[138:141], v[166:169], v[44:47]
	v_mfma_f32_16x16x32_bf16 v[40:43], v[150:153], v[166:169], v[40:43]
	v_mfma_f32_16x16x32_bf16 v[28:31], v[138:141], v[174:177], v[28:31]
	v_mfma_f32_16x16x32_bf16 v[24:27], v[150:153], v[174:177], v[24:27]
	v_mfma_f32_16x16x32_bf16 v[12:15], v[138:141], v[188:191], v[12:15]
	v_mfma_f32_16x16x32_bf16 v[8:11], v[150:153], v[188:191], v[8:11]
	v_mfma_f32_16x16x32_bf16 v[60:63], v[146:149], v[162:165], v[60:63]
	v_mfma_f32_16x16x32_bf16 v[56:59], v[154:157], v[162:165], v[56:59]
	v_mfma_f32_16x16x32_bf16 v[44:47], v[146:149], v[170:173], v[44:47]
	v_mfma_f32_16x16x32_bf16 v[40:43], v[154:157], v[170:173], v[40:43]
	v_mfma_f32_16x16x32_bf16 v[28:31], v[146:149], v[178:181], v[28:31]
	v_mfma_f32_16x16x32_bf16 v[24:27], v[154:157], v[178:181], v[24:27]
	v_mfma_f32_16x16x32_bf16 v[12:15], v[146:149], v[192:195], v[12:15]
	v_mfma_f32_16x16x32_bf16 v[8:11], v[154:157], v[192:195], v[8:11]
	s_barrier
	s_setprio 0
	v_add_u32_e32 v154, 0x18000, v144
	ds_read_b128 v[138:141], v154
	ds_read_b128 v[146:149], v154 offset:1024
	ds_read_b128 v[150:153], v154 offset:2048
	ds_read_b128 v[154:157], v154 offset:3072
	s_add_u32 s48, s24, 0x80000
	s_addc_u32 s49, s25, 0
	s_add_i32 s50, s50, s34
	v_lshl_add_u64 v[246:247], s[48:49], 0, v[184:185]
	s_mov_b32 m0, s50
	s_nop 0
	global_load_lds_dwordx4 v[246:247], off
	v_lshl_add_u64 v[248:249], s[48:49], 0, v[132:133]
	s_add_i32 m0, s50, 0x2000
	s_nop 0
	global_load_lds_dwordx4 v[248:249], off
	s_waitcnt vmcnt(6)
	s_setprio 1
	s_barrier
	v_mfma_f32_16x16x32_bf16 v[52:55], v[202:205], v[158:161], v[52:55]
	v_mfma_f32_16x16x32_bf16 v[48:51], v[210:213], v[158:161], v[48:51]
	v_mfma_f32_16x16x32_bf16 v[36:39], v[202:205], v[166:169], v[36:39]
	v_mfma_f32_16x16x32_bf16 v[32:35], v[210:213], v[166:169], v[32:35]
	v_mfma_f32_16x16x32_bf16 v[20:23], v[202:205], v[174:177], v[20:23]
	v_mfma_f32_16x16x32_bf16 v[16:19], v[210:213], v[174:177], v[16:19]
	v_mfma_f32_16x16x32_bf16 v[4:7], v[202:205], v[188:191], v[4:7]
	v_mfma_f32_16x16x32_bf16 v[0:3], v[210:213], v[188:191], v[0:3]
	v_mfma_f32_16x16x32_bf16 v[52:55], v[206:209], v[162:165], v[52:55]
	v_mfma_f32_16x16x32_bf16 v[48:51], v[214:217], v[162:165], v[48:51]
	v_mfma_f32_16x16x32_bf16 v[36:39], v[206:209], v[170:173], v[36:39]
	v_mfma_f32_16x16x32_bf16 v[32:35], v[214:217], v[170:173], v[32:35]
	v_mfma_f32_16x16x32_bf16 v[20:23], v[206:209], v[178:181], v[20:23]
	v_mfma_f32_16x16x32_bf16 v[16:19], v[214:217], v[178:181], v[16:19]
	v_mfma_f32_16x16x32_bf16 v[4:7], v[206:209], v[192:195], v[4:7]
	v_mfma_f32_16x16x32_bf16 v[0:3], v[214:217], v[192:195], v[0:3]
	s_barrier
	s_setprio 0
	s_add_i32 s48, 0, 0x18000
	s_add_u32 s26, s26, 0x80000
	s_addc_u32 s27, s27, 0
	s_mov_b32 m0, s37
	v_lshl_add_u64 v[202:203], s[26:27], 0, v[128:129]
	ds_read_b128 v[158:161], v145 offset:32768
	ds_read_b128 v[162:165], v145 offset:33792
	ds_read_b128 v[166:169], v145 offset:34816
	ds_read_b128 v[170:173], v145 offset:35840
	ds_read_b128 v[174:177], v145 offset:36864
	ds_read_b128 v[178:181], v145 offset:37888
	ds_read_b128 v[188:191], v145 offset:38912
	ds_read_b128 v[192:195], v145 offset:39936
	global_load_lds_dwordx4 v[202:203], off
	v_lshl_add_u64 v[202:203], s[26:27], 0, v[130:131]
	s_mov_b32 m0, s38
	s_nop 0
	global_load_lds_dwordx4 v[202:203], off
	s_waitcnt lgkmcnt(8)
	s_setprio 1
	s_barrier
	s_waitcnt lgkmcnt(0)
	v_mfma_f32_16x16x32_bf16 v[124:127], v[138:141], v[158:161], v[124:127]
	v_mfma_f32_16x16x32_bf16 v[120:123], v[150:153], v[158:161], v[120:123]
	v_mfma_f32_16x16x32_bf16 v[108:111], v[138:141], v[166:169], v[108:111]
	v_mfma_f32_16x16x32_bf16 v[104:107], v[150:153], v[166:169], v[104:107]
	v_mfma_f32_16x16x32_bf16 v[92:95], v[138:141], v[174:177], v[92:95]
	v_mfma_f32_16x16x32_bf16 v[88:91], v[150:153], v[174:177], v[88:91]
	v_mfma_f32_16x16x32_bf16 v[76:79], v[138:141], v[188:191], v[76:79]
	v_mfma_f32_16x16x32_bf16 v[72:75], v[150:153], v[188:191], v[72:75]
	v_mfma_f32_16x16x32_bf16 v[124:127], v[146:149], v[162:165], v[124:127]
	v_mfma_f32_16x16x32_bf16 v[120:123], v[154:157], v[162:165], v[120:123]
	v_mfma_f32_16x16x32_bf16 v[108:111], v[146:149], v[170:173], v[108:111]
	v_mfma_f32_16x16x32_bf16 v[104:107], v[154:157], v[170:173], v[104:107]
	v_mfma_f32_16x16x32_bf16 v[92:95], v[146:149], v[178:181], v[92:95]
	v_mfma_f32_16x16x32_bf16 v[88:91], v[154:157], v[178:181], v[88:91]
	v_mfma_f32_16x16x32_bf16 v[76:79], v[146:149], v[192:195], v[76:79]
	v_mfma_f32_16x16x32_bf16 v[72:75], v[154:157], v[192:195], v[72:75]
	s_barrier
	s_setprio 0
	s_add_i32 s26, 0, 0x1c000
	s_add_i32 s27, s48, s34
	v_add_u32_e32 v187, s26, v144
	v_lshl_add_u64 v[182:183], v[182:183], 0, s[52:53]
	s_mov_b32 m0, s27
	ds_read_b128 v[202:205], v187
	ds_read_b128 v[206:209], v187 offset:1024
	ds_read_b128 v[210:213], v187 offset:2048
	ds_read_b128 v[214:217], v187 offset:3072
	global_load_lds_dwordx4 v[182:183], off
	v_lshl_add_u64 v[182:183], v[196:197], 0, s[52:53]
	s_add_i32 m0, s27, 0x2000
	s_nop 0
	global_load_lds_dwordx4 v[182:183], off
	s_setprio 1
	s_barrier
	s_waitcnt lgkmcnt(0)
	v_mfma_f32_16x16x32_bf16 v[116:119], v[202:205], v[158:161], v[116:119]
	v_mfma_f32_16x16x32_bf16 v[112:115], v[210:213], v[158:161], v[112:115]
	v_mfma_f32_16x16x32_bf16 v[100:103], v[202:205], v[166:169], v[100:103]
	v_mfma_f32_16x16x32_bf16 v[96:99], v[210:213], v[166:169], v[96:99]
	v_mfma_f32_16x16x32_bf16 v[84:87], v[202:205], v[174:177], v[84:87]
	v_mfma_f32_16x16x32_bf16 v[80:83], v[210:213], v[174:177], v[80:83]
	v_mfma_f32_16x16x32_bf16 v[68:71], v[202:205], v[188:191], v[68:71]
	v_mfma_f32_16x16x32_bf16 v[64:67], v[210:213], v[188:191], v[64:67]
	v_mfma_f32_16x16x32_bf16 v[116:119], v[206:209], v[162:165], v[116:119]
	v_mfma_f32_16x16x32_bf16 v[112:115], v[214:217], v[162:165], v[112:115]
	v_mfma_f32_16x16x32_bf16 v[100:103], v[206:209], v[170:173], v[100:103]
	v_mfma_f32_16x16x32_bf16 v[96:99], v[214:217], v[170:173], v[96:99]
	v_mfma_f32_16x16x32_bf16 v[84:87], v[206:209], v[178:181], v[84:87]
	v_mfma_f32_16x16x32_bf16 v[80:83], v[214:217], v[178:181], v[80:83]
	v_mfma_f32_16x16x32_bf16 v[68:71], v[206:209], v[192:195], v[68:71]
	v_mfma_f32_16x16x32_bf16 v[64:67], v[214:217], v[192:195], v[64:67]
	s_barrier
	s_setprio 0
	s_mov_b32 m0, s42
	v_lshl_add_u64 v[182:183], v[218:219], 0, s[52:53]
	ds_read_b128 v[158:161], v145 offset:49152
	ds_read_b128 v[162:165], v145 offset:50176
	ds_read_b128 v[166:169], v145 offset:51200
	ds_read_b128 v[170:173], v145 offset:52224
	ds_read_b128 v[174:177], v145 offset:53248
	ds_read_b128 v[178:181], v145 offset:54272
	ds_read_b128 v[188:191], v145 offset:55296
	ds_read_b128 v[192:195], v145 offset:56320
	global_load_lds_dwordx4 v[182:183], off
	v_lshl_add_u64 v[182:183], v[220:221], 0, s[52:53]
	s_mov_b32 m0, s43
	s_nop 0
	global_load_lds_dwordx4 v[182:183], off
	s_setprio 1
	s_waitcnt vmcnt(10)
	s_barrier
	s_waitcnt lgkmcnt(0)
	v_mfma_f32_16x16x32_bf16 v[60:63], v[138:141], v[158:161], v[60:63]
	v_mfma_f32_16x16x32_bf16 v[56:59], v[150:153], v[158:161], v[56:59]
	v_mfma_f32_16x16x32_bf16 v[44:47], v[138:141], v[166:169], v[44:47]
	v_mfma_f32_16x16x32_bf16 v[40:43], v[150:153], v[166:169], v[40:43]
	v_mfma_f32_16x16x32_bf16 v[28:31], v[138:141], v[174:177], v[28:31]
	v_mfma_f32_16x16x32_bf16 v[24:27], v[150:153], v[174:177], v[24:27]
	v_mfma_f32_16x16x32_bf16 v[12:15], v[138:141], v[188:191], v[12:15]
	v_mfma_f32_16x16x32_bf16 v[8:11], v[150:153], v[188:191], v[8:11]
	v_mfma_f32_16x16x32_bf16 v[60:63], v[146:149], v[162:165], v[60:63]
	v_mfma_f32_16x16x32_bf16 v[56:59], v[154:157], v[162:165], v[56:59]
	v_mfma_f32_16x16x32_bf16 v[44:47], v[146:149], v[170:173], v[44:47]
	v_mfma_f32_16x16x32_bf16 v[40:43], v[154:157], v[170:173], v[40:43]
	v_mfma_f32_16x16x32_bf16 v[28:31], v[146:149], v[178:181], v[28:31]
	v_mfma_f32_16x16x32_bf16 v[24:27], v[154:157], v[178:181], v[24:27]
	v_mfma_f32_16x16x32_bf16 v[12:15], v[146:149], v[192:195], v[12:15]
	v_mfma_f32_16x16x32_bf16 v[8:11], v[154:157], v[192:195], v[8:11]
	s_barrier
	s_setprio 0
	v_add_u32_e32 v154, 0x10000, v144
	ds_read_b128 v[138:141], v154
	ds_read_b128 v[146:149], v154 offset:1024
	ds_read_b128 v[150:153], v154 offset:2048
	ds_read_b128 v[154:157], v154 offset:3072
	s_add_u32 s24, s24, 0x80080
	s_addc_u32 s25, s25, 0
	s_add_i32 s26, s26, s34
	v_lshl_add_u64 v[250:251], s[24:25], 0, v[184:185]
	s_mov_b32 m0, s26
	s_nop 0
	global_load_lds_dwordx4 v[250:251], off
	v_lshl_add_u64 v[252:253], s[24:25], 0, v[132:133]
	s_add_i32 m0, s26, 0x2000
	s_nop 0
	global_load_lds_dwordx4 v[252:253], off
	s_waitcnt vmcnt(6)
	s_setprio 1
	s_barrier
	v_mfma_f32_16x16x32_bf16 v[52:55], v[202:205], v[158:161], v[52:55]
	v_mfma_f32_16x16x32_bf16 v[48:51], v[210:213], v[158:161], v[48:51]
	v_mfma_f32_16x16x32_bf16 v[36:39], v[202:205], v[166:169], v[36:39]
	v_mfma_f32_16x16x32_bf16 v[32:35], v[210:213], v[166:169], v[32:35]
	v_mfma_f32_16x16x32_bf16 v[20:23], v[202:205], v[174:177], v[20:23]
	v_mfma_f32_16x16x32_bf16 v[16:19], v[210:213], v[174:177], v[16:19]
	v_mfma_f32_16x16x32_bf16 v[4:7], v[202:205], v[188:191], v[4:7]
	v_mfma_f32_16x16x32_bf16 v[0:3], v[210:213], v[188:191], v[0:3]
	v_mfma_f32_16x16x32_bf16 v[52:55], v[206:209], v[162:165], v[52:55]
	v_mfma_f32_16x16x32_bf16 v[48:51], v[214:217], v[162:165], v[48:51]
	v_mfma_f32_16x16x32_bf16 v[36:39], v[206:209], v[170:173], v[36:39]
	v_mfma_f32_16x16x32_bf16 v[32:35], v[214:217], v[170:173], v[32:35]
	v_mfma_f32_16x16x32_bf16 v[20:23], v[206:209], v[178:181], v[20:23]
	v_mfma_f32_16x16x32_bf16 v[16:19], v[214:217], v[178:181], v[16:19]
	v_mfma_f32_16x16x32_bf16 v[4:7], v[206:209], v[192:195], v[4:7]
	v_mfma_f32_16x16x32_bf16 v[0:3], v[214:217], v[192:195], v[0:3]
	s_barrier
	s_setprio 0
	s_add_i32 s47, s47, 2
	s_add_u32 s22, s22, 0x100
	s_addc_u32 s23, s23, 0
	s_add_u32 s45, s45, 0x100
	s_addc_u32 s46, s46, 0
	s_cmp_gt_u32 s47, 29
	s_cbranch_scc0 .LBB0_169
	s_waitcnt lgkmcnt(0)
	v_mov_b32_e32 v141, v143
	v_mov_b32_e32 v138, v142
	s_lshl_b32 s1, s20, 8
	s_add_i32 s1, s1, s40
	v_add_u32_e32 v138, s1, v138
	s_cmp_gt_i32 s0, 1
	s_mov_b64 s[20:21], -1
	s_cbranch_scc0 .LBB0_174
	s_andn2_b64 vcc, exec, s[6:7]
	s_cbranch_vccnz .LBB0_173
	v_ashrrev_i32_e32 v139, 31, v138
	v_lshlrev_b32_e32 v146, 3, v141
	v_lshlrev_b64 v[148:149], 8, v[138:139]
	v_ashrrev_i32_e32 v147, 31, v146
	v_lshl_add_u64 v[148:149], s[8:9], 0, v[148:149]
	v_lshl_add_u64 v[146:147], v[146:147], 2, v[148:149]
	v_add_co_u32_e32 v150, vcc, 0x1000, v146
	s_mov_b64 s[20:21], 0x1000
	s_nop 0
	v_addc_co_u32_e32 v151, vcc, 0, v147, vcc
	s_movk_i32 s1, 0x2000
	global_store_dwordx4 v[146:147], v[124:127], off
	global_store_dwordx4 v[146:147], v[120:123], off offset:16
	v_lshl_add_u64 v[148:149], v[146:147], 0, s[20:21]
	global_store_dwordx4 v[150:151], v[108:111], off
	global_store_dwordx4 v[148:149], v[104:107], off offset:16
	v_add_co_u32_e32 v150, vcc, s1, v146
	v_lshl_add_u64 v[148:149], v[146:147], 0, s[82:83]
	s_nop 0
	v_addc_co_u32_e32 v151, vcc, 0, v147, vcc
	global_store_dwordx4 v[150:151], v[92:95], off
	global_store_dwordx4 v[148:149], v[88:91], off offset:16
	v_add_co_u32_e32 v150, vcc, 0x3000, v146
	s_mov_b64 s[20:21], 0x3000
	s_nop 0
	v_addc_co_u32_e32 v151, vcc, 0, v147, vcc
	s_mov_b32 s1, 0x8000
	v_lshl_add_u64 v[148:149], v[146:147], 0, s[20:21]
	global_store_dwordx4 v[150:151], v[76:79], off
	global_store_dwordx4 v[148:149], v[72:75], off offset:16
	v_add_co_u32_e32 v150, vcc, s1, v146
	v_lshl_add_u64 v[148:149], v[146:147], 0, s[84:85]
	s_nop 0
	v_addc_co_u32_e32 v151, vcc, 0, v147, vcc
	global_store_dwordx4 v[150:151], v[60:63], off
	global_store_dwordx4 v[148:149], v[56:59], off offset:16
	v_add_co_u32_e32 v150, vcc, 0x9000, v146
	s_mov_b64 s[20:21], 0x9000
	s_nop 0
	v_addc_co_u32_e32 v151, vcc, 0, v147, vcc
	v_lshl_add_u64 v[148:149], v[146:147], 0, s[20:21]
	global_store_dwordx4 v[150:151], v[44:47], off
	global_store_dwordx4 v[148:149], v[40:43], off offset:16
	s_mov_b64 s[20:21], 0xa000
	v_add_co_u32_e32 v150, vcc, 0xa000, v146
	v_lshl_add_u64 v[148:149], v[146:147], 0, s[20:21]
	s_nop 0
	v_addc_co_u32_e32 v151, vcc, 0, v147, vcc
	s_mov_b64 s[20:21], 0xb000
	global_store_dwordx4 v[150:151], v[28:31], off
	global_store_dwordx4 v[148:149], v[24:27], off offset:16
	v_lshl_add_u64 v[148:149], v[146:147], 0, s[20:21]
	v_add_co_u32_e32 v146, vcc, 0xb000, v146
	s_nop 1
	v_addc_co_u32_e32 v147, vcc, 0, v147, vcc
	global_store_dwordx4 v[146:147], v[12:15], off
	global_store_dwordx4 v[148:149], v[8:11], off offset:16

.LBB0_206:
	s_ashr_i32 s9, s8, 31
	s_lshl_b64 s[14:15], s[8:9], 20
	s_add_u32 s14, s27, s14
	s_addc_u32 s15, s28, s15
	s_and_b64 s[16:17], s[24:25], exec
	s_cselect_b32 s1, s15, s21
	s_cselect_b32 s9, s14, s20
	s_ashr_i32 s11, s10, 31
	s_lshl_b64 s[16:17], s[10:11], 20
	s_add_u32 s16, s29, s16
	s_addc_u32 s17, s30, s17
	s_and_b64 s[24:25], s[24:25], exec
	s_cselect_b32 s11, s17, s23
	s_cselect_b32 s19, s16, s22
	s_add_u32 s20, s20, 0x80080
	s_addc_u32 s21, s21, 0
	s_add_u32 s44, s22, 0x100
	v_mov_b32_e32 v0, 0
	s_addc_u32 s45, s23, 0
	s_mov_b32 s46, -2
	v_mov_b32_e32 v1, v0
	v_mov_b32_e32 v2, v0
	v_mov_b32_e32 v3, v0
	v_mov_b32_e32 v4, v0
	v_mov_b32_e32 v5, v0
	v_mov_b32_e32 v6, v0
	v_mov_b32_e32 v7, v0
	v_mov_b32_e32 v16, v0
	v_mov_b32_e32 v17, v0
	v_mov_b32_e32 v18, v0
	v_mov_b32_e32 v19, v0
	v_mov_b32_e32 v20, v0
	v_mov_b32_e32 v21, v0
	v_mov_b32_e32 v22, v0
	v_mov_b32_e32 v23, v0
	v_mov_b32_e32 v32, v0
	v_mov_b32_e32 v33, v0
	v_mov_b32_e32 v34, v0
	v_mov_b32_e32 v35, v0
	v_mov_b32_e32 v36, v0
	v_mov_b32_e32 v37, v0
	v_mov_b32_e32 v38, v0
	v_mov_b32_e32 v39, v0
	v_mov_b32_e32 v48, v0
	v_mov_b32_e32 v49, v0
	v_mov_b32_e32 v50, v0
	v_mov_b32_e32 v51, v0
	v_mov_b32_e32 v52, v0
	v_mov_b32_e32 v53, v0
	v_mov_b32_e32 v54, v0
	v_mov_b32_e32 v55, v0
	v_mov_b32_e32 v8, v0
	v_mov_b32_e32 v9, v0
	v_mov_b32_e32 v10, v0
	v_mov_b32_e32 v11, v0
	v_mov_b32_e32 v12, v0
	v_mov_b32_e32 v13, v0
	v_mov_b32_e32 v14, v0
	v_mov_b32_e32 v15, v0
	v_mov_b32_e32 v24, v0
	v_mov_b32_e32 v25, v0
	v_mov_b32_e32 v26, v0
	v_mov_b32_e32 v27, v0
	v_mov_b32_e32 v28, v0
	v_mov_b32_e32 v29, v0
	v_mov_b32_e32 v30, v0
	v_mov_b32_e32 v31, v0
	v_mov_b32_e32 v40, v0
	v_mov_b32_e32 v41, v0
	v_mov_b32_e32 v42, v0
	v_mov_b32_e32 v43, v0
	v_mov_b32_e32 v44, v0
	v_mov_b32_e32 v45, v0
	v_mov_b32_e32 v46, v0
	v_mov_b32_e32 v47, v0
	v_mov_b32_e32 v56, v0
	v_mov_b32_e32 v57, v0
	v_mov_b32_e32 v58, v0
	v_mov_b32_e32 v59, v0
	v_mov_b32_e32 v60, v0
	v_mov_b32_e32 v61, v0
	v_mov_b32_e32 v62, v0
	v_mov_b32_e32 v63, v0
	v_mov_b32_e32 v64, v0
	v_mov_b32_e32 v65, v0
	v_mov_b32_e32 v66, v0
	v_mov_b32_e32 v67, v0
	v_mov_b32_e32 v68, v0
	v_mov_b32_e32 v69, v0
	v_mov_b32_e32 v70, v0
	v_mov_b32_e32 v71, v0
	v_mov_b32_e32 v80, v0
	v_mov_b32_e32 v81, v0
	v_mov_b32_e32 v82, v0
	v_mov_b32_e32 v83, v0
	v_mov_b32_e32 v84, v0
	v_mov_b32_e32 v85, v0
	v_mov_b32_e32 v86, v0
	v_mov_b32_e32 v87, v0
	v_mov_b32_e32 v96, v0
	v_mov_b32_e32 v97, v0
	v_mov_b32_e32 v98, v0
	v_mov_b32_e32 v99, v0
	v_mov_b32_e32 v100, v0
	v_mov_b32_e32 v101, v0
	v_mov_b32_e32 v102, v0
	v_mov_b32_e32 v103, v0
	v_mov_b32_e32 v112, v0
	v_mov_b32_e32 v113, v0
	v_mov_b32_e32 v114, v0
	v_mov_b32_e32 v115, v0
	v_mov_b32_e32 v116, v0
	v_mov_b32_e32 v117, v0
	v_mov_b32_e32 v118, v0
	v_mov_b32_e32 v119, v0
	v_mov_b32_e32 v72, v0
	v_mov_b32_e32 v73, v0
	v_mov_b32_e32 v74, v0
	v_mov_b32_e32 v75, v0
	v_mov_b32_e32 v76, v0
	v_mov_b32_e32 v77, v0
	v_mov_b32_e32 v78, v0
	v_mov_b32_e32 v79, v0
	v_mov_b32_e32 v88, v0
	v_mov_b32_e32 v89, v0
	v_mov_b32_e32 v90, v0
	v_mov_b32_e32 v91, v0
	v_mov_b32_e32 v92, v0
	v_mov_b32_e32 v93, v0
	v_mov_b32_e32 v94, v0
	v_mov_b32_e32 v95, v0
	v_mov_b32_e32 v104, v0
	v_mov_b32_e32 v105, v0
	v_mov_b32_e32 v106, v0
	v_mov_b32_e32 v107, v0
	v_mov_b32_e32 v108, v0
	v_mov_b32_e32 v109, v0
	v_mov_b32_e32 v110, v0
	v_mov_b32_e32 v111, v0
	v_mov_b32_e32 v120, v0
	v_mov_b32_e32 v121, v0
	v_mov_b32_e32 v122, v0
	v_mov_b32_e32 v123, v0
	v_mov_b32_e32 v124, v0
	v_mov_b32_e32 v125, v0
	v_mov_b32_e32 v126, v0
	v_mov_b32_e32 v127, v0
	s_mov_b64 s[52:53], 0x80
	v_add_u32_e32 v154, 0x10000, v144
	ds_read_b128 v[138:141], v154
	ds_read_b128 v[146:149], v154 offset:1024
	ds_read_b128 v[150:153], v154 offset:2048
	ds_read_b128 v[154:157], v154 offset:3072
.LBB0_207:
	s_add_u32 s22, s20, 0xfff80080
	s_addc_u32 s23, s21, -1
	s_add_i32 s47, 0, 0x10000
	s_cmp_eq_u32 s46, 28
	s_cselect_b32 s25, s1, s23
	s_cselect_b32 s24, s9, s22
	s_cselect_b32 s23, s11, s45
	s_cselect_b32 s22, s19, s44
	v_lshl_add_u64 v[182:183], s[20:21], 0, v[134:135]
	s_add_i32 m0, s33, 0xc000
	ds_read_b128 v[158:161], v145
	ds_read_b128 v[162:165], v145 offset:1024
	ds_read_b128 v[166:169], v145 offset:2048
	ds_read_b128 v[170:173], v145 offset:3072
	ds_read_b128 v[174:177], v145 offset:4096
	ds_read_b128 v[178:181], v145 offset:5120
	ds_read_b128 v[188:191], v145 offset:6144
	ds_read_b128 v[192:195], v145 offset:7168
	global_load_lds_dwordx4 v[182:183], off
	v_lshl_add_u64 v[182:183], s[20:21], 0, v[136:137]
	s_add_i32 m0, s33, 0xe000
	s_nop 0
	global_load_lds_dwordx4 v[182:183], off
	s_waitcnt lgkmcnt(8)
	s_setprio 1
	s_barrier
	s_waitcnt lgkmcnt(0)
	v_mfma_f32_16x16x32_bf16 v[124:127], v[138:141], v[158:161], v[124:127]
	v_mfma_f32_16x16x32_bf16 v[120:123], v[150:153], v[158:161], v[120:123]
	v_mfma_f32_16x16x32_bf16 v[108:111], v[138:141], v[166:169], v[108:111]
	v_mfma_f32_16x16x32_bf16 v[104:107], v[150:153], v[166:169], v[104:107]
	v_mfma_f32_16x16x32_bf16 v[92:95], v[138:141], v[174:177], v[92:95]
	v_mfma_f32_16x16x32_bf16 v[88:91], v[150:153], v[174:177], v[88:91]
	v_mfma_f32_16x16x32_bf16 v[76:79], v[138:141], v[188:191], v[76:79]
	v_mfma_f32_16x16x32_bf16 v[72:75], v[150:153], v[188:191], v[72:75]
	v_mfma_f32_16x16x32_bf16 v[124:127], v[146:149], v[162:165], v[124:127]
	v_mfma_f32_16x16x32_bf16 v[120:123], v[154:157], v[162:165], v[120:123]
	v_mfma_f32_16x16x32_bf16 v[108:111], v[146:149], v[170:173], v[108:111]
	v_mfma_f32_16x16x32_bf16 v[104:107], v[154:157], v[170:173], v[104:107]
	v_mfma_f32_16x16x32_bf16 v[92:95], v[146:149], v[178:181], v[92:95]
	v_mfma_f32_16x16x32_bf16 v[88:91], v[154:157], v[178:181], v[88:91]
	v_mfma_f32_16x16x32_bf16 v[76:79], v[146:149], v[192:195], v[76:79]
	v_mfma_f32_16x16x32_bf16 v[72:75], v[154:157], v[192:195], v[72:75]
	s_barrier
	s_setprio 0
	s_add_i32 s50, 0, 0x14000
	v_add_u32_e32 v182, s50, v144
	s_add_i32 s47, s47, s31
	ds_read_b128 v[202:205], v182
	ds_read_b128 v[206:209], v182 offset:1024
	ds_read_b128 v[210:213], v182 offset:2048
	ds_read_b128 v[214:217], v182 offset:3072
	v_lshl_add_u64 v[182:183], s[22:23], 0, v[184:185]
	s_mov_b32 m0, s47
	v_lshl_add_u64 v[196:197], s[22:23], 0, v[132:133]
	global_load_lds_dwordx4 v[182:183], off
	s_add_i32 m0, s47, 0x2000
	s_nop 0
	global_load_lds_dwordx4 v[196:197], off
	s_setprio 1
	s_barrier
	s_waitcnt lgkmcnt(0)
	v_mfma_f32_16x16x32_bf16 v[116:119], v[202:205], v[158:161], v[116:119]
	v_mfma_f32_16x16x32_bf16 v[112:115], v[210:213], v[158:161], v[112:115]
	v_mfma_f32_16x16x32_bf16 v[100:103], v[202:205], v[166:169], v[100:103]
	v_mfma_f32_16x16x32_bf16 v[96:99], v[210:213], v[166:169], v[96:99]
	v_mfma_f32_16x16x32_bf16 v[84:87], v[202:205], v[174:177], v[84:87]
	v_mfma_f32_16x16x32_bf16 v[80:83], v[210:213], v[174:177], v[80:83]
	v_mfma_f32_16x16x32_bf16 v[68:71], v[202:205], v[188:191], v[68:71]
	v_mfma_f32_16x16x32_bf16 v[64:67], v[210:213], v[188:191], v[64:67]
	v_mfma_f32_16x16x32_bf16 v[116:119], v[206:209], v[162:165], v[116:119]
	v_mfma_f32_16x16x32_bf16 v[112:115], v[214:217], v[162:165], v[112:115]
	v_mfma_f32_16x16x32_bf16 v[100:103], v[206:209], v[170:173], v[100:103]
	v_mfma_f32_16x16x32_bf16 v[96:99], v[214:217], v[170:173], v[96:99]
	v_mfma_f32_16x16x32_bf16 v[84:87], v[206:209], v[178:181], v[84:87]
	v_mfma_f32_16x16x32_bf16 v[80:83], v[214:217], v[178:181], v[80:83]
	v_mfma_f32_16x16x32_bf16 v[68:71], v[206:209], v[192:195], v[68:71]
	v_mfma_f32_16x16x32_bf16 v[64:67], v[214:217], v[192:195], v[64:67]
	s_barrier
	s_setprio 0
	s_mov_b32 m0, s33
	v_lshl_add_u64 v[218:219], s[24:25], 0, v[128:129]
	ds_read_b128 v[158:161], v145 offset:16384
	ds_read_b128 v[162:165], v145 offset:17408
	ds_read_b128 v[166:169], v145 offset:18432
	ds_read_b128 v[170:173], v145 offset:19456
	ds_read_b128 v[174:177], v145 offset:20480
	ds_read_b128 v[178:181], v145 offset:21504
	ds_read_b128 v[188:191], v145 offset:22528
	ds_read_b128 v[192:195], v145 offset:23552
	global_load_lds_dwordx4 v[218:219], off
	v_lshl_add_u64 v[220:221], s[24:25], 0, v[130:131]
	s_mov_b32 m0, s34
	s_nop 0
	global_load_lds_dwordx4 v[220:221], off
	s_setprio 1
	s_waitcnt vmcnt(10)
	s_barrier
	s_waitcnt lgkmcnt(0)
	v_mfma_f32_16x16x32_bf16 v[60:63], v[138:141], v[158:161], v[60:63]
	v_mfma_f32_16x16x32_bf16 v[56:59], v[150:153], v[158:161], v[56:59]
	v_mfma_f32_16x16x32_bf16 v[44:47], v[138:141], v[166:169], v[44:47]
	v_mfma_f32_16x16x32_bf16 v[40:43], v[150:153], v[166:169], v[40:43]
	v_mfma_f32_16x16x32_bf16 v[28:31], v[138:141], v[174:177], v[28:31]
	v_mfma_f32_16x16x32_bf16 v[24:27], v[150:153], v[174:177], v[24:27]
	v_mfma_f32_16x16x32_bf16 v[12:15], v[138:141], v[188:191], v[12:15]
	v_mfma_f32_16x16x32_bf16 v[8:11], v[150:153], v[188:191], v[8:11]
	v_mfma_f32_16x16x32_bf16 v[60:63], v[146:149], v[162:165], v[60:63]
	v_mfma_f32_16x16x32_bf16 v[56:59], v[154:157], v[162:165], v[56:59]
	v_mfma_f32_16x16x32_bf16 v[44:47], v[146:149], v[170:173], v[44:47]
	v_mfma_f32_16x16x32_bf16 v[40:43], v[154:157], v[170:173], v[40:43]
	v_mfma_f32_16x16x32_bf16 v[28:31], v[146:149], v[178:181], v[28:31]
	v_mfma_f32_16x16x32_bf16 v[24:27], v[154:157], v[178:181], v[24:27]
	v_mfma_f32_16x16x32_bf16 v[12:15], v[146:149], v[192:195], v[12:15]
	v_mfma_f32_16x16x32_bf16 v[8:11], v[154:157], v[192:195], v[8:11]
	s_barrier
	s_setprio 0
	v_add_u32_e32 v154, 0x18000, v144
	ds_read_b128 v[138:141], v154
	ds_read_b128 v[146:149], v154 offset:1024
	ds_read_b128 v[150:153], v154 offset:2048
	ds_read_b128 v[154:157], v154 offset:3072
	s_add_u32 s48, s22, 0x80000
	s_addc_u32 s49, s23, 0
	s_add_i32 s47, s50, s31
	v_lshl_add_u64 v[246:247], s[48:49], 0, v[184:185]
	s_mov_b32 m0, s47
	s_nop 0
	global_load_lds_dwordx4 v[246:247], off
	v_lshl_add_u64 v[248:249], s[48:49], 0, v[132:133]
	s_add_i32 m0, s47, 0x2000
	s_nop 0
	global_load_lds_dwordx4 v[248:249], off
	s_waitcnt vmcnt(6)
	s_setprio 1
	s_barrier
	v_mfma_f32_16x16x32_bf16 v[52:55], v[202:205], v[158:161], v[52:55]
	v_mfma_f32_16x16x32_bf16 v[48:51], v[210:213], v[158:161], v[48:51]
	v_mfma_f32_16x16x32_bf16 v[36:39], v[202:205], v[166:169], v[36:39]
	v_mfma_f32_16x16x32_bf16 v[32:35], v[210:213], v[166:169], v[32:35]
	v_mfma_f32_16x16x32_bf16 v[20:23], v[202:205], v[174:177], v[20:23]
	v_mfma_f32_16x16x32_bf16 v[16:19], v[210:213], v[174:177], v[16:19]
	v_mfma_f32_16x16x32_bf16 v[4:7], v[202:205], v[188:191], v[4:7]
	v_mfma_f32_16x16x32_bf16 v[0:3], v[210:213], v[188:191], v[0:3]
	v_mfma_f32_16x16x32_bf16 v[52:55], v[206:209], v[162:165], v[52:55]
	v_mfma_f32_16x16x32_bf16 v[48:51], v[214:217], v[162:165], v[48:51]
	v_mfma_f32_16x16x32_bf16 v[36:39], v[206:209], v[170:173], v[36:39]
	v_mfma_f32_16x16x32_bf16 v[32:35], v[214:217], v[170:173], v[32:35]
	v_mfma_f32_16x16x32_bf16 v[20:23], v[206:209], v[178:181], v[20:23]
	v_mfma_f32_16x16x32_bf16 v[16:19], v[214:217], v[178:181], v[16:19]
	v_mfma_f32_16x16x32_bf16 v[4:7], v[206:209], v[192:195], v[4:7]
	v_mfma_f32_16x16x32_bf16 v[0:3], v[214:217], v[192:195], v[0:3]
	s_barrier
	s_setprio 0
	s_add_i32 s47, 0, 0x18000
	s_add_u32 s24, s24, 0x80000
	s_addc_u32 s25, s25, 0
	s_mov_b32 m0, s35
	v_lshl_add_u64 v[202:203], s[24:25], 0, v[128:129]
	ds_read_b128 v[158:161], v145 offset:32768
	ds_read_b128 v[162:165], v145 offset:33792
	ds_read_b128 v[166:169], v145 offset:34816
	ds_read_b128 v[170:173], v145 offset:35840
	ds_read_b128 v[174:177], v145 offset:36864
	ds_read_b128 v[178:181], v145 offset:37888
	ds_read_b128 v[188:191], v145 offset:38912
	ds_read_b128 v[192:195], v145 offset:39936
	global_load_lds_dwordx4 v[202:203], off
	v_lshl_add_u64 v[202:203], s[24:25], 0, v[130:131]
	s_mov_b32 m0, s36
	s_nop 0
	global_load_lds_dwordx4 v[202:203], off
	s_waitcnt lgkmcnt(8)
	s_setprio 1
	s_barrier
	s_waitcnt lgkmcnt(0)
	v_mfma_f32_16x16x32_bf16 v[124:127], v[138:141], v[158:161], v[124:127]
	v_mfma_f32_16x16x32_bf16 v[120:123], v[150:153], v[158:161], v[120:123]
	v_mfma_f32_16x16x32_bf16 v[108:111], v[138:141], v[166:169], v[108:111]
	v_mfma_f32_16x16x32_bf16 v[104:107], v[150:153], v[166:169], v[104:107]
	v_mfma_f32_16x16x32_bf16 v[92:95], v[138:141], v[174:177], v[92:95]
	v_mfma_f32_16x16x32_bf16 v[88:91], v[150:153], v[174:177], v[88:91]
	v_mfma_f32_16x16x32_bf16 v[76:79], v[138:141], v[188:191], v[76:79]
	v_mfma_f32_16x16x32_bf16 v[72:75], v[150:153], v[188:191], v[72:75]
	v_mfma_f32_16x16x32_bf16 v[124:127], v[146:149], v[162:165], v[124:127]
	v_mfma_f32_16x16x32_bf16 v[120:123], v[154:157], v[162:165], v[120:123]
	v_mfma_f32_16x16x32_bf16 v[108:111], v[146:149], v[170:173], v[108:111]
	v_mfma_f32_16x16x32_bf16 v[104:107], v[154:157], v[170:173], v[104:107]
	v_mfma_f32_16x16x32_bf16 v[92:95], v[146:149], v[178:181], v[92:95]
	v_mfma_f32_16x16x32_bf16 v[88:91], v[154:157], v[178:181], v[88:91]
	v_mfma_f32_16x16x32_bf16 v[76:79], v[146:149], v[192:195], v[76:79]
	v_mfma_f32_16x16x32_bf16 v[72:75], v[154:157], v[192:195], v[72:75]
	s_barrier
	s_setprio 0
	s_add_i32 s24, 0, 0x1c000
	s_add_i32 s25, s47, s31
	v_add_u32_e32 v187, s24, v144
	v_lshl_add_u64 v[182:183], v[182:183], 0, s[52:53]
	s_mov_b32 m0, s25
	ds_read_b128 v[202:205], v187
	ds_read_b128 v[206:209], v187 offset:1024
	ds_read_b128 v[210:213], v187 offset:2048
	ds_read_b128 v[214:217], v187 offset:3072
	global_load_lds_dwordx4 v[182:183], off
	v_lshl_add_u64 v[182:183], v[196:197], 0, s[52:53]
	s_add_i32 m0, s25, 0x2000
	s_nop 0
	global_load_lds_dwordx4 v[182:183], off
	s_setprio 1
	s_barrier
	s_waitcnt lgkmcnt(0)
	v_mfma_f32_16x16x32_bf16 v[116:119], v[202:205], v[158:161], v[116:119]
	v_mfma_f32_16x16x32_bf16 v[112:115], v[210:213], v[158:161], v[112:115]
	v_mfma_f32_16x16x32_bf16 v[100:103], v[202:205], v[166:169], v[100:103]
	v_mfma_f32_16x16x32_bf16 v[96:99], v[210:213], v[166:169], v[96:99]
	v_mfma_f32_16x16x32_bf16 v[84:87], v[202:205], v[174:177], v[84:87]
	v_mfma_f32_16x16x32_bf16 v[80:83], v[210:213], v[174:177], v[80:83]
	v_mfma_f32_16x16x32_bf16 v[68:71], v[202:205], v[188:191], v[68:71]
	v_mfma_f32_16x16x32_bf16 v[64:67], v[210:213], v[188:191], v[64:67]
	v_mfma_f32_16x16x32_bf16 v[116:119], v[206:209], v[162:165], v[116:119]
	v_mfma_f32_16x16x32_bf16 v[112:115], v[214:217], v[162:165], v[112:115]
	v_mfma_f32_16x16x32_bf16 v[100:103], v[206:209], v[170:173], v[100:103]
	v_mfma_f32_16x16x32_bf16 v[96:99], v[214:217], v[170:173], v[96:99]
	v_mfma_f32_16x16x32_bf16 v[84:87], v[206:209], v[178:181], v[84:87]
	v_mfma_f32_16x16x32_bf16 v[80:83], v[214:217], v[178:181], v[80:83]
	v_mfma_f32_16x16x32_bf16 v[68:71], v[206:209], v[192:195], v[68:71]
	v_mfma_f32_16x16x32_bf16 v[64:67], v[214:217], v[192:195], v[64:67]
	s_barrier
	s_setprio 0
	s_mov_b32 m0, s40
	v_lshl_add_u64 v[182:183], v[218:219], 0, s[52:53]
	ds_read_b128 v[158:161], v145 offset:49152
	ds_read_b128 v[162:165], v145 offset:50176
	ds_read_b128 v[166:169], v145 offset:51200
	ds_read_b128 v[170:173], v145 offset:52224
	ds_read_b128 v[174:177], v145 offset:53248
	ds_read_b128 v[178:181], v145 offset:54272
	ds_read_b128 v[188:191], v145 offset:55296
	ds_read_b128 v[192:195], v145 offset:56320
	global_load_lds_dwordx4 v[182:183], off
	v_lshl_add_u64 v[182:183], v[220:221], 0, s[52:53]
	s_mov_b32 m0, s41
	s_nop 0
	global_load_lds_dwordx4 v[182:183], off
	s_setprio 1
	s_waitcnt vmcnt(10)
	s_barrier
	s_waitcnt lgkmcnt(0)
	v_mfma_f32_16x16x32_bf16 v[60:63], v[138:141], v[158:161], v[60:63]
	v_mfma_f32_16x16x32_bf16 v[56:59], v[150:153], v[158:161], v[56:59]
	v_mfma_f32_16x16x32_bf16 v[44:47], v[138:141], v[166:169], v[44:47]
	v_mfma_f32_16x16x32_bf16 v[40:43], v[150:153], v[166:169], v[40:43]
	v_mfma_f32_16x16x32_bf16 v[28:31], v[138:141], v[174:177], v[28:31]
	v_mfma_f32_16x16x32_bf16 v[24:27], v[150:153], v[174:177], v[24:27]
	v_mfma_f32_16x16x32_bf16 v[12:15], v[138:141], v[188:191], v[12:15]
	v_mfma_f32_16x16x32_bf16 v[8:11], v[150:153], v[188:191], v[8:11]
	v_mfma_f32_16x16x32_bf16 v[60:63], v[146:149], v[162:165], v[60:63]
	v_mfma_f32_16x16x32_bf16 v[56:59], v[154:157], v[162:165], v[56:59]
	v_mfma_f32_16x16x32_bf16 v[44:47], v[146:149], v[170:173], v[44:47]
	v_mfma_f32_16x16x32_bf16 v[40:43], v[154:157], v[170:173], v[40:43]
	v_mfma_f32_16x16x32_bf16 v[28:31], v[146:149], v[178:181], v[28:31]
	v_mfma_f32_16x16x32_bf16 v[24:27], v[154:157], v[178:181], v[24:27]
	v_mfma_f32_16x16x32_bf16 v[12:15], v[146:149], v[192:195], v[12:15]
	v_mfma_f32_16x16x32_bf16 v[8:11], v[154:157], v[192:195], v[8:11]
	s_barrier
	s_setprio 0
	v_add_u32_e32 v154, 0x10000, v144
	ds_read_b128 v[138:141], v154
	ds_read_b128 v[146:149], v154 offset:1024
	ds_read_b128 v[150:153], v154 offset:2048
	ds_read_b128 v[154:157], v154 offset:3072
	s_add_u32 s22, s22, 0x80080
	s_addc_u32 s23, s23, 0
	s_add_i32 s24, s24, s31
	v_lshl_add_u64 v[250:251], s[22:23], 0, v[184:185]
	s_mov_b32 m0, s24
	s_nop 0
	global_load_lds_dwordx4 v[250:251], off
	v_lshl_add_u64 v[252:253], s[22:23], 0, v[132:133]
	s_add_i32 m0, s24, 0x2000
	s_nop 0
	global_load_lds_dwordx4 v[252:253], off
	s_waitcnt vmcnt(6)
	s_setprio 1
	s_barrier
	v_mfma_f32_16x16x32_bf16 v[52:55], v[202:205], v[158:161], v[52:55]
	v_mfma_f32_16x16x32_bf16 v[48:51], v[210:213], v[158:161], v[48:51]
	v_mfma_f32_16x16x32_bf16 v[36:39], v[202:205], v[166:169], v[36:39]
	v_mfma_f32_16x16x32_bf16 v[32:35], v[210:213], v[166:169], v[32:35]
	v_mfma_f32_16x16x32_bf16 v[20:23], v[202:205], v[174:177], v[20:23]
	v_mfma_f32_16x16x32_bf16 v[16:19], v[210:213], v[174:177], v[16:19]
	v_mfma_f32_16x16x32_bf16 v[4:7], v[202:205], v[188:191], v[4:7]
	v_mfma_f32_16x16x32_bf16 v[0:3], v[210:213], v[188:191], v[0:3]
	v_mfma_f32_16x16x32_bf16 v[52:55], v[206:209], v[162:165], v[52:55]
	v_mfma_f32_16x16x32_bf16 v[48:51], v[214:217], v[162:165], v[48:51]
	v_mfma_f32_16x16x32_bf16 v[36:39], v[206:209], v[170:173], v[36:39]
	v_mfma_f32_16x16x32_bf16 v[32:35], v[214:217], v[170:173], v[32:35]
	v_mfma_f32_16x16x32_bf16 v[20:23], v[206:209], v[178:181], v[20:23]
	v_mfma_f32_16x16x32_bf16 v[16:19], v[214:217], v[178:181], v[16:19]
	v_mfma_f32_16x16x32_bf16 v[4:7], v[206:209], v[192:195], v[4:7]
	v_mfma_f32_16x16x32_bf16 v[0:3], v[214:217], v[192:195], v[0:3]
	s_barrier
	s_setprio 0
	s_add_i32 s46, s46, 2
	s_add_u32 s20, s20, 0x100
	s_addc_u32 s21, s21, 0
	s_add_u32 s44, s44, 0x100
	s_addc_u32 s45, s45, 0
	s_cmp_gt_u32 s46, 29
	s_cbranch_scc0 .LBB0_207
	s_waitcnt lgkmcnt(0)
	v_mov_b32_e32 v138, v142
	v_mov_b32_e32 v146, v143
	s_lshl_b32 s1, s18, 8
	s_add_i32 s1, s1, s38
	v_add_u32_e32 v138, s1, v138
	s_lshl_b32 s1, s0, 8
	s_cmp_lt_i32 s0, 2
	v_lshlrev_b32_e32 v147, 3, v146
	s_mov_b64 s[18:19], -1
	v_ashrrev_i32_e32 v139, 31, v138
	s_cbranch_scc1 .LBB0_210
	v_mul_f32_e32 v140, 0xbfb8aa3b, v124
	v_mul_f32_e32 v149, 0xbfb8aa3b, v125
	v_mul_f32_e32 v150, 0xbfb8aa3b, v126
	v_mul_f32_e32 v153, 0xbfb8aa3b, v120
	v_exp_f32_e32 v148, v140
	v_exp_f32_e32 v149, v149
	v_exp_f32_e32 v150, v150
	v_mul_f32_e32 v151, 0xbfb8aa3b, v127
	v_exp_f32_e32 v153, v153
	v_mul_f32_e32 v154, 0xbfb8aa3b, v121
	v_exp_f32_e32 v151, v151
	v_exp_f32_e32 v154, v154
	v_mul_f32_e32 v155, 0xbfb8aa3b, v122
	v_mul_f32_e32 v156, 0xbfb8aa3b, v123
	v_add_f32_e32 v148, 1.0, v148
	v_add_f32_e32 v149, 1.0, v149
	v_add_f32_e32 v150, 1.0, v150
	v_add_f32_e32 v153, 1.0, v153
	v_exp_f32_e32 v155, v155
	v_exp_f32_e32 v156, v156
	v_rcp_f32_e32 v148, v148
	v_rcp_f32_e32 v149, v149
	v_rcp_f32_e32 v150, v150
	v_add_f32_e32 v151, 1.0, v151
	v_rcp_f32_e32 v153, v153
	v_add_f32_e32 v154, 1.0, v154
	v_rcp_f32_e32 v151, v151
	v_rcp_f32_e32 v154, v154
	v_add_f32_e32 v155, 1.0, v155
	v_add_f32_e32 v156, 1.0, v156
	s_add_i32 s9, s42, s1
	v_mul_f32_e32 v148, v124, v148
	v_mul_f32_e32 v149, v125, v149
	v_mul_f32_e32 v150, v126, v150
	v_rcp_f32_e32 v155, v155
	v_rcp_f32_e32 v156, v156
	v_mul_f32_e32 v153, v120, v153
	v_lshlrev_b64 v[140:141], 12, v[138:139]
	v_add_u32_e32 v152, s9, v147
	v_mul_f32_e32 v151, v127, v151
	v_mul_f32_e32 v154, v121, v154
	v_cvt_pk_bf16_f32 v148, v148, v149
	v_cvt_pk_bf16_f32 v149, v150, v151
	v_cvt_pk_bf16_f32 v150, v153, v154
	v_mul_f32_e32 v153, 0xbfb8aa3b, v116
	v_lshl_add_u64 v[140:141], s[6:7], 0, v[140:141]
	v_exp_f32_e32 v154, v153
	v_ashrrev_i32_e32 v153, 31, v152
	v_lshl_add_u64 v[140:141], v[152:153], 1, v[140:141]
	v_mul_f32_e32 v155, v122, v155
	v_mul_f32_e32 v156, v123, v156
	v_cvt_pk_bf16_f32 v151, v155, v156
	global_store_dwordx4 v[140:141], v[148:151], off
	v_mul_f32_e32 v152, 0xbfb8aa3b, v112
	v_mul_f32_e32 v153, 0xbfb8aa3b, v113
	v_mul_f32_e32 v149, 0xbfb8aa3b, v117
	v_mul_f32_e32 v150, 0xbfb8aa3b, v118
	v_exp_f32_e32 v149, v149
	v_exp_f32_e32 v150, v150
	v_mul_f32_e32 v151, 0xbfb8aa3b, v119
	v_add_f32_e32 v148, 1.0, v154
	v_exp_f32_e32 v151, v151
	v_mul_f32_e32 v154, 0xbfb8aa3b, v114
	v_mul_f32_e32 v155, 0xbfb8aa3b, v115
	v_exp_f32_e32 v152, v152
	v_exp_f32_e32 v153, v153
	v_exp_f32_e32 v154, v154
	v_exp_f32_e32 v155, v155
	v_add_f32_e32 v149, 1.0, v149
	v_add_f32_e32 v150, 1.0, v150
	v_rcp_f32_e32 v148, v148
	v_rcp_f32_e32 v149, v149
	v_rcp_f32_e32 v150, v150
	v_add_f32_e32 v151, 1.0, v151
	v_rcp_f32_e32 v151, v151
	v_add_f32_e32 v152, 1.0, v152
	v_add_f32_e32 v153, 1.0, v153
	v_add_f32_e32 v154, 1.0, v154
	v_add_f32_e32 v155, 1.0, v155
	v_rcp_f32_e32 v152, v152
	v_rcp_f32_e32 v153, v153
	v_rcp_f32_e32 v154, v154
	v_rcp_f32_e32 v155, v155
	v_mul_f32_e32 v148, v116, v148
	v_mul_f32_e32 v149, v117, v149
	v_mul_f32_e32 v150, v118, v150
	v_mul_f32_e32 v151, v119, v151
	v_cvt_pk_bf16_f32 v148, v148, v149
	v_cvt_pk_bf16_f32 v149, v150, v151
	v_mul_f32_e32 v150, 0xbfb8aa3b, v108
	v_mul_f32_e32 v152, v112, v152
	v_mul_f32_e32 v153, v113, v153
	v_mul_f32_e32 v154, v114, v154
	v_mul_f32_e32 v155, v115, v155
	v_exp_f32_e32 v156, v150
	v_cvt_pk_bf16_f32 v150, v152, v153
	v_cvt_pk_bf16_f32 v151, v154, v155
	global_store_dwordx4 v[140:141], v[148:151], off offset:256
	v_mul_f32_e32 v154, 0xbfb8aa3b, v106
	v_mul_f32_e32 v152, 0xbfb8aa3b, v104
	v_mul_f32_e32 v149, 0xbfb8aa3b, v109
	v_mul_f32_e32 v150, 0xbfb8aa3b, v110
	v_mul_f32_e32 v151, 0xbfb8aa3b, v111
	v_exp_f32_e32 v149, v149
	v_exp_f32_e32 v150, v150
	v_exp_f32_e32 v151, v151
	v_mul_f32_e32 v153, 0xbfb8aa3b, v105
	v_exp_f32_e32 v154, v154
	v_mul_f32_e32 v155, 0xbfb8aa3b, v107
	v_exp_f32_e32 v152, v152
	v_exp_f32_e32 v153, v153
	v_exp_f32_e32 v155, v155
	v_add_f32_e32 v148, 1.0, v156
	v_add_f32_e32 v149, 1.0, v149
	v_add_f32_e32 v150, 1.0, v150
	v_add_f32_e32 v151, 1.0, v151
	v_add_f32_e32 v154, 1.0, v154
	v_rcp_f32_e32 v148, v148
	v_rcp_f32_e32 v149, v149
	v_rcp_f32_e32 v150, v150
	v_rcp_f32_e32 v151, v151
	v_add_f32_e32 v152, 1.0, v152
	v_add_f32_e32 v153, 1.0, v153
	v_rcp_f32_e32 v154, v154
	v_add_f32_e32 v155, 1.0, v155
	v_rcp_f32_e32 v152, v152
	v_rcp_f32_e32 v153, v153
	v_rcp_f32_e32 v155, v155
	v_mul_f32_e32 v148, v108, v148
	v_mul_f32_e32 v149, v109, v149
	v_mul_f32_e32 v150, v110, v150
	v_mul_f32_e32 v151, v111, v151
	v_mul_f32_e32 v154, v106, v154
	v_mul_f32_e32 v152, v104, v152
	v_mul_f32_e32 v153, v105, v153
	v_mul_f32_e32 v155, v107, v155
	v_cvt_pk_bf16_f32 v148, v148, v149
	v_cvt_pk_bf16_f32 v149, v150, v151
	v_cvt_pk_bf16_f32 v150, v152, v153
	v_cvt_pk_bf16_f32 v151, v154, v155
	v_mul_f32_e32 v154, 0xbfb8aa3b, v100
	s_mov_b32 s9, 0x10000
	v_exp_f32_e32 v156, v154
	v_add_co_u32_e32 v154, vcc, s9, v140
	v_mul_f32_e32 v157, 0xbfb8aa3b, v99
	s_nop 0
	v_addc_co_u32_e32 v155, vcc, 0, v141, vcc
	global_store_dwordx4 v[154:155], v[148:151], off
	v_mul_f32_e32 v154, 0xbfb8aa3b, v96
	v_mul_f32_e32 v155, 0xbfb8aa3b, v97
	v_mul_f32_e32 v149, 0xbfb8aa3b, v101
	v_mul_f32_e32 v150, 0xbfb8aa3b, v102
	v_exp_f32_e32 v149, v149
	v_exp_f32_e32 v150, v150
	v_mul_f32_e32 v151, 0xbfb8aa3b, v103
	v_add_f32_e32 v148, 1.0, v156
	v_exp_f32_e32 v151, v151
	v_mul_f32_e32 v156, 0xbfb8aa3b, v98
	v_exp_f32_e32 v154, v154
	v_exp_f32_e32 v155, v155
	v_exp_f32_e32 v156, v156
	v_exp_f32_e32 v157, v157
	v_add_f32_e32 v149, 1.0, v149
	v_add_f32_e32 v150, 1.0, v150
	v_rcp_f32_e32 v148, v148
	v_rcp_f32_e32 v149, v149
	v_rcp_f32_e32 v150, v150
	v_add_f32_e32 v151, 1.0, v151
	v_rcp_f32_e32 v151, v151
	v_add_f32_e32 v154, 1.0, v154
	v_add_f32_e32 v155, 1.0, v155
	v_add_f32_e32 v156, 1.0, v156
	v_add_f32_e32 v157, 1.0, v157
	v_rcp_f32_e32 v154, v154
	v_rcp_f32_e32 v155, v155
	v_rcp_f32_e32 v156, v156
	v_rcp_f32_e32 v157, v157
	v_mul_f32_e32 v148, v100, v148
	v_mul_f32_e32 v149, v101, v149
	v_mul_f32_e32 v150, v102, v150
	s_mov_b64 s[18:19], 0x10000
	v_mul_f32_e32 v151, v103, v151
	v_cvt_pk_bf16_f32 v148, v148, v149
	v_cvt_pk_bf16_f32 v149, v150, v151
	v_mul_f32_e32 v150, 0xbfb8aa3b, v92
	v_lshl_add_u64 v[152:153], v[140:141], 0, s[18:19]
	v_mul_f32_e32 v154, v96, v154
	v_mul_f32_e32 v155, v97, v155
	v_mul_f32_e32 v156, v98, v156
	v_mul_f32_e32 v157, v99, v157
	v_exp_f32_e32 v158, v150
	v_cvt_pk_bf16_f32 v150, v154, v155
	v_cvt_pk_bf16_f32 v151, v156, v157
	global_store_dwordx4 v[152:153], v[148:151], off offset:256
	v_mul_f32_e32 v154, 0xbfb8aa3b, v90
	v_mul_f32_e32 v152, 0xbfb8aa3b, v88
	v_mul_f32_e32 v149, 0xbfb8aa3b, v93
	v_mul_f32_e32 v150, 0xbfb8aa3b, v94
	v_mul_f32_e32 v151, 0xbfb8aa3b, v95
	v_exp_f32_e32 v149, v149
	v_exp_f32_e32 v150, v150
	v_exp_f32_e32 v151, v151
	v_mul_f32_e32 v153, 0xbfb8aa3b, v89
	v_exp_f32_e32 v154, v154
	v_mul_f32_e32 v155, 0xbfb8aa3b, v91
	v_exp_f32_e32 v152, v152
	v_exp_f32_e32 v153, v153
	v_exp_f32_e32 v155, v155
	v_add_f32_e32 v148, 1.0, v158
	v_add_f32_e32 v149, 1.0, v149
	v_add_f32_e32 v150, 1.0, v150
	v_add_f32_e32 v151, 1.0, v151
	v_add_f32_e32 v154, 1.0, v154
	v_rcp_f32_e32 v148, v148
	v_rcp_f32_e32 v149, v149
	v_rcp_f32_e32 v150, v150
	v_rcp_f32_e32 v151, v151
	v_add_f32_e32 v152, 1.0, v152
	v_add_f32_e32 v153, 1.0, v153
	v_rcp_f32_e32 v154, v154
	v_add_f32_e32 v155, 1.0, v155
	v_rcp_f32_e32 v152, v152
	v_rcp_f32_e32 v153, v153
	v_rcp_f32_e32 v155, v155
	v_mul_f32_e32 v148, v92, v148
	v_mul_f32_e32 v149, v93, v149
	v_mul_f32_e32 v150, v94, v150
	v_mul_f32_e32 v151, v95, v151
	v_mul_f32_e32 v154, v90, v154
	v_mul_f32_e32 v152, v88, v152
	v_mul_f32_e32 v153, v89, v153
	v_mul_f32_e32 v155, v91, v155
	v_cvt_pk_bf16_f32 v148, v148, v149
	v_cvt_pk_bf16_f32 v149, v150, v151
	v_cvt_pk_bf16_f32 v150, v152, v153
	v_cvt_pk_bf16_f32 v151, v154, v155
	v_mul_f32_e32 v154, 0xbfb8aa3b, v84
	s_mov_b32 s9, 0x20000
	v_exp_f32_e32 v156, v154
	v_add_co_u32_e32 v154, vcc, s9, v140
	v_mul_f32_e32 v157, 0xbfb8aa3b, v83
	s_nop 0
	v_addc_co_u32_e32 v155, vcc, 0, v141, vcc
	global_store_dwordx4 v[154:155], v[148:151], off
	v_mul_f32_e32 v154, 0xbfb8aa3b, v80
	v_mul_f32_e32 v155, 0xbfb8aa3b, v81
	v_mul_f32_e32 v149, 0xbfb8aa3b, v85
	v_mul_f32_e32 v150, 0xbfb8aa3b, v86
	v_exp_f32_e32 v149, v149
	v_exp_f32_e32 v150, v150
	v_mul_f32_e32 v151, 0xbfb8aa3b, v87
	v_add_f32_e32 v148, 1.0, v156
	v_exp_f32_e32 v151, v151
	v_mul_f32_e32 v156, 0xbfb8aa3b, v82
	v_exp_f32_e32 v154, v154
	v_exp_f32_e32 v155, v155
	v_exp_f32_e32 v156, v156
	v_exp_f32_e32 v157, v157
	v_add_f32_e32 v149, 1.0, v149
	v_add_f32_e32 v150, 1.0, v150
	v_rcp_f32_e32 v148, v148
	v_rcp_f32_e32 v149, v149
	v_rcp_f32_e32 v150, v150
	v_add_f32_e32 v151, 1.0, v151
	v_rcp_f32_e32 v151, v151
	v_add_f32_e32 v154, 1.0, v154
	v_add_f32_e32 v155, 1.0, v155
	v_add_f32_e32 v156, 1.0, v156
	v_add_f32_e32 v157, 1.0, v157
	v_rcp_f32_e32 v154, v154
	v_rcp_f32_e32 v155, v155
	v_rcp_f32_e32 v156, v156
	v_rcp_f32_e32 v157, v157
	v_mul_f32_e32 v148, v84, v148
	v_mul_f32_e32 v149, v85, v149
	v_mul_f32_e32 v150, v86, v150
	s_mov_b64 s[18:19], 0x20000
	v_mul_f32_e32 v151, v87, v151
	v_cvt_pk_bf16_f32 v148, v148, v149
	v_cvt_pk_bf16_f32 v149, v150, v151
	v_mul_f32_e32 v150, 0xbfb8aa3b, v76
	v_lshl_add_u64 v[152:153], v[140:141], 0, s[18:19]
	v_mul_f32_e32 v154, v80, v154
	v_mul_f32_e32 v155, v81, v155
	v_mul_f32_e32 v156, v82, v156
	v_mul_f32_e32 v157, v83, v157
	v_exp_f32_e32 v158, v150
	v_cvt_pk_bf16_f32 v150, v154, v155
	v_cvt_pk_bf16_f32 v151, v156, v157
	global_store_dwordx4 v[152:153], v[148:151], off offset:256
	v_mul_f32_e32 v154, 0xbfb8aa3b, v74
	v_mul_f32_e32 v152, 0xbfb8aa3b, v72
	v_mul_f32_e32 v149, 0xbfb8aa3b, v77
	v_mul_f32_e32 v150, 0xbfb8aa3b, v78
	v_mul_f32_e32 v151, 0xbfb8aa3b, v79
	v_exp_f32_e32 v149, v149
	v_exp_f32_e32 v150, v150
	v_exp_f32_e32 v151, v151
	v_mul_f32_e32 v153, 0xbfb8aa3b, v73
	v_exp_f32_e32 v154, v154
	v_mul_f32_e32 v155, 0xbfb8aa3b, v75
	v_exp_f32_e32 v152, v152
	v_exp_f32_e32 v153, v153
	v_exp_f32_e32 v155, v155
	v_add_f32_e32 v148, 1.0, v158
	v_add_f32_e32 v149, 1.0, v149
	v_add_f32_e32 v150, 1.0, v150
	v_add_f32_e32 v151, 1.0, v151
	v_add_f32_e32 v154, 1.0, v154
	v_rcp_f32_e32 v148, v148
	v_rcp_f32_e32 v149, v149
	v_rcp_f32_e32 v150, v150
	v_rcp_f32_e32 v151, v151
	v_add_f32_e32 v152, 1.0, v152
	v_add_f32_e32 v153, 1.0, v153
	v_rcp_f32_e32 v154, v154
	v_add_f32_e32 v155, 1.0, v155
	v_rcp_f32_e32 v152, v152
	v_rcp_f32_e32 v153, v153
	v_rcp_f32_e32 v155, v155
	v_mul_f32_e32 v148, v76, v148
	v_mul_f32_e32 v149, v77, v149
	v_mul_f32_e32 v150, v78, v150
	v_mul_f32_e32 v151, v79, v151
	v_mul_f32_e32 v154, v74, v154
	v_mul_f32_e32 v152, v72, v152
	v_mul_f32_e32 v153, v73, v153
	v_mul_f32_e32 v155, v75, v155
	v_cvt_pk_bf16_f32 v148, v148, v149
	v_cvt_pk_bf16_f32 v149, v150, v151
	v_cvt_pk_bf16_f32 v150, v152, v153
	v_cvt_pk_bf16_f32 v151, v154, v155
	v_mul_f32_e32 v154, 0xbfb8aa3b, v68
	s_mov_b32 s9, 0x30000
	v_exp_f32_e32 v156, v154
	v_add_co_u32_e32 v154, vcc, s9, v140
	v_mul_f32_e32 v157, 0xbfb8aa3b, v67
	s_nop 0
	v_addc_co_u32_e32 v155, vcc, 0, v141, vcc
	global_store_dwordx4 v[154:155], v[148:151], off
	v_mul_f32_e32 v154, 0xbfb8aa3b, v64
	v_mul_f32_e32 v155, 0xbfb8aa3b, v65
	v_mul_f32_e32 v149, 0xbfb8aa3b, v69
	v_mul_f32_e32 v150, 0xbfb8aa3b, v70
	v_exp_f32_e32 v149, v149
	v_exp_f32_e32 v150, v150
	v_mul_f32_e32 v151, 0xbfb8aa3b, v71
	v_add_f32_e32 v148, 1.0, v156
	v_exp_f32_e32 v151, v151
	v_mul_f32_e32 v156, 0xbfb8aa3b, v66
	v_exp_f32_e32 v154, v154
	v_exp_f32_e32 v155, v155
	v_exp_f32_e32 v156, v156
	v_exp_f32_e32 v157, v157
	v_add_f32_e32 v149, 1.0, v149
	v_add_f32_e32 v150, 1.0, v150
	v_rcp_f32_e32 v148, v148
	v_rcp_f32_e32 v149, v149
	v_rcp_f32_e32 v150, v150
	v_add_f32_e32 v151, 1.0, v151
	v_rcp_f32_e32 v151, v151
	v_add_f32_e32 v154, 1.0, v154
	v_add_f32_e32 v155, 1.0, v155
	v_add_f32_e32 v156, 1.0, v156
	v_add_f32_e32 v157, 1.0, v157
	v_rcp_f32_e32 v154, v154
	v_rcp_f32_e32 v155, v155
	v_rcp_f32_e32 v156, v156
	v_rcp_f32_e32 v157, v157
	v_mul_f32_e32 v148, v68, v148
	v_mul_f32_e32 v149, v69, v149
	v_mul_f32_e32 v150, v70, v150
	s_mov_b64 s[18:19], 0x30000
	v_mul_f32_e32 v151, v71, v151
	v_cvt_pk_bf16_f32 v148, v148, v149
	v_cvt_pk_bf16_f32 v149, v150, v151
	v_mul_f32_e32 v150, 0xbfb8aa3b, v60
	v_lshl_add_u64 v[152:153], v[140:141], 0, s[18:19]
	v_mul_f32_e32 v154, v64, v154
	v_mul_f32_e32 v155, v65, v155
	v_mul_f32_e32 v156, v66, v156
	v_mul_f32_e32 v157, v67, v157
	v_exp_f32_e32 v158, v150
	v_cvt_pk_bf16_f32 v150, v154, v155
	v_cvt_pk_bf16_f32 v151, v156, v157
	global_store_dwordx4 v[152:153], v[148:151], off offset:256
	v_mul_f32_e32 v154, 0xbfb8aa3b, v58
	v_mul_f32_e32 v152, 0xbfb8aa3b, v56
	v_mul_f32_e32 v149, 0xbfb8aa3b, v61
	v_mul_f32_e32 v150, 0xbfb8aa3b, v62
	v_mul_f32_e32 v151, 0xbfb8aa3b, v63
	v_exp_f32_e32 v149, v149
	v_exp_f32_e32 v150, v150
	v_exp_f32_e32 v151, v151
	v_mul_f32_e32 v153, 0xbfb8aa3b, v57
	v_exp_f32_e32 v154, v154
	v_mul_f32_e32 v155, 0xbfb8aa3b, v59
	v_exp_f32_e32 v152, v152
	v_exp_f32_e32 v153, v153
	v_exp_f32_e32 v155, v155
	v_add_f32_e32 v148, 1.0, v158
	v_add_f32_e32 v149, 1.0, v149
	v_add_f32_e32 v150, 1.0, v150
	v_add_f32_e32 v151, 1.0, v151
	v_add_f32_e32 v154, 1.0, v154
	v_rcp_f32_e32 v148, v148
	v_rcp_f32_e32 v149, v149
	v_rcp_f32_e32 v150, v150
	v_rcp_f32_e32 v151, v151
	v_add_f32_e32 v152, 1.0, v152
	v_add_f32_e32 v153, 1.0, v153
	v_rcp_f32_e32 v154, v154
	v_add_f32_e32 v155, 1.0, v155
	v_rcp_f32_e32 v152, v152
	v_rcp_f32_e32 v153, v153
	v_rcp_f32_e32 v155, v155
	v_mul_f32_e32 v148, v60, v148
	v_mul_f32_e32 v149, v61, v149
	v_mul_f32_e32 v150, v62, v150
	v_mul_f32_e32 v151, v63, v151
	v_mul_f32_e32 v154, v58, v154
	v_mul_f32_e32 v152, v56, v152
	v_mul_f32_e32 v153, v57, v153
	v_mul_f32_e32 v155, v59, v155
	v_cvt_pk_bf16_f32 v148, v148, v149
	v_cvt_pk_bf16_f32 v149, v150, v151
	v_cvt_pk_bf16_f32 v150, v152, v153
	v_cvt_pk_bf16_f32 v151, v154, v155
	v_mul_f32_e32 v154, 0xbfb8aa3b, v52
	s_mov_b32 s9, 0x80000
	v_exp_f32_e32 v156, v154
	v_add_co_u32_e32 v154, vcc, s9, v140
	v_mul_f32_e32 v157, 0xbfb8aa3b, v51
	s_nop 0
	v_addc_co_u32_e32 v155, vcc, 0, v141, vcc
	global_store_dwordx4 v[154:155], v[148:151], off
	v_mul_f32_e32 v154, 0xbfb8aa3b, v48
	v_mul_f32_e32 v155, 0xbfb8aa3b, v49
	v_mul_f32_e32 v149, 0xbfb8aa3b, v53
	v_mul_f32_e32 v150, 0xbfb8aa3b, v54
	v_exp_f32_e32 v149, v149
	v_exp_f32_e32 v150, v150
	v_mul_f32_e32 v151, 0xbfb8aa3b, v55
	v_add_f32_e32 v148, 1.0, v156
	v_exp_f32_e32 v151, v151
	v_mul_f32_e32 v156, 0xbfb8aa3b, v50
	v_exp_f32_e32 v154, v154
	v_exp_f32_e32 v155, v155
	v_exp_f32_e32 v156, v156
	v_exp_f32_e32 v157, v157
	v_add_f32_e32 v149, 1.0, v149
	v_add_f32_e32 v150, 1.0, v150
	v_rcp_f32_e32 v148, v148
	v_rcp_f32_e32 v149, v149
	v_rcp_f32_e32 v150, v150
	v_add_f32_e32 v151, 1.0, v151
	v_rcp_f32_e32 v151, v151
	v_add_f32_e32 v154, 1.0, v154
	v_add_f32_e32 v155, 1.0, v155
	v_add_f32_e32 v156, 1.0, v156
	v_add_f32_e32 v157, 1.0, v157
	v_rcp_f32_e32 v154, v154
	v_rcp_f32_e32 v155, v155
	v_rcp_f32_e32 v156, v156
	v_rcp_f32_e32 v157, v157
	v_mul_f32_e32 v148, v52, v148
	v_mul_f32_e32 v149, v53, v149
	v_mul_f32_e32 v150, v54, v150
	s_mov_b64 s[18:19], 0x80000
	v_mul_f32_e32 v151, v55, v151
	v_cvt_pk_bf16_f32 v148, v148, v149
	v_cvt_pk_bf16_f32 v149, v150, v151
	v_mul_f32_e32 v150, 0xbfb8aa3b, v44
	v_lshl_add_u64 v[152:153], v[140:141], 0, s[18:19]
	v_mul_f32_e32 v154, v48, v154
	v_mul_f32_e32 v155, v49, v155
	v_mul_f32_e32 v156, v50, v156
	v_mul_f32_e32 v157, v51, v157
	v_exp_f32_e32 v158, v150
	v_cvt_pk_bf16_f32 v150, v154, v155
	v_cvt_pk_bf16_f32 v151, v156, v157
	global_store_dwordx4 v[152:153], v[148:151], off offset:256
	v_mul_f32_e32 v154, 0xbfb8aa3b, v42
	v_mul_f32_e32 v152, 0xbfb8aa3b, v40
	v_mul_f32_e32 v149, 0xbfb8aa3b, v45
	v_mul_f32_e32 v150, 0xbfb8aa3b, v46
	v_mul_f32_e32 v151, 0xbfb8aa3b, v47
	v_exp_f32_e32 v149, v149
	v_exp_f32_e32 v150, v150
	v_exp_f32_e32 v151, v151
	v_mul_f32_e32 v153, 0xbfb8aa3b, v41
	v_exp_f32_e32 v154, v154
	v_mul_f32_e32 v155, 0xbfb8aa3b, v43
	v_exp_f32_e32 v152, v152
	v_exp_f32_e32 v153, v153
	v_exp_f32_e32 v155, v155
	v_add_f32_e32 v148, 1.0, v158
	v_add_f32_e32 v149, 1.0, v149
	v_add_f32_e32 v150, 1.0, v150
	v_add_f32_e32 v151, 1.0, v151
	v_add_f32_e32 v154, 1.0, v154
	v_rcp_f32_e32 v148, v148
	v_rcp_f32_e32 v149, v149
	v_rcp_f32_e32 v150, v150
	v_rcp_f32_e32 v151, v151
	v_add_f32_e32 v152, 1.0, v152
	v_add_f32_e32 v153, 1.0, v153
	v_rcp_f32_e32 v154, v154
	v_add_f32_e32 v155, 1.0, v155
	v_rcp_f32_e32 v152, v152
	v_rcp_f32_e32 v153, v153
	v_rcp_f32_e32 v155, v155
	v_mul_f32_e32 v148, v44, v148
	v_mul_f32_e32 v149, v45, v149
	v_mul_f32_e32 v150, v46, v150
	v_mul_f32_e32 v151, v47, v151
	v_mul_f32_e32 v154, v42, v154
	v_mul_f32_e32 v152, v40, v152
	v_mul_f32_e32 v153, v41, v153
	v_mul_f32_e32 v155, v43, v155
	v_cvt_pk_bf16_f32 v148, v148, v149
	v_cvt_pk_bf16_f32 v149, v150, v151
	v_cvt_pk_bf16_f32 v150, v152, v153
	v_cvt_pk_bf16_f32 v151, v154, v155
	v_mul_f32_e32 v154, 0xbfb8aa3b, v36
	s_mov_b32 s9, 0x90000
	v_exp_f32_e32 v156, v154
	v_add_co_u32_e32 v154, vcc, s9, v140
	v_mul_f32_e32 v157, 0xbfb8aa3b, v35
	s_nop 0
	v_addc_co_u32_e32 v155, vcc, 0, v141, vcc
	global_store_dwordx4 v[154:155], v[148:151], off
	v_mul_f32_e32 v154, 0xbfb8aa3b, v32
	v_mul_f32_e32 v155, 0xbfb8aa3b, v33
	v_mul_f32_e32 v149, 0xbfb8aa3b, v37
	v_mul_f32_e32 v150, 0xbfb8aa3b, v38
	v_exp_f32_e32 v149, v149
	v_exp_f32_e32 v150, v150
	v_mul_f32_e32 v151, 0xbfb8aa3b, v39
	v_add_f32_e32 v148, 1.0, v156
	v_exp_f32_e32 v151, v151
	v_mul_f32_e32 v156, 0xbfb8aa3b, v34
	v_exp_f32_e32 v154, v154
	v_exp_f32_e32 v155, v155
	v_exp_f32_e32 v156, v156
	v_exp_f32_e32 v157, v157
	v_add_f32_e32 v149, 1.0, v149
	v_add_f32_e32 v150, 1.0, v150
	v_rcp_f32_e32 v148, v148
	v_rcp_f32_e32 v149, v149
	v_rcp_f32_e32 v150, v150
	v_add_f32_e32 v151, 1.0, v151
	v_rcp_f32_e32 v151, v151
	v_add_f32_e32 v154, 1.0, v154
	v_add_f32_e32 v155, 1.0, v155
	v_add_f32_e32 v156, 1.0, v156
	v_add_f32_e32 v157, 1.0, v157
	v_rcp_f32_e32 v154, v154
	v_rcp_f32_e32 v155, v155
	v_rcp_f32_e32 v156, v156
	v_rcp_f32_e32 v157, v157
	v_mul_f32_e32 v148, v36, v148
	v_mul_f32_e32 v149, v37, v149
	v_mul_f32_e32 v150, v38, v150
	s_mov_b64 s[18:19], 0x90000
	v_mul_f32_e32 v151, v39, v151
	v_cvt_pk_bf16_f32 v148, v148, v149
	v_cvt_pk_bf16_f32 v149, v150, v151
	v_mul_f32_e32 v150, 0xbfb8aa3b, v28
	v_lshl_add_u64 v[152:153], v[140:141], 0, s[18:19]
	v_mul_f32_e32 v154, v32, v154
	v_mul_f32_e32 v155, v33, v155
	v_mul_f32_e32 v156, v34, v156
	v_mul_f32_e32 v157, v35, v157
	v_exp_f32_e32 v158, v150
	v_cvt_pk_bf16_f32 v150, v154, v155
	v_cvt_pk_bf16_f32 v151, v156, v157
	global_store_dwordx4 v[152:153], v[148:151], off offset:256
	v_mul_f32_e32 v154, 0xbfb8aa3b, v26
	v_mul_f32_e32 v152, 0xbfb8aa3b, v24
	v_mul_f32_e32 v149, 0xbfb8aa3b, v29
	v_mul_f32_e32 v150, 0xbfb8aa3b, v30
	v_mul_f32_e32 v151, 0xbfb8aa3b, v31
	v_exp_f32_e32 v149, v149
	v_exp_f32_e32 v150, v150
	v_exp_f32_e32 v151, v151
	v_mul_f32_e32 v153, 0xbfb8aa3b, v25
	v_exp_f32_e32 v154, v154
	v_mul_f32_e32 v155, 0xbfb8aa3b, v27
	v_exp_f32_e32 v152, v152
	v_exp_f32_e32 v153, v153
	v_exp_f32_e32 v155, v155
	v_add_f32_e32 v148, 1.0, v158
	v_add_f32_e32 v149, 1.0, v149
	v_add_f32_e32 v150, 1.0, v150
	v_add_f32_e32 v151, 1.0, v151
	v_add_f32_e32 v154, 1.0, v154
	v_rcp_f32_e32 v148, v148
	v_rcp_f32_e32 v149, v149
	v_rcp_f32_e32 v150, v150
	v_rcp_f32_e32 v151, v151
	v_add_f32_e32 v152, 1.0, v152
	v_add_f32_e32 v153, 1.0, v153
	v_rcp_f32_e32 v154, v154
	v_add_f32_e32 v155, 1.0, v155
	v_rcp_f32_e32 v152, v152
	v_rcp_f32_e32 v153, v153
	v_rcp_f32_e32 v155, v155
	v_mul_f32_e32 v148, v28, v148
	v_mul_f32_e32 v149, v29, v149
	v_mul_f32_e32 v150, v30, v150
	v_mul_f32_e32 v151, v31, v151
	v_mul_f32_e32 v154, v26, v154
	v_mul_f32_e32 v152, v24, v152
	v_mul_f32_e32 v153, v25, v153
	v_mul_f32_e32 v155, v27, v155
	v_cvt_pk_bf16_f32 v148, v148, v149
	v_cvt_pk_bf16_f32 v149, v150, v151
	v_cvt_pk_bf16_f32 v150, v152, v153
	v_cvt_pk_bf16_f32 v151, v154, v155
	v_mul_f32_e32 v154, 0xbfb8aa3b, v20
	s_mov_b32 s9, 0xa0000
	v_exp_f32_e32 v156, v154
	v_add_co_u32_e32 v154, vcc, s9, v140
	v_mul_f32_e32 v157, 0xbfb8aa3b, v19
	s_nop 0
	v_addc_co_u32_e32 v155, vcc, 0, v141, vcc
	global_store_dwordx4 v[154:155], v[148:151], off
	v_mul_f32_e32 v154, 0xbfb8aa3b, v16
	v_mul_f32_e32 v155, 0xbfb8aa3b, v17
	v_mul_f32_e32 v149, 0xbfb8aa3b, v21
	v_mul_f32_e32 v150, 0xbfb8aa3b, v22
	v_exp_f32_e32 v149, v149
	v_exp_f32_e32 v150, v150
	v_mul_f32_e32 v151, 0xbfb8aa3b, v23
	v_exp_f32_e32 v151, v151
	v_add_f32_e32 v148, 1.0, v156
	v_exp_f32_e32 v154, v154
	v_exp_f32_e32 v155, v155
	v_mul_f32_e32 v156, 0xbfb8aa3b, v18
	v_exp_f32_e32 v156, v156
	v_exp_f32_e32 v157, v157
	v_add_f32_e32 v149, 1.0, v149
	v_add_f32_e32 v150, 1.0, v150
	v_rcp_f32_e32 v148, v148
	v_rcp_f32_e32 v149, v149
	v_rcp_f32_e32 v150, v150
	v_add_f32_e32 v151, 1.0, v151
	v_rcp_f32_e32 v151, v151
	v_add_f32_e32 v154, 1.0, v154
	v_add_f32_e32 v155, 1.0, v155
	v_rcp_f32_e32 v154, v154
	v_rcp_f32_e32 v155, v155
	v_add_f32_e32 v156, 1.0, v156
	v_add_f32_e32 v157, 1.0, v157
	v_rcp_f32_e32 v156, v156
	v_rcp_f32_e32 v157, v157
	v_mul_f32_e32 v148, v20, v148
	v_mul_f32_e32 v149, v21, v149
	v_mul_f32_e32 v150, v22, v150
	s_mov_b64 s[18:19], 0xa0000
	v_mul_f32_e32 v151, v23, v151
	v_cvt_pk_bf16_f32 v148, v148, v149
	v_cvt_pk_bf16_f32 v149, v150, v151
	v_mul_f32_e32 v150, 0xbfb8aa3b, v12
	v_lshl_add_u64 v[152:153], v[140:141], 0, s[18:19]
	v_mul_f32_e32 v154, v16, v154
	v_mul_f32_e32 v155, v17, v155
	v_exp_f32_e32 v158, v150
	v_cvt_pk_bf16_f32 v150, v154, v155
	v_mul_f32_e32 v156, v18, v156
	v_mul_f32_e32 v157, v19, v157
	v_cvt_pk_bf16_f32 v151, v156, v157
	global_store_dwordx4 v[152:153], v[148:151], off offset:256
	v_mul_f32_e32 v152, 0xbfb8aa3b, v8
	v_mul_f32_e32 v153, 0xbfb8aa3b, v9
	v_mul_f32_e32 v149, 0xbfb8aa3b, v13
	v_mul_f32_e32 v150, 0xbfb8aa3b, v14
	v_exp_f32_e32 v149, v149
	v_exp_f32_e32 v150, v150
	v_mul_f32_e32 v151, 0xbfb8aa3b, v15
	v_exp_f32_e32 v152, v152
	v_exp_f32_e32 v153, v153
	v_exp_f32_e32 v151, v151
	v_mul_f32_e32 v154, 0xbfb8aa3b, v10
	v_mul_f32_e32 v155, 0xbfb8aa3b, v11
	v_exp_f32_e32 v154, v154
	v_exp_f32_e32 v155, v155
	v_add_f32_e32 v148, 1.0, v158
	v_add_f32_e32 v149, 1.0, v149
	v_add_f32_e32 v150, 1.0, v150
	v_add_f32_e32 v152, 1.0, v152
	v_add_f32_e32 v153, 1.0, v153
	v_rcp_f32_e32 v148, v148
	v_rcp_f32_e32 v149, v149
	v_rcp_f32_e32 v150, v150
	v_add_f32_e32 v151, 1.0, v151
	v_rcp_f32_e32 v152, v152
	v_rcp_f32_e32 v153, v153
	v_rcp_f32_e32 v151, v151
	v_add_f32_e32 v154, 1.0, v154
	v_add_f32_e32 v155, 1.0, v155
	v_rcp_f32_e32 v154, v154
	v_rcp_f32_e32 v155, v155
	v_mul_f32_e32 v148, v12, v148
	v_mul_f32_e32 v149, v13, v149
	v_mul_f32_e32 v150, v14, v150
	v_mul_f32_e32 v152, v8, v152
	v_mul_f32_e32 v153, v9, v153
	s_mov_b64 s[18:19], 0xb0000
	s_mov_b32 s9, 0xb0000
	v_mul_f32_e32 v151, v15, v151
	v_cvt_pk_bf16_f32 v148, v148, v149
	v_cvt_pk_bf16_f32 v149, v150, v151
	v_cvt_pk_bf16_f32 v150, v152, v153
	v_lshl_add_u64 v[152:153], v[140:141], 0, s[18:19]
	v_add_co_u32_e32 v140, vcc, s9, v140
	v_mul_f32_e32 v154, v10, v154
	s_nop 0
	v_addc_co_u32_e32 v141, vcc, 0, v141, vcc
	v_mul_f32_e32 v155, v11, v155
	v_cvt_pk_bf16_f32 v151, v154, v155
	global_store_dwordx4 v[140:141], v[148:151], off
	v_mul_f32_e32 v154, 0xbfb8aa3b, v4
	v_exp_f32_e32 v154, v154
	v_mul_f32_e32 v148, 0xbfb8aa3b, v6
	v_exp_f32_e32 v148, v148
	v_mul_f32_e32 v149, 0xbfb8aa3b, v7
	v_exp_f32_e32 v149, v149
	v_mul_f32_e32 v151, 0xbfb8aa3b, v1
	v_add_f32_e32 v148, 1.0, v148
	v_rcp_f32_e32 v148, v148
	v_exp_f32_e32 v151, v151
	v_add_f32_e32 v140, 1.0, v154
	v_mul_f32_e32 v141, 0xbfb8aa3b, v5
	v_mul_f32_e32 v150, v6, v148
	v_add_f32_e32 v148, 1.0, v149
	v_mul_f32_e32 v149, 0xbfb8aa3b, v0
	v_rcp_f32_e32 v148, v148
	v_exp_f32_e32 v149, v149
	v_mul_f32_e32 v155, 0xbfb8aa3b, v3
	v_exp_f32_e32 v141, v141
	v_mul_f32_e32 v154, v7, v148
	v_add_f32_e32 v148, 1.0, v149
	v_add_f32_e32 v149, 1.0, v151
	v_mul_f32_e32 v151, 0xbfb8aa3b, v2
	v_exp_f32_e32 v151, v151
	v_exp_f32_e32 v155, v155
	v_add_f32_e32 v141, 1.0, v141
	v_rcp_f32_e32 v140, v140
	v_add_f32_e32 v151, 1.0, v151
	v_rcp_f32_e32 v151, v151
	v_add_f32_e32 v155, 1.0, v155
	v_rcp_f32_e32 v141, v141
	v_rcp_f32_e32 v148, v148
	v_rcp_f32_e32 v149, v149
	v_rcp_f32_e32 v155, v155
	v_mul_f32_e32 v151, v2, v151
	s_mov_b64 s[18:19], 0
	v_mul_f32_e32 v140, v4, v140
	v_mul_f32_e32 v141, v5, v141
	v_mul_f32_e32 v156, v0, v148
	v_mul_f32_e32 v157, v1, v149
	v_mul_f32_e32 v155, v3, v155
	v_cvt_pk_bf16_f32 v148, v140, v141
	v_cvt_pk_bf16_f32 v149, v150, v154
	v_cvt_pk_bf16_f32 v150, v156, v157
	v_cvt_pk_bf16_f32 v151, v151, v155
	global_store_dwordx4 v[152:153], v[148:151], off offset:256

.LBB0_283:
	s_add_u32 s54, s16, s29
	s_addc_u32 s55, s17, 0
	s_add_u32 s56, s18, 0x100
	v_mov_b32_e32 v0, 0
	s_addc_u32 s57, s19, 0
	s_mov_b64 s[18:19], 0
	v_mov_b32_e32 v1, v0
	v_mov_b32_e32 v2, v0
	v_mov_b32_e32 v3, v0
	v_mov_b32_e32 v4, v0
	v_mov_b32_e32 v5, v0
	v_mov_b32_e32 v6, v0
	v_mov_b32_e32 v7, v0
	v_mov_b32_e32 v16, v0
	v_mov_b32_e32 v17, v0
	v_mov_b32_e32 v18, v0
	v_mov_b32_e32 v19, v0
	v_mov_b32_e32 v20, v0
	v_mov_b32_e32 v21, v0
	v_mov_b32_e32 v22, v0
	v_mov_b32_e32 v23, v0
	v_mov_b32_e32 v32, v0
	v_mov_b32_e32 v33, v0
	v_mov_b32_e32 v34, v0
	v_mov_b32_e32 v35, v0
	v_mov_b32_e32 v36, v0
	v_mov_b32_e32 v37, v0
	v_mov_b32_e32 v38, v0
	v_mov_b32_e32 v39, v0
	v_mov_b32_e32 v48, v0
	v_mov_b32_e32 v49, v0
	v_mov_b32_e32 v50, v0
	v_mov_b32_e32 v51, v0
	v_mov_b32_e32 v52, v0
	v_mov_b32_e32 v53, v0
	v_mov_b32_e32 v54, v0
	v_mov_b32_e32 v55, v0
	v_mov_b32_e32 v8, v0
	v_mov_b32_e32 v9, v0
	v_mov_b32_e32 v10, v0
	v_mov_b32_e32 v11, v0
	v_mov_b32_e32 v12, v0
	v_mov_b32_e32 v13, v0
	v_mov_b32_e32 v14, v0
	v_mov_b32_e32 v15, v0
	v_mov_b32_e32 v24, v0
	v_mov_b32_e32 v25, v0
	v_mov_b32_e32 v26, v0
	v_mov_b32_e32 v27, v0
	v_mov_b32_e32 v28, v0
	v_mov_b32_e32 v29, v0
	v_mov_b32_e32 v30, v0
	v_mov_b32_e32 v31, v0
	v_mov_b32_e32 v40, v0
	v_mov_b32_e32 v41, v0
	v_mov_b32_e32 v42, v0
	v_mov_b32_e32 v43, v0
	v_mov_b32_e32 v44, v0
	v_mov_b32_e32 v45, v0
	v_mov_b32_e32 v46, v0
	v_mov_b32_e32 v47, v0
	v_mov_b32_e32 v56, v0
	v_mov_b32_e32 v57, v0
	v_mov_b32_e32 v58, v0
	v_mov_b32_e32 v59, v0
	v_mov_b32_e32 v60, v0
	v_mov_b32_e32 v61, v0
	v_mov_b32_e32 v62, v0
	v_mov_b32_e32 v63, v0
	v_mov_b32_e32 v64, v0
	v_mov_b32_e32 v65, v0
	v_mov_b32_e32 v66, v0
	v_mov_b32_e32 v67, v0
	v_mov_b32_e32 v68, v0
	v_mov_b32_e32 v69, v0
	v_mov_b32_e32 v70, v0
	v_mov_b32_e32 v71, v0
	v_mov_b32_e32 v80, v0
	v_mov_b32_e32 v81, v0
	v_mov_b32_e32 v82, v0
	v_mov_b32_e32 v83, v0
	v_mov_b32_e32 v84, v0
	v_mov_b32_e32 v85, v0
	v_mov_b32_e32 v86, v0
	v_mov_b32_e32 v87, v0
	v_mov_b32_e32 v96, v0
	v_mov_b32_e32 v97, v0
	v_mov_b32_e32 v98, v0
	v_mov_b32_e32 v99, v0
	v_mov_b32_e32 v100, v0
	v_mov_b32_e32 v101, v0
	v_mov_b32_e32 v102, v0
	v_mov_b32_e32 v103, v0
	v_mov_b32_e32 v112, v0
	v_mov_b32_e32 v113, v0
	v_mov_b32_e32 v114, v0
	v_mov_b32_e32 v115, v0
	v_mov_b32_e32 v116, v0
	v_mov_b32_e32 v117, v0
	v_mov_b32_e32 v118, v0
	v_mov_b32_e32 v119, v0
	v_mov_b32_e32 v72, v0
	v_mov_b32_e32 v73, v0
	v_mov_b32_e32 v74, v0
	v_mov_b32_e32 v75, v0
	v_mov_b32_e32 v76, v0
	v_mov_b32_e32 v77, v0
	v_mov_b32_e32 v78, v0
	v_mov_b32_e32 v79, v0
	v_mov_b32_e32 v88, v0
	v_mov_b32_e32 v89, v0
	v_mov_b32_e32 v90, v0
	v_mov_b32_e32 v91, v0
	v_mov_b32_e32 v92, v0
	v_mov_b32_e32 v93, v0
	v_mov_b32_e32 v94, v0
	v_mov_b32_e32 v95, v0
	v_mov_b32_e32 v104, v0
	v_mov_b32_e32 v105, v0
	v_mov_b32_e32 v106, v0
	v_mov_b32_e32 v107, v0
	v_mov_b32_e32 v108, v0
	v_mov_b32_e32 v109, v0
	v_mov_b32_e32 v110, v0
	v_mov_b32_e32 v111, v0
	v_mov_b32_e32 v120, v0
	v_mov_b32_e32 v121, v0
	v_mov_b32_e32 v122, v0
	v_mov_b32_e32 v123, v0
	v_mov_b32_e32 v124, v0
	v_mov_b32_e32 v125, v0
	v_mov_b32_e32 v126, v0
	v_mov_b32_e32 v127, v0
	s_mov_b64 s[78:79], 0x80
	v_add_u32_e32 v140, 0x10000, v154
	ds_read_b128 v[128:131], v140
	ds_read_b128 v[132:135], v140 offset:1024
	ds_read_b128 v[136:139], v140 offset:2048
	ds_read_b128 v[140:143], v140 offset:3072
.LBB0_284:
	s_add_u32 s20, s18, 1
	s_addc_u32 s21, s19, 0
	s_lshl_b64 s[58:59], s[20:21], s48
	s_add_u32 s20, s18, 2
	s_addc_u32 s21, s19, 0
	s_lshl_b64 s[22:23], s[20:21], s48
	s_add_u32 s19, s16, s22
	s_addc_u32 s22, s17, s23
	s_cmp_eq_u32 s49, s18
	s_cselect_b32 s23, s15, s22
	s_cselect_b32 s22, s14, s19
	s_cselect_b32 s24, s0, s56
	s_cselect_b32 s25, s1, s57
	s_add_u32 s18, s22, s4
	s_addc_u32 s19, s23, s5
	s_add_i32 s60, 0, 0x10000
	s_add_u32 s58, s54, s58
	s_addc_u32 s59, s55, s59
	v_lshl_add_u64 v[150:151], s[58:59], 0, v[144:145]
	s_add_i32 m0, s36, 0xc000
	ds_read_b128 v[156:159], v155
	ds_read_b128 v[160:163], v155 offset:1024
	ds_read_b128 v[164:167], v155 offset:2048
	ds_read_b128 v[168:171], v155 offset:3072
	ds_read_b128 v[172:175], v155 offset:4096
	ds_read_b128 v[176:179], v155 offset:5120
	ds_read_b128 v[180:183], v155 offset:6144
	ds_read_b128 v[188:191], v155 offset:7168
	global_load_lds_dwordx4 v[150:151], off
	v_lshl_add_u64 v[150:151], s[58:59], 0, v[146:147]
	s_add_i32 m0, s36, 0xe000
	s_nop 0
	global_load_lds_dwordx4 v[150:151], off
	s_waitcnt lgkmcnt(8)
	s_setprio 1
	s_barrier
	s_waitcnt lgkmcnt(0)
	v_mfma_f32_16x16x32_bf16 v[124:127], v[128:131], v[156:159], v[124:127]
	v_mfma_f32_16x16x32_bf16 v[120:123], v[136:139], v[156:159], v[120:123]
	v_mfma_f32_16x16x32_bf16 v[108:111], v[128:131], v[164:167], v[108:111]
	v_mfma_f32_16x16x32_bf16 v[104:107], v[136:139], v[164:167], v[104:107]
	v_mfma_f32_16x16x32_bf16 v[92:95], v[128:131], v[172:175], v[92:95]
	v_mfma_f32_16x16x32_bf16 v[88:91], v[136:139], v[172:175], v[88:91]
	v_mfma_f32_16x16x32_bf16 v[76:79], v[128:131], v[180:183], v[76:79]
	v_mfma_f32_16x16x32_bf16 v[72:75], v[136:139], v[180:183], v[72:75]
	v_mfma_f32_16x16x32_bf16 v[124:127], v[132:135], v[160:163], v[124:127]
	v_mfma_f32_16x16x32_bf16 v[120:123], v[140:143], v[160:163], v[120:123]
	v_mfma_f32_16x16x32_bf16 v[108:111], v[132:135], v[168:171], v[108:111]
	v_mfma_f32_16x16x32_bf16 v[104:107], v[140:143], v[168:171], v[104:107]
	v_mfma_f32_16x16x32_bf16 v[92:95], v[132:135], v[176:179], v[92:95]
	v_mfma_f32_16x16x32_bf16 v[88:91], v[140:143], v[176:179], v[88:91]
	v_mfma_f32_16x16x32_bf16 v[76:79], v[132:135], v[188:191], v[76:79]
	v_mfma_f32_16x16x32_bf16 v[72:75], v[140:143], v[188:191], v[72:75]
	s_barrier
	s_setprio 0
	s_add_i32 s58, 0, 0x14000
	v_add_u32_e32 v150, s58, v154
	s_add_i32 s59, s60, s33
	ds_read_b128 v[192:195], v150
	ds_read_b128 v[202:205], v150 offset:1024
	ds_read_b128 v[206:209], v150 offset:2048
	ds_read_b128 v[210:213], v150 offset:3072
	v_lshl_add_u64 v[150:151], s[24:25], 0, v[184:185]
	s_mov_b32 m0, s59
	v_lshl_add_u64 v[196:197], s[24:25], 0, v[148:149]
	global_load_lds_dwordx4 v[150:151], off
	s_add_i32 m0, s59, 0x2000
	s_nop 0
	global_load_lds_dwordx4 v[196:197], off
	s_setprio 1
	s_barrier
	s_waitcnt lgkmcnt(0)
	v_mfma_f32_16x16x32_bf16 v[116:119], v[192:195], v[156:159], v[116:119]
	v_mfma_f32_16x16x32_bf16 v[112:115], v[206:209], v[156:159], v[112:115]
	v_mfma_f32_16x16x32_bf16 v[100:103], v[192:195], v[164:167], v[100:103]
	v_mfma_f32_16x16x32_bf16 v[96:99], v[206:209], v[164:167], v[96:99]
	v_mfma_f32_16x16x32_bf16 v[84:87], v[192:195], v[172:175], v[84:87]
	v_mfma_f32_16x16x32_bf16 v[80:83], v[206:209], v[172:175], v[80:83]
	v_mfma_f32_16x16x32_bf16 v[68:71], v[192:195], v[180:183], v[68:71]
	v_mfma_f32_16x16x32_bf16 v[64:67], v[206:209], v[180:183], v[64:67]
	v_mfma_f32_16x16x32_bf16 v[116:119], v[202:205], v[160:163], v[116:119]
	v_mfma_f32_16x16x32_bf16 v[112:115], v[210:213], v[160:163], v[112:115]
	v_mfma_f32_16x16x32_bf16 v[100:103], v[202:205], v[168:171], v[100:103]
	v_mfma_f32_16x16x32_bf16 v[96:99], v[210:213], v[168:171], v[96:99]
	v_mfma_f32_16x16x32_bf16 v[84:87], v[202:205], v[176:179], v[84:87]
	v_mfma_f32_16x16x32_bf16 v[80:83], v[210:213], v[176:179], v[80:83]
	v_mfma_f32_16x16x32_bf16 v[68:71], v[202:205], v[188:191], v[68:71]
	v_mfma_f32_16x16x32_bf16 v[64:67], v[210:213], v[188:191], v[64:67]
	s_barrier
	s_setprio 0
	s_mov_b32 m0, s36
	v_lshl_add_u64 v[214:215], s[22:23], 0, v[144:145]
	ds_read_b128 v[156:159], v155 offset:16384
	ds_read_b128 v[160:163], v155 offset:17408
	ds_read_b128 v[164:167], v155 offset:18432
	ds_read_b128 v[168:171], v155 offset:19456
	ds_read_b128 v[172:175], v155 offset:20480
	ds_read_b128 v[176:179], v155 offset:21504
	ds_read_b128 v[180:183], v155 offset:22528
	ds_read_b128 v[188:191], v155 offset:23552
	global_load_lds_dwordx4 v[214:215], off
	v_lshl_add_u64 v[214:215], s[22:23], 0, v[146:147]
	s_mov_b32 m0, s37
	s_nop 0
	global_load_lds_dwordx4 v[214:215], off
	s_setprio 1
	s_waitcnt vmcnt(10)
	s_barrier
	s_waitcnt lgkmcnt(0)
	v_mfma_f32_16x16x32_bf16 v[60:63], v[128:131], v[156:159], v[60:63]
	v_mfma_f32_16x16x32_bf16 v[56:59], v[136:139], v[156:159], v[56:59]
	v_mfma_f32_16x16x32_bf16 v[44:47], v[128:131], v[164:167], v[44:47]
	v_mfma_f32_16x16x32_bf16 v[40:43], v[136:139], v[164:167], v[40:43]
	v_mfma_f32_16x16x32_bf16 v[28:31], v[128:131], v[172:175], v[28:31]
	v_mfma_f32_16x16x32_bf16 v[24:27], v[136:139], v[172:175], v[24:27]
	v_mfma_f32_16x16x32_bf16 v[12:15], v[128:131], v[180:183], v[12:15]
	v_mfma_f32_16x16x32_bf16 v[8:11], v[136:139], v[180:183], v[8:11]
	v_mfma_f32_16x16x32_bf16 v[60:63], v[132:135], v[160:163], v[60:63]
	v_mfma_f32_16x16x32_bf16 v[56:59], v[140:143], v[160:163], v[56:59]
	v_mfma_f32_16x16x32_bf16 v[44:47], v[132:135], v[168:171], v[44:47]
	v_mfma_f32_16x16x32_bf16 v[40:43], v[140:143], v[168:171], v[40:43]
	v_mfma_f32_16x16x32_bf16 v[28:31], v[132:135], v[176:179], v[28:31]
	v_mfma_f32_16x16x32_bf16 v[24:27], v[140:143], v[176:179], v[24:27]
	v_mfma_f32_16x16x32_bf16 v[12:15], v[132:135], v[188:191], v[12:15]
	v_mfma_f32_16x16x32_bf16 v[8:11], v[140:143], v[188:191], v[8:11]
	s_barrier
	s_setprio 0
	v_add_u32_e32 v140, 0x18000, v154
	ds_read_b128 v[128:131], v140
	ds_read_b128 v[132:135], v140 offset:1024
	ds_read_b128 v[136:139], v140 offset:2048
	ds_read_b128 v[140:143], v140 offset:3072
	s_add_u32 s24, s24, s28
	s_addc_u32 s25, s25, 0
	s_add_i32 s58, s58, s33
	v_lshl_add_u64 v[214:215], s[24:25], 0, v[184:185]
	s_mov_b32 m0, s58
	v_lshl_add_u64 v[216:217], s[24:25], 0, v[148:149]
	global_load_lds_dwordx4 v[214:215], off
	s_add_i32 m0, s58, 0x2000
	s_nop 0
	global_load_lds_dwordx4 v[216:217], off
	s_waitcnt vmcnt(6)
	s_setprio 1
	s_barrier
	v_mfma_f32_16x16x32_bf16 v[52:55], v[192:195], v[156:159], v[52:55]
	v_mfma_f32_16x16x32_bf16 v[48:51], v[206:209], v[156:159], v[48:51]
	v_mfma_f32_16x16x32_bf16 v[36:39], v[192:195], v[164:167], v[36:39]
	v_mfma_f32_16x16x32_bf16 v[32:35], v[206:209], v[164:167], v[32:35]
	v_mfma_f32_16x16x32_bf16 v[20:23], v[192:195], v[172:175], v[20:23]
	v_mfma_f32_16x16x32_bf16 v[16:19], v[206:209], v[172:175], v[16:19]
	v_mfma_f32_16x16x32_bf16 v[4:7], v[192:195], v[180:183], v[4:7]
	v_mfma_f32_16x16x32_bf16 v[0:3], v[206:209], v[180:183], v[0:3]
	v_mfma_f32_16x16x32_bf16 v[52:55], v[202:205], v[160:163], v[52:55]
	v_mfma_f32_16x16x32_bf16 v[48:51], v[210:213], v[160:163], v[48:51]
	v_mfma_f32_16x16x32_bf16 v[36:39], v[202:205], v[168:171], v[36:39]
	v_mfma_f32_16x16x32_bf16 v[32:35], v[210:213], v[168:171], v[32:35]
	v_mfma_f32_16x16x32_bf16 v[20:23], v[202:205], v[176:179], v[20:23]
	v_mfma_f32_16x16x32_bf16 v[16:19], v[210:213], v[176:179], v[16:19]
	v_mfma_f32_16x16x32_bf16 v[4:7], v[202:205], v[188:191], v[4:7]
	v_mfma_f32_16x16x32_bf16 v[0:3], v[210:213], v[188:191], v[0:3]
	s_barrier
	s_setprio 0
	s_add_i32 s24, 0, 0x18000
	s_add_u32 s22, s22, s29
	s_addc_u32 s23, s23, 0
	s_mov_b32 m0, s38
	v_lshl_add_u64 v[192:193], s[22:23], 0, v[144:145]
	ds_read_b128 v[156:159], v155 offset:32768
	ds_read_b128 v[160:163], v155 offset:33792
	ds_read_b128 v[164:167], v155 offset:34816
	ds_read_b128 v[168:171], v155 offset:35840
	ds_read_b128 v[172:175], v155 offset:36864
	ds_read_b128 v[176:179], v155 offset:37888
	ds_read_b128 v[180:183], v155 offset:38912
	ds_read_b128 v[188:191], v155 offset:39936
	global_load_lds_dwordx4 v[192:193], off
	v_lshl_add_u64 v[192:193], s[22:23], 0, v[146:147]
	s_mov_b32 m0, s39
	s_nop 0
	global_load_lds_dwordx4 v[192:193], off
	s_waitcnt lgkmcnt(8)
	s_setprio 1
	s_barrier
	s_waitcnt lgkmcnt(0)
	v_mfma_f32_16x16x32_bf16 v[124:127], v[128:131], v[156:159], v[124:127]
	v_mfma_f32_16x16x32_bf16 v[120:123], v[136:139], v[156:159], v[120:123]
	v_mfma_f32_16x16x32_bf16 v[108:111], v[128:131], v[164:167], v[108:111]
	v_mfma_f32_16x16x32_bf16 v[104:107], v[136:139], v[164:167], v[104:107]
	v_mfma_f32_16x16x32_bf16 v[92:95], v[128:131], v[172:175], v[92:95]
	v_mfma_f32_16x16x32_bf16 v[88:91], v[136:139], v[172:175], v[88:91]
	v_mfma_f32_16x16x32_bf16 v[76:79], v[128:131], v[180:183], v[76:79]
	v_mfma_f32_16x16x32_bf16 v[72:75], v[136:139], v[180:183], v[72:75]
	v_mfma_f32_16x16x32_bf16 v[124:127], v[132:135], v[160:163], v[124:127]
	v_mfma_f32_16x16x32_bf16 v[120:123], v[140:143], v[160:163], v[120:123]
	v_mfma_f32_16x16x32_bf16 v[108:111], v[132:135], v[168:171], v[108:111]
	v_mfma_f32_16x16x32_bf16 v[104:107], v[140:143], v[168:171], v[104:107]
	v_mfma_f32_16x16x32_bf16 v[92:95], v[132:135], v[176:179], v[92:95]
	v_mfma_f32_16x16x32_bf16 v[88:91], v[140:143], v[176:179], v[88:91]
	v_mfma_f32_16x16x32_bf16 v[76:79], v[132:135], v[188:191], v[76:79]
	v_mfma_f32_16x16x32_bf16 v[72:75], v[140:143], v[188:191], v[72:75]
	s_barrier
	s_setprio 0
	s_add_i32 s22, 0, 0x1c000
	s_add_i32 s23, s24, s33
	v_add_u32_e32 v187, s22, v154
	v_lshl_add_u64 v[150:151], v[150:151], 0, s[78:79]
	s_mov_b32 m0, s23
	ds_read_b128 v[192:195], v187
	ds_read_b128 v[202:205], v187 offset:1024
	ds_read_b128 v[206:209], v187 offset:2048
	ds_read_b128 v[210:213], v187 offset:3072
	global_load_lds_dwordx4 v[150:151], off
	v_lshl_add_u64 v[150:151], v[196:197], 0, s[78:79]
	s_add_i32 m0, s23, 0x2000
	s_nop 0
	global_load_lds_dwordx4 v[150:151], off
	s_setprio 1
	s_barrier
	s_waitcnt lgkmcnt(0)
	v_mfma_f32_16x16x32_bf16 v[116:119], v[192:195], v[156:159], v[116:119]
	v_mfma_f32_16x16x32_bf16 v[112:115], v[206:209], v[156:159], v[112:115]
	v_mfma_f32_16x16x32_bf16 v[100:103], v[192:195], v[164:167], v[100:103]
	v_mfma_f32_16x16x32_bf16 v[96:99], v[206:209], v[164:167], v[96:99]
	v_mfma_f32_16x16x32_bf16 v[84:87], v[192:195], v[172:175], v[84:87]
	v_mfma_f32_16x16x32_bf16 v[80:83], v[206:209], v[172:175], v[80:83]
	v_mfma_f32_16x16x32_bf16 v[68:71], v[192:195], v[180:183], v[68:71]
	v_mfma_f32_16x16x32_bf16 v[64:67], v[206:209], v[180:183], v[64:67]
	v_mfma_f32_16x16x32_bf16 v[116:119], v[202:205], v[160:163], v[116:119]
	v_mfma_f32_16x16x32_bf16 v[112:115], v[210:213], v[160:163], v[112:115]
	v_mfma_f32_16x16x32_bf16 v[100:103], v[202:205], v[168:171], v[100:103]
	v_mfma_f32_16x16x32_bf16 v[96:99], v[210:213], v[168:171], v[96:99]
	v_mfma_f32_16x16x32_bf16 v[84:87], v[202:205], v[176:179], v[84:87]
	v_mfma_f32_16x16x32_bf16 v[80:83], v[210:213], v[176:179], v[80:83]
	v_mfma_f32_16x16x32_bf16 v[68:71], v[202:205], v[188:191], v[68:71]
	v_mfma_f32_16x16x32_bf16 v[64:67], v[210:213], v[188:191], v[64:67]
	s_barrier
	s_setprio 0
	s_mov_b32 m0, s46
	v_lshl_add_u64 v[150:151], s[18:19], 0, v[144:145]
	ds_read_b128 v[156:159], v155 offset:49152
	ds_read_b128 v[160:163], v155 offset:50176
	ds_read_b128 v[164:167], v155 offset:51200
	ds_read_b128 v[168:171], v155 offset:52224
	ds_read_b128 v[172:175], v155 offset:53248
	ds_read_b128 v[176:179], v155 offset:54272
	ds_read_b128 v[180:183], v155 offset:55296
	ds_read_b128 v[188:191], v155 offset:56320
	global_load_lds_dwordx4 v[150:151], off
	v_lshl_add_u64 v[150:151], s[18:19], 0, v[146:147]
	s_mov_b32 m0, s47
	s_nop 0
	global_load_lds_dwordx4 v[150:151], off
	s_setprio 1
	s_waitcnt vmcnt(10)
	s_barrier
	s_waitcnt lgkmcnt(0)
	v_mfma_f32_16x16x32_bf16 v[60:63], v[128:131], v[156:159], v[60:63]
	v_mfma_f32_16x16x32_bf16 v[56:59], v[136:139], v[156:159], v[56:59]
	v_mfma_f32_16x16x32_bf16 v[44:47], v[128:131], v[164:167], v[44:47]
	v_mfma_f32_16x16x32_bf16 v[40:43], v[136:139], v[164:167], v[40:43]
	v_mfma_f32_16x16x32_bf16 v[28:31], v[128:131], v[172:175], v[28:31]
	v_mfma_f32_16x16x32_bf16 v[24:27], v[136:139], v[172:175], v[24:27]
	v_mfma_f32_16x16x32_bf16 v[12:15], v[128:131], v[180:183], v[12:15]
	v_mfma_f32_16x16x32_bf16 v[8:11], v[136:139], v[180:183], v[8:11]
	v_mfma_f32_16x16x32_bf16 v[60:63], v[132:135], v[160:163], v[60:63]
	v_mfma_f32_16x16x32_bf16 v[56:59], v[140:143], v[160:163], v[56:59]
	v_mfma_f32_16x16x32_bf16 v[44:47], v[132:135], v[168:171], v[44:47]
	v_mfma_f32_16x16x32_bf16 v[40:43], v[140:143], v[168:171], v[40:43]
	v_mfma_f32_16x16x32_bf16 v[28:31], v[132:135], v[176:179], v[28:31]
	v_mfma_f32_16x16x32_bf16 v[24:27], v[140:143], v[176:179], v[24:27]
	v_mfma_f32_16x16x32_bf16 v[12:15], v[132:135], v[188:191], v[12:15]
	v_mfma_f32_16x16x32_bf16 v[8:11], v[140:143], v[188:191], v[8:11]
	s_barrier
	s_setprio 0
	v_add_u32_e32 v140, 0x10000, v154
	ds_read_b128 v[128:131], v140
	ds_read_b128 v[132:135], v140 offset:1024
	ds_read_b128 v[136:139], v140 offset:2048
	ds_read_b128 v[140:143], v140 offset:3072
	s_add_i32 s18, s22, s33
	v_lshl_add_u64 v[246:247], v[214:215], 0, s[78:79]
	s_mov_b32 m0, s18
	s_nop 0
	global_load_lds_dwordx4 v[246:247], off
	v_lshl_add_u64 v[248:249], v[216:217], 0, s[78:79]
	s_add_i32 m0, s18, 0x2000
	s_nop 0
	global_load_lds_dwordx4 v[248:249], off
	s_waitcnt vmcnt(6)
	s_setprio 1
	s_barrier
	v_mfma_f32_16x16x32_bf16 v[52:55], v[192:195], v[156:159], v[52:55]
	v_mfma_f32_16x16x32_bf16 v[48:51], v[206:209], v[156:159], v[48:51]
	v_mfma_f32_16x16x32_bf16 v[36:39], v[192:195], v[164:167], v[36:39]
	v_mfma_f32_16x16x32_bf16 v[32:35], v[206:209], v[164:167], v[32:35]
	v_mfma_f32_16x16x32_bf16 v[20:23], v[192:195], v[172:175], v[20:23]
	v_mfma_f32_16x16x32_bf16 v[16:19], v[206:209], v[172:175], v[16:19]
	v_mfma_f32_16x16x32_bf16 v[4:7], v[192:195], v[180:183], v[4:7]
	v_mfma_f32_16x16x32_bf16 v[0:3], v[206:209], v[180:183], v[0:3]
	v_mfma_f32_16x16x32_bf16 v[52:55], v[202:205], v[160:163], v[52:55]
	v_mfma_f32_16x16x32_bf16 v[48:51], v[210:213], v[160:163], v[48:51]
	v_mfma_f32_16x16x32_bf16 v[36:39], v[202:205], v[168:171], v[36:39]
	v_mfma_f32_16x16x32_bf16 v[32:35], v[210:213], v[168:171], v[32:35]
	v_mfma_f32_16x16x32_bf16 v[20:23], v[202:205], v[176:179], v[20:23]
	v_mfma_f32_16x16x32_bf16 v[16:19], v[210:213], v[176:179], v[16:19]
	v_mfma_f32_16x16x32_bf16 v[4:7], v[202:205], v[188:191], v[4:7]
	v_mfma_f32_16x16x32_bf16 v[0:3], v[210:213], v[188:191], v[0:3]
	s_barrier
	s_setprio 0
	s_add_u32 s56, s56, 0x100
	s_addc_u32 s57, s57, 0
	s_cmp_ge_u32 s20, s40
	s_mov_b64 s[18:19], s[20:21]
	s_cbranch_scc0 .LBB0_284
	s_waitcnt lgkmcnt(0)
	s_lshl_b32 s16, s52, 8
	s_add_i32 s18, s16, s41
	s_lshl_b32 s16, s53, 8
	v_mov_b32_e32 v156, v153
	v_mov_b32_e32 v128, v152
	s_or_b32 s16, s16, s42
	s_mov_b32 s53, s51
	v_lshl_add_u32 v150, v128, 2, s16
	s_ashr_i32 s16, s52, 5
	s_mul_hi_i32 s17, s16, 0x6000
	s_mulk_i32 s16, 0x6000
	v_add_u32_e32 v156, s18, v156
	s_add_u32 s16, s44, s16
	v_ashrrev_i32_e32 v157, 31, v156
	s_addc_u32 s17, s45, s17
	v_ashrrev_i32_e32 v151, 31, v150
	v_lshlrev_b64 v[156:157], 11, v[156:157]
	v_lshl_add_u64 v[128:129], v[150:151], 2, s[16:17]
	v_lshl_add_u64 v[150:151], v[156:157], 0, v[150:151]
	v_lshlrev_b64 v[150:151], 2, v[150:151]
	global_load_dwordx4 v[140:143], v[128:129], off
	global_load_dwordx4 v[136:139], v[128:129], off offset:64
	global_load_dwordx4 v[132:135], v[128:129], off offset:512
	s_nop 0
	global_load_dwordx4 v[128:131], v[128:129], off offset:576
	v_readlane_b32 s18, v244, 20
	v_readlane_b32 s19, v244, 21
	s_and_b64 vcc, exec, s[12:13]
	s_mov_b32 s52, s50
	s_add_u32 s16, s8, 0x0
	s_addc_u32 s17, s9, 0
	global_load_dwordx4 v[156:159], v150, s[16:17]
	global_load_dwordx4 v[160:163], v150, s[16:17] offset:64
	global_load_dwordx4 v[164:167], v150, s[16:17] offset:512
	global_load_dwordx4 v[168:171], v150, s[16:17] offset:576
	s_add_u32 s16, s8, 0x20000
	s_addc_u32 s17, s9, 0
	global_load_dwordx4 v[172:175], v150, s[16:17]
	global_load_dwordx4 v[176:179], v150, s[16:17] offset:64
	global_load_dwordx4 v[180:183], v150, s[16:17] offset:512
	global_load_dwordx4 v[188:191], v150, s[16:17] offset:576
	s_add_u32 s16, s8, 0x40000
	s_addc_u32 s17, s9, 0
	global_load_dwordx4 v[192:195], v150, s[16:17]
	global_load_dwordx4 v[202:205], v150, s[16:17] offset:64
	global_load_dwordx4 v[206:209], v150, s[16:17] offset:512
	global_load_dwordx4 v[210:213], v150, s[16:17] offset:576
	s_waitcnt vmcnt(8)
	v_pk_fma_f32 v[158:159], v[126:127], v[142:143], v[158:159]
	v_pk_fma_f32 v[156:157], v[124:125], v[140:141], v[156:157]
	v_pk_fma_f32 v[162:163], v[122:123], v[138:139], v[162:163]
	v_pk_fma_f32 v[160:161], v[120:121], v[136:137], v[160:161]
	v_pk_fma_f32 v[166:167], v[118:119], v[134:135], v[166:167]
	v_pk_fma_f32 v[164:165], v[116:117], v[132:133], v[164:165]
	v_pk_fma_f32 v[170:171], v[114:115], v[130:131], v[170:171]
	v_pk_fma_f32 v[168:169], v[112:113], v[128:129], v[168:169]
	s_add_u32 s16, s18, 0x0
	s_addc_u32 s17, s19, 0
	global_store_dwordx4 v150, v[156:159], s[16:17]
	global_store_dwordx4 v150, v[160:163], s[16:17] offset:64
	global_store_dwordx4 v150, v[164:167], s[16:17] offset:512
	global_store_dwordx4 v150, v[168:171], s[16:17] offset:576
	s_add_u32 s16, s8, 0x60000
	s_addc_u32 s17, s9, 0
	global_load_dwordx4 v[124:127], v150, s[16:17]
	global_load_dwordx4 v[120:123], v150, s[16:17] offset:64
	global_load_dwordx4 v[116:119], v150, s[16:17] offset:512
	global_load_dwordx4 v[112:115], v150, s[16:17] offset:576
	s_waitcnt vmcnt(12)
	v_pk_fma_f32 v[174:175], v[110:111], v[142:143], v[174:175]
	v_pk_fma_f32 v[172:173], v[108:109], v[140:141], v[172:173]
	v_pk_fma_f32 v[178:179], v[106:107], v[138:139], v[178:179]
	v_pk_fma_f32 v[176:177], v[104:105], v[136:137], v[176:177]
	v_pk_fma_f32 v[182:183], v[102:103], v[134:135], v[182:183]
	v_pk_fma_f32 v[180:181], v[100:101], v[132:133], v[180:181]
	v_pk_fma_f32 v[190:191], v[98:99], v[130:131], v[190:191]
	v_pk_fma_f32 v[188:189], v[96:97], v[128:129], v[188:189]
	s_add_u32 s16, s18, 0x20000
	s_addc_u32 s17, s19, 0
	global_store_dwordx4 v150, v[172:175], s[16:17]
	global_store_dwordx4 v150, v[176:179], s[16:17] offset:64
	global_store_dwordx4 v150, v[180:183], s[16:17] offset:512
	global_store_dwordx4 v150, v[188:191], s[16:17] offset:576
	s_add_u32 s16, s8, 0x100000
	s_addc_u32 s17, s9, 0
	global_load_dwordx4 v[108:111], v150, s[16:17]
	global_load_dwordx4 v[104:107], v150, s[16:17] offset:64
	global_load_dwordx4 v[100:103], v150, s[16:17] offset:512
	global_load_dwordx4 v[96:99], v150, s[16:17] offset:576
	s_waitcnt vmcnt(16)
	v_pk_fma_f32 v[194:195], v[94:95], v[142:143], v[194:195]
	v_pk_fma_f32 v[192:193], v[92:93], v[140:141], v[192:193]
	v_pk_fma_f32 v[204:205], v[90:91], v[138:139], v[204:205]
	v_pk_fma_f32 v[202:203], v[88:89], v[136:137], v[202:203]
	v_pk_fma_f32 v[208:209], v[86:87], v[134:135], v[208:209]
	v_pk_fma_f32 v[206:207], v[84:85], v[132:133], v[206:207]
	v_pk_fma_f32 v[212:213], v[82:83], v[130:131], v[212:213]
	v_pk_fma_f32 v[210:211], v[80:81], v[128:129], v[210:211]
	s_add_u32 s16, s18, 0x40000
	s_addc_u32 s17, s19, 0
	global_store_dwordx4 v150, v[192:195], s[16:17]
	global_store_dwordx4 v150, v[202:205], s[16:17] offset:64
	global_store_dwordx4 v150, v[206:209], s[16:17] offset:512
	global_store_dwordx4 v150, v[210:213], s[16:17] offset:576
	s_add_u32 s16, s8, 0x120000
	s_addc_u32 s17, s9, 0
	global_load_dwordx4 v[92:95], v150, s[16:17]
	global_load_dwordx4 v[88:91], v150, s[16:17] offset:64
	global_load_dwordx4 v[84:87], v150, s[16:17] offset:512
	global_load_dwordx4 v[80:83], v150, s[16:17] offset:576
	s_waitcnt vmcnt(16)
	v_pk_fma_f32 v[126:127], v[78:79], v[142:143], v[126:127]
	v_pk_fma_f32 v[124:125], v[76:77], v[140:141], v[124:125]
	v_pk_fma_f32 v[122:123], v[74:75], v[138:139], v[122:123]
	v_pk_fma_f32 v[120:121], v[72:73], v[136:137], v[120:121]
	v_pk_fma_f32 v[118:119], v[70:71], v[134:135], v[118:119]
	v_pk_fma_f32 v[116:117], v[68:69], v[132:133], v[116:117]
	v_pk_fma_f32 v[114:115], v[66:67], v[130:131], v[114:115]
	v_pk_fma_f32 v[112:113], v[64:65], v[128:129], v[112:113]
	s_add_u32 s16, s18, 0x60000
	s_addc_u32 s17, s19, 0
	global_store_dwordx4 v150, v[124:127], s[16:17]
	global_store_dwordx4 v150, v[120:123], s[16:17] offset:64
	global_store_dwordx4 v150, v[116:119], s[16:17] offset:512
	global_store_dwordx4 v150, v[112:115], s[16:17] offset:576
	s_add_u32 s16, s8, 0x140000
	s_addc_u32 s17, s9, 0
	global_load_dwordx4 v[76:79], v150, s[16:17]
	global_load_dwordx4 v[72:75], v150, s[16:17] offset:64
	global_load_dwordx4 v[68:71], v150, s[16:17] offset:512
	global_load_dwordx4 v[64:67], v150, s[16:17] offset:576
	s_waitcnt vmcnt(16)
	v_pk_fma_f32 v[110:111], v[62:63], v[142:143], v[110:111]
	v_pk_fma_f32 v[108:109], v[60:61], v[140:141], v[108:109]
	v_pk_fma_f32 v[106:107], v[58:59], v[138:139], v[106:107]
	v_pk_fma_f32 v[104:105], v[56:57], v[136:137], v[104:105]
	v_pk_fma_f32 v[102:103], v[54:55], v[134:135], v[102:103]
	v_pk_fma_f32 v[100:101], v[52:53], v[132:133], v[100:101]
	v_pk_fma_f32 v[98:99], v[50:51], v[130:131], v[98:99]
	v_pk_fma_f32 v[96:97], v[48:49], v[128:129], v[96:97]
	s_add_u32 s16, s18, 0x100000
	s_addc_u32 s17, s19, 0
	global_store_dwordx4 v150, v[108:111], s[16:17]
	global_store_dwordx4 v150, v[104:107], s[16:17] offset:64
	global_store_dwordx4 v150, v[100:103], s[16:17] offset:512
	global_store_dwordx4 v150, v[96:99], s[16:17] offset:576
	s_add_u32 s16, s8, 0x160000
	s_addc_u32 s17, s9, 0
	global_load_dwordx4 v[60:63], v150, s[16:17]
	global_load_dwordx4 v[56:59], v150, s[16:17] offset:64
	global_load_dwordx4 v[52:55], v150, s[16:17] offset:512
	global_load_dwordx4 v[48:51], v150, s[16:17] offset:576
	s_waitcnt vmcnt(16)
	v_pk_fma_f32 v[94:95], v[46:47], v[142:143], v[94:95]
	v_pk_fma_f32 v[92:93], v[44:45], v[140:141], v[92:93]
	v_pk_fma_f32 v[90:91], v[42:43], v[138:139], v[90:91]
	v_pk_fma_f32 v[88:89], v[40:41], v[136:137], v[88:89]
	v_pk_fma_f32 v[86:87], v[38:39], v[134:135], v[86:87]
	v_pk_fma_f32 v[84:85], v[36:37], v[132:133], v[84:85]
	v_pk_fma_f32 v[82:83], v[34:35], v[130:131], v[82:83]
	v_pk_fma_f32 v[80:81], v[32:33], v[128:129], v[80:81]
	s_add_u32 s16, s18, 0x120000
	s_addc_u32 s17, s19, 0
	global_store_dwordx4 v150, v[92:95], s[16:17]
	global_store_dwordx4 v150, v[88:91], s[16:17] offset:64
	global_store_dwordx4 v150, v[84:87], s[16:17] offset:512
	global_store_dwordx4 v150, v[80:83], s[16:17] offset:576
	s_waitcnt vmcnt(12)
	v_pk_fma_f32 v[78:79], v[30:31], v[142:143], v[78:79]
	v_pk_fma_f32 v[76:77], v[28:29], v[140:141], v[76:77]
	v_pk_fma_f32 v[74:75], v[26:27], v[138:139], v[74:75]
	v_pk_fma_f32 v[72:73], v[24:25], v[136:137], v[72:73]
	v_pk_fma_f32 v[70:71], v[22:23], v[134:135], v[70:71]
	v_pk_fma_f32 v[68:69], v[20:21], v[132:133], v[68:69]
	v_pk_fma_f32 v[66:67], v[18:19], v[130:131], v[66:67]
	v_pk_fma_f32 v[64:65], v[16:17], v[128:129], v[64:65]
	s_add_u32 s16, s18, 0x140000
	s_addc_u32 s17, s19, 0
	global_store_dwordx4 v150, v[76:79], s[16:17]
	global_store_dwordx4 v150, v[72:75], s[16:17] offset:64
	global_store_dwordx4 v150, v[68:71], s[16:17] offset:512
	global_store_dwordx4 v150, v[64:67], s[16:17] offset:576
	s_waitcnt vmcnt(8)
	v_pk_fma_f32 v[62:63], v[14:15], v[142:143], v[62:63]
	v_pk_fma_f32 v[60:61], v[12:13], v[140:141], v[60:61]
	v_pk_fma_f32 v[58:59], v[10:11], v[138:139], v[58:59]
	v_pk_fma_f32 v[56:57], v[8:9], v[136:137], v[56:57]
	v_pk_fma_f32 v[54:55], v[6:7], v[134:135], v[54:55]
	v_pk_fma_f32 v[52:53], v[4:5], v[132:133], v[52:53]
	v_pk_fma_f32 v[50:51], v[2:3], v[130:131], v[50:51]
	v_pk_fma_f32 v[48:49], v[0:1], v[128:129], v[48:49]
	s_add_u32 s16, s18, 0x160000
	s_addc_u32 s17, s19, 0
	global_store_dwordx4 v150, v[60:63], s[16:17]
	global_store_dwordx4 v150, v[56:59], s[16:17] offset:64
	global_store_dwordx4 v150, v[52:55], s[16:17] offset:512
	global_store_dwordx4 v150, v[48:51], s[16:17] offset:576
	s_mov_b64 s[16:17], s[14:15]
	s_mov_b64 s[18:19], s[0:1]
	s_cbranch_vccz .LBB0_273
	s_waitcnt vmcnt(0)
	s_cmpk_gt_u32 s27, 0xff
	s_cbranch_scc1 .LBB0_288
	s_barrier

.LBB0_313:
	s_ashr_i32 s5, s4, 31
	s_lshl_b64 s[12:13], s[4:5], 20
	s_add_u32 s12, s27, s12
	s_addc_u32 s13, s28, s13
	s_and_b64 s[14:15], s[22:23], exec
	s_cselect_b32 s5, s13, s19
	s_cselect_b32 s42, s12, s18
	s_ashr_i32 s9, s8, 31
	s_lshl_b64 s[14:15], s[8:9], 20
	s_add_u32 s14, s24, s14
	s_addc_u32 s15, s25, s15
	s_and_b64 s[22:23], s[22:23], exec
	s_cselect_b32 s9, s15, s21
	s_cselect_b32 s43, s14, s20
	s_add_u32 s18, s18, 0x80080
	s_addc_u32 s19, s19, 0
	s_add_u32 s44, s20, 0x100
	v_mov_b32_e32 v0, 0
	s_addc_u32 s45, s21, 0
	s_mov_b32 s46, -2
	v_mov_b32_e32 v1, v0
	v_mov_b32_e32 v2, v0
	v_mov_b32_e32 v3, v0
	v_mov_b32_e32 v8, v0
	v_mov_b32_e32 v9, v0
	v_mov_b32_e32 v10, v0
	v_mov_b32_e32 v11, v0
	v_mov_b32_e32 v16, v0
	v_mov_b32_e32 v17, v0
	v_mov_b32_e32 v18, v0
	v_mov_b32_e32 v19, v0
	v_mov_b32_e32 v24, v0
	v_mov_b32_e32 v25, v0
	v_mov_b32_e32 v26, v0
	v_mov_b32_e32 v27, v0
	v_mov_b32_e32 v32, v0
	v_mov_b32_e32 v33, v0
	v_mov_b32_e32 v34, v0
	v_mov_b32_e32 v35, v0
	v_mov_b32_e32 v40, v0
	v_mov_b32_e32 v41, v0
	v_mov_b32_e32 v42, v0
	v_mov_b32_e32 v43, v0
	v_mov_b32_e32 v48, v0
	v_mov_b32_e32 v49, v0
	v_mov_b32_e32 v50, v0
	v_mov_b32_e32 v51, v0
	v_mov_b32_e32 v56, v0
	v_mov_b32_e32 v57, v0
	v_mov_b32_e32 v58, v0
	v_mov_b32_e32 v59, v0
	v_mov_b32_e32 v4, v0
	v_mov_b32_e32 v5, v0
	v_mov_b32_e32 v6, v0
	v_mov_b32_e32 v7, v0
	v_mov_b32_e32 v12, v0
	v_mov_b32_e32 v13, v0
	v_mov_b32_e32 v14, v0
	v_mov_b32_e32 v15, v0
	v_mov_b32_e32 v20, v0
	v_mov_b32_e32 v21, v0
	v_mov_b32_e32 v22, v0
	v_mov_b32_e32 v23, v0
	v_mov_b32_e32 v28, v0
	v_mov_b32_e32 v29, v0
	v_mov_b32_e32 v30, v0
	v_mov_b32_e32 v31, v0
	v_mov_b32_e32 v36, v0
	v_mov_b32_e32 v37, v0
	v_mov_b32_e32 v38, v0
	v_mov_b32_e32 v39, v0
	v_mov_b32_e32 v44, v0
	v_mov_b32_e32 v45, v0
	v_mov_b32_e32 v46, v0
	v_mov_b32_e32 v47, v0
	v_mov_b32_e32 v52, v0
	v_mov_b32_e32 v53, v0
	v_mov_b32_e32 v54, v0
	v_mov_b32_e32 v55, v0
	v_mov_b32_e32 v60, v0
	v_mov_b32_e32 v61, v0
	v_mov_b32_e32 v62, v0
	v_mov_b32_e32 v63, v0
	v_mov_b32_e32 v64, v0
	v_mov_b32_e32 v65, v0
	v_mov_b32_e32 v66, v0
	v_mov_b32_e32 v67, v0
	v_mov_b32_e32 v72, v0
	v_mov_b32_e32 v73, v0
	v_mov_b32_e32 v74, v0
	v_mov_b32_e32 v75, v0
	v_mov_b32_e32 v80, v0
	v_mov_b32_e32 v81, v0
	v_mov_b32_e32 v82, v0
	v_mov_b32_e32 v83, v0
	v_mov_b32_e32 v88, v0
	v_mov_b32_e32 v89, v0
	v_mov_b32_e32 v90, v0
	v_mov_b32_e32 v91, v0
	v_mov_b32_e32 v96, v0
	v_mov_b32_e32 v97, v0
	v_mov_b32_e32 v98, v0
	v_mov_b32_e32 v99, v0
	v_mov_b32_e32 v104, v0
	v_mov_b32_e32 v105, v0
	v_mov_b32_e32 v106, v0
	v_mov_b32_e32 v107, v0
	v_mov_b32_e32 v112, v0
	v_mov_b32_e32 v113, v0
	v_mov_b32_e32 v114, v0
	v_mov_b32_e32 v115, v0
	v_mov_b32_e32 v120, v0
	v_mov_b32_e32 v121, v0
	v_mov_b32_e32 v122, v0
	v_mov_b32_e32 v123, v0
	v_mov_b32_e32 v68, v0
	v_mov_b32_e32 v69, v0
	v_mov_b32_e32 v70, v0
	v_mov_b32_e32 v71, v0
	v_mov_b32_e32 v76, v0
	v_mov_b32_e32 v77, v0
	v_mov_b32_e32 v78, v0
	v_mov_b32_e32 v79, v0
	v_mov_b32_e32 v84, v0
	v_mov_b32_e32 v85, v0
	v_mov_b32_e32 v86, v0
	v_mov_b32_e32 v87, v0
	v_mov_b32_e32 v92, v0
	v_mov_b32_e32 v93, v0
	v_mov_b32_e32 v94, v0
	v_mov_b32_e32 v95, v0
	v_mov_b32_e32 v100, v0
	v_mov_b32_e32 v101, v0
	v_mov_b32_e32 v102, v0
	v_mov_b32_e32 v103, v0
	v_mov_b32_e32 v108, v0
	v_mov_b32_e32 v109, v0
	v_mov_b32_e32 v110, v0
	v_mov_b32_e32 v111, v0
	v_mov_b32_e32 v116, v0
	v_mov_b32_e32 v117, v0
	v_mov_b32_e32 v118, v0
	v_mov_b32_e32 v119, v0
	v_mov_b32_e32 v124, v0
	v_mov_b32_e32 v125, v0
	v_mov_b32_e32 v126, v0
	v_mov_b32_e32 v127, v0
	s_mov_b64 s[52:53], 0x80
	v_add_u32_e32 v156, 0x10000, v142
	ds_read_b128 v[144:147], v156
	ds_read_b128 v[148:151], v156 offset:1024
	ds_read_b128 v[152:155], v156 offset:2048
	ds_read_b128 v[156:159], v156 offset:3072
.LBB0_314:
	s_add_u32 s20, s18, 0xfff80080
	s_addc_u32 s21, s19, -1
	s_add_i32 s47, 0, 0x10000
	s_cmp_eq_u32 s46, 28
	s_cselect_b32 s23, s5, s21
	s_cselect_b32 s22, s42, s20
	s_cselect_b32 s21, s9, s45
	s_cselect_b32 s20, s43, s44
	v_lshl_add_u64 v[196:197], s[18:19], 0, v[136:137]
	s_add_i32 m0, s17, 0xc000
	ds_read_b128 v[160:163], v143
	ds_read_b128 v[164:167], v143 offset:1024
	ds_read_b128 v[168:171], v143 offset:2048
	ds_read_b128 v[172:175], v143 offset:3072
	ds_read_b128 v[176:179], v143 offset:4096
	ds_read_b128 v[180:183], v143 offset:5120
	ds_read_b128 v[188:191], v143 offset:6144
	ds_read_b128 v[192:195], v143 offset:7168
	global_load_lds_dwordx4 v[196:197], off
	v_lshl_add_u64 v[196:197], s[18:19], 0, v[138:139]
	s_add_i32 m0, s17, 0xe000
	s_nop 0
	global_load_lds_dwordx4 v[196:197], off
	s_waitcnt lgkmcnt(8)
	s_setprio 1
	s_barrier
	s_waitcnt lgkmcnt(0)
	v_mfma_f32_16x16x32_bf16 v[124:127], v[144:147], v[160:163], v[124:127]
	v_mfma_f32_16x16x32_bf16 v[116:119], v[152:155], v[160:163], v[116:119]
	v_mfma_f32_16x16x32_bf16 v[108:111], v[144:147], v[168:171], v[108:111]
	v_mfma_f32_16x16x32_bf16 v[100:103], v[152:155], v[168:171], v[100:103]
	v_mfma_f32_16x16x32_bf16 v[92:95], v[144:147], v[176:179], v[92:95]
	v_mfma_f32_16x16x32_bf16 v[84:87], v[152:155], v[176:179], v[84:87]
	v_mfma_f32_16x16x32_bf16 v[76:79], v[144:147], v[188:191], v[76:79]
	v_mfma_f32_16x16x32_bf16 v[68:71], v[152:155], v[188:191], v[68:71]
	v_mfma_f32_16x16x32_bf16 v[124:127], v[148:151], v[164:167], v[124:127]
	v_mfma_f32_16x16x32_bf16 v[116:119], v[156:159], v[164:167], v[116:119]
	v_mfma_f32_16x16x32_bf16 v[108:111], v[148:151], v[172:175], v[108:111]
	v_mfma_f32_16x16x32_bf16 v[100:103], v[156:159], v[172:175], v[100:103]
	v_mfma_f32_16x16x32_bf16 v[92:95], v[148:151], v[180:183], v[92:95]
	v_mfma_f32_16x16x32_bf16 v[84:87], v[156:159], v[180:183], v[84:87]
	v_mfma_f32_16x16x32_bf16 v[76:79], v[148:151], v[192:195], v[76:79]
	v_mfma_f32_16x16x32_bf16 v[68:71], v[156:159], v[192:195], v[68:71]
	s_barrier
	s_setprio 0
	s_add_i32 s50, 0, 0x14000
	s_add_i32 s47, s47, s31
	v_add_u32_e32 v184, s50, v142
	v_lshl_add_u64 v[196:197], s[20:21], 0, v[130:131]
	s_mov_b32 m0, s47
	ds_read_b128 v[202:205], v184
	ds_read_b128 v[206:209], v184 offset:1024
	ds_read_b128 v[210:213], v184 offset:2048
	ds_read_b128 v[214:217], v184 offset:3072
	global_load_lds_dwordx4 v[196:197], off
	v_lshl_add_u64 v[218:219], s[20:21], 0, v[134:135]
	s_add_i32 m0, s47, 0x2000
	s_nop 0
	global_load_lds_dwordx4 v[218:219], off
	s_setprio 1
	s_barrier
	s_waitcnt lgkmcnt(0)
	v_mfma_f32_16x16x32_bf16 v[120:123], v[202:205], v[160:163], v[120:123]
	v_mfma_f32_16x16x32_bf16 v[112:115], v[210:213], v[160:163], v[112:115]
	v_mfma_f32_16x16x32_bf16 v[104:107], v[202:205], v[168:171], v[104:107]
	v_mfma_f32_16x16x32_bf16 v[96:99], v[210:213], v[168:171], v[96:99]
	v_mfma_f32_16x16x32_bf16 v[88:91], v[202:205], v[176:179], v[88:91]
	v_mfma_f32_16x16x32_bf16 v[80:83], v[210:213], v[176:179], v[80:83]
	v_mfma_f32_16x16x32_bf16 v[72:75], v[202:205], v[188:191], v[72:75]
	v_mfma_f32_16x16x32_bf16 v[64:67], v[210:213], v[188:191], v[64:67]
	v_mfma_f32_16x16x32_bf16 v[120:123], v[206:209], v[164:167], v[120:123]
	v_mfma_f32_16x16x32_bf16 v[112:115], v[214:217], v[164:167], v[112:115]
	v_mfma_f32_16x16x32_bf16 v[104:107], v[206:209], v[172:175], v[104:107]
	v_mfma_f32_16x16x32_bf16 v[96:99], v[214:217], v[172:175], v[96:99]
	v_mfma_f32_16x16x32_bf16 v[88:91], v[206:209], v[180:183], v[88:91]
	v_mfma_f32_16x16x32_bf16 v[80:83], v[214:217], v[180:183], v[80:83]
	v_mfma_f32_16x16x32_bf16 v[72:75], v[206:209], v[192:195], v[72:75]
	v_mfma_f32_16x16x32_bf16 v[64:67], v[214:217], v[192:195], v[64:67]
	s_barrier
	s_setprio 0
	s_mov_b32 m0, s17
	v_lshl_add_u64 v[220:221], s[22:23], 0, v[128:129]
	ds_read_b128 v[160:163], v143 offset:16384
	ds_read_b128 v[164:167], v143 offset:17408
	ds_read_b128 v[168:171], v143 offset:18432
	ds_read_b128 v[172:175], v143 offset:19456
	ds_read_b128 v[176:179], v143 offset:20480
	ds_read_b128 v[180:183], v143 offset:21504
	ds_read_b128 v[188:191], v143 offset:22528
	ds_read_b128 v[192:195], v143 offset:23552
	global_load_lds_dwordx4 v[220:221], off
	v_lshl_add_u64 v[222:223], s[22:23], 0, v[132:133]
	s_mov_b32 m0, s33
	s_nop 0
	global_load_lds_dwordx4 v[222:223], off
	s_setprio 1
	s_waitcnt vmcnt(10)
	s_barrier
	s_waitcnt lgkmcnt(0)
	v_mfma_f32_16x16x32_bf16 v[60:63], v[144:147], v[160:163], v[60:63]
	v_mfma_f32_16x16x32_bf16 v[52:55], v[152:155], v[160:163], v[52:55]
	v_mfma_f32_16x16x32_bf16 v[44:47], v[144:147], v[168:171], v[44:47]
	v_mfma_f32_16x16x32_bf16 v[36:39], v[152:155], v[168:171], v[36:39]
	v_mfma_f32_16x16x32_bf16 v[28:31], v[144:147], v[176:179], v[28:31]
	v_mfma_f32_16x16x32_bf16 v[20:23], v[152:155], v[176:179], v[20:23]
	v_mfma_f32_16x16x32_bf16 v[12:15], v[144:147], v[188:191], v[12:15]
	v_mfma_f32_16x16x32_bf16 v[4:7], v[152:155], v[188:191], v[4:7]
	v_mfma_f32_16x16x32_bf16 v[60:63], v[148:151], v[164:167], v[60:63]
	v_mfma_f32_16x16x32_bf16 v[52:55], v[156:159], v[164:167], v[52:55]
	v_mfma_f32_16x16x32_bf16 v[44:47], v[148:151], v[172:175], v[44:47]
	v_mfma_f32_16x16x32_bf16 v[36:39], v[156:159], v[172:175], v[36:39]
	v_mfma_f32_16x16x32_bf16 v[28:31], v[148:151], v[180:183], v[28:31]
	v_mfma_f32_16x16x32_bf16 v[20:23], v[156:159], v[180:183], v[20:23]
	v_mfma_f32_16x16x32_bf16 v[12:15], v[148:151], v[192:195], v[12:15]
	v_mfma_f32_16x16x32_bf16 v[4:7], v[156:159], v[192:195], v[4:7]
	s_barrier
	s_setprio 0
	v_add_u32_e32 v156, 0x18000, v142
	ds_read_b128 v[144:147], v156
	ds_read_b128 v[148:151], v156 offset:1024
	ds_read_b128 v[152:155], v156 offset:2048
	ds_read_b128 v[156:159], v156 offset:3072
	s_add_u32 s48, s20, 0x80000
	s_addc_u32 s49, s21, 0
	s_add_i32 s47, s50, s31
	v_lshl_add_u64 v[246:247], s[48:49], 0, v[130:131]
	s_mov_b32 m0, s47
	s_nop 0
	global_load_lds_dwordx4 v[246:247], off
	v_lshl_add_u64 v[248:249], s[48:49], 0, v[134:135]
	s_add_i32 m0, s47, 0x2000
	s_nop 0
	global_load_lds_dwordx4 v[248:249], off
	s_waitcnt vmcnt(6)
	s_setprio 1
	s_barrier
	v_mfma_f32_16x16x32_bf16 v[56:59], v[202:205], v[160:163], v[56:59]
	v_mfma_f32_16x16x32_bf16 v[48:51], v[210:213], v[160:163], v[48:51]
	v_mfma_f32_16x16x32_bf16 v[40:43], v[202:205], v[168:171], v[40:43]
	v_mfma_f32_16x16x32_bf16 v[32:35], v[210:213], v[168:171], v[32:35]
	v_mfma_f32_16x16x32_bf16 v[24:27], v[202:205], v[176:179], v[24:27]
	v_mfma_f32_16x16x32_bf16 v[16:19], v[210:213], v[176:179], v[16:19]
	v_mfma_f32_16x16x32_bf16 v[8:11], v[202:205], v[188:191], v[8:11]
	v_mfma_f32_16x16x32_bf16 v[0:3], v[210:213], v[188:191], v[0:3]
	v_mfma_f32_16x16x32_bf16 v[56:59], v[206:209], v[164:167], v[56:59]
	v_mfma_f32_16x16x32_bf16 v[48:51], v[214:217], v[164:167], v[48:51]
	v_mfma_f32_16x16x32_bf16 v[40:43], v[206:209], v[172:175], v[40:43]
	v_mfma_f32_16x16x32_bf16 v[32:35], v[214:217], v[172:175], v[32:35]
	v_mfma_f32_16x16x32_bf16 v[24:27], v[206:209], v[180:183], v[24:27]
	v_mfma_f32_16x16x32_bf16 v[16:19], v[214:217], v[180:183], v[16:19]
	v_mfma_f32_16x16x32_bf16 v[8:11], v[206:209], v[192:195], v[8:11]
	v_mfma_f32_16x16x32_bf16 v[0:3], v[214:217], v[192:195], v[0:3]
	s_barrier
	s_setprio 0
	s_add_i32 s47, 0, 0x18000
	s_add_u32 s22, s22, 0x80000
	s_addc_u32 s23, s23, 0
	s_mov_b32 m0, s34
	v_lshl_add_u64 v[202:203], s[22:23], 0, v[128:129]
	ds_read_b128 v[160:163], v143 offset:32768
	ds_read_b128 v[164:167], v143 offset:33792
	ds_read_b128 v[168:171], v143 offset:34816
	ds_read_b128 v[172:175], v143 offset:35840
	ds_read_b128 v[176:179], v143 offset:36864
	ds_read_b128 v[180:183], v143 offset:37888
	ds_read_b128 v[188:191], v143 offset:38912
	ds_read_b128 v[192:195], v143 offset:39936
	global_load_lds_dwordx4 v[202:203], off
	v_lshl_add_u64 v[202:203], s[22:23], 0, v[132:133]
	s_mov_b32 m0, s35
	s_nop 0
	global_load_lds_dwordx4 v[202:203], off
	s_waitcnt lgkmcnt(8)
	s_setprio 1
	s_barrier
	s_waitcnt lgkmcnt(0)
	v_mfma_f32_16x16x32_bf16 v[124:127], v[144:147], v[160:163], v[124:127]
	v_mfma_f32_16x16x32_bf16 v[116:119], v[152:155], v[160:163], v[116:119]
	v_mfma_f32_16x16x32_bf16 v[108:111], v[144:147], v[168:171], v[108:111]
	v_mfma_f32_16x16x32_bf16 v[100:103], v[152:155], v[168:171], v[100:103]
	v_mfma_f32_16x16x32_bf16 v[92:95], v[144:147], v[176:179], v[92:95]
	v_mfma_f32_16x16x32_bf16 v[84:87], v[152:155], v[176:179], v[84:87]
	v_mfma_f32_16x16x32_bf16 v[76:79], v[144:147], v[188:191], v[76:79]
	v_mfma_f32_16x16x32_bf16 v[68:71], v[152:155], v[188:191], v[68:71]
	v_mfma_f32_16x16x32_bf16 v[124:127], v[148:151], v[164:167], v[124:127]
	v_mfma_f32_16x16x32_bf16 v[116:119], v[156:159], v[164:167], v[116:119]
	v_mfma_f32_16x16x32_bf16 v[108:111], v[148:151], v[172:175], v[108:111]
	v_mfma_f32_16x16x32_bf16 v[100:103], v[156:159], v[172:175], v[100:103]
	v_mfma_f32_16x16x32_bf16 v[92:95], v[148:151], v[180:183], v[92:95]
	v_mfma_f32_16x16x32_bf16 v[84:87], v[156:159], v[180:183], v[84:87]
	v_mfma_f32_16x16x32_bf16 v[76:79], v[148:151], v[192:195], v[76:79]
	v_mfma_f32_16x16x32_bf16 v[68:71], v[156:159], v[192:195], v[68:71]
	s_barrier
	s_setprio 0
	s_add_i32 s22, 0, 0x1c000
	s_add_i32 s23, s47, s31
	v_add_u32_e32 v184, s22, v142
	v_lshl_add_u64 v[196:197], v[196:197], 0, s[52:53]
	s_mov_b32 m0, s23
	ds_read_b128 v[202:205], v184
	ds_read_b128 v[206:209], v184 offset:1024
	ds_read_b128 v[210:213], v184 offset:2048
	ds_read_b128 v[214:217], v184 offset:3072
	global_load_lds_dwordx4 v[196:197], off
	v_lshl_add_u64 v[196:197], v[218:219], 0, s[52:53]
	s_add_i32 m0, s23, 0x2000
	s_nop 0
	global_load_lds_dwordx4 v[196:197], off
	s_setprio 1
	s_barrier
	s_waitcnt lgkmcnt(0)
	v_mfma_f32_16x16x32_bf16 v[120:123], v[202:205], v[160:163], v[120:123]
	v_mfma_f32_16x16x32_bf16 v[112:115], v[210:213], v[160:163], v[112:115]
	v_mfma_f32_16x16x32_bf16 v[104:107], v[202:205], v[168:171], v[104:107]
	v_mfma_f32_16x16x32_bf16 v[96:99], v[210:213], v[168:171], v[96:99]
	v_mfma_f32_16x16x32_bf16 v[88:91], v[202:205], v[176:179], v[88:91]
	v_mfma_f32_16x16x32_bf16 v[80:83], v[210:213], v[176:179], v[80:83]
	v_mfma_f32_16x16x32_bf16 v[72:75], v[202:205], v[188:191], v[72:75]
	v_mfma_f32_16x16x32_bf16 v[64:67], v[210:213], v[188:191], v[64:67]
	v_mfma_f32_16x16x32_bf16 v[120:123], v[206:209], v[164:167], v[120:123]
	v_mfma_f32_16x16x32_bf16 v[112:115], v[214:217], v[164:167], v[112:115]
	v_mfma_f32_16x16x32_bf16 v[104:107], v[206:209], v[172:175], v[104:107]
	v_mfma_f32_16x16x32_bf16 v[96:99], v[214:217], v[172:175], v[96:99]
	v_mfma_f32_16x16x32_bf16 v[88:91], v[206:209], v[180:183], v[88:91]
	v_mfma_f32_16x16x32_bf16 v[80:83], v[214:217], v[180:183], v[80:83]
	v_mfma_f32_16x16x32_bf16 v[72:75], v[206:209], v[192:195], v[72:75]
	v_mfma_f32_16x16x32_bf16 v[64:67], v[214:217], v[192:195], v[64:67]
	s_barrier
	s_setprio 0
	s_mov_b32 m0, s38
	v_lshl_add_u64 v[196:197], v[220:221], 0, s[52:53]
	ds_read_b128 v[160:163], v143 offset:49152
	ds_read_b128 v[164:167], v143 offset:50176
	ds_read_b128 v[168:171], v143 offset:51200
	ds_read_b128 v[172:175], v143 offset:52224
	ds_read_b128 v[176:179], v143 offset:53248
	ds_read_b128 v[180:183], v143 offset:54272
	ds_read_b128 v[188:191], v143 offset:55296
	ds_read_b128 v[192:195], v143 offset:56320
	global_load_lds_dwordx4 v[196:197], off
	v_lshl_add_u64 v[196:197], v[222:223], 0, s[52:53]
	s_mov_b32 m0, s39
	s_nop 0
	global_load_lds_dwordx4 v[196:197], off
	s_setprio 1
	s_waitcnt vmcnt(10)
	s_barrier
	s_waitcnt lgkmcnt(0)
	v_mfma_f32_16x16x32_bf16 v[60:63], v[144:147], v[160:163], v[60:63]
	v_mfma_f32_16x16x32_bf16 v[52:55], v[152:155], v[160:163], v[52:55]
	v_mfma_f32_16x16x32_bf16 v[44:47], v[144:147], v[168:171], v[44:47]
	v_mfma_f32_16x16x32_bf16 v[36:39], v[152:155], v[168:171], v[36:39]
	v_mfma_f32_16x16x32_bf16 v[28:31], v[144:147], v[176:179], v[28:31]
	v_mfma_f32_16x16x32_bf16 v[20:23], v[152:155], v[176:179], v[20:23]
	v_mfma_f32_16x16x32_bf16 v[12:15], v[144:147], v[188:191], v[12:15]
	v_mfma_f32_16x16x32_bf16 v[4:7], v[152:155], v[188:191], v[4:7]
	v_mfma_f32_16x16x32_bf16 v[60:63], v[148:151], v[164:167], v[60:63]
	v_mfma_f32_16x16x32_bf16 v[52:55], v[156:159], v[164:167], v[52:55]
	v_mfma_f32_16x16x32_bf16 v[44:47], v[148:151], v[172:175], v[44:47]
	v_mfma_f32_16x16x32_bf16 v[36:39], v[156:159], v[172:175], v[36:39]
	v_mfma_f32_16x16x32_bf16 v[28:31], v[148:151], v[180:183], v[28:31]
	v_mfma_f32_16x16x32_bf16 v[20:23], v[156:159], v[180:183], v[20:23]
	v_mfma_f32_16x16x32_bf16 v[12:15], v[148:151], v[192:195], v[12:15]
	v_mfma_f32_16x16x32_bf16 v[4:7], v[156:159], v[192:195], v[4:7]
	s_barrier
	s_setprio 0
	v_add_u32_e32 v156, 0x10000, v142
	ds_read_b128 v[144:147], v156
	ds_read_b128 v[148:151], v156 offset:1024
	ds_read_b128 v[152:155], v156 offset:2048
	ds_read_b128 v[156:159], v156 offset:3072
	s_add_u32 s20, s20, 0x80080
	s_addc_u32 s21, s21, 0
	s_add_i32 s22, s22, s31
	v_lshl_add_u64 v[250:251], s[20:21], 0, v[130:131]
	s_mov_b32 m0, s22
	s_nop 0
	global_load_lds_dwordx4 v[250:251], off
	v_lshl_add_u64 v[252:253], s[20:21], 0, v[134:135]
	s_add_i32 m0, s22, 0x2000
	s_nop 0
	global_load_lds_dwordx4 v[252:253], off
	s_waitcnt vmcnt(6)
	s_setprio 1
	s_barrier
	v_mfma_f32_16x16x32_bf16 v[56:59], v[202:205], v[160:163], v[56:59]
	v_mfma_f32_16x16x32_bf16 v[48:51], v[210:213], v[160:163], v[48:51]
	v_mfma_f32_16x16x32_bf16 v[40:43], v[202:205], v[168:171], v[40:43]
	v_mfma_f32_16x16x32_bf16 v[32:35], v[210:213], v[168:171], v[32:35]
	v_mfma_f32_16x16x32_bf16 v[24:27], v[202:205], v[176:179], v[24:27]
	v_mfma_f32_16x16x32_bf16 v[16:19], v[210:213], v[176:179], v[16:19]
	v_mfma_f32_16x16x32_bf16 v[8:11], v[202:205], v[188:191], v[8:11]
	v_mfma_f32_16x16x32_bf16 v[0:3], v[210:213], v[188:191], v[0:3]
	v_mfma_f32_16x16x32_bf16 v[56:59], v[206:209], v[164:167], v[56:59]
	v_mfma_f32_16x16x32_bf16 v[48:51], v[214:217], v[164:167], v[48:51]
	v_mfma_f32_16x16x32_bf16 v[40:43], v[206:209], v[172:175], v[40:43]
	v_mfma_f32_16x16x32_bf16 v[32:35], v[214:217], v[172:175], v[32:35]
	v_mfma_f32_16x16x32_bf16 v[24:27], v[206:209], v[180:183], v[24:27]
	v_mfma_f32_16x16x32_bf16 v[16:19], v[214:217], v[180:183], v[16:19]
	v_mfma_f32_16x16x32_bf16 v[8:11], v[206:209], v[192:195], v[8:11]
	v_mfma_f32_16x16x32_bf16 v[0:3], v[214:217], v[192:195], v[0:3]
	s_barrier
	s_setprio 0
	s_add_i32 s46, s46, 2
	s_add_u32 s18, s18, 0x100
	s_addc_u32 s19, s19, 0
	s_add_u32 s44, s44, 0x100
	s_addc_u32 s45, s45, 0
	s_cmp_gt_u32 s46, 29
	s_cbranch_scc0 .LBB0_314
	s_waitcnt lgkmcnt(0)
	v_mov_b32_e32 v144, v140
	v_mov_b32_e32 v145, v141
	s_lshl_b32 s5, s16, 8
	s_add_i32 s5, s5, s36
	v_add_u32_e32 v144, s5, v144
	s_lshl_b32 s5, s41, 7
	s_or_b32 s5, s5, s37
	v_lshl_add_u32 v145, v145, 3, s5
	v_ashrrev_i32_e32 v146, 6, v145
	v_and_b32_e32 v152, 56, v145
	v_mul_f32_e32 v145, 0x3d372713, v124
	v_fma_f32 v145, v124, v145, 1.0
	v_mul_f32_e32 v145, v124, v145
	v_mul_f32_e32 v145, 0xc0135761, v145
	v_exp_f32_e32 v148, v145
	v_mul_f32_e32 v145, 0xbfb8aa3b, v120
	v_exp_f32_e32 v149, v145
	v_mul_f32_e32 v145, 0x3d372713, v125
	v_fma_f32 v145, v125, v145, 1.0
	v_mul_f32_e32 v145, v125, v145
	v_mul_f32_e32 v145, 0xc0135761, v145
	v_exp_f32_e32 v150, v145
	v_mul_f32_e32 v145, 0xbfb8aa3b, v121
	v_exp_f32_e32 v151, v145
	v_pk_add_f32 v[148:149], v[148:149], 1.0 op_sel_hi:[1,0]
	v_mul_f32_e32 v120, v124, v120
	v_mul_f32_e32 v145, v148, v149
	v_pk_add_f32 v[148:149], v[150:151], 1.0 op_sel_hi:[1,0]
	v_rcp_f32_e32 v145, v145
	v_mul_f32_e32 v148, v148, v149
	v_rcp_f32_e32 v148, v148
	v_mul_f32_e32 v124, 0x3d372713, v127
	v_mul_f32_e32 v149, v120, v145
	v_mul_f32_e32 v120, v125, v121
	v_mul_f32_e32 v148, v120, v148
	v_mul_f32_e32 v120, 0x3d372713, v126
	v_fma_f32 v120, v126, v120, 1.0
	v_mul_f32_e32 v120, v126, v120
	v_mul_f32_e32 v120, 0xc0135761, v120
	v_mul_f32_e32 v121, 0xbfb8aa3b, v122
	v_fma_f32 v124, v127, v124, 1.0
	v_exp_f32_e32 v120, v120
	v_exp_f32_e32 v121, v121
	v_mul_f32_e32 v124, v127, v124
	v_mul_f32_e32 v124, 0xc0135761, v124
	v_mul_f32_e32 v125, 0xbfb8aa3b, v123
	v_exp_f32_e32 v124, v124
	v_exp_f32_e32 v125, v125
	v_pk_add_f32 v[120:121], v[120:121], 1.0 op_sel_hi:[1,0]
	v_ashrrev_i32_e32 v147, 31, v146
	v_mul_f32_e32 v120, v120, v121
	v_rcp_f32_e32 v145, v120
	v_pk_add_f32 v[120:121], v[124:125], 1.0 op_sel_hi:[1,0]
	v_lshlrev_b64 v[146:147], 22, v[146:147]
	v_mul_f32_e32 v120, v120, v121
	v_rcp_f32_e32 v120, v120
	v_mul_f32_e32 v121, v126, v122
	v_mul_f32_e32 v124, v121, v145
	v_mul_f32_e32 v121, v127, v123
	v_mul_f32_e32 v125, v121, v120
	v_mul_f32_e32 v120, 0x3d372713, v116
	v_fma_f32 v120, v116, v120, 1.0
	v_mul_f32_e32 v120, v116, v120
	v_mul_f32_e32 v122, 0x3d372713, v117
	v_mul_f32_e32 v120, 0xc0135761, v120
	v_mul_f32_e32 v121, 0xbfb8aa3b, v112
	v_fma_f32 v122, v117, v122, 1.0
	v_exp_f32_e32 v120, v120
	v_exp_f32_e32 v121, v121
	v_mul_f32_e32 v122, v117, v122
	v_mul_f32_e32 v122, 0xc0135761, v122
	v_mul_f32_e32 v123, 0xbfb8aa3b, v113
	v_exp_f32_e32 v122, v122
	v_exp_f32_e32 v123, v123
	v_pk_add_f32 v[120:121], v[120:121], 1.0 op_sel_hi:[1,0]
	v_mul_f32_e32 v112, v116, v112
	v_mul_f32_e32 v120, v120, v121
	v_rcp_f32_e32 v126, v120
	v_pk_add_f32 v[120:121], v[122:123], 1.0 op_sel_hi:[1,0]
	v_mul_f32_e32 v116, 0x3d372713, v119
	v_mul_f32_e32 v120, v120, v121
	v_rcp_f32_e32 v120, v120
	v_mul_f32_e32 v121, v112, v126
	v_mul_f32_e32 v112, v117, v113
	v_mul_f32_e32 v113, 0xbfb8aa3b, v114
	v_mul_f32_e32 v120, v112, v120
	v_mul_f32_e32 v112, 0x3d372713, v118
	v_fma_f32 v112, v118, v112, 1.0
	v_mul_f32_e32 v112, v118, v112
	v_mul_f32_e32 v112, 0xc0135761, v112
	v_fma_f32 v116, v119, v116, 1.0
	v_exp_f32_e32 v112, v112
	v_exp_f32_e32 v113, v113
	v_mul_f32_e32 v116, v119, v116
	v_mul_f32_e32 v116, 0xc0135761, v116
	v_mul_f32_e32 v117, 0xbfb8aa3b, v115
	v_exp_f32_e32 v116, v116
	v_exp_f32_e32 v117, v117
	v_pk_add_f32 v[112:113], v[112:113], 1.0 op_sel_hi:[1,0]
	v_ashrrev_i32_e32 v145, 31, v144
	v_mul_f32_e32 v112, v112, v113
	v_rcp_f32_e32 v122, v112
	v_pk_add_f32 v[112:113], v[116:117], 1.0 op_sel_hi:[1,0]
	v_lshlrev_b32_e32 v184, 1, v152
	v_mul_f32_e32 v112, v112, v113
	v_rcp_f32_e32 v112, v112
	v_mul_f32_e32 v113, v118, v114
	v_mul_f32_e32 v114, v119, v115
	v_mul_f32_e32 v113, v113, v122
	v_mul_f32_e32 v112, v114, v112
	v_cvt_pk_bf16_f32 v114, v149, v148
	v_cvt_pk_bf16_f32 v115, v124, v125
	v_cvt_pk_bf16_f32 v116, v121, v120
	v_cvt_pk_bf16_f32 v117, v113, v112
	v_lshl_add_u64 v[112:113], s[0:1], 0, v[146:147]
	v_lshlrev_b64 v[118:119], 7, v[144:145]
	v_lshl_add_u64 v[112:113], v[112:113], 0, v[118:119]
	v_lshl_add_u64 v[112:113], v[112:113], 0, v[184:185]
	global_store_dwordx4 v[112:113], v[114:117], off
	s_movk_i32 s5, 0x1000
	s_mov_b32 s41, s8
	v_mul_f32_e32 v114, 0x3d372713, v108
	v_fma_f32 v114, v108, v114, 1.0
	v_mul_f32_e32 v114, v108, v114
	v_mul_f32_e32 v116, 0x3d372713, v109
	v_mul_f32_e32 v114, 0xc0135761, v114
	v_mul_f32_e32 v115, 0xbfb8aa3b, v104
	v_fma_f32 v116, v109, v116, 1.0
	v_exp_f32_e32 v114, v114
	v_exp_f32_e32 v115, v115
	v_mul_f32_e32 v116, v109, v116
	v_mul_f32_e32 v116, 0xc0135761, v116
	v_mul_f32_e32 v117, 0xbfb8aa3b, v105
	v_exp_f32_e32 v116, v116
	v_exp_f32_e32 v117, v117
	v_pk_add_f32 v[114:115], v[114:115], 1.0 op_sel_hi:[1,0]
	v_mul_f32_e32 v104, v108, v104
	v_mul_f32_e32 v114, v114, v115
	v_rcp_f32_e32 v118, v114
	v_pk_add_f32 v[114:115], v[116:117], 1.0 op_sel_hi:[1,0]
	v_mul_f32_e32 v108, 0x3d372713, v111
	v_mul_f32_e32 v114, v114, v115
	v_rcp_f32_e32 v114, v114
	v_mul_f32_e32 v115, v104, v118
	v_mul_f32_e32 v104, v109, v105
	v_mul_f32_e32 v105, 0xbfb8aa3b, v106
	v_mul_f32_e32 v114, v104, v114
	v_mul_f32_e32 v104, 0x3d372713, v110
	v_fma_f32 v104, v110, v104, 1.0
	v_mul_f32_e32 v104, v110, v104
	v_mul_f32_e32 v104, 0xc0135761, v104
	v_fma_f32 v108, v111, v108, 1.0
	v_exp_f32_e32 v104, v104
	v_exp_f32_e32 v105, v105
	v_mul_f32_e32 v108, v111, v108
	v_mul_f32_e32 v108, 0xc0135761, v108
	v_mul_f32_e32 v109, 0xbfb8aa3b, v107
	v_exp_f32_e32 v108, v108
	v_exp_f32_e32 v109, v109
	v_pk_add_f32 v[104:105], v[104:105], 1.0 op_sel_hi:[1,0]
	s_mov_b32 s16, s4
	v_mul_f32_e32 v104, v104, v105
	v_rcp_f32_e32 v116, v104
	v_pk_add_f32 v[104:105], v[108:109], 1.0 op_sel_hi:[1,0]
	s_mov_b64 s[20:21], s[14:15]
	v_mul_f32_e32 v104, v104, v105
	v_rcp_f32_e32 v104, v104
	v_mul_f32_e32 v105, v110, v106
	v_mul_f32_e32 v108, v105, v116
	v_mul_f32_e32 v105, v111, v107
	v_mul_f32_e32 v109, v105, v104
	v_mul_f32_e32 v104, 0x3d372713, v100
	v_fma_f32 v104, v100, v104, 1.0
	v_mul_f32_e32 v104, v100, v104
	v_mul_f32_e32 v106, 0x3d372713, v101
	v_mul_f32_e32 v104, 0xc0135761, v104
	v_mul_f32_e32 v105, 0xbfb8aa3b, v96
	v_fma_f32 v106, v101, v106, 1.0
	v_exp_f32_e32 v104, v104
	v_exp_f32_e32 v105, v105
	v_mul_f32_e32 v106, v101, v106
	v_mul_f32_e32 v106, 0xc0135761, v106
	v_mul_f32_e32 v107, 0xbfb8aa3b, v97
	v_exp_f32_e32 v106, v106
	v_exp_f32_e32 v107, v107
	v_pk_add_f32 v[104:105], v[104:105], 1.0 op_sel_hi:[1,0]
	v_mul_f32_e32 v96, v100, v96
	v_mul_f32_e32 v104, v104, v105
	v_rcp_f32_e32 v110, v104
	v_pk_add_f32 v[104:105], v[106:107], 1.0 op_sel_hi:[1,0]
	v_mul_f32_e32 v100, 0x3d372713, v103
	v_mul_f32_e32 v104, v104, v105
	v_rcp_f32_e32 v104, v104
	v_mul_f32_e32 v105, v96, v110
	v_mul_f32_e32 v96, v101, v97
	v_mul_f32_e32 v97, 0xbfb8aa3b, v98
	v_mul_f32_e32 v104, v96, v104
	v_mul_f32_e32 v96, 0x3d372713, v102
	v_fma_f32 v96, v102, v96, 1.0
	v_mul_f32_e32 v96, v102, v96
	v_mul_f32_e32 v96, 0xc0135761, v96
	v_fma_f32 v100, v103, v100, 1.0
	v_exp_f32_e32 v96, v96
	v_exp_f32_e32 v97, v97
	v_mul_f32_e32 v100, v103, v100
	v_mul_f32_e32 v100, 0xc0135761, v100
	v_mul_f32_e32 v101, 0xbfb8aa3b, v99
	v_exp_f32_e32 v100, v100
	v_exp_f32_e32 v101, v101
	v_pk_add_f32 v[96:97], v[96:97], 1.0 op_sel_hi:[1,0]
	s_mov_b64 s[18:19], s[12:13]
	v_mul_f32_e32 v96, v96, v97
	v_rcp_f32_e32 v106, v96
	v_pk_add_f32 v[96:97], v[100:101], 1.0 op_sel_hi:[1,0]
	s_nop 0
	v_mul_f32_e32 v96, v96, v97
	v_rcp_f32_e32 v96, v96
	v_mul_f32_e32 v97, v102, v98
	v_mul_f32_e32 v100, v97, v106
	v_mul_f32_e32 v97, v103, v99
	v_mul_f32_e32 v99, v97, v96
	v_cvt_pk_bf16_f32 v96, v115, v114
	v_cvt_pk_bf16_f32 v97, v108, v109
	v_cvt_pk_bf16_f32 v98, v105, v104
	v_cvt_pk_bf16_f32 v99, v100, v99
	global_store_dwordx4 v[112:113], v[96:99], off offset:2048
	s_nop 1
	v_mul_f32_e32 v96, 0x3d372713, v92
	v_fma_f32 v96, v92, v96, 1.0
	v_mul_f32_e32 v96, v92, v96
	v_mul_f32_e32 v98, 0x3d372713, v93
	v_mul_f32_e32 v96, 0xc0135761, v96
	v_mul_f32_e32 v97, 0xbfb8aa3b, v88
	v_fma_f32 v98, v93, v98, 1.0
	v_exp_f32_e32 v96, v96
	v_exp_f32_e32 v97, v97
	v_mul_f32_e32 v98, v93, v98
	v_mul_f32_e32 v98, 0xc0135761, v98
	v_mul_f32_e32 v99, 0xbfb8aa3b, v89
	v_exp_f32_e32 v98, v98
	v_exp_f32_e32 v99, v99
	v_pk_add_f32 v[96:97], v[96:97], 1.0 op_sel_hi:[1,0]
	v_mul_f32_e32 v88, v92, v88
	v_mul_f32_e32 v96, v96, v97
	v_rcp_f32_e32 v100, v96
	v_pk_add_f32 v[96:97], v[98:99], 1.0 op_sel_hi:[1,0]
	v_mul_f32_e32 v92, 0x3d372713, v95
	v_mul_f32_e32 v96, v96, v97
	v_rcp_f32_e32 v96, v96
	v_mul_f32_e32 v97, v88, v100
	v_mul_f32_e32 v88, v93, v89
	v_mul_f32_e32 v89, 0xbfb8aa3b, v90
	v_mul_f32_e32 v96, v88, v96
	v_mul_f32_e32 v88, 0x3d372713, v94
	v_fma_f32 v88, v94, v88, 1.0
	v_mul_f32_e32 v88, v94, v88
	v_mul_f32_e32 v88, 0xc0135761, v88
	v_fma_f32 v92, v95, v92, 1.0
	v_exp_f32_e32 v88, v88
	v_exp_f32_e32 v89, v89
	v_mul_f32_e32 v92, v95, v92
	v_mul_f32_e32 v92, 0xc0135761, v92
	v_mul_f32_e32 v93, 0xbfb8aa3b, v91
	v_exp_f32_e32 v92, v92
	v_exp_f32_e32 v93, v93
	v_pk_add_f32 v[88:89], v[88:89], 1.0 op_sel_hi:[1,0]
	s_nop 0
	v_mul_f32_e32 v88, v88, v89
	v_rcp_f32_e32 v98, v88
	v_pk_add_f32 v[88:89], v[92:93], 1.0 op_sel_hi:[1,0]
	s_nop 0
	v_mul_f32_e32 v88, v88, v89
	v_rcp_f32_e32 v88, v88
	v_mul_f32_e32 v89, v94, v90
	v_mul_f32_e32 v92, v89, v98
	v_mul_f32_e32 v89, v95, v91
	v_mul_f32_e32 v93, v89, v88
	v_mul_f32_e32 v88, 0x3d372713, v84
	v_fma_f32 v88, v84, v88, 1.0
	v_mul_f32_e32 v88, v84, v88
	v_mul_f32_e32 v90, 0x3d372713, v85
	v_mul_f32_e32 v88, 0xc0135761, v88
	v_mul_f32_e32 v89, 0xbfb8aa3b, v80
	v_fma_f32 v90, v85, v90, 1.0
	v_exp_f32_e32 v88, v88
	v_exp_f32_e32 v89, v89
	v_mul_f32_e32 v90, v85, v90
	v_mul_f32_e32 v90, 0xc0135761, v90
	v_mul_f32_e32 v91, 0xbfb8aa3b, v81
	v_exp_f32_e32 v90, v90
	v_exp_f32_e32 v91, v91
	v_pk_add_f32 v[88:89], v[88:89], 1.0 op_sel_hi:[1,0]
	v_mul_f32_e32 v80, v84, v80
	v_mul_f32_e32 v88, v88, v89
	v_rcp_f32_e32 v94, v88
	v_pk_add_f32 v[88:89], v[90:91], 1.0 op_sel_hi:[1,0]
	v_mul_f32_e32 v84, 0x3d372713, v87
	v_mul_f32_e32 v88, v88, v89
	v_rcp_f32_e32 v88, v88
	v_mul_f32_e32 v89, v80, v94
	v_mul_f32_e32 v80, v85, v81
	v_mul_f32_e32 v81, 0xbfb8aa3b, v82
	v_mul_f32_e32 v88, v80, v88
	v_mul_f32_e32 v80, 0x3d372713, v86
	v_fma_f32 v80, v86, v80, 1.0
	v_mul_f32_e32 v80, v86, v80
	v_mul_f32_e32 v80, 0xc0135761, v80
	v_fma_f32 v84, v87, v84, 1.0
	v_exp_f32_e32 v80, v80
	v_exp_f32_e32 v81, v81
	v_mul_f32_e32 v84, v87, v84
	v_mul_f32_e32 v84, 0xc0135761, v84
	v_mul_f32_e32 v85, 0xbfb8aa3b, v83
	v_exp_f32_e32 v84, v84
	v_exp_f32_e32 v85, v85
	v_pk_add_f32 v[80:81], v[80:81], 1.0 op_sel_hi:[1,0]
	s_nop 0
	v_mul_f32_e32 v80, v80, v81
	v_rcp_f32_e32 v90, v80
	v_pk_add_f32 v[80:81], v[84:85], 1.0 op_sel_hi:[1,0]
	s_nop 0
	v_mul_f32_e32 v80, v80, v81
	v_rcp_f32_e32 v80, v80
	v_mul_f32_e32 v81, v86, v82
	v_mul_f32_e32 v84, v81, v90
	v_mul_f32_e32 v81, v87, v83
	v_mul_f32_e32 v83, v81, v80
	v_cvt_pk_bf16_f32 v80, v97, v96
	v_cvt_pk_bf16_f32 v81, v92, v93
	v_cvt_pk_bf16_f32 v82, v89, v88
	v_cvt_pk_bf16_f32 v83, v84, v83
	v_add_co_u32_e32 v84, vcc, s5, v112
	s_movk_i32 s5, 0x4000
	s_nop 0
	v_addc_co_u32_e32 v85, vcc, 0, v113, vcc
	global_store_dwordx4 v[84:85], v[80:83], off
	s_nop 1
	v_mul_f32_e32 v80, 0x3d372713, v76
	v_fma_f32 v80, v76, v80, 1.0
	v_mul_f32_e32 v80, v76, v80
	v_mul_f32_e32 v82, 0x3d372713, v77
	v_mul_f32_e32 v80, 0xc0135761, v80
	v_mul_f32_e32 v81, 0xbfb8aa3b, v72
	v_fma_f32 v82, v77, v82, 1.0
	v_exp_f32_e32 v80, v80
	v_exp_f32_e32 v81, v81
	v_mul_f32_e32 v82, v77, v82
	v_mul_f32_e32 v82, 0xc0135761, v82
	v_mul_f32_e32 v83, 0xbfb8aa3b, v73
	v_exp_f32_e32 v82, v82
	v_exp_f32_e32 v83, v83
	v_pk_add_f32 v[80:81], v[80:81], 1.0 op_sel_hi:[1,0]
	v_mul_f32_e32 v72, v76, v72
	v_mul_f32_e32 v80, v80, v81
	v_rcp_f32_e32 v86, v80
	v_pk_add_f32 v[80:81], v[82:83], 1.0 op_sel_hi:[1,0]
	v_mul_f32_e32 v76, 0x3d372713, v79
	v_mul_f32_e32 v80, v80, v81
	v_rcp_f32_e32 v80, v80
	v_mul_f32_e32 v81, v72, v86
	v_mul_f32_e32 v72, v77, v73
	v_mul_f32_e32 v73, 0xbfb8aa3b, v74
	v_mul_f32_e32 v80, v72, v80
	v_mul_f32_e32 v72, 0x3d372713, v78
	v_fma_f32 v72, v78, v72, 1.0
	v_mul_f32_e32 v72, v78, v72
	v_mul_f32_e32 v72, 0xc0135761, v72
	v_fma_f32 v76, v79, v76, 1.0
	v_exp_f32_e32 v72, v72
	v_exp_f32_e32 v73, v73
	v_mul_f32_e32 v76, v79, v76
	v_mul_f32_e32 v76, 0xc0135761, v76
	v_mul_f32_e32 v77, 0xbfb8aa3b, v75
	v_exp_f32_e32 v76, v76
	v_exp_f32_e32 v77, v77
	v_pk_add_f32 v[72:73], v[72:73], 1.0 op_sel_hi:[1,0]
	s_nop 0
	v_mul_f32_e32 v72, v72, v73
	v_rcp_f32_e32 v82, v72
	v_pk_add_f32 v[72:73], v[76:77], 1.0 op_sel_hi:[1,0]
	s_nop 0
	v_mul_f32_e32 v72, v72, v73
	v_rcp_f32_e32 v72, v72
	v_mul_f32_e32 v73, v78, v74
	v_mul_f32_e32 v76, v73, v82
	v_mul_f32_e32 v73, v79, v75
	v_mul_f32_e32 v77, v73, v72
	v_mul_f32_e32 v72, 0x3d372713, v68
	v_fma_f32 v72, v68, v72, 1.0
	v_mul_f32_e32 v72, v68, v72
	v_mul_f32_e32 v74, 0x3d372713, v69
	v_mul_f32_e32 v72, 0xc0135761, v72
	v_mul_f32_e32 v73, 0xbfb8aa3b, v64
	v_fma_f32 v74, v69, v74, 1.0
	v_exp_f32_e32 v72, v72
	v_exp_f32_e32 v73, v73
	v_mul_f32_e32 v74, v69, v74
	v_mul_f32_e32 v74, 0xc0135761, v74
	v_mul_f32_e32 v75, 0xbfb8aa3b, v65
	v_exp_f32_e32 v74, v74
	v_exp_f32_e32 v75, v75
	v_pk_add_f32 v[72:73], v[72:73], 1.0 op_sel_hi:[1,0]
	v_mul_f32_e32 v64, v68, v64
	v_mul_f32_e32 v72, v72, v73
	v_rcp_f32_e32 v78, v72
	v_pk_add_f32 v[72:73], v[74:75], 1.0 op_sel_hi:[1,0]
	v_mul_f32_e32 v68, 0x3d372713, v71
	v_mul_f32_e32 v72, v72, v73
	v_rcp_f32_e32 v72, v72
	v_mul_f32_e32 v73, v64, v78
	v_mul_f32_e32 v64, v69, v65
	v_mul_f32_e32 v65, 0xbfb8aa3b, v66
	v_mul_f32_e32 v72, v64, v72
	v_mul_f32_e32 v64, 0x3d372713, v70
	v_fma_f32 v64, v70, v64, 1.0
	v_mul_f32_e32 v64, v70, v64
	v_mul_f32_e32 v64, 0xc0135761, v64
	v_fma_f32 v68, v71, v68, 1.0
	v_exp_f32_e32 v64, v64
	v_exp_f32_e32 v65, v65
	v_mul_f32_e32 v68, v71, v68
	v_mul_f32_e32 v68, 0xc0135761, v68
	v_mul_f32_e32 v69, 0xbfb8aa3b, v67
	v_exp_f32_e32 v68, v68
	v_exp_f32_e32 v69, v69
	v_pk_add_f32 v[64:65], v[64:65], 1.0 op_sel_hi:[1,0]
	s_nop 0
	v_mul_f32_e32 v64, v64, v65
	v_rcp_f32_e32 v74, v64
	v_pk_add_f32 v[64:65], v[68:69], 1.0 op_sel_hi:[1,0]
	s_nop 0
	v_mul_f32_e32 v64, v64, v65
	v_rcp_f32_e32 v64, v64
	v_mul_f32_e32 v65, v70, v66
	v_mul_f32_e32 v68, v65, v74
	v_mul_f32_e32 v65, v71, v67
	v_mul_f32_e32 v67, v65, v64
	v_cvt_pk_bf16_f32 v64, v81, v80
	v_cvt_pk_bf16_f32 v65, v76, v77
	v_cvt_pk_bf16_f32 v66, v73, v72
	v_cvt_pk_bf16_f32 v67, v68, v67
	global_store_dwordx4 v[84:85], v[64:67], off offset:2048
	s_nop 1
	v_mul_f32_e32 v64, 0x3d372713, v60
	v_fma_f32 v64, v60, v64, 1.0
	v_mul_f32_e32 v64, v60, v64
	v_mul_f32_e32 v66, 0x3d372713, v61
	v_mul_f32_e32 v64, 0xc0135761, v64
	v_mul_f32_e32 v65, 0xbfb8aa3b, v56
	v_fma_f32 v66, v61, v66, 1.0
	v_exp_f32_e32 v64, v64
	v_exp_f32_e32 v65, v65
	v_mul_f32_e32 v66, v61, v66
	v_mul_f32_e32 v66, 0xc0135761, v66
	v_mul_f32_e32 v67, 0xbfb8aa3b, v57
	v_exp_f32_e32 v66, v66
	v_exp_f32_e32 v67, v67
	v_pk_add_f32 v[64:65], v[64:65], 1.0 op_sel_hi:[1,0]
	v_mul_f32_e32 v56, v60, v56
	v_mul_f32_e32 v64, v64, v65
	v_rcp_f32_e32 v68, v64
	v_pk_add_f32 v[64:65], v[66:67], 1.0 op_sel_hi:[1,0]
	v_mul_f32_e32 v60, 0x3d372713, v63
	v_mul_f32_e32 v64, v64, v65
	v_rcp_f32_e32 v64, v64
	v_mul_f32_e32 v65, v56, v68
	v_mul_f32_e32 v56, v61, v57
	v_mul_f32_e32 v57, 0xbfb8aa3b, v58
	v_mul_f32_e32 v64, v56, v64
	v_mul_f32_e32 v56, 0x3d372713, v62
	v_fma_f32 v56, v62, v56, 1.0
	v_mul_f32_e32 v56, v62, v56
	v_mul_f32_e32 v56, 0xc0135761, v56
	v_fma_f32 v60, v63, v60, 1.0
	v_exp_f32_e32 v56, v56
	v_exp_f32_e32 v57, v57
	v_mul_f32_e32 v60, v63, v60
	v_mul_f32_e32 v60, 0xc0135761, v60
	v_mul_f32_e32 v61, 0xbfb8aa3b, v59
	v_exp_f32_e32 v60, v60
	v_exp_f32_e32 v61, v61
	v_pk_add_f32 v[56:57], v[56:57], 1.0 op_sel_hi:[1,0]
	s_nop 0
	v_mul_f32_e32 v56, v56, v57
	v_rcp_f32_e32 v66, v56
	v_pk_add_f32 v[56:57], v[60:61], 1.0 op_sel_hi:[1,0]
	s_nop 0
	v_mul_f32_e32 v56, v56, v57
	v_rcp_f32_e32 v56, v56
	v_mul_f32_e32 v57, v62, v58
	v_mul_f32_e32 v60, v57, v66
	v_mul_f32_e32 v57, v63, v59
	v_mul_f32_e32 v61, v57, v56
	v_mul_f32_e32 v56, 0x3d372713, v52
	v_fma_f32 v56, v52, v56, 1.0
	v_mul_f32_e32 v56, v52, v56
	v_mul_f32_e32 v58, 0x3d372713, v53
	v_mul_f32_e32 v56, 0xc0135761, v56
	v_mul_f32_e32 v57, 0xbfb8aa3b, v48
	v_fma_f32 v58, v53, v58, 1.0
	v_exp_f32_e32 v56, v56
	v_exp_f32_e32 v57, v57
	v_mul_f32_e32 v58, v53, v58
	v_mul_f32_e32 v58, 0xc0135761, v58
	v_mul_f32_e32 v59, 0xbfb8aa3b, v49
	v_exp_f32_e32 v58, v58
	v_exp_f32_e32 v59, v59
	v_pk_add_f32 v[56:57], v[56:57], 1.0 op_sel_hi:[1,0]
	v_mul_f32_e32 v48, v52, v48
	v_mul_f32_e32 v56, v56, v57
	v_rcp_f32_e32 v62, v56
	v_pk_add_f32 v[56:57], v[58:59], 1.0 op_sel_hi:[1,0]
	v_mul_f32_e32 v52, 0x3d372713, v55
	v_mul_f32_e32 v56, v56, v57
	v_rcp_f32_e32 v56, v56
	v_mul_f32_e32 v57, v48, v62
	v_mul_f32_e32 v48, v53, v49
	v_mul_f32_e32 v49, 0xbfb8aa3b, v50
	v_mul_f32_e32 v56, v48, v56
	v_mul_f32_e32 v48, 0x3d372713, v54
	v_fma_f32 v48, v54, v48, 1.0
	v_mul_f32_e32 v48, v54, v48
	v_mul_f32_e32 v48, 0xc0135761, v48
	v_fma_f32 v52, v55, v52, 1.0
	v_exp_f32_e32 v48, v48
	v_exp_f32_e32 v49, v49
	v_mul_f32_e32 v52, v55, v52
	v_mul_f32_e32 v52, 0xc0135761, v52
	v_mul_f32_e32 v53, 0xbfb8aa3b, v51
	v_exp_f32_e32 v52, v52
	v_exp_f32_e32 v53, v53
	v_pk_add_f32 v[48:49], v[48:49], 1.0 op_sel_hi:[1,0]
	s_nop 0
	v_mul_f32_e32 v48, v48, v49
	v_rcp_f32_e32 v58, v48
	v_pk_add_f32 v[48:49], v[52:53], 1.0 op_sel_hi:[1,0]
	s_nop 0
	v_mul_f32_e32 v48, v48, v49
	v_rcp_f32_e32 v48, v48
	v_mul_f32_e32 v49, v54, v50
	v_mul_f32_e32 v50, v55, v51
	v_add_co_u32_e32 v54, vcc, s5, v112
	v_mul_f32_e32 v48, v50, v48
	s_nop 0
	v_addc_co_u32_e32 v55, vcc, 0, v113, vcc
	s_movk_i32 s5, 0x5000
	v_mul_f32_e32 v49, v49, v58
	v_cvt_pk_bf16_f32 v50, v65, v64
	v_cvt_pk_bf16_f32 v51, v60, v61
	v_cvt_pk_bf16_f32 v52, v57, v56
	v_cvt_pk_bf16_f32 v53, v49, v48
	v_add_co_u32_e32 v48, vcc, s5, v112
	s_nop 1
	v_addc_co_u32_e32 v49, vcc, 0, v113, vcc
	global_store_dwordx4 v[48:49], v[50:53], off offset:-4096
	s_and_b64 vcc, exec, s[2:3]
	s_nop 0
	v_mul_f32_e32 v50, 0x3d372713, v44
	v_fma_f32 v50, v44, v50, 1.0
	v_mul_f32_e32 v50, v44, v50
	v_mul_f32_e32 v52, 0x3d372713, v45
	v_mul_f32_e32 v50, 0xc0135761, v50
	v_mul_f32_e32 v51, 0xbfb8aa3b, v40
	v_fma_f32 v52, v45, v52, 1.0
	v_exp_f32_e32 v50, v50
	v_exp_f32_e32 v51, v51
	v_mul_f32_e32 v52, v45, v52
	v_mul_f32_e32 v52, 0xc0135761, v52
	v_mul_f32_e32 v53, 0xbfb8aa3b, v41
	v_exp_f32_e32 v52, v52
	v_exp_f32_e32 v53, v53
	v_pk_add_f32 v[50:51], v[50:51], 1.0 op_sel_hi:[1,0]
	v_mul_f32_e32 v40, v44, v40
	v_mul_f32_e32 v50, v50, v51
	v_rcp_f32_e32 v56, v50
	v_pk_add_f32 v[50:51], v[52:53], 1.0 op_sel_hi:[1,0]
	v_mul_f32_e32 v44, 0x3d372713, v47
	v_mul_f32_e32 v50, v50, v51
	v_rcp_f32_e32 v50, v50
	v_mul_f32_e32 v51, v40, v56
	v_mul_f32_e32 v40, v45, v41
	v_mul_f32_e32 v41, 0xbfb8aa3b, v42
	v_mul_f32_e32 v50, v40, v50
	v_mul_f32_e32 v40, 0x3d372713, v46
	v_fma_f32 v40, v46, v40, 1.0
	v_mul_f32_e32 v40, v46, v40
	v_mul_f32_e32 v40, 0xc0135761, v40
	v_fma_f32 v44, v47, v44, 1.0
	v_exp_f32_e32 v40, v40
	v_exp_f32_e32 v41, v41
	v_mul_f32_e32 v44, v47, v44
	v_mul_f32_e32 v44, 0xc0135761, v44
	v_mul_f32_e32 v45, 0xbfb8aa3b, v43
	v_exp_f32_e32 v44, v44
	v_exp_f32_e32 v45, v45
	v_pk_add_f32 v[40:41], v[40:41], 1.0 op_sel_hi:[1,0]
	s_nop 0
	v_mul_f32_e32 v40, v40, v41
	v_rcp_f32_e32 v52, v40
	v_pk_add_f32 v[40:41], v[44:45], 1.0 op_sel_hi:[1,0]
	s_nop 0
	v_mul_f32_e32 v40, v40, v41
	v_rcp_f32_e32 v40, v40
	v_mul_f32_e32 v41, v46, v42
	v_mul_f32_e32 v44, v41, v52
	v_mul_f32_e32 v41, v47, v43
	v_mul_f32_e32 v45, v41, v40
	v_mul_f32_e32 v40, 0x3d372713, v36
	v_fma_f32 v40, v36, v40, 1.0
	v_mul_f32_e32 v40, v36, v40
	v_mul_f32_e32 v42, 0x3d372713, v37
	v_mul_f32_e32 v40, 0xc0135761, v40
	v_mul_f32_e32 v41, 0xbfb8aa3b, v32
	v_fma_f32 v42, v37, v42, 1.0
	v_exp_f32_e32 v40, v40
	v_exp_f32_e32 v41, v41
	v_mul_f32_e32 v42, v37, v42
	v_mul_f32_e32 v42, 0xc0135761, v42
	v_mul_f32_e32 v43, 0xbfb8aa3b, v33
	v_exp_f32_e32 v42, v42
	v_exp_f32_e32 v43, v43
	v_pk_add_f32 v[40:41], v[40:41], 1.0 op_sel_hi:[1,0]
	v_mul_f32_e32 v32, v36, v32
	v_mul_f32_e32 v40, v40, v41
	v_rcp_f32_e32 v46, v40
	v_pk_add_f32 v[40:41], v[42:43], 1.0 op_sel_hi:[1,0]
	v_mul_f32_e32 v36, 0x3d372713, v39
	v_mul_f32_e32 v40, v40, v41
	v_rcp_f32_e32 v40, v40
	v_mul_f32_e32 v41, v32, v46
	v_mul_f32_e32 v32, v37, v33
	v_mul_f32_e32 v33, 0xbfb8aa3b, v34
	v_mul_f32_e32 v40, v32, v40
	v_mul_f32_e32 v32, 0x3d372713, v38
	v_fma_f32 v32, v38, v32, 1.0
	v_mul_f32_e32 v32, v38, v32
	v_mul_f32_e32 v32, 0xc0135761, v32
	v_fma_f32 v36, v39, v36, 1.0
	v_exp_f32_e32 v32, v32
	v_exp_f32_e32 v33, v33
	v_mul_f32_e32 v36, v39, v36
	v_mul_f32_e32 v36, 0xc0135761, v36
	v_mul_f32_e32 v37, 0xbfb8aa3b, v35
	v_exp_f32_e32 v36, v36
	v_exp_f32_e32 v37, v37
	v_pk_add_f32 v[32:33], v[32:33], 1.0 op_sel_hi:[1,0]
	s_nop 0
	v_mul_f32_e32 v32, v32, v33
	v_rcp_f32_e32 v42, v32
	v_pk_add_f32 v[32:33], v[36:37], 1.0 op_sel_hi:[1,0]
	s_nop 0
	v_mul_f32_e32 v32, v32, v33
	v_rcp_f32_e32 v32, v32
	v_mul_f32_e32 v33, v38, v34
	v_mul_f32_e32 v36, v33, v42
	v_mul_f32_e32 v33, v39, v35
	v_mul_f32_e32 v35, v33, v32
	v_cvt_pk_bf16_f32 v32, v51, v50
	v_cvt_pk_bf16_f32 v33, v44, v45
	v_cvt_pk_bf16_f32 v34, v41, v40
	v_cvt_pk_bf16_f32 v35, v36, v35
	global_store_dwordx4 v[54:55], v[32:35], off offset:2048
	s_nop 1
	v_mul_f32_e32 v32, 0x3d372713, v28
	v_fma_f32 v32, v28, v32, 1.0
	v_mul_f32_e32 v32, v28, v32
	v_mul_f32_e32 v34, 0x3d372713, v29
	v_mul_f32_e32 v32, 0xc0135761, v32
	v_mul_f32_e32 v33, 0xbfb8aa3b, v24
	v_fma_f32 v34, v29, v34, 1.0
	v_exp_f32_e32 v32, v32
	v_exp_f32_e32 v33, v33
	v_mul_f32_e32 v34, v29, v34
	v_mul_f32_e32 v34, 0xc0135761, v34
	v_mul_f32_e32 v35, 0xbfb8aa3b, v25
	v_exp_f32_e32 v34, v34
	v_exp_f32_e32 v35, v35
	v_pk_add_f32 v[32:33], v[32:33], 1.0 op_sel_hi:[1,0]
	v_mul_f32_e32 v24, v28, v24
	v_mul_f32_e32 v32, v32, v33
	v_rcp_f32_e32 v36, v32
	v_pk_add_f32 v[32:33], v[34:35], 1.0 op_sel_hi:[1,0]
	v_mul_f32_e32 v28, 0x3d372713, v31
	v_mul_f32_e32 v32, v32, v33
	v_rcp_f32_e32 v32, v32
	v_mul_f32_e32 v33, v24, v36
	v_mul_f32_e32 v24, v29, v25
	v_mul_f32_e32 v25, 0xbfb8aa3b, v26
	v_mul_f32_e32 v32, v24, v32
	v_mul_f32_e32 v24, 0x3d372713, v30
	v_fma_f32 v24, v30, v24, 1.0
	v_mul_f32_e32 v24, v30, v24
	v_mul_f32_e32 v24, 0xc0135761, v24
	v_fma_f32 v28, v31, v28, 1.0
	v_exp_f32_e32 v24, v24
	v_exp_f32_e32 v25, v25
	v_mul_f32_e32 v28, v31, v28
	v_mul_f32_e32 v28, 0xc0135761, v28
	v_mul_f32_e32 v29, 0xbfb8aa3b, v27
	v_exp_f32_e32 v28, v28
	v_exp_f32_e32 v29, v29
	v_pk_add_f32 v[24:25], v[24:25], 1.0 op_sel_hi:[1,0]
	s_nop 0
	v_mul_f32_e32 v24, v24, v25
	v_rcp_f32_e32 v34, v24
	v_pk_add_f32 v[24:25], v[28:29], 1.0 op_sel_hi:[1,0]
	s_nop 0
	v_mul_f32_e32 v24, v24, v25
	v_rcp_f32_e32 v24, v24
	v_mul_f32_e32 v25, v30, v26
	v_mul_f32_e32 v28, v25, v34
	v_mul_f32_e32 v25, v31, v27
	v_mul_f32_e32 v29, v25, v24
	v_mul_f32_e32 v24, 0x3d372713, v20
	v_fma_f32 v24, v20, v24, 1.0
	v_mul_f32_e32 v24, v20, v24
	v_mul_f32_e32 v26, 0x3d372713, v21
	v_mul_f32_e32 v24, 0xc0135761, v24
	v_mul_f32_e32 v25, 0xbfb8aa3b, v16
	v_fma_f32 v26, v21, v26, 1.0
	v_exp_f32_e32 v24, v24
	v_exp_f32_e32 v25, v25
	v_mul_f32_e32 v26, v21, v26
	v_mul_f32_e32 v26, 0xc0135761, v26
	v_mul_f32_e32 v27, 0xbfb8aa3b, v17
	v_exp_f32_e32 v26, v26
	v_exp_f32_e32 v27, v27
	v_pk_add_f32 v[24:25], v[24:25], 1.0 op_sel_hi:[1,0]
	v_mul_f32_e32 v16, v20, v16
	v_mul_f32_e32 v24, v24, v25
	v_rcp_f32_e32 v30, v24
	v_pk_add_f32 v[24:25], v[26:27], 1.0 op_sel_hi:[1,0]
	v_mul_f32_e32 v20, 0x3d372713, v23
	v_mul_f32_e32 v24, v24, v25
	v_rcp_f32_e32 v24, v24
	v_mul_f32_e32 v25, v16, v30
	v_mul_f32_e32 v16, v21, v17
	v_mul_f32_e32 v17, 0xbfb8aa3b, v18
	v_mul_f32_e32 v24, v16, v24
	v_mul_f32_e32 v16, 0x3d372713, v22
	v_fma_f32 v16, v22, v16, 1.0
	v_mul_f32_e32 v16, v22, v16
	v_mul_f32_e32 v16, 0xc0135761, v16
	v_fma_f32 v20, v23, v20, 1.0
	v_exp_f32_e32 v16, v16
	v_exp_f32_e32 v17, v17
	v_mul_f32_e32 v20, v23, v20
	v_mul_f32_e32 v20, 0xc0135761, v20
	v_mul_f32_e32 v21, 0xbfb8aa3b, v19
	v_exp_f32_e32 v20, v20
	v_exp_f32_e32 v21, v21
	v_pk_add_f32 v[16:17], v[16:17], 1.0 op_sel_hi:[1,0]
	s_nop 0
	v_mul_f32_e32 v16, v16, v17
	v_rcp_f32_e32 v26, v16
	v_pk_add_f32 v[16:17], v[20:21], 1.0 op_sel_hi:[1,0]
	s_nop 0
	v_mul_f32_e32 v16, v16, v17
	v_rcp_f32_e32 v16, v16
	v_mul_f32_e32 v17, v22, v18
	v_mul_f32_e32 v20, v17, v26
	v_mul_f32_e32 v17, v23, v19
	v_mul_f32_e32 v19, v17, v16
	v_cvt_pk_bf16_f32 v16, v33, v32
	v_cvt_pk_bf16_f32 v17, v28, v29
	v_cvt_pk_bf16_f32 v18, v25, v24
	v_cvt_pk_bf16_f32 v19, v20, v19
	global_store_dwordx4 v[48:49], v[16:19], off
	s_nop 1
	v_mul_f32_e32 v16, 0x3d372713, v12
	v_fma_f32 v16, v12, v16, 1.0
	v_mul_f32_e32 v16, v12, v16
	v_mul_f32_e32 v18, 0x3d372713, v13
	v_mul_f32_e32 v16, 0xc0135761, v16
	v_mul_f32_e32 v17, 0xbfb8aa3b, v8
	v_fma_f32 v18, v13, v18, 1.0
	v_exp_f32_e32 v16, v16
	v_exp_f32_e32 v17, v17
	v_mul_f32_e32 v18, v13, v18
	v_mul_f32_e32 v18, 0xc0135761, v18
	v_mul_f32_e32 v19, 0xbfb8aa3b, v9
	v_exp_f32_e32 v18, v18
	v_exp_f32_e32 v19, v19
	v_pk_add_f32 v[16:17], v[16:17], 1.0 op_sel_hi:[1,0]
	v_mul_f32_e32 v8, v12, v8
	v_mul_f32_e32 v16, v16, v17
	v_rcp_f32_e32 v20, v16
	v_pk_add_f32 v[16:17], v[18:19], 1.0 op_sel_hi:[1,0]
	v_mul_f32_e32 v12, 0x3d372713, v15
	v_mul_f32_e32 v16, v16, v17
	v_rcp_f32_e32 v16, v16
	v_mul_f32_e32 v17, v8, v20
	v_mul_f32_e32 v8, v13, v9
	v_mul_f32_e32 v9, 0xbfb8aa3b, v10
	v_mul_f32_e32 v16, v8, v16
	v_mul_f32_e32 v8, 0x3d372713, v14
	v_fma_f32 v8, v14, v8, 1.0
	v_mul_f32_e32 v8, v14, v8
	v_mul_f32_e32 v8, 0xc0135761, v8
	v_fma_f32 v12, v15, v12, 1.0
	v_exp_f32_e32 v8, v8
	v_exp_f32_e32 v9, v9
	v_mul_f32_e32 v12, v15, v12
	v_mul_f32_e32 v12, 0xc0135761, v12
	v_mul_f32_e32 v13, 0xbfb8aa3b, v11
	v_exp_f32_e32 v12, v12
	v_exp_f32_e32 v13, v13
	v_pk_add_f32 v[8:9], v[8:9], 1.0 op_sel_hi:[1,0]
	s_nop 0
	v_mul_f32_e32 v8, v8, v9
	v_rcp_f32_e32 v18, v8
	v_pk_add_f32 v[8:9], v[12:13], 1.0 op_sel_hi:[1,0]
	s_nop 0
	v_mul_f32_e32 v8, v8, v9
	v_rcp_f32_e32 v8, v8
	v_mul_f32_e32 v9, v14, v10
	v_mul_f32_e32 v12, v9, v18
	v_mul_f32_e32 v9, v15, v11
	v_mul_f32_e32 v13, v9, v8
	v_mul_f32_e32 v8, 0x3d372713, v4
	v_fma_f32 v8, v4, v8, 1.0
	v_mul_f32_e32 v8, v4, v8
	v_mul_f32_e32 v10, 0x3d372713, v5
	v_mul_f32_e32 v8, 0xc0135761, v8
	v_mul_f32_e32 v9, 0xbfb8aa3b, v0
	v_fma_f32 v10, v5, v10, 1.0
	v_exp_f32_e32 v8, v8
	v_exp_f32_e32 v9, v9
	v_mul_f32_e32 v10, v5, v10
	v_mul_f32_e32 v10, 0xc0135761, v10
	v_mul_f32_e32 v11, 0xbfb8aa3b, v1
	v_exp_f32_e32 v10, v10
	v_exp_f32_e32 v11, v11
	v_pk_add_f32 v[8:9], v[8:9], 1.0 op_sel_hi:[1,0]
	v_mul_f32_e32 v0, v4, v0
	v_mul_f32_e32 v8, v8, v9
	v_rcp_f32_e32 v14, v8
	v_pk_add_f32 v[8:9], v[10:11], 1.0 op_sel_hi:[1,0]
	v_mul_f32_e32 v4, 0x3d372713, v7
	v_mul_f32_e32 v8, v8, v9
	v_rcp_f32_e32 v8, v8
	v_mul_f32_e32 v9, v0, v14
	v_mul_f32_e32 v0, v5, v1
	v_mul_f32_e32 v1, 0xbfb8aa3b, v2
	v_mul_f32_e32 v8, v0, v8
	v_mul_f32_e32 v0, 0x3d372713, v6
	v_fma_f32 v0, v6, v0, 1.0
	v_mul_f32_e32 v0, v6, v0
	v_mul_f32_e32 v0, 0xc0135761, v0
	v_fma_f32 v4, v7, v4, 1.0
	v_exp_f32_e32 v0, v0
	v_exp_f32_e32 v1, v1
	v_mul_f32_e32 v4, v7, v4
	v_mul_f32_e32 v4, 0xc0135761, v4
	v_mul_f32_e32 v5, 0xbfb8aa3b, v3
	v_exp_f32_e32 v4, v4
	v_exp_f32_e32 v5, v5
	v_pk_add_f32 v[0:1], v[0:1], 1.0 op_sel_hi:[1,0]
	s_nop 0
	v_mul_f32_e32 v0, v0, v1
	v_rcp_f32_e32 v10, v0
	v_pk_add_f32 v[0:1], v[4:5], 1.0 op_sel_hi:[1,0]
	s_nop 0
	v_mul_f32_e32 v0, v0, v1
	v_rcp_f32_e32 v0, v0
	v_mul_f32_e32 v1, v6, v2
	v_mul_f32_e32 v4, v1, v10
	v_mul_f32_e32 v1, v7, v3
	v_mul_f32_e32 v3, v1, v0
	v_cvt_pk_bf16_f32 v0, v17, v16
	v_cvt_pk_bf16_f32 v1, v12, v13
	v_cvt_pk_bf16_f32 v2, v9, v8
	v_cvt_pk_bf16_f32 v3, v4, v3
	global_store_dwordx4 v[48:49], v[0:3], off offset:2048
	s_cbranch_vccz .LBB0_307
	s_waitcnt vmcnt(0)
	s_cmpk_gt_u32 s30, 0xff
	s_cbranch_scc1 .LBB0_318
	s_barrier

.LBB0_333:
	s_ashr_i32 s17, s16, 31
	s_lshl_b64 s[20:21], s[16:17], 20
	s_add_u32 s20, s31, s20
	s_addc_u32 s21, s33, s21
	s_and_b64 s[22:23], s[24:25], exec
	s_cselect_b32 s17, s21, s1
	s_cselect_b32 s46, s20, s0
	s_ashr_i32 s19, s18, 31
	s_lshl_b64 s[22:23], s[18:19], 20
	s_add_u32 s22, s27, s22
	s_addc_u32 s23, s28, s23
	s_and_b64 s[24:25], s[24:25], exec
	s_cselect_b32 s19, s23, s5
	s_cselect_b32 s47, s22, s4
	s_add_u32 s0, s0, 0x80080
	s_addc_u32 s1, s1, 0
	s_add_u32 s48, s4, 0x100
	v_mov_b32_e32 v0, 0
	s_addc_u32 s49, s5, 0
	s_mov_b32 s50, -2
	v_mov_b32_e32 v1, v0
	v_mov_b32_e32 v2, v0
	v_mov_b32_e32 v3, v0
	v_mov_b32_e32 v4, v0
	v_mov_b32_e32 v5, v0
	v_mov_b32_e32 v6, v0
	v_mov_b32_e32 v7, v0
	v_mov_b32_e32 v16, v0
	v_mov_b32_e32 v17, v0
	v_mov_b32_e32 v18, v0
	v_mov_b32_e32 v19, v0
	v_mov_b32_e32 v20, v0
	v_mov_b32_e32 v21, v0
	v_mov_b32_e32 v22, v0
	v_mov_b32_e32 v23, v0
	v_mov_b32_e32 v32, v0
	v_mov_b32_e32 v33, v0
	v_mov_b32_e32 v34, v0
	v_mov_b32_e32 v35, v0
	v_mov_b32_e32 v36, v0
	v_mov_b32_e32 v37, v0
	v_mov_b32_e32 v38, v0
	v_mov_b32_e32 v39, v0
	v_mov_b32_e32 v48, v0
	v_mov_b32_e32 v49, v0
	v_mov_b32_e32 v50, v0
	v_mov_b32_e32 v51, v0
	v_mov_b32_e32 v52, v0
	v_mov_b32_e32 v53, v0
	v_mov_b32_e32 v54, v0
	v_mov_b32_e32 v55, v0
	v_mov_b32_e32 v8, v0
	v_mov_b32_e32 v9, v0
	v_mov_b32_e32 v10, v0
	v_mov_b32_e32 v11, v0
	v_mov_b32_e32 v12, v0
	v_mov_b32_e32 v13, v0
	v_mov_b32_e32 v14, v0
	v_mov_b32_e32 v15, v0
	v_mov_b32_e32 v24, v0
	v_mov_b32_e32 v25, v0
	v_mov_b32_e32 v26, v0
	v_mov_b32_e32 v27, v0
	v_mov_b32_e32 v28, v0
	v_mov_b32_e32 v29, v0
	v_mov_b32_e32 v30, v0
	v_mov_b32_e32 v31, v0
	v_mov_b32_e32 v40, v0
	v_mov_b32_e32 v41, v0
	v_mov_b32_e32 v42, v0
	v_mov_b32_e32 v43, v0
	v_mov_b32_e32 v44, v0
	v_mov_b32_e32 v45, v0
	v_mov_b32_e32 v46, v0
	v_mov_b32_e32 v47, v0
	v_mov_b32_e32 v60, v0
	v_mov_b32_e32 v61, v0
	v_mov_b32_e32 v62, v0
	v_mov_b32_e32 v63, v0
	v_mov_b32_e32 v64, v0
	v_mov_b32_e32 v65, v0
	v_mov_b32_e32 v66, v0
	v_mov_b32_e32 v67, v0
	v_mov_b32_e32 v72, v0
	v_mov_b32_e32 v73, v0
	v_mov_b32_e32 v74, v0
	v_mov_b32_e32 v75, v0
	v_mov_b32_e32 v76, v0
	v_mov_b32_e32 v77, v0
	v_mov_b32_e32 v78, v0
	v_mov_b32_e32 v79, v0
	v_mov_b32_e32 v96, v0
	v_mov_b32_e32 v97, v0
	v_mov_b32_e32 v98, v0
	v_mov_b32_e32 v99, v0
	v_mov_b32_e32 v100, v0
	v_mov_b32_e32 v101, v0
	v_mov_b32_e32 v102, v0
	v_mov_b32_e32 v103, v0
	v_mov_b32_e32 v80, v0
	v_mov_b32_e32 v81, v0
	v_mov_b32_e32 v82, v0
	v_mov_b32_e32 v83, v0
	v_mov_b32_e32 v112, v0
	v_mov_b32_e32 v113, v0
	v_mov_b32_e32 v114, v0
	v_mov_b32_e32 v115, v0
	v_mov_b32_e32 v56, v0
	v_mov_b32_e32 v57, v0
	v_mov_b32_e32 v58, v0
	v_mov_b32_e32 v59, v0
	v_mov_b32_e32 v120, v0
	v_mov_b32_e32 v121, v0
	v_mov_b32_e32 v122, v0
	v_mov_b32_e32 v123, v0
	v_mov_b32_e32 v84, v0
	v_mov_b32_e32 v85, v0
	v_mov_b32_e32 v86, v0
	v_mov_b32_e32 v87, v0
	v_mov_b32_e32 v92, v0
	v_mov_b32_e32 v93, v0
	v_mov_b32_e32 v94, v0
	v_mov_b32_e32 v95, v0
	v_mov_b32_e32 v104, v0
	v_mov_b32_e32 v105, v0
	v_mov_b32_e32 v106, v0
	v_mov_b32_e32 v107, v0
	v_mov_b32_e32 v108, v0
	v_mov_b32_e32 v109, v0
	v_mov_b32_e32 v110, v0
	v_mov_b32_e32 v111, v0
	v_mov_b32_e32 v88, v0
	v_mov_b32_e32 v89, v0
	v_mov_b32_e32 v90, v0
	v_mov_b32_e32 v91, v0
	v_mov_b32_e32 v116, v0
	v_mov_b32_e32 v117, v0
	v_mov_b32_e32 v118, v0
	v_mov_b32_e32 v119, v0
	v_mov_b32_e32 v68, v0
	v_mov_b32_e32 v69, v0
	v_mov_b32_e32 v70, v0
	v_mov_b32_e32 v71, v0
	v_mov_b32_e32 v124, v0
	v_mov_b32_e32 v125, v0
	v_mov_b32_e32 v126, v0
	v_mov_b32_e32 v127, v0
	s_mov_b64 s[56:57], 0x80
	v_add_u32_e32 v156, 0x10000, v142
	ds_read_b128 v[144:147], v156
	ds_read_b128 v[148:151], v156 offset:1024
	ds_read_b128 v[152:155], v156 offset:2048
	ds_read_b128 v[156:159], v156 offset:3072
.LBB0_334:
	s_add_u32 s4, s0, 0xfff80080
	s_addc_u32 s5, s1, -1
	s_add_i32 s51, 0, 0x10000
	v_add_u32_e32 v138, s51, v142
	s_cmp_eq_u32 s50, 28
	s_cselect_b32 s25, s17, s5
	s_cselect_b32 s24, s46, s4
	s_cselect_b32 s5, s19, s49
	s_cselect_b32 s4, s47, s48
	v_lshl_add_u64 v[138:139], s[0:1], 0, v[134:135]
	s_add_i32 m0, s3, 0xc000
	ds_read_b128 v[160:163], v143
	ds_read_b128 v[164:167], v143 offset:1024
	ds_read_b128 v[168:171], v143 offset:2048
	ds_read_b128 v[172:175], v143 offset:3072
	ds_read_b128 v[176:179], v143 offset:4096
	ds_read_b128 v[180:183], v143 offset:5120
	ds_read_b128 v[188:191], v143 offset:6144
	ds_read_b128 v[192:195], v143 offset:7168
	global_load_lds_dwordx4 v[138:139], off
	v_lshl_add_u64 v[138:139], s[0:1], 0, v[136:137]
	s_add_i32 m0, s3, 0xe000
	s_nop 0
	global_load_lds_dwordx4 v[138:139], off
	s_waitcnt lgkmcnt(8)
	s_setprio 1
	s_barrier
	s_waitcnt lgkmcnt(0)
	v_mfma_f32_16x16x32_bf16 v[124:127], v[144:147], v[160:163], v[124:127]
	v_mfma_f32_16x16x32_bf16 v[68:71], v[152:155], v[160:163], v[68:71]
	v_mfma_f32_16x16x32_bf16 v[116:119], v[144:147], v[168:171], v[116:119]
	v_mfma_f32_16x16x32_bf16 v[88:91], v[152:155], v[168:171], v[88:91]
	v_mfma_f32_16x16x32_bf16 v[108:111], v[144:147], v[176:179], v[108:111]
	v_mfma_f32_16x16x32_bf16 v[104:107], v[152:155], v[176:179], v[104:107]
	v_mfma_f32_16x16x32_bf16 v[92:95], v[144:147], v[188:191], v[92:95]
	v_mfma_f32_16x16x32_bf16 v[84:87], v[152:155], v[188:191], v[84:87]
	v_mfma_f32_16x16x32_bf16 v[124:127], v[148:151], v[164:167], v[124:127]
	v_mfma_f32_16x16x32_bf16 v[68:71], v[156:159], v[164:167], v[68:71]
	v_mfma_f32_16x16x32_bf16 v[116:119], v[148:151], v[172:175], v[116:119]
	v_mfma_f32_16x16x32_bf16 v[88:91], v[156:159], v[172:175], v[88:91]
	v_mfma_f32_16x16x32_bf16 v[108:111], v[148:151], v[180:183], v[108:111]
	v_mfma_f32_16x16x32_bf16 v[104:107], v[156:159], v[180:183], v[104:107]
	v_mfma_f32_16x16x32_bf16 v[92:95], v[148:151], v[192:195], v[92:95]
	v_mfma_f32_16x16x32_bf16 v[84:87], v[156:159], v[192:195], v[84:87]
	s_barrier
	s_setprio 0
	s_add_i32 s54, 0, 0x14000
	v_add_u32_e32 v138, s54, v142
	s_add_i32 s51, s51, s35
	ds_read_b128 v[202:205], v138
	ds_read_b128 v[206:209], v138 offset:1024
	ds_read_b128 v[210:213], v138 offset:2048
	ds_read_b128 v[214:217], v138 offset:3072
	v_lshl_add_u64 v[138:139], s[4:5], 0, v[184:185]
	s_mov_b32 m0, s51
	v_lshl_add_u64 v[196:197], s[4:5], 0, v[132:133]
	global_load_lds_dwordx4 v[138:139], off
	s_add_i32 m0, s51, 0x2000
	s_nop 0
	global_load_lds_dwordx4 v[196:197], off
	s_setprio 1
	s_barrier
	s_waitcnt lgkmcnt(0)
	v_mfma_f32_16x16x32_bf16 v[120:123], v[202:205], v[160:163], v[120:123]
	v_mfma_f32_16x16x32_bf16 v[56:59], v[210:213], v[160:163], v[56:59]
	v_mfma_f32_16x16x32_bf16 v[112:115], v[202:205], v[168:171], v[112:115]
	v_mfma_f32_16x16x32_bf16 v[80:83], v[210:213], v[168:171], v[80:83]
	v_mfma_f32_16x16x32_bf16 v[100:103], v[202:205], v[176:179], v[100:103]
	v_mfma_f32_16x16x32_bf16 v[96:99], v[210:213], v[176:179], v[96:99]
	v_mfma_f32_16x16x32_bf16 v[76:79], v[202:205], v[188:191], v[76:79]
	v_mfma_f32_16x16x32_bf16 v[72:75], v[210:213], v[188:191], v[72:75]
	v_mfma_f32_16x16x32_bf16 v[120:123], v[206:209], v[164:167], v[120:123]
	v_mfma_f32_16x16x32_bf16 v[56:59], v[214:217], v[164:167], v[56:59]
	v_mfma_f32_16x16x32_bf16 v[112:115], v[206:209], v[172:175], v[112:115]
	v_mfma_f32_16x16x32_bf16 v[80:83], v[214:217], v[172:175], v[80:83]
	v_mfma_f32_16x16x32_bf16 v[100:103], v[206:209], v[180:183], v[100:103]
	v_mfma_f32_16x16x32_bf16 v[96:99], v[214:217], v[180:183], v[96:99]
	v_mfma_f32_16x16x32_bf16 v[76:79], v[206:209], v[192:195], v[76:79]
	v_mfma_f32_16x16x32_bf16 v[72:75], v[214:217], v[192:195], v[72:75]
	s_barrier
	s_setprio 0
	s_mov_b32 m0, s3
	v_lshl_add_u64 v[218:219], s[24:25], 0, v[128:129]
	ds_read_b128 v[160:163], v143 offset:16384
	ds_read_b128 v[164:167], v143 offset:17408
	ds_read_b128 v[168:171], v143 offset:18432
	ds_read_b128 v[172:175], v143 offset:19456
	ds_read_b128 v[176:179], v143 offset:20480
	ds_read_b128 v[180:183], v143 offset:21504
	ds_read_b128 v[188:191], v143 offset:22528
	ds_read_b128 v[192:195], v143 offset:23552
	global_load_lds_dwordx4 v[218:219], off
	v_lshl_add_u64 v[220:221], s[24:25], 0, v[130:131]
	s_mov_b32 m0, s36
	s_nop 0
	global_load_lds_dwordx4 v[220:221], off
	s_setprio 1
	s_waitcnt vmcnt(10)
	s_barrier
	s_waitcnt lgkmcnt(0)
	v_mfma_f32_16x16x32_bf16 v[64:67], v[144:147], v[160:163], v[64:67]
	v_mfma_f32_16x16x32_bf16 v[60:63], v[152:155], v[160:163], v[60:63]
	v_mfma_f32_16x16x32_bf16 v[44:47], v[144:147], v[168:171], v[44:47]
	v_mfma_f32_16x16x32_bf16 v[40:43], v[152:155], v[168:171], v[40:43]
	v_mfma_f32_16x16x32_bf16 v[28:31], v[144:147], v[176:179], v[28:31]
	v_mfma_f32_16x16x32_bf16 v[24:27], v[152:155], v[176:179], v[24:27]
	v_mfma_f32_16x16x32_bf16 v[12:15], v[144:147], v[188:191], v[12:15]
	v_mfma_f32_16x16x32_bf16 v[8:11], v[152:155], v[188:191], v[8:11]
	v_mfma_f32_16x16x32_bf16 v[64:67], v[148:151], v[164:167], v[64:67]
	v_mfma_f32_16x16x32_bf16 v[60:63], v[156:159], v[164:167], v[60:63]
	v_mfma_f32_16x16x32_bf16 v[44:47], v[148:151], v[172:175], v[44:47]
	v_mfma_f32_16x16x32_bf16 v[40:43], v[156:159], v[172:175], v[40:43]
	v_mfma_f32_16x16x32_bf16 v[28:31], v[148:151], v[180:183], v[28:31]
	v_mfma_f32_16x16x32_bf16 v[24:27], v[156:159], v[180:183], v[24:27]
	v_mfma_f32_16x16x32_bf16 v[12:15], v[148:151], v[192:195], v[12:15]
	v_mfma_f32_16x16x32_bf16 v[8:11], v[156:159], v[192:195], v[8:11]
	s_barrier
	s_setprio 0
	v_add_u32_e32 v156, 0x18000, v142
	ds_read_b128 v[144:147], v156
	ds_read_b128 v[148:151], v156 offset:1024
	ds_read_b128 v[152:155], v156 offset:2048
	ds_read_b128 v[156:159], v156 offset:3072
	s_add_u32 s52, s4, 0x80000
	s_addc_u32 s53, s5, 0
	s_add_i32 s51, s54, s35
	v_lshl_add_u64 v[246:247], s[52:53], 0, v[184:185]
	s_mov_b32 m0, s51
	s_nop 0
	global_load_lds_dwordx4 v[246:247], off
	v_lshl_add_u64 v[248:249], s[52:53], 0, v[132:133]
	s_add_i32 m0, s51, 0x2000
	s_nop 0
	global_load_lds_dwordx4 v[248:249], off
	s_waitcnt vmcnt(6)
	s_setprio 1
	s_barrier
	v_mfma_f32_16x16x32_bf16 v[52:55], v[202:205], v[160:163], v[52:55]
	v_mfma_f32_16x16x32_bf16 v[48:51], v[210:213], v[160:163], v[48:51]
	v_mfma_f32_16x16x32_bf16 v[36:39], v[202:205], v[168:171], v[36:39]
	v_mfma_f32_16x16x32_bf16 v[32:35], v[210:213], v[168:171], v[32:35]
	v_mfma_f32_16x16x32_bf16 v[20:23], v[202:205], v[176:179], v[20:23]
	v_mfma_f32_16x16x32_bf16 v[16:19], v[210:213], v[176:179], v[16:19]
	v_mfma_f32_16x16x32_bf16 v[4:7], v[202:205], v[188:191], v[4:7]
	v_mfma_f32_16x16x32_bf16 v[0:3], v[210:213], v[188:191], v[0:3]
	v_mfma_f32_16x16x32_bf16 v[52:55], v[206:209], v[164:167], v[52:55]
	v_mfma_f32_16x16x32_bf16 v[48:51], v[214:217], v[164:167], v[48:51]
	v_mfma_f32_16x16x32_bf16 v[36:39], v[206:209], v[172:175], v[36:39]
	v_mfma_f32_16x16x32_bf16 v[32:35], v[214:217], v[172:175], v[32:35]
	v_mfma_f32_16x16x32_bf16 v[20:23], v[206:209], v[180:183], v[20:23]
	v_mfma_f32_16x16x32_bf16 v[16:19], v[214:217], v[180:183], v[16:19]
	v_mfma_f32_16x16x32_bf16 v[4:7], v[206:209], v[192:195], v[4:7]
	v_mfma_f32_16x16x32_bf16 v[0:3], v[214:217], v[192:195], v[0:3]
	s_barrier
	s_setprio 0
	s_add_i32 s51, 0, 0x18000
	s_add_u32 s24, s24, 0x80000
	s_addc_u32 s25, s25, 0
	s_mov_b32 m0, s37
	v_lshl_add_u64 v[202:203], s[24:25], 0, v[128:129]
	ds_read_b128 v[160:163], v143 offset:32768
	ds_read_b128 v[164:167], v143 offset:33792
	ds_read_b128 v[168:171], v143 offset:34816
	ds_read_b128 v[172:175], v143 offset:35840
	ds_read_b128 v[176:179], v143 offset:36864
	ds_read_b128 v[180:183], v143 offset:37888
	ds_read_b128 v[188:191], v143 offset:38912
	ds_read_b128 v[192:195], v143 offset:39936
	global_load_lds_dwordx4 v[202:203], off
	v_lshl_add_u64 v[202:203], s[24:25], 0, v[130:131]
	s_mov_b32 m0, s38
	s_nop 0
	global_load_lds_dwordx4 v[202:203], off
	s_waitcnt lgkmcnt(8)
	s_setprio 1
	s_barrier
	s_waitcnt lgkmcnt(0)
	v_mfma_f32_16x16x32_bf16 v[124:127], v[144:147], v[160:163], v[124:127]
	v_mfma_f32_16x16x32_bf16 v[68:71], v[152:155], v[160:163], v[68:71]
	v_mfma_f32_16x16x32_bf16 v[116:119], v[144:147], v[168:171], v[116:119]
	v_mfma_f32_16x16x32_bf16 v[88:91], v[152:155], v[168:171], v[88:91]
	v_mfma_f32_16x16x32_bf16 v[108:111], v[144:147], v[176:179], v[108:111]
	v_mfma_f32_16x16x32_bf16 v[104:107], v[152:155], v[176:179], v[104:107]
	v_mfma_f32_16x16x32_bf16 v[92:95], v[144:147], v[188:191], v[92:95]
	v_mfma_f32_16x16x32_bf16 v[84:87], v[152:155], v[188:191], v[84:87]
	v_mfma_f32_16x16x32_bf16 v[124:127], v[148:151], v[164:167], v[124:127]
	v_mfma_f32_16x16x32_bf16 v[68:71], v[156:159], v[164:167], v[68:71]
	v_mfma_f32_16x16x32_bf16 v[116:119], v[148:151], v[172:175], v[116:119]
	v_mfma_f32_16x16x32_bf16 v[88:91], v[156:159], v[172:175], v[88:91]
	v_mfma_f32_16x16x32_bf16 v[108:111], v[148:151], v[180:183], v[108:111]
	v_mfma_f32_16x16x32_bf16 v[104:107], v[156:159], v[180:183], v[104:107]
	v_mfma_f32_16x16x32_bf16 v[92:95], v[148:151], v[192:195], v[92:95]
	v_mfma_f32_16x16x32_bf16 v[84:87], v[156:159], v[192:195], v[84:87]
	s_barrier
	s_setprio 0
	s_add_i32 s24, 0, 0x1c000
	s_add_i32 s25, s51, s35
	v_add_u32_e32 v187, s24, v142
	v_lshl_add_u64 v[138:139], v[138:139], 0, s[56:57]
	s_mov_b32 m0, s25
	ds_read_b128 v[202:205], v187
	ds_read_b128 v[206:209], v187 offset:1024
	ds_read_b128 v[210:213], v187 offset:2048
	ds_read_b128 v[214:217], v187 offset:3072
	global_load_lds_dwordx4 v[138:139], off
	v_lshl_add_u64 v[138:139], v[196:197], 0, s[56:57]
	s_add_i32 m0, s25, 0x2000
	s_nop 0
	global_load_lds_dwordx4 v[138:139], off
	s_setprio 1
	s_barrier
	s_waitcnt lgkmcnt(0)
	v_mfma_f32_16x16x32_bf16 v[120:123], v[202:205], v[160:163], v[120:123]
	v_mfma_f32_16x16x32_bf16 v[56:59], v[210:213], v[160:163], v[56:59]
	v_mfma_f32_16x16x32_bf16 v[112:115], v[202:205], v[168:171], v[112:115]
	v_mfma_f32_16x16x32_bf16 v[80:83], v[210:213], v[168:171], v[80:83]
	v_mfma_f32_16x16x32_bf16 v[100:103], v[202:205], v[176:179], v[100:103]
	v_mfma_f32_16x16x32_bf16 v[96:99], v[210:213], v[176:179], v[96:99]
	v_mfma_f32_16x16x32_bf16 v[76:79], v[202:205], v[188:191], v[76:79]
	v_mfma_f32_16x16x32_bf16 v[72:75], v[210:213], v[188:191], v[72:75]
	v_mfma_f32_16x16x32_bf16 v[120:123], v[206:209], v[164:167], v[120:123]
	v_mfma_f32_16x16x32_bf16 v[56:59], v[214:217], v[164:167], v[56:59]
	v_mfma_f32_16x16x32_bf16 v[112:115], v[206:209], v[172:175], v[112:115]
	v_mfma_f32_16x16x32_bf16 v[80:83], v[214:217], v[172:175], v[80:83]
	v_mfma_f32_16x16x32_bf16 v[100:103], v[206:209], v[180:183], v[100:103]
	v_mfma_f32_16x16x32_bf16 v[96:99], v[214:217], v[180:183], v[96:99]
	v_mfma_f32_16x16x32_bf16 v[76:79], v[206:209], v[192:195], v[76:79]
	v_mfma_f32_16x16x32_bf16 v[72:75], v[214:217], v[192:195], v[72:75]
	s_barrier
	s_setprio 0
	s_mov_b32 m0, s41
	v_lshl_add_u64 v[138:139], v[218:219], 0, s[56:57]
	ds_read_b128 v[160:163], v143 offset:49152
	ds_read_b128 v[164:167], v143 offset:50176
	ds_read_b128 v[168:171], v143 offset:51200
	ds_read_b128 v[172:175], v143 offset:52224
	ds_read_b128 v[176:179], v143 offset:53248
	ds_read_b128 v[180:183], v143 offset:54272
	ds_read_b128 v[188:191], v143 offset:55296
	ds_read_b128 v[192:195], v143 offset:56320
	global_load_lds_dwordx4 v[138:139], off
	v_lshl_add_u64 v[138:139], v[220:221], 0, s[56:57]
	s_mov_b32 m0, s42
	s_nop 0
	global_load_lds_dwordx4 v[138:139], off
	s_setprio 1
	s_waitcnt vmcnt(10)
	s_barrier
	s_waitcnt lgkmcnt(0)
	v_mfma_f32_16x16x32_bf16 v[64:67], v[144:147], v[160:163], v[64:67]
	v_mfma_f32_16x16x32_bf16 v[60:63], v[152:155], v[160:163], v[60:63]
	v_mfma_f32_16x16x32_bf16 v[44:47], v[144:147], v[168:171], v[44:47]
	v_mfma_f32_16x16x32_bf16 v[40:43], v[152:155], v[168:171], v[40:43]
	v_mfma_f32_16x16x32_bf16 v[28:31], v[144:147], v[176:179], v[28:31]
	v_mfma_f32_16x16x32_bf16 v[24:27], v[152:155], v[176:179], v[24:27]
	v_mfma_f32_16x16x32_bf16 v[12:15], v[144:147], v[188:191], v[12:15]
	v_mfma_f32_16x16x32_bf16 v[8:11], v[152:155], v[188:191], v[8:11]
	v_mfma_f32_16x16x32_bf16 v[64:67], v[148:151], v[164:167], v[64:67]
	v_mfma_f32_16x16x32_bf16 v[60:63], v[156:159], v[164:167], v[60:63]
	v_mfma_f32_16x16x32_bf16 v[44:47], v[148:151], v[172:175], v[44:47]
	v_mfma_f32_16x16x32_bf16 v[40:43], v[156:159], v[172:175], v[40:43]
	v_mfma_f32_16x16x32_bf16 v[28:31], v[148:151], v[180:183], v[28:31]
	v_mfma_f32_16x16x32_bf16 v[24:27], v[156:159], v[180:183], v[24:27]
	v_mfma_f32_16x16x32_bf16 v[12:15], v[148:151], v[192:195], v[12:15]
	v_mfma_f32_16x16x32_bf16 v[8:11], v[156:159], v[192:195], v[8:11]
	s_barrier
	s_setprio 0
	v_add_u32_e32 v156, 0x10000, v142
	ds_read_b128 v[144:147], v156
	ds_read_b128 v[148:151], v156 offset:1024
	ds_read_b128 v[152:155], v156 offset:2048
	ds_read_b128 v[156:159], v156 offset:3072
	s_add_u32 s4, s4, 0x80080
	s_addc_u32 s5, s5, 0
	s_add_i32 s24, s24, s35
	v_lshl_add_u64 v[138:139], s[4:5], 0, v[184:185]
	s_mov_b32 m0, s24
	s_nop 0
	global_load_lds_dwordx4 v[138:139], off
	v_lshl_add_u64 v[138:139], s[4:5], 0, v[132:133]
	s_add_i32 m0, s24, 0x2000
	s_nop 0
	global_load_lds_dwordx4 v[138:139], off
	s_waitcnt vmcnt(6)
	s_setprio 1
	s_barrier
	v_mfma_f32_16x16x32_bf16 v[52:55], v[202:205], v[160:163], v[52:55]
	v_mfma_f32_16x16x32_bf16 v[48:51], v[210:213], v[160:163], v[48:51]
	v_mfma_f32_16x16x32_bf16 v[36:39], v[202:205], v[168:171], v[36:39]
	v_mfma_f32_16x16x32_bf16 v[32:35], v[210:213], v[168:171], v[32:35]
	v_mfma_f32_16x16x32_bf16 v[20:23], v[202:205], v[176:179], v[20:23]
	v_mfma_f32_16x16x32_bf16 v[16:19], v[210:213], v[176:179], v[16:19]
	v_mfma_f32_16x16x32_bf16 v[4:7], v[202:205], v[188:191], v[4:7]
	v_mfma_f32_16x16x32_bf16 v[0:3], v[210:213], v[188:191], v[0:3]
	v_mfma_f32_16x16x32_bf16 v[52:55], v[206:209], v[164:167], v[52:55]
	v_mfma_f32_16x16x32_bf16 v[48:51], v[214:217], v[164:167], v[48:51]
	v_mfma_f32_16x16x32_bf16 v[36:39], v[206:209], v[172:175], v[36:39]
	v_mfma_f32_16x16x32_bf16 v[32:35], v[214:217], v[172:175], v[32:35]
	v_mfma_f32_16x16x32_bf16 v[20:23], v[206:209], v[180:183], v[20:23]
	v_mfma_f32_16x16x32_bf16 v[16:19], v[214:217], v[180:183], v[16:19]
	v_mfma_f32_16x16x32_bf16 v[4:7], v[206:209], v[192:195], v[4:7]
	v_mfma_f32_16x16x32_bf16 v[0:3], v[214:217], v[192:195], v[0:3]
	s_barrier
	s_setprio 0
	s_add_i32 s50, s50, 2
	s_add_u32 s0, s0, 0x100
	s_addc_u32 s1, s1, 0
	s_add_u32 s48, s48, 0x100
	s_addc_u32 s49, s49, 0
	s_cmp_gt_u32 s50, 29
	s_cbranch_scc0 .LBB0_334
	s_waitcnt lgkmcnt(0)
	v_mul_f32_e32 v148, 0x3d372713, v125
	v_fma_f32 v148, v125, v148, 1.0
	v_mul_f32_e32 v148, v125, v148
	v_mul_f32_e32 v139, 0x3d372713, v124
	v_mul_f32_e32 v148, 0xc0135761, v148
	v_fma_f32 v139, v124, v139, 1.0
	v_exp_f32_e32 v148, v148
	v_mul_f32_e32 v149, 0x3d372713, v126
	v_mul_f32_e32 v139, v124, v139
	v_fma_f32 v149, v126, v149, 1.0
	v_mul_f32_e32 v139, 0xc0135761, v139
	v_mul_f32_e32 v149, v126, v149
	v_exp_f32_e32 v145, v139
	v_mul_f32_e32 v149, 0xc0135761, v149
	v_exp_f32_e32 v149, v149
	v_add_f32_e32 v148, 1.0, v148
	v_mul_f32_e32 v150, 0x3d372713, v127
	v_rcp_f32_e32 v148, v148
	v_fma_f32 v150, v127, v150, 1.0
	v_mul_f32_e32 v150, v127, v150
	v_add_f32_e32 v145, 1.0, v145
	v_mul_f32_e32 v150, 0xc0135761, v150
	v_rcp_f32_e32 v145, v145
	v_add_f32_e32 v149, 1.0, v149
	v_exp_f32_e32 v150, v150
	v_rcp_f32_e32 v149, v149
	v_mul_f32_e32 v125, v125, v148
	v_mul_f32_e32 v148, 0x3d372713, v68
	v_fma_f32 v148, v68, v148, 1.0
	v_mul_f32_e32 v148, v68, v148
	v_mul_f32_e32 v124, v124, v145
	v_add_f32_e32 v145, 1.0, v150
	v_mul_f32_e32 v148, 0xc0135761, v148
	v_mul_f32_e32 v126, v126, v149
	v_rcp_f32_e32 v145, v145
	v_exp_f32_e32 v148, v148
	v_mul_f32_e32 v149, 0x3d372713, v69
	v_fma_f32 v149, v69, v149, 1.0
	v_mul_f32_e32 v149, v69, v149
	v_mul_f32_e32 v149, 0xc0135761, v149
	v_exp_f32_e32 v149, v149
	v_mul_f32_e32 v127, v127, v145
	v_add_f32_e32 v145, 1.0, v148
	v_rcp_f32_e32 v145, v145
	v_mov_b32_e32 v138, v141
	v_mov_b32_e32 v144, v140
	s_lshl_b32 s0, s2, 8
	v_add_f32_e32 v148, 1.0, v149
	s_add_i32 s0, s0, s39
	v_mul_f32_e32 v149, 0x3d372713, v70
	v_rcp_f32_e32 v148, v148
	v_mul_f32_e32 v145, v68, v145
	v_cvt_pk_bf16_f32 v68, v124, v125
	v_mul_f32_e32 v124, 0x3d372713, v120
	v_add_u32_e32 v146, s0, v144
	s_lshl_b32 s0, s45, 8
	v_fma_f32 v149, v70, v149, 1.0
	v_fma_f32 v124, v120, v124, 1.0
	s_or_b32 s0, s0, s40
	v_ashrrev_i32_e32 v147, 31, v146
	v_mul_f32_e32 v149, v70, v149
	v_mul_f32_e32 v124, v120, v124
	v_lshl_add_u32 v138, v138, 3, s0
	v_lshlrev_b64 v[146:147], 16, v[146:147]
	v_mul_f32_e32 v149, 0xc0135761, v149
	v_mul_f32_e32 v124, 0xc0135761, v124
	v_ashrrev_i32_e32 v139, 31, v138
	v_exp_f32_e32 v149, v149
	v_mul_f32_e32 v148, v69, v148
	v_cvt_pk_bf16_f32 v69, v126, v127
	v_exp_f32_e32 v126, v124
	v_lshl_add_u64 v[124:125], s[8:9], 0, v[146:147]
	v_lshl_add_u64 v[124:125], v[138:139], 1, v[124:125]
	v_mul_f32_e32 v127, 0x3d372713, v121
	v_mul_f32_e32 v139, 0x3d372713, v122
	v_fma_f32 v127, v121, v127, 1.0
	v_fma_f32 v139, v122, v139, 1.0
	v_mul_f32_e32 v127, v121, v127
	v_mul_f32_e32 v139, v122, v139
	v_add_f32_e32 v149, 1.0, v149
	v_mul_f32_e32 v127, 0xc0135761, v127
	v_mul_f32_e32 v139, 0xc0135761, v139
	v_rcp_f32_e32 v149, v149
	v_exp_f32_e32 v127, v127
	v_exp_f32_e32 v139, v139
	v_add_f32_e32 v126, 1.0, v126
	v_mul_f32_e32 v149, v70, v149
	v_cvt_pk_bf16_f32 v70, v145, v148
	v_add_f32_e32 v127, 1.0, v127
	v_add_f32_e32 v139, 1.0, v139
	v_mul_f32_e32 v145, 0x3d372713, v123
	v_rcp_f32_e32 v127, v127
	v_rcp_f32_e32 v139, v139
	v_fma_f32 v145, v123, v145, 1.0
	v_mul_f32_e32 v145, v123, v145
	v_mul_f32_e32 v145, 0xc0135761, v145
	v_rcp_f32_e32 v126, v126
	v_exp_f32_e32 v145, v145
	v_mul_f32_e32 v121, v121, v127
	v_mul_f32_e32 v122, v122, v139
	v_mul_f32_e32 v127, 0x3d372713, v56
	v_mul_f32_e32 v139, 0x3d372713, v57
	v_fma_f32 v127, v56, v127, 1.0
	v_fma_f32 v139, v57, v139, 1.0
	v_mul_f32_e32 v127, v56, v127
	v_mul_f32_e32 v139, v57, v139
	v_mul_f32_e32 v120, v120, v126
	v_add_f32_e32 v126, 1.0, v145
	v_mul_f32_e32 v127, 0xc0135761, v127
	v_mul_f32_e32 v139, 0xc0135761, v139
	v_mul_f32_e32 v150, 0x3d372713, v71
	v_rcp_f32_e32 v126, v126
	v_exp_f32_e32 v127, v127
	v_exp_f32_e32 v139, v139
	v_fma_f32 v150, v71, v150, 1.0
	v_mul_f32_e32 v150, v71, v150
	v_mul_f32_e32 v150, 0xc0135761, v150
	v_exp_f32_e32 v150, v150
	v_mul_f32_e32 v123, v123, v126
	v_add_f32_e32 v126, 1.0, v127
	v_add_f32_e32 v127, 1.0, v139
	v_mul_f32_e32 v139, 0x3d372713, v58
	v_fma_f32 v139, v58, v139, 1.0
	v_mul_f32_e32 v139, v58, v139
	v_mul_f32_e32 v139, 0xc0135761, v139
	v_add_f32_e32 v150, 1.0, v150
	v_exp_f32_e32 v139, v139
	v_rcp_f32_e32 v150, v150
	v_rcp_f32_e32 v126, v126
	v_rcp_f32_e32 v127, v127
	v_add_f32_e32 v139, 1.0, v139
	v_mul_f32_e32 v71, v71, v150
	v_rcp_f32_e32 v139, v139
	v_cvt_pk_bf16_f32 v71, v149, v71
	global_store_dwordx4 v[124:125], v[68:71], off
	v_mul_f32_e32 v126, v56, v126
	v_mul_f32_e32 v127, v57, v127
	v_cvt_pk_bf16_f32 v56, v120, v121
	v_cvt_pk_bf16_f32 v57, v122, v123
	v_mul_f32_e32 v121, 0x3d372713, v117
	v_mul_f32_e32 v122, 0x3d372713, v118
	v_fma_f32 v121, v117, v121, 1.0
	v_fma_f32 v122, v118, v122, 1.0
	v_mul_f32_e32 v121, v117, v121
	v_mul_f32_e32 v122, v118, v122
	v_mul_f32_e32 v139, v58, v139
	v_mul_f32_e32 v58, 0x3d372713, v116
	v_mul_f32_e32 v121, 0xc0135761, v121
	v_mul_f32_e32 v122, 0xc0135761, v122
	v_fma_f32 v58, v116, v58, 1.0
	v_exp_f32_e32 v121, v121
	v_exp_f32_e32 v122, v122
	v_mul_f32_e32 v58, v116, v58
	v_mul_f32_e32 v58, 0xc0135761, v58
	v_exp_f32_e32 v120, v58
	v_add_f32_e32 v121, 1.0, v121
	v_add_f32_e32 v122, 1.0, v122
	v_mul_f32_e32 v123, 0x3d372713, v119
	v_rcp_f32_e32 v121, v121
	v_rcp_f32_e32 v122, v122
	v_fma_f32 v123, v119, v123, 1.0
	v_mul_f32_e32 v123, v119, v123
	v_add_f32_e32 v120, 1.0, v120
	v_mul_f32_e32 v123, 0xc0135761, v123
	v_rcp_f32_e32 v120, v120
	v_exp_f32_e32 v123, v123
	v_mul_f32_e32 v117, v117, v121
	v_mul_f32_e32 v118, v118, v122
	v_mul_f32_e32 v121, 0x3d372713, v88
	v_mul_f32_e32 v122, 0x3d372713, v89
	v_fma_f32 v121, v88, v121, 1.0
	v_fma_f32 v122, v89, v122, 1.0
	v_mul_f32_e32 v121, v88, v121
	v_mul_f32_e32 v122, v89, v122
	v_mul_f32_e32 v145, 0x3d372713, v59
	v_mul_f32_e32 v116, v116, v120
	v_add_f32_e32 v120, 1.0, v123
	v_mul_f32_e32 v121, 0xc0135761, v121
	v_mul_f32_e32 v122, 0xc0135761, v122
	v_fma_f32 v145, v59, v145, 1.0
	v_rcp_f32_e32 v120, v120
	v_exp_f32_e32 v121, v121
	v_exp_f32_e32 v122, v122
	v_mul_f32_e32 v145, v59, v145
	v_mul_f32_e32 v145, 0xc0135761, v145
	v_exp_f32_e32 v145, v145
	v_mul_f32_e32 v119, v119, v120
	v_add_f32_e32 v120, 1.0, v121
	v_add_f32_e32 v121, 1.0, v122
	v_mul_f32_e32 v122, 0x3d372713, v90
	v_fma_f32 v122, v90, v122, 1.0
	v_mul_f32_e32 v122, v90, v122
	v_add_f32_e32 v145, 1.0, v145
	v_mul_f32_e32 v122, 0xc0135761, v122
	v_mul_f32_e32 v123, 0x3d372713, v91
	v_rcp_f32_e32 v145, v145
	v_exp_f32_e32 v122, v122
	v_fma_f32 v123, v91, v123, 1.0
	v_rcp_f32_e32 v120, v120
	v_mul_f32_e32 v123, v91, v123
	v_rcp_f32_e32 v121, v121
	v_mul_f32_e32 v123, 0xc0135761, v123
	v_exp_f32_e32 v123, v123
	v_mul_f32_e32 v59, v59, v145
	v_add_f32_e32 v122, 1.0, v122
	v_cvt_pk_bf16_f32 v58, v126, v127
	v_cvt_pk_bf16_f32 v59, v139, v59
	global_store_dwordx4 v[124:125], v[56:59], off offset:256
	v_rcp_f32_e32 v122, v122
	v_mul_f32_e32 v120, v88, v120
	v_mul_f32_e32 v121, v89, v121
	v_cvt_pk_bf16_f32 v88, v116, v117
	v_cvt_pk_bf16_f32 v89, v118, v119
	v_mul_f32_e32 v118, 0x3d372713, v112
	v_fma_f32 v118, v112, v118, 1.0
	v_add_f32_e32 v123, 1.0, v123
	v_mul_f32_e32 v118, v112, v118
	v_rcp_f32_e32 v123, v123
	v_mul_f32_e32 v118, 0xc0135761, v118
	v_mul_f32_e32 v122, v90, v122
	v_cvt_pk_bf16_f32 v90, v120, v121
	s_mov_b64 s[0:1], 0x100000
	v_exp_f32_e32 v120, v118
	v_lshl_add_u64 v[116:117], v[124:125], 0, s[0:1]
	s_mov_b32 s0, 0x100000
	v_add_co_u32_e32 v118, vcc, s0, v124
	v_mul_f32_e32 v91, v91, v123
	s_nop 0
	v_addc_co_u32_e32 v119, vcc, 0, v125, vcc
	v_cvt_pk_bf16_f32 v91, v122, v91
	global_store_dwordx4 v[118:119], v[88:91], off
	v_add_f32_e32 v118, 1.0, v120
	v_mul_f32_e32 v119, 0x3d372713, v113
	v_mul_f32_e32 v120, 0x3d372713, v114
	v_fma_f32 v119, v113, v119, 1.0
	v_fma_f32 v120, v114, v120, 1.0
	v_mul_f32_e32 v119, v113, v119
	v_mul_f32_e32 v120, v114, v120
	v_mul_f32_e32 v119, 0xc0135761, v119
	v_mul_f32_e32 v120, 0xc0135761, v120
	v_exp_f32_e32 v119, v119
	v_exp_f32_e32 v120, v120
	v_mul_f32_e32 v121, 0x3d372713, v115
	v_fma_f32 v121, v115, v121, 1.0
	v_add_f32_e32 v119, 1.0, v119
	v_add_f32_e32 v120, 1.0, v120
	v_rcp_f32_e32 v119, v119
	v_rcp_f32_e32 v120, v120
	v_mul_f32_e32 v121, v115, v121
	v_mul_f32_e32 v121, 0xc0135761, v121
	v_rcp_f32_e32 v118, v118
	v_exp_f32_e32 v121, v121
	v_mul_f32_e32 v113, v113, v119
	v_mul_f32_e32 v114, v114, v120
	v_mul_f32_e32 v119, 0x3d372713, v80
	v_mul_f32_e32 v120, 0x3d372713, v81
	v_fma_f32 v119, v80, v119, 1.0
	v_fma_f32 v120, v81, v120, 1.0
	v_mul_f32_e32 v119, v80, v119
	v_mul_f32_e32 v120, v81, v120
	v_mul_f32_e32 v112, v112, v118
	v_add_f32_e32 v118, 1.0, v121
	v_mul_f32_e32 v119, 0xc0135761, v119
	v_mul_f32_e32 v120, 0xc0135761, v120
	v_rcp_f32_e32 v118, v118
	v_exp_f32_e32 v119, v119
	v_exp_f32_e32 v120, v120
	v_mul_f32_e32 v121, 0x3d372713, v83
	v_mul_f32_e32 v115, v115, v118
	v_add_f32_e32 v118, 1.0, v119
	v_add_f32_e32 v119, 1.0, v120
	v_mul_f32_e32 v120, 0x3d372713, v82
	v_fma_f32 v120, v82, v120, 1.0
	v_mul_f32_e32 v120, v82, v120
	v_mul_f32_e32 v120, 0xc0135761, v120
	v_exp_f32_e32 v120, v120
	v_rcp_f32_e32 v118, v118
	v_rcp_f32_e32 v119, v119
	v_fma_f32 v121, v83, v121, 1.0
	v_add_f32_e32 v120, 1.0, v120
	v_rcp_f32_e32 v120, v120
	v_mul_f32_e32 v118, v80, v118
	v_mul_f32_e32 v119, v81, v119
	v_cvt_pk_bf16_f32 v80, v112, v113
	v_cvt_pk_bf16_f32 v81, v114, v115
	v_mul_f32_e32 v113, 0x3d372713, v109
	v_mul_f32_e32 v114, 0x3d372713, v110
	v_fma_f32 v113, v109, v113, 1.0
	v_fma_f32 v114, v110, v114, 1.0
	v_mul_f32_e32 v113, v109, v113
	v_mul_f32_e32 v114, v110, v114
	v_mul_f32_e32 v120, v82, v120
	v_mul_f32_e32 v82, 0x3d372713, v108
	v_mul_f32_e32 v113, 0xc0135761, v113
	v_mul_f32_e32 v114, 0xc0135761, v114
	v_fma_f32 v82, v108, v82, 1.0
	v_exp_f32_e32 v113, v113
	v_exp_f32_e32 v114, v114
	v_mul_f32_e32 v82, v108, v82
	v_mul_f32_e32 v82, 0xc0135761, v82
	v_exp_f32_e32 v112, v82
	v_add_f32_e32 v113, 1.0, v113
	v_add_f32_e32 v114, 1.0, v114
	v_mul_f32_e32 v115, 0x3d372713, v111
	v_rcp_f32_e32 v113, v113
	v_rcp_f32_e32 v114, v114
	v_fma_f32 v115, v111, v115, 1.0
	v_mul_f32_e32 v115, v111, v115
	v_add_f32_e32 v112, 1.0, v112
	v_mul_f32_e32 v115, 0xc0135761, v115
	v_rcp_f32_e32 v112, v112
	v_exp_f32_e32 v115, v115
	v_mul_f32_e32 v109, v109, v113
	v_mul_f32_e32 v110, v110, v114
	v_mul_f32_e32 v113, 0x3d372713, v104
	v_mul_f32_e32 v114, 0x3d372713, v105
	v_fma_f32 v113, v104, v113, 1.0
	v_fma_f32 v114, v105, v114, 1.0
	v_mul_f32_e32 v113, v104, v113
	v_mul_f32_e32 v114, v105, v114
	v_mul_f32_e32 v108, v108, v112
	v_add_f32_e32 v112, 1.0, v115
	v_mul_f32_e32 v113, 0xc0135761, v113
	v_mul_f32_e32 v114, 0xc0135761, v114
	v_rcp_f32_e32 v112, v112
	v_exp_f32_e32 v113, v113
	v_exp_f32_e32 v114, v114
	v_mul_f32_e32 v121, v83, v121
	v_mul_f32_e32 v121, 0xc0135761, v121
	v_exp_f32_e32 v121, v121
	v_mul_f32_e32 v111, v111, v112
	v_add_f32_e32 v112, 1.0, v113
	v_add_f32_e32 v113, 1.0, v114
	v_mul_f32_e32 v114, 0x3d372713, v106
	v_fma_f32 v114, v106, v114, 1.0
	v_mul_f32_e32 v114, v106, v114
	v_add_f32_e32 v121, 1.0, v121
	v_mul_f32_e32 v114, 0xc0135761, v114
	v_mul_f32_e32 v115, 0x3d372713, v107
	v_rcp_f32_e32 v121, v121
	v_exp_f32_e32 v114, v114
	v_fma_f32 v115, v107, v115, 1.0
	v_rcp_f32_e32 v112, v112
	v_mul_f32_e32 v115, v107, v115
	v_rcp_f32_e32 v113, v113
	v_mul_f32_e32 v115, 0xc0135761, v115
	v_exp_f32_e32 v115, v115
	v_mul_f32_e32 v83, v83, v121
	v_add_f32_e32 v114, 1.0, v114
	v_cvt_pk_bf16_f32 v82, v118, v119
	v_cvt_pk_bf16_f32 v83, v120, v83
	global_store_dwordx4 v[116:117], v[80:83], off offset:256
	v_rcp_f32_e32 v114, v114
	v_mul_f32_e32 v112, v104, v112
	v_mul_f32_e32 v113, v105, v113
	v_cvt_pk_bf16_f32 v104, v108, v109
	v_cvt_pk_bf16_f32 v105, v110, v111
	v_mul_f32_e32 v110, 0x3d372713, v100
	v_fma_f32 v110, v100, v110, 1.0
	v_add_f32_e32 v115, 1.0, v115
	v_mul_f32_e32 v110, v100, v110
	v_rcp_f32_e32 v115, v115
	v_mul_f32_e32 v110, 0xc0135761, v110
	v_mul_f32_e32 v114, v106, v114
	v_cvt_pk_bf16_f32 v106, v112, v113
	s_mov_b64 s[0:1], 0x200000
	v_exp_f32_e32 v112, v110
	v_lshl_add_u64 v[108:109], v[124:125], 0, s[0:1]
	s_mov_b32 s0, 0x200000
	v_add_co_u32_e32 v110, vcc, s0, v124
	v_mul_f32_e32 v107, v107, v115
	s_nop 0
	v_addc_co_u32_e32 v111, vcc, 0, v125, vcc
	v_cvt_pk_bf16_f32 v107, v114, v107
	global_store_dwordx4 v[110:111], v[104:107], off
	v_add_f32_e32 v110, 1.0, v112
	v_mul_f32_e32 v111, 0x3d372713, v101
	v_mul_f32_e32 v112, 0x3d372713, v102
	v_fma_f32 v111, v101, v111, 1.0
	v_fma_f32 v112, v102, v112, 1.0
	v_mul_f32_e32 v111, v101, v111
	v_mul_f32_e32 v112, v102, v112
	v_mul_f32_e32 v111, 0xc0135761, v111
	v_mul_f32_e32 v112, 0xc0135761, v112
	v_exp_f32_e32 v111, v111
	v_exp_f32_e32 v112, v112
	v_mul_f32_e32 v113, 0x3d372713, v103
	v_fma_f32 v113, v103, v113, 1.0
	v_add_f32_e32 v111, 1.0, v111
	v_add_f32_e32 v112, 1.0, v112
	v_rcp_f32_e32 v111, v111
	v_rcp_f32_e32 v112, v112
	v_mul_f32_e32 v113, v103, v113
	v_mul_f32_e32 v113, 0xc0135761, v113
	v_rcp_f32_e32 v110, v110
	v_exp_f32_e32 v113, v113
	v_mul_f32_e32 v101, v101, v111
	v_mul_f32_e32 v102, v102, v112
	v_mul_f32_e32 v111, 0x3d372713, v96
	v_mul_f32_e32 v112, 0x3d372713, v97
	v_fma_f32 v111, v96, v111, 1.0
	v_fma_f32 v112, v97, v112, 1.0
	v_mul_f32_e32 v111, v96, v111
	v_mul_f32_e32 v112, v97, v112
	v_mul_f32_e32 v100, v100, v110
	v_add_f32_e32 v110, 1.0, v113
	v_mul_f32_e32 v111, 0xc0135761, v111
	v_mul_f32_e32 v112, 0xc0135761, v112
	v_rcp_f32_e32 v110, v110
	v_exp_f32_e32 v111, v111
	v_exp_f32_e32 v112, v112
	v_mul_f32_e32 v113, 0x3d372713, v99
	v_mul_f32_e32 v103, v103, v110
	v_add_f32_e32 v110, 1.0, v111
	v_add_f32_e32 v111, 1.0, v112
	v_mul_f32_e32 v112, 0x3d372713, v98
	v_fma_f32 v112, v98, v112, 1.0
	v_mul_f32_e32 v112, v98, v112
	v_mul_f32_e32 v112, 0xc0135761, v112
	v_exp_f32_e32 v112, v112
	v_rcp_f32_e32 v110, v110
	v_rcp_f32_e32 v111, v111
	v_fma_f32 v113, v99, v113, 1.0
	v_add_f32_e32 v112, 1.0, v112
	v_rcp_f32_e32 v112, v112
	v_mul_f32_e32 v110, v96, v110
	v_mul_f32_e32 v111, v97, v111
	v_cvt_pk_bf16_f32 v96, v100, v101
	v_cvt_pk_bf16_f32 v97, v102, v103
	v_mul_f32_e32 v101, 0x3d372713, v93
	v_mul_f32_e32 v102, 0x3d372713, v94
	v_fma_f32 v101, v93, v101, 1.0
	v_fma_f32 v102, v94, v102, 1.0
	v_mul_f32_e32 v101, v93, v101
	v_mul_f32_e32 v102, v94, v102
	v_mul_f32_e32 v112, v98, v112
	v_mul_f32_e32 v98, 0x3d372713, v92
	v_mul_f32_e32 v101, 0xc0135761, v101
	v_mul_f32_e32 v102, 0xc0135761, v102
	v_fma_f32 v98, v92, v98, 1.0
	v_exp_f32_e32 v101, v101
	v_exp_f32_e32 v102, v102
	v_mul_f32_e32 v98, v92, v98
	v_mul_f32_e32 v98, 0xc0135761, v98
	v_exp_f32_e32 v100, v98
	v_add_f32_e32 v101, 1.0, v101
	v_add_f32_e32 v102, 1.0, v102
	v_mul_f32_e32 v103, 0x3d372713, v95
	v_rcp_f32_e32 v101, v101
	v_rcp_f32_e32 v102, v102
	v_fma_f32 v103, v95, v103, 1.0
	v_mul_f32_e32 v103, v95, v103
	v_add_f32_e32 v100, 1.0, v100
	v_mul_f32_e32 v103, 0xc0135761, v103
	v_rcp_f32_e32 v100, v100
	v_exp_f32_e32 v103, v103
	v_mul_f32_e32 v93, v93, v101
	v_mul_f32_e32 v94, v94, v102
	v_mul_f32_e32 v101, 0x3d372713, v84
	v_mul_f32_e32 v102, 0x3d372713, v85
	v_fma_f32 v101, v84, v101, 1.0
	v_fma_f32 v102, v85, v102, 1.0
	v_mul_f32_e32 v101, v84, v101
	v_mul_f32_e32 v102, v85, v102
	v_mul_f32_e32 v92, v92, v100
	v_add_f32_e32 v100, 1.0, v103
	v_mul_f32_e32 v101, 0xc0135761, v101
	v_mul_f32_e32 v102, 0xc0135761, v102
	v_rcp_f32_e32 v100, v100
	v_exp_f32_e32 v101, v101
	v_exp_f32_e32 v102, v102
	v_mul_f32_e32 v113, v99, v113
	v_mul_f32_e32 v113, 0xc0135761, v113
	v_exp_f32_e32 v113, v113
	v_mul_f32_e32 v95, v95, v100
	v_add_f32_e32 v100, 1.0, v101
	v_add_f32_e32 v101, 1.0, v102
	v_mul_f32_e32 v102, 0x3d372713, v86
	v_fma_f32 v102, v86, v102, 1.0
	v_mul_f32_e32 v102, v86, v102
	v_add_f32_e32 v113, 1.0, v113
	v_mul_f32_e32 v102, 0xc0135761, v102
	v_mul_f32_e32 v103, 0x3d372713, v87
	v_rcp_f32_e32 v113, v113
	v_exp_f32_e32 v102, v102
	v_fma_f32 v103, v87, v103, 1.0
	v_rcp_f32_e32 v100, v100
	v_mul_f32_e32 v103, v87, v103
	v_rcp_f32_e32 v101, v101
	v_mul_f32_e32 v103, 0xc0135761, v103
	v_exp_f32_e32 v103, v103
	v_mul_f32_e32 v99, v99, v113
	v_add_f32_e32 v102, 1.0, v102
	v_cvt_pk_bf16_f32 v98, v110, v111
	v_cvt_pk_bf16_f32 v99, v112, v99
	global_store_dwordx4 v[108:109], v[96:99], off offset:256
	v_rcp_f32_e32 v102, v102
	v_mul_f32_e32 v100, v84, v100
	v_mul_f32_e32 v101, v85, v101
	v_cvt_pk_bf16_f32 v84, v92, v93
	v_cvt_pk_bf16_f32 v85, v94, v95
	v_mul_f32_e32 v94, 0x3d372713, v76
	v_fma_f32 v94, v76, v94, 1.0
	v_add_f32_e32 v103, 1.0, v103
	v_mul_f32_e32 v94, v76, v94
	v_rcp_f32_e32 v103, v103
	v_mul_f32_e32 v94, 0xc0135761, v94
	v_mul_f32_e32 v102, v86, v102
	v_cvt_pk_bf16_f32 v86, v100, v101
	s_mov_b64 s[0:1], 0x300000
	v_exp_f32_e32 v100, v94
	v_lshl_add_u64 v[92:93], v[124:125], 0, s[0:1]
	s_mov_b32 s0, 0x300000
	v_add_co_u32_e32 v94, vcc, s0, v124
	v_mul_f32_e32 v87, v87, v103
	s_nop 0
	v_addc_co_u32_e32 v95, vcc, 0, v125, vcc
	v_cvt_pk_bf16_f32 v87, v102, v87
	global_store_dwordx4 v[94:95], v[84:87], off
	v_add_f32_e32 v94, 1.0, v100
	v_mul_f32_e32 v95, 0x3d372713, v77
	v_mul_f32_e32 v100, 0x3d372713, v78
	v_fma_f32 v95, v77, v95, 1.0
	v_fma_f32 v100, v78, v100, 1.0
	v_mul_f32_e32 v95, v77, v95
	v_mul_f32_e32 v100, v78, v100
	v_mul_f32_e32 v95, 0xc0135761, v95
	v_mul_f32_e32 v100, 0xc0135761, v100
	v_exp_f32_e32 v95, v95
	v_exp_f32_e32 v100, v100
	v_mul_f32_e32 v101, 0x3d372713, v79
	v_fma_f32 v101, v79, v101, 1.0
	v_add_f32_e32 v95, 1.0, v95
	v_add_f32_e32 v100, 1.0, v100
	v_rcp_f32_e32 v95, v95
	v_rcp_f32_e32 v100, v100
	v_mul_f32_e32 v101, v79, v101
	v_mul_f32_e32 v101, 0xc0135761, v101
	v_rcp_f32_e32 v94, v94
	v_exp_f32_e32 v101, v101
	v_mul_f32_e32 v77, v77, v95
	v_mul_f32_e32 v78, v78, v100
	v_mul_f32_e32 v95, 0x3d372713, v72
	v_mul_f32_e32 v100, 0x3d372713, v73
	v_fma_f32 v95, v72, v95, 1.0
	v_fma_f32 v100, v73, v100, 1.0
	v_mul_f32_e32 v95, v72, v95
	v_mul_f32_e32 v100, v73, v100
	v_mul_f32_e32 v76, v76, v94
	v_add_f32_e32 v94, 1.0, v101
	v_mul_f32_e32 v95, 0xc0135761, v95
	v_mul_f32_e32 v100, 0xc0135761, v100
	v_rcp_f32_e32 v94, v94
	v_exp_f32_e32 v95, v95
	v_exp_f32_e32 v100, v100
	v_mul_f32_e32 v101, 0x3d372713, v75
	v_mul_f32_e32 v79, v79, v94
	v_add_f32_e32 v94, 1.0, v95
	v_add_f32_e32 v95, 1.0, v100
	v_mul_f32_e32 v100, 0x3d372713, v74
	v_fma_f32 v100, v74, v100, 1.0
	v_mul_f32_e32 v100, v74, v100
	v_mul_f32_e32 v100, 0xc0135761, v100
	v_exp_f32_e32 v100, v100
	v_rcp_f32_e32 v94, v94
	v_rcp_f32_e32 v95, v95
	v_fma_f32 v101, v75, v101, 1.0
	v_add_f32_e32 v100, 1.0, v100
	v_rcp_f32_e32 v100, v100
	v_mul_f32_e32 v94, v72, v94
	v_mul_f32_e32 v95, v73, v95
	v_cvt_pk_bf16_f32 v72, v76, v77
	v_cvt_pk_bf16_f32 v73, v78, v79
	v_mul_f32_e32 v77, 0x3d372713, v65
	v_mul_f32_e32 v78, 0x3d372713, v66
	v_fma_f32 v77, v65, v77, 1.0
	v_fma_f32 v78, v66, v78, 1.0
	v_mul_f32_e32 v77, v65, v77
	v_mul_f32_e32 v78, v66, v78
	v_mul_f32_e32 v100, v74, v100
	v_mul_f32_e32 v74, 0x3d372713, v64
	v_mul_f32_e32 v77, 0xc0135761, v77
	v_mul_f32_e32 v78, 0xc0135761, v78
	v_fma_f32 v74, v64, v74, 1.0
	v_exp_f32_e32 v77, v77
	v_exp_f32_e32 v78, v78
	v_mul_f32_e32 v74, v64, v74
	v_mul_f32_e32 v74, 0xc0135761, v74
	v_exp_f32_e32 v76, v74
	v_add_f32_e32 v77, 1.0, v77
	v_add_f32_e32 v78, 1.0, v78
	v_mul_f32_e32 v79, 0x3d372713, v67
	v_rcp_f32_e32 v77, v77
	v_rcp_f32_e32 v78, v78
	v_fma_f32 v79, v67, v79, 1.0
	v_mul_f32_e32 v79, v67, v79
	v_add_f32_e32 v76, 1.0, v76
	v_mul_f32_e32 v79, 0xc0135761, v79
	v_rcp_f32_e32 v76, v76
	v_exp_f32_e32 v79, v79
	v_mul_f32_e32 v65, v65, v77
	v_mul_f32_e32 v66, v66, v78
	v_mul_f32_e32 v77, 0x3d372713, v60
	v_mul_f32_e32 v78, 0x3d372713, v61
	v_fma_f32 v77, v60, v77, 1.0
	v_fma_f32 v78, v61, v78, 1.0
	v_mul_f32_e32 v77, v60, v77
	v_mul_f32_e32 v78, v61, v78
	v_mul_f32_e32 v64, v64, v76
	v_add_f32_e32 v76, 1.0, v79
	v_mul_f32_e32 v77, 0xc0135761, v77
	v_mul_f32_e32 v78, 0xc0135761, v78
	v_rcp_f32_e32 v76, v76
	v_exp_f32_e32 v77, v77
	v_exp_f32_e32 v78, v78
	v_mul_f32_e32 v101, v75, v101
	v_mul_f32_e32 v101, 0xc0135761, v101
	v_exp_f32_e32 v101, v101
	v_mul_f32_e32 v67, v67, v76
	v_add_f32_e32 v76, 1.0, v77
	v_add_f32_e32 v77, 1.0, v78
	v_mul_f32_e32 v78, 0x3d372713, v62
	v_fma_f32 v78, v62, v78, 1.0
	v_mul_f32_e32 v78, v62, v78
	v_add_f32_e32 v101, 1.0, v101
	v_mul_f32_e32 v78, 0xc0135761, v78
	v_mul_f32_e32 v79, 0x3d372713, v63
	v_rcp_f32_e32 v101, v101
	v_exp_f32_e32 v78, v78
	v_fma_f32 v79, v63, v79, 1.0
	v_rcp_f32_e32 v76, v76
	v_mul_f32_e32 v79, v63, v79
	v_rcp_f32_e32 v77, v77
	v_mul_f32_e32 v79, 0xc0135761, v79
	v_exp_f32_e32 v79, v79
	v_mul_f32_e32 v75, v75, v101
	v_add_f32_e32 v78, 1.0, v78
	v_cvt_pk_bf16_f32 v74, v94, v95
	v_cvt_pk_bf16_f32 v75, v100, v75
	global_store_dwordx4 v[92:93], v[72:75], off offset:256
	v_rcp_f32_e32 v78, v78
	v_mul_f32_e32 v76, v60, v76
	v_mul_f32_e32 v77, v61, v77
	v_cvt_pk_bf16_f32 v60, v64, v65
	v_cvt_pk_bf16_f32 v61, v66, v67
	v_mul_f32_e32 v66, 0x3d372713, v52
	v_fma_f32 v66, v52, v66, 1.0
	v_add_f32_e32 v79, 1.0, v79
	v_mul_f32_e32 v66, v52, v66
	v_rcp_f32_e32 v79, v79
	v_mul_f32_e32 v66, 0xc0135761, v66
	v_mul_f32_e32 v78, v62, v78
	v_cvt_pk_bf16_f32 v62, v76, v77
	v_exp_f32_e32 v76, v66
	v_add_co_u32_e32 v66, vcc, s67, v124
	v_mul_f32_e32 v63, v63, v79
	s_nop 0
	v_addc_co_u32_e32 v67, vcc, 0, v125, vcc
	v_cvt_pk_bf16_f32 v63, v78, v63
	global_store_dwordx4 v[66:67], v[60:63], off
	v_add_f32_e32 v66, 1.0, v76
	v_mul_f32_e32 v67, 0x3d372713, v53
	v_mul_f32_e32 v76, 0x3d372713, v54
	v_fma_f32 v67, v53, v67, 1.0
	v_fma_f32 v76, v54, v76, 1.0
	v_mul_f32_e32 v67, v53, v67
	v_mul_f32_e32 v76, v54, v76
	v_mul_f32_e32 v67, 0xc0135761, v67
	v_mul_f32_e32 v76, 0xc0135761, v76
	v_exp_f32_e32 v67, v67
	v_exp_f32_e32 v76, v76
	v_mul_f32_e32 v77, 0x3d372713, v55
	v_fma_f32 v77, v55, v77, 1.0
	v_add_f32_e32 v67, 1.0, v67
	v_add_f32_e32 v76, 1.0, v76
	v_rcp_f32_e32 v67, v67
	v_rcp_f32_e32 v76, v76
	v_mul_f32_e32 v77, v55, v77
	v_mul_f32_e32 v77, 0xc0135761, v77
	v_rcp_f32_e32 v66, v66
	v_exp_f32_e32 v77, v77
	v_mul_f32_e32 v53, v53, v67
	v_mul_f32_e32 v54, v54, v76
	v_mul_f32_e32 v67, 0x3d372713, v48
	v_mul_f32_e32 v76, 0x3d372713, v49
	v_fma_f32 v67, v48, v67, 1.0
	v_fma_f32 v76, v49, v76, 1.0
	v_mul_f32_e32 v67, v48, v67
	v_mul_f32_e32 v76, v49, v76
	v_mul_f32_e32 v52, v52, v66
	v_add_f32_e32 v66, 1.0, v77
	v_mul_f32_e32 v67, 0xc0135761, v67
	v_mul_f32_e32 v76, 0xc0135761, v76
	v_rcp_f32_e32 v66, v66
	v_exp_f32_e32 v67, v67
	v_exp_f32_e32 v76, v76
	v_mul_f32_e32 v77, 0x3d372713, v51
	v_mul_f32_e32 v55, v55, v66
	v_add_f32_e32 v66, 1.0, v67
	v_add_f32_e32 v67, 1.0, v76
	v_mul_f32_e32 v76, 0x3d372713, v50
	v_fma_f32 v76, v50, v76, 1.0
	v_mul_f32_e32 v76, v50, v76
	v_mul_f32_e32 v76, 0xc0135761, v76
	v_exp_f32_e32 v76, v76
	v_rcp_f32_e32 v66, v66
	v_rcp_f32_e32 v67, v67
	v_fma_f32 v77, v51, v77, 1.0
	v_add_f32_e32 v76, 1.0, v76
	v_rcp_f32_e32 v76, v76
	v_mul_f32_e32 v66, v48, v66
	v_mul_f32_e32 v67, v49, v67
	v_cvt_pk_bf16_f32 v48, v52, v53
	v_cvt_pk_bf16_f32 v49, v54, v55
	v_mul_f32_e32 v53, 0x3d372713, v45
	v_mul_f32_e32 v54, 0x3d372713, v46
	v_fma_f32 v53, v45, v53, 1.0
	v_fma_f32 v54, v46, v54, 1.0
	v_mul_f32_e32 v53, v45, v53
	v_mul_f32_e32 v54, v46, v54
	v_mul_f32_e32 v76, v50, v76
	v_mul_f32_e32 v50, 0x3d372713, v44
	v_mul_f32_e32 v53, 0xc0135761, v53
	v_mul_f32_e32 v54, 0xc0135761, v54
	v_fma_f32 v50, v44, v50, 1.0
	v_exp_f32_e32 v53, v53
	v_exp_f32_e32 v54, v54
	v_mul_f32_e32 v50, v44, v50
	v_mul_f32_e32 v50, 0xc0135761, v50
	v_exp_f32_e32 v52, v50
	v_add_f32_e32 v53, 1.0, v53
	v_add_f32_e32 v54, 1.0, v54
	v_mul_f32_e32 v55, 0x3d372713, v47
	v_rcp_f32_e32 v53, v53
	v_rcp_f32_e32 v54, v54
	v_fma_f32 v55, v47, v55, 1.0
	v_mul_f32_e32 v55, v47, v55
	v_add_f32_e32 v52, 1.0, v52
	v_mul_f32_e32 v55, 0xc0135761, v55
	v_rcp_f32_e32 v52, v52
	v_exp_f32_e32 v55, v55
	v_mul_f32_e32 v45, v45, v53
	v_mul_f32_e32 v46, v46, v54
	v_mul_f32_e32 v53, 0x3d372713, v40
	v_mul_f32_e32 v54, 0x3d372713, v41
	v_fma_f32 v53, v40, v53, 1.0
	v_fma_f32 v54, v41, v54, 1.0
	v_mul_f32_e32 v53, v40, v53
	v_mul_f32_e32 v54, v41, v54
	v_mul_f32_e32 v44, v44, v52
	v_add_f32_e32 v52, 1.0, v55
	v_mul_f32_e32 v53, 0xc0135761, v53
	v_mul_f32_e32 v54, 0xc0135761, v54
	v_rcp_f32_e32 v52, v52
	v_exp_f32_e32 v53, v53
	v_exp_f32_e32 v54, v54
	v_mul_f32_e32 v77, v51, v77
	v_mul_f32_e32 v77, 0xc0135761, v77
	v_exp_f32_e32 v77, v77
	v_mul_f32_e32 v47, v47, v52
	v_add_f32_e32 v52, 1.0, v53
	v_add_f32_e32 v53, 1.0, v54
	v_mul_f32_e32 v54, 0x3d372713, v42
	v_fma_f32 v54, v42, v54, 1.0
	v_mul_f32_e32 v54, v42, v54
	v_add_f32_e32 v77, 1.0, v77
	v_mul_f32_e32 v54, 0xc0135761, v54
	v_mul_f32_e32 v55, 0x3d372713, v43
	v_rcp_f32_e32 v77, v77
	v_exp_f32_e32 v54, v54
	v_fma_f32 v55, v43, v55, 1.0
	v_rcp_f32_e32 v52, v52
	v_mul_f32_e32 v55, v43, v55
	v_rcp_f32_e32 v53, v53
	v_mul_f32_e32 v55, 0xc0135761, v55
	s_mov_b64 s[0:1], 0x800000
	v_exp_f32_e32 v55, v55
	v_lshl_add_u64 v[64:65], v[124:125], 0, s[0:1]
	v_mul_f32_e32 v51, v51, v77
	v_add_f32_e32 v54, 1.0, v54
	v_cvt_pk_bf16_f32 v50, v66, v67
	v_cvt_pk_bf16_f32 v51, v76, v51
	global_store_dwordx4 v[64:65], v[48:51], off offset:256
	v_rcp_f32_e32 v54, v54
	v_mul_f32_e32 v52, v40, v52
	v_mul_f32_e32 v53, v41, v53
	v_cvt_pk_bf16_f32 v40, v44, v45
	v_cvt_pk_bf16_f32 v41, v46, v47
	v_mul_f32_e32 v46, 0x3d372713, v36
	v_fma_f32 v46, v36, v46, 1.0
	v_add_f32_e32 v55, 1.0, v55
	v_mul_f32_e32 v46, v36, v46
	v_rcp_f32_e32 v55, v55
	v_mul_f32_e32 v46, 0xc0135761, v46
	v_mul_f32_e32 v54, v42, v54
	v_cvt_pk_bf16_f32 v42, v52, v53
	s_mov_b64 s[0:1], 0x900000
	v_exp_f32_e32 v52, v46
	v_lshl_add_u64 v[44:45], v[124:125], 0, s[0:1]
	s_mov_b32 s0, 0x900000
	v_add_co_u32_e32 v46, vcc, s0, v124
	v_mul_f32_e32 v43, v43, v55
	s_nop 0
	v_addc_co_u32_e32 v47, vcc, 0, v125, vcc
	v_cvt_pk_bf16_f32 v43, v54, v43
	global_store_dwordx4 v[46:47], v[40:43], off
	v_add_f32_e32 v46, 1.0, v52
	v_mul_f32_e32 v47, 0x3d372713, v37
	v_mul_f32_e32 v52, 0x3d372713, v38
	v_fma_f32 v47, v37, v47, 1.0
	v_fma_f32 v52, v38, v52, 1.0
	v_mul_f32_e32 v47, v37, v47
	v_mul_f32_e32 v52, v38, v52
	v_mul_f32_e32 v47, 0xc0135761, v47
	v_mul_f32_e32 v52, 0xc0135761, v52
	v_exp_f32_e32 v47, v47
	v_exp_f32_e32 v52, v52
	v_mul_f32_e32 v53, 0x3d372713, v39
	v_fma_f32 v53, v39, v53, 1.0
	v_add_f32_e32 v47, 1.0, v47
	v_add_f32_e32 v52, 1.0, v52
	v_rcp_f32_e32 v47, v47
	v_rcp_f32_e32 v52, v52
	v_mul_f32_e32 v53, v39, v53
	v_mul_f32_e32 v53, 0xc0135761, v53
	v_rcp_f32_e32 v46, v46
	v_exp_f32_e32 v53, v53
	v_mul_f32_e32 v37, v37, v47
	v_mul_f32_e32 v38, v38, v52
	v_mul_f32_e32 v47, 0x3d372713, v32
	v_mul_f32_e32 v52, 0x3d372713, v33
	v_fma_f32 v47, v32, v47, 1.0
	v_fma_f32 v52, v33, v52, 1.0
	v_mul_f32_e32 v47, v32, v47
	v_mul_f32_e32 v52, v33, v52
	v_mul_f32_e32 v36, v36, v46
	v_add_f32_e32 v46, 1.0, v53
	v_mul_f32_e32 v47, 0xc0135761, v47
	v_mul_f32_e32 v52, 0xc0135761, v52
	v_rcp_f32_e32 v46, v46
	v_exp_f32_e32 v47, v47
	v_exp_f32_e32 v52, v52
	v_mul_f32_e32 v53, 0x3d372713, v35
	v_mul_f32_e32 v39, v39, v46
	v_add_f32_e32 v46, 1.0, v47
	v_add_f32_e32 v47, 1.0, v52
	v_mul_f32_e32 v52, 0x3d372713, v34
	v_fma_f32 v52, v34, v52, 1.0
	v_mul_f32_e32 v52, v34, v52
	v_mul_f32_e32 v52, 0xc0135761, v52
	v_exp_f32_e32 v52, v52
	v_rcp_f32_e32 v46, v46
	v_rcp_f32_e32 v47, v47
	v_fma_f32 v53, v35, v53, 1.0
	v_add_f32_e32 v52, 1.0, v52
	v_rcp_f32_e32 v52, v52
	v_mul_f32_e32 v46, v32, v46
	v_mul_f32_e32 v47, v33, v47
	v_cvt_pk_bf16_f32 v32, v36, v37
	v_cvt_pk_bf16_f32 v33, v38, v39
	v_mul_f32_e32 v37, 0x3d372713, v29
	v_mul_f32_e32 v38, 0x3d372713, v30
	v_fma_f32 v37, v29, v37, 1.0
	v_fma_f32 v38, v30, v38, 1.0
	v_mul_f32_e32 v37, v29, v37
	v_mul_f32_e32 v38, v30, v38
	v_mul_f32_e32 v52, v34, v52
	v_mul_f32_e32 v34, 0x3d372713, v28
	v_mul_f32_e32 v37, 0xc0135761, v37
	v_mul_f32_e32 v38, 0xc0135761, v38
	v_fma_f32 v34, v28, v34, 1.0
	v_exp_f32_e32 v37, v37
	v_exp_f32_e32 v38, v38
	v_mul_f32_e32 v34, v28, v34
	v_mul_f32_e32 v34, 0xc0135761, v34
	v_exp_f32_e32 v36, v34
	v_add_f32_e32 v37, 1.0, v37
	v_add_f32_e32 v38, 1.0, v38
	v_mul_f32_e32 v39, 0x3d372713, v31
	v_rcp_f32_e32 v37, v37
	v_rcp_f32_e32 v38, v38
	v_fma_f32 v39, v31, v39, 1.0
	v_mul_f32_e32 v39, v31, v39
	v_add_f32_e32 v36, 1.0, v36
	v_mul_f32_e32 v39, 0xc0135761, v39
	v_rcp_f32_e32 v36, v36
	v_exp_f32_e32 v39, v39
	v_mul_f32_e32 v29, v29, v37
	v_mul_f32_e32 v30, v30, v38
	v_mul_f32_e32 v37, 0x3d372713, v24
	v_mul_f32_e32 v38, 0x3d372713, v25
	v_fma_f32 v37, v24, v37, 1.0
	v_fma_f32 v38, v25, v38, 1.0
	v_mul_f32_e32 v37, v24, v37
	v_mul_f32_e32 v38, v25, v38
	v_mul_f32_e32 v28, v28, v36
	v_add_f32_e32 v36, 1.0, v39
	v_mul_f32_e32 v37, 0xc0135761, v37
	v_mul_f32_e32 v38, 0xc0135761, v38
	v_rcp_f32_e32 v36, v36
	v_exp_f32_e32 v37, v37
	v_exp_f32_e32 v38, v38
	v_mul_f32_e32 v53, v35, v53
	v_mul_f32_e32 v53, 0xc0135761, v53
	v_exp_f32_e32 v53, v53
	v_mul_f32_e32 v31, v31, v36
	v_add_f32_e32 v36, 1.0, v37
	v_add_f32_e32 v37, 1.0, v38
	v_mul_f32_e32 v38, 0x3d372713, v26
	v_fma_f32 v38, v26, v38, 1.0
	v_mul_f32_e32 v38, v26, v38
	v_add_f32_e32 v53, 1.0, v53
	v_mul_f32_e32 v38, 0xc0135761, v38
	v_mul_f32_e32 v39, 0x3d372713, v27
	v_rcp_f32_e32 v53, v53
	v_exp_f32_e32 v38, v38
	v_fma_f32 v39, v27, v39, 1.0
	v_rcp_f32_e32 v36, v36
	v_mul_f32_e32 v39, v27, v39
	v_rcp_f32_e32 v37, v37
	v_mul_f32_e32 v39, 0xc0135761, v39
	v_exp_f32_e32 v39, v39
	v_mul_f32_e32 v35, v35, v53
	v_add_f32_e32 v38, 1.0, v38
	v_cvt_pk_bf16_f32 v34, v46, v47
	v_cvt_pk_bf16_f32 v35, v52, v35
	global_store_dwordx4 v[44:45], v[32:35], off offset:256
	v_rcp_f32_e32 v38, v38
	v_mul_f32_e32 v36, v24, v36
	v_mul_f32_e32 v37, v25, v37
	v_cvt_pk_bf16_f32 v24, v28, v29
	v_cvt_pk_bf16_f32 v25, v30, v31
	v_mul_f32_e32 v30, 0x3d372713, v20
	v_fma_f32 v30, v20, v30, 1.0
	v_add_f32_e32 v39, 1.0, v39
	v_mul_f32_e32 v30, v20, v30
	v_rcp_f32_e32 v39, v39
	v_mul_f32_e32 v30, 0xc0135761, v30
	v_mul_f32_e32 v38, v26, v38
	v_cvt_pk_bf16_f32 v26, v36, v37
	s_mov_b64 s[0:1], 0xa00000
	v_exp_f32_e32 v36, v30
	v_lshl_add_u64 v[28:29], v[124:125], 0, s[0:1]
	s_mov_b32 s0, 0xa00000
	v_add_co_u32_e32 v30, vcc, s0, v124
	v_mul_f32_e32 v27, v27, v39
	s_nop 0
	v_addc_co_u32_e32 v31, vcc, 0, v125, vcc
	v_cvt_pk_bf16_f32 v27, v38, v27
	global_store_dwordx4 v[30:31], v[24:27], off
	v_add_f32_e32 v30, 1.0, v36
	v_mul_f32_e32 v31, 0x3d372713, v21
	v_mul_f32_e32 v36, 0x3d372713, v22
	v_fma_f32 v31, v21, v31, 1.0
	v_fma_f32 v36, v22, v36, 1.0
	v_mul_f32_e32 v31, v21, v31
	v_mul_f32_e32 v36, v22, v36
	v_mul_f32_e32 v31, 0xc0135761, v31
	v_mul_f32_e32 v36, 0xc0135761, v36
	v_exp_f32_e32 v31, v31
	v_exp_f32_e32 v36, v36
	v_mul_f32_e32 v37, 0x3d372713, v23
	v_fma_f32 v37, v23, v37, 1.0
	v_add_f32_e32 v31, 1.0, v31
	v_add_f32_e32 v36, 1.0, v36
	v_rcp_f32_e32 v31, v31
	v_rcp_f32_e32 v36, v36
	v_mul_f32_e32 v37, v23, v37
	v_mul_f32_e32 v37, 0xc0135761, v37
	v_rcp_f32_e32 v30, v30
	v_exp_f32_e32 v37, v37
	v_mul_f32_e32 v21, v21, v31
	v_mul_f32_e32 v22, v22, v36
	v_mul_f32_e32 v31, 0x3d372713, v16
	v_mul_f32_e32 v36, 0x3d372713, v17
	v_fma_f32 v31, v16, v31, 1.0
	v_fma_f32 v36, v17, v36, 1.0
	v_mul_f32_e32 v31, v16, v31
	v_mul_f32_e32 v36, v17, v36
	v_mul_f32_e32 v20, v20, v30
	v_add_f32_e32 v30, 1.0, v37
	v_mul_f32_e32 v31, 0xc0135761, v31
	v_mul_f32_e32 v36, 0xc0135761, v36
	v_rcp_f32_e32 v30, v30
	v_exp_f32_e32 v31, v31
	v_exp_f32_e32 v36, v36
	v_mul_f32_e32 v37, 0x3d372713, v19
	v_mul_f32_e32 v23, v23, v30
	v_add_f32_e32 v30, 1.0, v31
	v_add_f32_e32 v31, 1.0, v36
	v_mul_f32_e32 v36, 0x3d372713, v18
	v_fma_f32 v36, v18, v36, 1.0
	v_mul_f32_e32 v36, v18, v36
	v_mul_f32_e32 v36, 0xc0135761, v36
	v_exp_f32_e32 v36, v36
	v_rcp_f32_e32 v30, v30
	v_rcp_f32_e32 v31, v31
	v_fma_f32 v37, v19, v37, 1.0
	v_add_f32_e32 v36, 1.0, v36
	v_rcp_f32_e32 v36, v36
	v_mul_f32_e32 v30, v16, v30
	v_mul_f32_e32 v31, v17, v31
	v_cvt_pk_bf16_f32 v16, v20, v21
	v_cvt_pk_bf16_f32 v17, v22, v23
	v_mul_f32_e32 v21, 0x3d372713, v13
	v_mul_f32_e32 v22, 0x3d372713, v14
	v_fma_f32 v21, v13, v21, 1.0
	v_fma_f32 v22, v14, v22, 1.0
	v_mul_f32_e32 v21, v13, v21
	v_mul_f32_e32 v22, v14, v22
	v_mul_f32_e32 v36, v18, v36
	v_mul_f32_e32 v18, 0x3d372713, v12
	v_mul_f32_e32 v21, 0xc0135761, v21
	v_mul_f32_e32 v22, 0xc0135761, v22
	v_fma_f32 v18, v12, v18, 1.0
	v_exp_f32_e32 v21, v21
	v_exp_f32_e32 v22, v22
	v_mul_f32_e32 v18, v12, v18
	v_mul_f32_e32 v18, 0xc0135761, v18
	v_exp_f32_e32 v20, v18
	v_add_f32_e32 v21, 1.0, v21
	v_add_f32_e32 v22, 1.0, v22
	v_mul_f32_e32 v23, 0x3d372713, v15
	v_rcp_f32_e32 v21, v21
	v_rcp_f32_e32 v22, v22
	v_fma_f32 v23, v15, v23, 1.0
	v_mul_f32_e32 v23, v15, v23
	v_add_f32_e32 v20, 1.0, v20
	v_mul_f32_e32 v23, 0xc0135761, v23
	v_rcp_f32_e32 v20, v20
	v_exp_f32_e32 v23, v23
	v_mul_f32_e32 v13, v13, v21
	v_mul_f32_e32 v14, v14, v22
	v_mul_f32_e32 v21, 0x3d372713, v8
	v_mul_f32_e32 v22, 0x3d372713, v9
	v_fma_f32 v21, v8, v21, 1.0
	v_fma_f32 v22, v9, v22, 1.0
	v_mul_f32_e32 v21, v8, v21
	v_mul_f32_e32 v22, v9, v22
	v_mul_f32_e32 v12, v12, v20
	v_add_f32_e32 v20, 1.0, v23
	v_mul_f32_e32 v21, 0xc0135761, v21
	v_mul_f32_e32 v22, 0xc0135761, v22
	v_rcp_f32_e32 v20, v20
	v_exp_f32_e32 v21, v21
	v_exp_f32_e32 v22, v22
	v_mul_f32_e32 v37, v19, v37
	v_mul_f32_e32 v37, 0xc0135761, v37
	v_exp_f32_e32 v37, v37
	v_mul_f32_e32 v15, v15, v20
	v_add_f32_e32 v20, 1.0, v21
	v_add_f32_e32 v21, 1.0, v22
	v_mul_f32_e32 v22, 0x3d372713, v10
	v_fma_f32 v22, v10, v22, 1.0
	v_mul_f32_e32 v22, v10, v22
	v_add_f32_e32 v37, 1.0, v37
	v_mul_f32_e32 v22, 0xc0135761, v22
	v_mul_f32_e32 v23, 0x3d372713, v11
	v_rcp_f32_e32 v37, v37
	v_exp_f32_e32 v22, v22
	v_fma_f32 v23, v11, v23, 1.0
	v_rcp_f32_e32 v20, v20
	v_mul_f32_e32 v23, v11, v23
	v_rcp_f32_e32 v21, v21
	v_mul_f32_e32 v23, 0xc0135761, v23
	v_exp_f32_e32 v23, v23
	v_mul_f32_e32 v19, v19, v37
	v_add_f32_e32 v22, 1.0, v22
	v_cvt_pk_bf16_f32 v18, v30, v31
	v_cvt_pk_bf16_f32 v19, v36, v19
	global_store_dwordx4 v[28:29], v[16:19], off offset:256
	v_rcp_f32_e32 v22, v22
	v_mul_f32_e32 v20, v8, v20
	v_mul_f32_e32 v21, v9, v21
	v_cvt_pk_bf16_f32 v8, v12, v13
	v_cvt_pk_bf16_f32 v9, v14, v15
	v_mul_f32_e32 v14, 0x3d372713, v4
	v_fma_f32 v14, v4, v14, 1.0
	v_add_f32_e32 v23, 1.0, v23
	v_mul_f32_e32 v14, v4, v14
	v_rcp_f32_e32 v23, v23
	v_mul_f32_e32 v14, 0xc0135761, v14
	v_mul_f32_e32 v22, v10, v22
	v_cvt_pk_bf16_f32 v10, v20, v21
	s_mov_b64 s[0:1], 0xb00000
	v_exp_f32_e32 v20, v14
	v_lshl_add_u64 v[12:13], v[124:125], 0, s[0:1]
	s_mov_b32 s0, 0xb00000
	v_add_co_u32_e32 v14, vcc, s0, v124
	v_mul_f32_e32 v11, v11, v23
	s_nop 0
	v_addc_co_u32_e32 v15, vcc, 0, v125, vcc
	v_cvt_pk_bf16_f32 v11, v22, v11
	global_store_dwordx4 v[14:15], v[8:11], off
	v_add_f32_e32 v14, 1.0, v20
	v_mul_f32_e32 v15, 0x3d372713, v5
	v_mul_f32_e32 v20, 0x3d372713, v6
	v_fma_f32 v15, v5, v15, 1.0
	v_fma_f32 v20, v6, v20, 1.0
	v_mul_f32_e32 v15, v5, v15
	v_mul_f32_e32 v20, v6, v20
	v_mul_f32_e32 v15, 0xc0135761, v15
	v_mul_f32_e32 v20, 0xc0135761, v20
	v_exp_f32_e32 v15, v15
	v_exp_f32_e32 v20, v20
	v_mul_f32_e32 v21, 0x3d372713, v7
	v_fma_f32 v21, v7, v21, 1.0
	v_add_f32_e32 v15, 1.0, v15
	v_add_f32_e32 v20, 1.0, v20
	v_rcp_f32_e32 v15, v15
	v_rcp_f32_e32 v20, v20
	v_mul_f32_e32 v21, v7, v21
	v_mul_f32_e32 v21, 0xc0135761, v21
	v_rcp_f32_e32 v14, v14
	v_exp_f32_e32 v21, v21
	v_mul_f32_e32 v5, v5, v15
	v_mul_f32_e32 v6, v6, v20
	v_mul_f32_e32 v15, 0x3d372713, v0
	v_mul_f32_e32 v20, 0x3d372713, v1
	v_fma_f32 v15, v0, v15, 1.0
	v_fma_f32 v20, v1, v20, 1.0
	v_mul_f32_e32 v15, v0, v15
	v_mul_f32_e32 v20, v1, v20
	v_mul_f32_e32 v4, v4, v14
	v_add_f32_e32 v14, 1.0, v21
	v_mul_f32_e32 v15, 0xc0135761, v15
	v_mul_f32_e32 v20, 0xc0135761, v20
	v_rcp_f32_e32 v14, v14
	v_exp_f32_e32 v15, v15
	v_exp_f32_e32 v20, v20
	v_mul_f32_e32 v21, 0x3d372713, v3
	v_mul_f32_e32 v7, v7, v14
	v_add_f32_e32 v14, 1.0, v15
	v_add_f32_e32 v15, 1.0, v20
	v_mul_f32_e32 v20, 0x3d372713, v2
	v_fma_f32 v21, v3, v21, 1.0
	v_fma_f32 v20, v2, v20, 1.0
	v_mul_f32_e32 v21, v3, v21
	v_mul_f32_e32 v20, v2, v20
	v_mul_f32_e32 v21, 0xc0135761, v21
	v_mul_f32_e32 v20, 0xc0135761, v20
	v_exp_f32_e32 v21, v21
	v_exp_f32_e32 v20, v20
	v_rcp_f32_e32 v14, v14
	v_rcp_f32_e32 v15, v15
	v_add_f32_e32 v21, 1.0, v21
	v_add_f32_e32 v20, 1.0, v20
	v_rcp_f32_e32 v21, v21
	v_rcp_f32_e32 v20, v20
	v_lshlrev_b32_e32 v46, 16, v88
	v_and_b32_e32 v47, 0xffff0000, v88
	v_mul_f32_e32 v14, v0, v14
	v_cvt_pk_bf16_f32 v0, v4, v5
	v_lshlrev_b32_e32 v64, 16, v68
	v_and_b32_e32 v65, 0xffff0000, v68
	v_pk_mul_f32 v[4:5], v[46:47], v[46:47]
	v_lshlrev_b32_e32 v52, 16, v104
	v_pk_fma_f32 v[4:5], v[64:65], v[64:65], v[4:5]
	v_and_b32_e32 v53, 0xffff0000, v104
	v_mul_f32_e32 v3, v3, v21
	v_pk_fma_f32 v[4:5], v[52:53], v[52:53], v[4:5]
	v_lshlrev_b32_e32 v44, 16, v84
	v_and_b32_e32 v45, 0xffff0000, v84
	v_mul_f32_e32 v15, v1, v15
	v_mul_f32_e32 v20, v2, v20
	v_cvt_pk_bf16_f32 v1, v6, v7
	v_cvt_pk_bf16_f32 v2, v14, v15
	v_cvt_pk_bf16_f32 v3, v20, v3
	global_store_dwordx4 v[12:13], v[0:3], off offset:256
	v_pk_fma_f32 v[12:13], v[44:45], v[44:45], v[4:5]
	v_and_b32_e32 v4, 0xffff0000, v60
	v_and_b32_e32 v5, 0xffff0000, v40
	v_pk_mul_f32 v[6:7], v[4:5], v[4:5]
	v_and_b32_e32 v28, 0xffff0000, v24
	v_and_b32_e32 v29, 0xffff0000, v8
	v_add_f32_e32 v6, v13, v6
	v_pk_mul_f32 v[30:31], v[28:29], v[28:29]
	v_add_f32_e32 v6, v6, v7
	v_add_f32_e32 v6, v6, v30
	v_lshlrev_b32_e32 v78, 16, v69
	v_and_b32_e32 v79, 0xffff0000, v69
	v_lshlrev_b32_e32 v68, 16, v89
	v_and_b32_e32 v69, 0xffff0000, v89
	v_add_f32_e32 v108, v6, v31
	v_pk_mul_f32 v[6:7], v[68:69], v[68:69]
	v_lshlrev_b32_e32 v76, 16, v105
	v_pk_fma_f32 v[6:7], v[78:79], v[78:79], v[6:7]
	v_and_b32_e32 v77, 0xffff0000, v105
	v_pk_fma_f32 v[6:7], v[76:77], v[76:77], v[6:7]
	v_lshlrev_b32_e32 v66, 16, v85
	v_and_b32_e32 v67, 0xffff0000, v85
	v_lshlrev_b32_e32 v38, 16, v61
	v_lshlrev_b32_e32 v39, 16, v41
	v_lshlrev_b32_e32 v20, 16, v40
	v_pk_fma_f32 v[54:55], v[66:67], v[66:67], v[6:7]
	v_and_b32_e32 v7, 0xffff0000, v41
	v_pk_mul_f32 v[40:41], v[38:39], v[38:39]
	v_and_b32_e32 v6, 0xffff0000, v61
	v_lshlrev_b32_e32 v36, 16, v25
	v_lshlrev_b32_e32 v37, 16, v9
	v_add_f32_e32 v13, v54, v40
	v_lshlrev_b32_e32 v14, 16, v60
	v_lshlrev_b32_e32 v22, 16, v24
	v_lshlrev_b32_e32 v24, 16, v8
	v_pk_mul_f32 v[60:61], v[6:7], v[6:7]
	v_and_b32_e32 v31, 0xffff0000, v9
	v_pk_mul_f32 v[8:9], v[36:37], v[36:37]
	v_add_f32_e32 v13, v13, v41
	v_and_b32_e32 v30, 0xffff0000, v25
	v_add_f32_e32 v8, v13, v8
	v_add_f32_e32 v13, v55, v60
	v_add_f32_e32 v105, v8, v9
	v_pk_mul_f32 v[8:9], v[30:31], v[30:31]
	v_add_f32_e32 v13, v13, v61
	v_add_f32_e32 v8, v13, v8
	v_lshlrev_b32_e32 v88, 16, v90
	v_and_b32_e32 v89, 0xffff0000, v90
	v_add_f32_e32 v104, v8, v9
	v_lshlrev_b32_e32 v94, 16, v70
	v_and_b32_e32 v95, 0xffff0000, v70
	v_pk_mul_f32 v[8:9], v[88:89], v[88:89]
	v_lshlrev_b32_e32 v92, 16, v106
	v_pk_fma_f32 v[8:9], v[94:95], v[94:95], v[8:9]
	v_and_b32_e32 v93, 0xffff0000, v106
	v_pk_fma_f32 v[8:9], v[92:93], v[92:93], v[8:9]
	v_lshlrev_b32_e32 v84, 16, v86
	v_and_b32_e32 v85, 0xffff0000, v86
	v_lshlrev_b32_e32 v60, 16, v62
	v_lshlrev_b32_e32 v61, 16, v42
	v_pk_fma_f32 v[110:111], v[84:85], v[84:85], v[8:9]
	v_pk_mul_f32 v[102:103], v[60:61], v[60:61]
	v_lshlrev_b32_e32 v54, 16, v26
	v_lshlrev_b32_e32 v55, 16, v10
	v_and_b32_e32 v41, 0xffff0000, v10
	v_add_f32_e32 v10, v110, v102
	v_and_b32_e32 v8, 0xffff0000, v62
	v_and_b32_e32 v9, 0xffff0000, v42
	v_pk_mul_f32 v[114:115], v[54:55], v[54:55]
	v_add_f32_e32 v10, v10, v103
	v_pk_mul_f32 v[112:113], v[8:9], v[8:9]
	v_add_f32_e32 v10, v10, v114
	v_add_f32_e32 v103, v10, v115
	v_add_f32_e32 v10, v111, v112
	v_and_b32_e32 v40, 0xffff0000, v26
	v_add_f32_e32 v10, v10, v113
	v_lshlrev_b32_e32 v112, 16, v91
	v_and_b32_e32 v113, 0xffff0000, v91
	v_pk_mul_f32 v[114:115], v[40:41], v[40:41]
	v_lshlrev_b32_e32 v110, 16, v71
	v_and_b32_e32 v111, 0xffff0000, v71
	v_pk_mul_f32 v[70:71], v[112:113], v[112:113]
	v_add_f32_e32 v10, v10, v114
	v_pk_fma_f32 v[70:71], v[110:111], v[110:111], v[70:71]
	v_lshlrev_b32_e32 v106, 16, v107
	v_and_b32_e32 v107, 0xffff0000, v107
	v_add_f32_e32 v102, v10, v115
	v_pk_fma_f32 v[70:71], v[106:107], v[106:107], v[70:71]
	v_lshlrev_b32_e32 v114, 16, v87
	v_and_b32_e32 v115, 0xffff0000, v87
	v_lshlrev_b32_e32 v86, 16, v63
	v_lshlrev_b32_e32 v87, 16, v43
	v_pk_fma_f32 v[90:91], v[114:115], v[114:115], v[70:71]
	v_and_b32_e32 v71, 0xffff0000, v43
	v_pk_mul_f32 v[42:43], v[86:87], v[86:87]
	v_lshlrev_b32_e32 v26, 16, v27
	v_and_b32_e32 v10, 0xffff0000, v27
	v_lshlrev_b32_e32 v27, 16, v11
	v_add_f32_e32 v13, v90, v42
	v_and_b32_e32 v70, 0xffff0000, v63
	v_pk_mul_f32 v[116:117], v[26:27], v[26:27]
	v_add_f32_e32 v13, v13, v43
	v_pk_mul_f32 v[62:63], v[70:71], v[70:71]
	v_add_f32_e32 v13, v13, v116
	v_and_b32_e32 v11, 0xffff0000, v11
	v_add_f32_e32 v101, v13, v117
	v_add_f32_e32 v13, v91, v62
	v_pk_mul_f32 v[42:43], v[10:11], v[10:11]
	v_add_f32_e32 v13, v13, v63
	v_add_f32_e32 v13, v13, v42
	v_lshlrev_b32_e32 v118, 16, v80
	v_and_b32_e32 v119, 0xffff0000, v80
	v_add_f32_e32 v13, v13, v43
	v_lshlrev_b32_e32 v116, 16, v56
	v_and_b32_e32 v117, 0xffff0000, v56
	v_pk_mul_f32 v[42:43], v[118:119], v[118:119]
	v_lshlrev_b32_e32 v120, 16, v96
	v_pk_fma_f32 v[42:43], v[116:117], v[116:117], v[42:43]
	v_and_b32_e32 v121, 0xffff0000, v96
	v_pk_fma_f32 v[42:43], v[120:121], v[120:121], v[42:43]
	v_lshlrev_b32_e32 v122, 16, v72
	v_and_b32_e32 v123, 0xffff0000, v72
	v_and_b32_e32 v124, 0xffff0000, v48
	v_and_b32_e32 v125, 0xffff0000, v32
	v_pk_fma_f32 v[42:43], v[122:123], v[122:123], v[42:43]
	v_pk_mul_f32 v[126:127], v[124:125], v[124:125]
	v_and_b32_e32 v90, 0xffff0000, v16
	v_lshlrev_b32_e32 v62, 16, v0
	v_and_b32_e32 v91, 0xffff0000, v0
	v_add_f32_e32 v0, v43, v126
	v_pk_mul_f32 v[146:147], v[90:91], v[90:91]
	v_add_f32_e32 v0, v0, v127
	v_add_f32_e32 v0, v0, v146
	v_lshlrev_b32_e32 v80, 16, v81
	v_and_b32_e32 v81, 0xffff0000, v81
	v_add_f32_e32 v109, v0, v147
	v_lshlrev_b32_e32 v126, 16, v57
	v_and_b32_e32 v127, 0xffff0000, v57
	v_pk_mul_f32 v[146:147], v[80:81], v[80:81]
	v_lshlrev_b32_e32 v96, 16, v97
	v_pk_fma_f32 v[146:147], v[126:127], v[126:127], v[146:147]
	v_and_b32_e32 v97, 0xffff0000, v97
	v_pk_fma_f32 v[146:147], v[96:97], v[96:97], v[146:147]
	v_lshlrev_b32_e32 v148, 16, v73
	v_and_b32_e32 v149, 0xffff0000, v73
	v_pk_fma_f32 v[72:73], v[148:149], v[148:149], v[146:147]
	v_lshlrev_b32_e32 v146, 16, v49
	v_lshlrev_b32_e32 v147, 16, v33
	v_pk_mul_f32 v[152:153], v[146:147], v[146:147]
	v_lshlrev_b32_e32 v56, 16, v48
	v_lshlrev_b32_e32 v48, 16, v32
	v_lshlrev_b32_e32 v32, 16, v16
	v_lshlrev_b32_e32 v16, 16, v17
	v_and_b32_e32 v0, 0xffff0000, v17
	v_lshlrev_b32_e32 v17, 16, v1
	v_add_f32_e32 v15, v72, v152
	v_and_b32_e32 v150, 0xffff0000, v49
	v_and_b32_e32 v151, 0xffff0000, v33
	v_pk_mul_f32 v[156:157], v[16:17], v[16:17]
	v_add_f32_e32 v15, v15, v153
	v_pk_mul_f32 v[154:155], v[150:151], v[150:151]
	v_add_f32_e32 v15, v15, v156
	v_and_b32_e32 v1, 0xffff0000, v1
	v_add_f32_e32 v139, v15, v157
	v_add_f32_e32 v15, v73, v154
	v_pk_mul_f32 v[152:153], v[0:1], v[0:1]
	v_add_f32_e32 v15, v15, v155
	v_add_f32_e32 v15, v15, v152
	v_lshlrev_b32_e32 v154, 16, v82
	v_and_b32_e32 v155, 0xffff0000, v82
	v_add_f32_e32 v72, v15, v153
	v_lshlrev_b32_e32 v152, 16, v58
	v_and_b32_e32 v153, 0xffff0000, v58
	v_pk_mul_f32 v[156:157], v[154:155], v[154:155]
	v_lshlrev_b32_e32 v158, 16, v98
	v_pk_fma_f32 v[156:157], v[152:153], v[152:153], v[156:157]
	v_and_b32_e32 v159, 0xffff0000, v98
	v_pk_fma_f32 v[156:157], v[158:159], v[158:159], v[156:157]
	v_lshlrev_b32_e32 v160, 16, v74
	v_and_b32_e32 v161, 0xffff0000, v74
	v_lshlrev_b32_e32 v162, 16, v50
	v_lshlrev_b32_e32 v163, 16, v34
	v_pk_fma_f32 v[156:157], v[160:161], v[160:161], v[156:157]
	v_pk_mul_f32 v[166:167], v[162:163], v[162:163]
	v_lshlrev_b32_e32 v170, 16, v18
	v_lshlrev_b32_e32 v171, 16, v2
	v_and_b32_e32 v173, 0xffff0000, v2
	v_add_f32_e32 v2, v156, v166
	v_and_b32_e32 v164, 0xffff0000, v50
	v_and_b32_e32 v165, 0xffff0000, v34
	v_pk_mul_f32 v[174:175], v[170:171], v[170:171]
	v_add_f32_e32 v2, v2, v167
	v_pk_mul_f32 v[168:169], v[164:165], v[164:165]
	v_add_f32_e32 v2, v2, v174
	v_and_b32_e32 v172, 0xffff0000, v18
	v_add_f32_e32 v50, v2, v175
	v_add_f32_e32 v2, v157, v168
	v_lshlrev_b32_e32 v82, 16, v83
	v_and_b32_e32 v83, 0xffff0000, v83
	v_pk_mul_f32 v[166:167], v[172:173], v[172:173]
	v_add_f32_e32 v2, v2, v169
	v_lshlrev_b32_e32 v58, 16, v59
	v_and_b32_e32 v59, 0xffff0000, v59
	v_pk_mul_f32 v[156:157], v[82:83], v[82:83]
	v_add_f32_e32 v2, v2, v166
	v_pk_fma_f32 v[156:157], v[58:59], v[58:59], v[156:157]
	v_lshlrev_b32_e32 v98, 16, v99
	v_and_b32_e32 v99, 0xffff0000, v99
	v_add_f32_e32 v43, v2, v167
	v_pk_fma_f32 v[156:157], v[98:99], v[98:99], v[156:157]
	v_lshlrev_b32_e32 v74, 16, v75
	v_and_b32_e32 v75, 0xffff0000, v75
	v_lshlrev_b32_e32 v166, 16, v51
	v_lshlrev_b32_e32 v167, 16, v35
	v_pk_fma_f32 v[156:157], v[74:75], v[74:75], v[156:157]
	v_and_b32_e32 v169, 0xffff0000, v35
	v_pk_mul_f32 v[34:35], v[166:167], v[166:167]
	v_lshlrev_b32_e32 v18, 16, v19
	v_and_b32_e32 v2, 0xffff0000, v19
	v_lshlrev_b32_e32 v19, 16, v3
	v_add_f32_e32 v15, v156, v34
	v_and_b32_e32 v168, 0xffff0000, v51
	v_pk_mul_f32 v[176:177], v[18:19], v[18:19]
	v_add_f32_e32 v15, v15, v35
	v_pk_mul_f32 v[174:175], v[168:169], v[168:169]
	v_add_f32_e32 v15, v15, v176
	v_and_b32_e32 v3, 0xffff0000, v3
	v_add_f32_e32 v35, v15, v177
	v_add_f32_e32 v15, v157, v174
	v_pk_add_f32 v[64:65], v[64:65], 0 op_sel_hi:[1,0]
	v_pk_mul_f32 v[176:177], v[2:3], v[2:3]
	v_add_f32_e32 v15, v15, v175
	v_pk_add_f32 v[78:79], v[78:79], 0 op_sel_hi:[1,0]
	v_pk_add_f32 v[46:47], v[64:65], v[46:47]
	v_add_f32_e32 v15, v15, v176
	v_pk_add_f32 v[94:95], v[94:95], 0 op_sel_hi:[1,0]
	v_pk_add_f32 v[68:69], v[78:79], v[68:69]
	v_pk_add_f32 v[46:47], v[46:47], v[52:53]
	v_add_f32_e32 v34, v15, v177
	v_pk_add_f32 v[110:111], v[110:111], 0 op_sel_hi:[1,0]
	v_pk_add_f32 v[88:89], v[94:95], v[88:89]
	v_pk_add_f32 v[52:53], v[68:69], v[76:77]
	v_pk_add_f32 v[44:45], v[46:47], v[44:45]
	v_mov_b32_e32 v15, v4
	v_pk_add_f32 v[116:117], v[116:117], 0 op_sel_hi:[1,0]
	v_pk_add_f32 v[126:127], v[126:127], 0 op_sel_hi:[1,0]
	v_pk_add_f32 v[110:111], v[110:111], v[112:113]
	v_pk_add_f32 v[64:65], v[88:89], v[92:93]
	v_pk_add_f32 v[52:53], v[52:53], v[66:67]
	v_pk_add_f32 v[44:45], v[44:45], v[14:15]
	v_mov_b32_e32 v46, v38
	v_mov_b32_e32 v47, v6
	v_mov_b32_e32 v21, v5
	v_pk_add_f32 v[80:81], v[126:127], v[80:81]
	v_pk_add_f32 v[116:117], v[116:117], v[118:119]
	v_pk_add_f32 v[68:69], v[110:111], v[106:107]
	v_pk_add_f32 v[64:65], v[64:65], v[84:85]
	v_pk_add_f32 v[46:47], v[52:53], v[46:47]
	v_mov_b32_e32 v52, v60
	v_mov_b32_e32 v53, v8
	v_mov_b32_e32 v6, v39
	v_pk_add_f32 v[4:5], v[44:45], v[20:21]
	v_mov_b32_e32 v23, v28
	v_pk_add_f32 v[76:77], v[116:117], v[120:121]
	v_pk_add_f32 v[78:79], v[80:81], v[96:97]
	v_pk_add_f32 v[68:69], v[68:69], v[114:115]
	v_pk_add_f32 v[52:53], v[64:65], v[52:53]
	v_mov_b32_e32 v64, v86
	v_mov_b32_e32 v65, v70
	v_mov_b32_e32 v8, v61
	v_pk_add_f32 v[6:7], v[46:47], v[6:7]
	v_pk_add_f32 v[38:39], v[4:5], v[22:23]
	v_mov_b32_e32 v4, v36
	v_mov_b32_e32 v5, v30
	v_pk_add_f32 v[78:79], v[78:79], v[148:149]
	v_pk_add_f32 v[76:77], v[76:77], v[122:123]
	v_pk_add_f32 v[64:65], v[68:69], v[64:65]
	v_mov_b32_e32 v57, v124
	v_mov_b32_e32 v68, v146
	v_mov_b32_e32 v69, v150
	v_mov_b32_e32 v70, v87
	v_pk_add_f32 v[8:9], v[52:53], v[8:9]
	v_pk_add_f32 v[44:45], v[6:7], v[4:5]
	v_mov_b32_e32 v4, v54
	v_mov_b32_e32 v5, v40
	v_pk_add_f32 v[66:67], v[76:77], v[56:57]
	v_pk_add_f32 v[68:69], v[78:79], v[68:69]
	v_mov_b32_e32 v150, v147
	v_mov_b32_e32 v49, v125
	v_pk_add_f32 v[64:65], v[64:65], v[70:71]
	v_pk_add_f32 v[46:47], v[8:9], v[4:5]
	v_mov_b32_e32 v4, v26
	v_mov_b32_e32 v5, v10
	v_mov_b32_e32 v57, v48
	v_pk_add_f32 v[68:69], v[68:69], v[150:151]
	v_pk_add_f32 v[66:67], v[66:67], v[48:49]
	v_pk_add_f32 v[52:53], v[64:65], v[4:5]
	v_mov_b32_e32 v33, v90
	v_mov_b32_e32 v4, v16
	v_mov_b32_e32 v5, v0
	v_mov_b32_e32 v25, v29
	v_pk_mul_f32 v[28:29], v[56:57], v[56:57]
	v_pk_add_f32 v[8:9], v[66:67], v[32:33]
	v_pk_add_f32 v[6:7], v[68:69], v[4:5]
	v_mov_b32_e32 v0, v17
	v_mov_b32_e32 v33, v62
	v_add_f32_e32 v15, v42, v28
	v_pk_add_f32 v[6:7], v[6:7], v[0:1]
	v_pk_mul_f32 v[0:1], v[32:33], v[32:33]
	v_add_f32_e32 v15, v15, v29
	v_add_f32_e32 v0, v15, v0
	v_mov_b32_e32 v15, v20
	v_pk_mul_f32 v[14:15], v[14:15], v[14:15]
	v_mov_b32_e32 v23, v24
	v_add_f32_e32 v12, v12, v14
	v_add_f32_e32 v21, v0, v1
	v_pk_mul_f32 v[0:1], v[22:23], v[22:23]
	v_add_f32_e32 v12, v12, v15
	v_add_f32_e32 v0, v12, v0
	v_add_f32_e32 v0, v0, v1
	v_bitop3_b32 v1, v144, 8, v144 bitop3:0xc
	v_mov_b32_e32 v10, v27
	v_mov_b32_e32 v30, v37
	v_pk_add_f32 v[26:27], v[38:39], v[24:25]
	v_cmp_eq_u32_e32 vcc, 1, v1
	v_mov_b32_e32 v60, v18
	v_mov_b32_e32 v61, v2
	v_mov_b32_e32 v2, v19
	v_pk_add_f32 v[18:19], v[44:45], v[30:31]
	v_cndmask_b32_e32 v12, v26, v27, vcc
	v_cmp_eq_u32_e32 vcc, 2, v1
	v_mov_b32_e32 v40, v55
	v_pk_add_f32 v[16:17], v[46:47], v[40:41]
	v_cndmask_b32_e32 v12, v12, v18, vcc
	v_cmp_eq_u32_e32 vcc, 3, v1
	v_pk_add_f32 v[152:153], v[152:153], 0 op_sel_hi:[1,0]
	v_pk_add_f32 v[58:59], v[58:59], 0 op_sel_hi:[1,0]
	v_cndmask_b32_e32 v12, v12, v19, vcc
	v_cmp_eq_u32_e32 vcc, 4, v1
	v_pk_add_f32 v[58:59], v[58:59], v[82:83]
	v_pk_add_f32 v[82:83], v[152:153], v[154:155]
	v_cndmask_b32_e32 v12, v12, v16, vcc
	v_cmp_eq_u32_e32 vcc, 5, v1
	v_pk_add_f32 v[10:11], v[52:53], v[10:11]
	v_pk_add_f32 v[80:81], v[82:83], v[158:159]
	v_cndmask_b32_e32 v12, v12, v17, vcc
	v_cmp_eq_u32_e32 vcc, 6, v1
	v_pk_add_f32 v[58:59], v[58:59], v[98:99]
	v_mov_b32_e32 v63, v91
	v_cndmask_b32_e32 v12, v12, v10, vcc
	v_cmp_eq_u32_e32 vcc, 7, v1
	v_pk_add_f32 v[58:59], v[58:59], v[74:75]
	v_pk_add_f32 v[74:75], v[80:81], v[160:161]
	v_mov_b32_e32 v76, v162
	v_mov_b32_e32 v77, v164
	v_pk_add_f32 v[8:9], v[8:9], v[62:63]
	v_cndmask_b32_e32 v12, v12, v11, vcc
	v_cmp_eq_u32_e32 vcc, 8, v1
	v_pk_add_f32 v[74:75], v[74:75], v[76:77]
	v_mov_b32_e32 v164, v163
	v_cndmask_b32_e32 v12, v12, v8, vcc
	v_cmp_eq_u32_e32 vcc, 9, v1
	v_mov_b32_e32 v76, v166
	v_mov_b32_e32 v77, v168
	v_pk_add_f32 v[74:75], v[74:75], v[164:165]
	v_mov_b32_e32 v4, v170
	v_mov_b32_e32 v5, v172
	v_cndmask_b32_e32 v12, v12, v9, vcc
	v_cmp_eq_u32_e32 vcc, 10, v1
	v_pk_add_f32 v[58:59], v[58:59], v[76:77]
	v_mov_b32_e32 v168, v167
	v_pk_add_f32 v[4:5], v[74:75], v[4:5]
	v_mov_b32_e32 v172, v171
	v_cndmask_b32_e32 v12, v12, v6, vcc
	v_cmp_eq_u32_e32 vcc, 11, v1
	v_pk_add_f32 v[58:59], v[58:59], v[168:169]
	v_pk_add_f32 v[4:5], v[4:5], v[172:173]
	v_cndmask_b32_e32 v12, v12, v7, vcc
	v_cmp_eq_u32_e32 vcc, 12, v1
	v_pk_add_f32 v[58:59], v[58:59], v[60:61]
	v_and_b32_e32 v100, 8, v144
	v_cndmask_b32_e32 v12, v12, v4, vcc
	v_cmp_eq_u32_e32 vcc, 13, v1
	v_pk_add_f32 v[2:3], v[58:59], v[2:3]
	v_xor_b32_e32 v20, 8, v199
	v_cndmask_b32_e32 v12, v12, v5, vcc
	v_cmp_eq_u32_e32 vcc, 14, v1
	s_mov_b32 s45, s18
	s_nop 0
	v_cndmask_b32_e32 v12, v12, v2, vcc
	v_cmp_eq_u32_e32 vcc, 15, v1
	s_nop 1
	v_cndmask_b32_e32 v12, v12, v3, vcc
	v_cmp_eq_u32_e32 vcc, 1, v100
	s_nop 1
	v_cndmask_b32_e32 v1, v26, v27, vcc
	v_cmp_eq_u32_e32 vcc, 2, v100
	s_nop 1
	v_cndmask_b32_e32 v1, v1, v18, vcc
	v_cmp_eq_u32_e32 vcc, 3, v100
	s_nop 1
	v_cndmask_b32_e32 v1, v1, v19, vcc
	v_cmp_eq_u32_e32 vcc, 4, v100
	s_nop 1
	v_cndmask_b32_e32 v1, v1, v16, vcc
	v_cmp_eq_u32_e32 vcc, 5, v100
	s_nop 1
	v_cndmask_b32_e32 v1, v1, v17, vcc
	v_cmp_eq_u32_e32 vcc, 6, v100
	s_nop 1
	v_cndmask_b32_e32 v1, v1, v10, vcc
	v_cmp_eq_u32_e32 vcc, 7, v100
	s_nop 1
	v_cndmask_b32_e32 v1, v1, v11, vcc
	v_cmp_ne_u32_e32 vcc, 0, v100
	s_nop 1
	v_cndmask_b32_e32 v1, v1, v8, vcc
	v_cmp_eq_u32_e32 vcc, 9, v100
	s_nop 1
	v_cndmask_b32_e32 v1, v1, v9, vcc
	v_cmp_eq_u32_e32 vcc, 10, v100
	s_nop 1
	v_cndmask_b32_e32 v1, v1, v6, vcc
	v_cmp_eq_u32_e32 vcc, 11, v100
	s_nop 1
	v_cndmask_b32_e32 v1, v1, v7, vcc
	v_cmp_eq_u32_e32 vcc, 12, v100
	s_nop 1
	v_cndmask_b32_e32 v1, v1, v4, vcc
	v_cmp_eq_u32_e32 vcc, 13, v100
	s_nop 1
	v_cndmask_b32_e32 v1, v1, v5, vcc
	v_cmp_eq_u32_e32 vcc, 14, v100
	s_nop 1
	v_cndmask_b32_e32 v14, v1, v2, vcc
	v_and_b32_e32 v1, 64, v199
	v_add_u32_e32 v1, 64, v1
	v_cmp_lt_i32_e64 s[0:1], v20, v1
	v_cmp_eq_u32_e32 vcc, 0, v100
	s_nop 0
	v_cndmask_b32_e64 v20, v199, v20, s[0:1]
	v_lshlrev_b32_e32 v24, 2, v20
	ds_bpermute_b32 v12, v24, v12
	v_cmp_eq_u32_e64 s[0:1], 15, v100
	v_cndmask_b32_e32 v15, v0, v21, vcc
	v_cndmask_b32_e32 v20, v21, v0, vcc
	v_cndmask_b32_e64 v14, v14, v3, s[0:1]
	s_waitcnt lgkmcnt(0)
	v_add_f32_e32 v0, v14, v12
	v_bitop3_b32 v12, v144, 9, 8 bitop3:0x6c
	v_cmp_eq_u32_e64 s[0:1], 1, v12
	ds_bpermute_b32 v15, v24, v15
	v_cndmask_b32_e32 v21, v108, v109, vcc
	v_cndmask_b32_e64 v14, v0, v27, s[0:1]
	v_cmp_eq_u32_e64 s[0:1], 2, v12
	ds_bpermute_b32 v21, v24, v21
	s_waitcnt lgkmcnt(0)
	v_add_f32_e32 v15, v20, v15
	v_cndmask_b32_e64 v14, v14, v18, s[0:1]
	v_cmp_eq_u32_e64 s[0:1], 3, v12
	s_nop 1
	v_cndmask_b32_e64 v14, v14, v19, s[0:1]
	v_cmp_eq_u32_e64 s[0:1], 4, v12
	s_nop 1
	v_cndmask_b32_e64 v14, v14, v16, s[0:1]
	v_cmp_eq_u32_e64 s[0:1], 5, v12
	s_nop 1
	v_cndmask_b32_e64 v14, v14, v17, s[0:1]
	v_cmp_eq_u32_e64 s[0:1], 6, v12
	s_nop 1
	v_cndmask_b32_e64 v14, v14, v10, s[0:1]
	v_cmp_eq_u32_e64 s[0:1], 7, v12
	s_nop 1
	v_cndmask_b32_e64 v14, v14, v11, s[0:1]
	v_cmp_eq_u32_e64 s[0:1], 8, v12
	s_nop 1
	v_cndmask_b32_e64 v14, v14, v8, s[0:1]
	v_cmp_eq_u32_e64 s[0:1], 9, v12
	s_nop 1
	v_cndmask_b32_e64 v14, v14, v9, s[0:1]
	v_cmp_eq_u32_e64 s[0:1], 10, v12
	s_nop 1
	v_cndmask_b32_e64 v14, v14, v6, s[0:1]
	v_cmp_eq_u32_e64 s[0:1], 11, v12
	s_nop 1
	v_cndmask_b32_e64 v14, v14, v7, s[0:1]
	v_cmp_eq_u32_e64 s[0:1], 12, v12
	s_nop 1
	v_cndmask_b32_e64 v14, v14, v4, s[0:1]
	v_cmp_eq_u32_e64 s[0:1], 13, v12
	s_nop 1
	v_cndmask_b32_e64 v14, v14, v5, s[0:1]
	v_cmp_eq_u32_e64 s[0:1], 14, v12
	s_nop 1
	v_cndmask_b32_e64 v14, v14, v2, s[0:1]
	v_cmp_eq_u32_e64 s[0:1], 15, v12
	s_nop 1
	v_cndmask_b32_e64 v12, v14, v3, s[0:1]
	v_or_b32_e32 v14, 1, v100
	v_cmp_eq_u32_e64 s[0:1], 1, v14
	ds_bpermute_b32 v12, v24, v12
	s_nop 0
	v_cndmask_b32_e64 v20, v0, v27, s[0:1]
	v_cmp_eq_u32_e64 s[0:1], 2, v14
	s_nop 1
	v_cndmask_b32_e64 v20, v20, v18, s[0:1]
	v_cmp_eq_u32_e64 s[0:1], 3, v14
	s_nop 1
	v_cndmask_b32_e64 v20, v20, v19, s[0:1]
	v_cmp_eq_u32_e64 s[0:1], 4, v14
	s_nop 1
	v_cndmask_b32_e64 v20, v20, v16, s[0:1]
	v_cmp_eq_u32_e64 s[0:1], 5, v14
	s_nop 1
	v_cndmask_b32_e64 v20, v20, v17, s[0:1]
	v_cmp_eq_u32_e64 s[0:1], 6, v14
	s_nop 1
	v_cndmask_b32_e64 v20, v20, v10, s[0:1]
	v_cmp_eq_u32_e64 s[0:1], 7, v14
	s_nop 1
	v_cndmask_b32_e64 v20, v20, v11, s[0:1]
	v_cmp_eq_u32_e64 s[0:1], 8, v14
	s_nop 1
	v_cndmask_b32_e64 v20, v20, v8, s[0:1]
	v_cmp_eq_u32_e64 s[0:1], 9, v14
	s_nop 1
	v_cndmask_b32_e64 v20, v20, v9, s[0:1]
	v_cmp_eq_u32_e64 s[0:1], 10, v14
	s_nop 1
	v_cndmask_b32_e64 v20, v20, v6, s[0:1]
	v_cmp_eq_u32_e64 s[0:1], 11, v14
	s_nop 1
	v_cndmask_b32_e64 v20, v20, v7, s[0:1]
	v_cmp_eq_u32_e64 s[0:1], 12, v14
	s_nop 1
	v_cndmask_b32_e64 v20, v20, v4, s[0:1]
	v_cmp_eq_u32_e64 s[0:1], 13, v14
	s_nop 1
	v_cndmask_b32_e64 v20, v20, v5, s[0:1]
	v_cmp_eq_u32_e64 s[0:1], 14, v14
	s_nop 1
	v_cndmask_b32_e64 v20, v20, v2, s[0:1]
	v_cmp_eq_u32_e64 s[0:1], 15, v14
	s_nop 1
	v_cndmask_b32_e64 v14, v20, v3, s[0:1]
	s_waitcnt lgkmcnt(0)
	v_add_f32_e32 v23, v14, v12
	v_bitop3_b32 v12, v144, 10, 8 bitop3:0x6c
	v_cmp_eq_u32_e64 s[0:1], 1, v12
	v_cndmask_b32_e32 v20, v109, v108, vcc
	v_add_f32_e32 v20, v20, v21
	v_cndmask_b32_e64 v14, v0, v23, s[0:1]
	v_cmp_eq_u32_e64 s[0:1], 2, v12
	s_nop 1
	v_cndmask_b32_e64 v14, v14, v18, s[0:1]
	v_cmp_eq_u32_e64 s[0:1], 3, v12
	s_nop 1
	v_cndmask_b32_e64 v14, v14, v19, s[0:1]
	v_cmp_eq_u32_e64 s[0:1], 4, v12
	s_nop 1
	v_cndmask_b32_e64 v14, v14, v16, s[0:1]
	v_cmp_eq_u32_e64 s[0:1], 5, v12
	s_nop 1
	v_cndmask_b32_e64 v14, v14, v17, s[0:1]
	v_cmp_eq_u32_e64 s[0:1], 6, v12
	s_nop 1
	v_cndmask_b32_e64 v14, v14, v10, s[0:1]
	v_cmp_eq_u32_e64 s[0:1], 7, v12
	s_nop 1
	v_cndmask_b32_e64 v14, v14, v11, s[0:1]
	v_cmp_eq_u32_e64 s[0:1], 8, v12
	s_nop 1
	v_cndmask_b32_e64 v14, v14, v8, s[0:1]
	v_cmp_eq_u32_e64 s[0:1], 9, v12
	s_nop 1
	v_cndmask_b32_e64 v14, v14, v9, s[0:1]
	v_cmp_eq_u32_e64 s[0:1], 10, v12
	s_nop 1
	v_cndmask_b32_e64 v14, v14, v6, s[0:1]
	v_cmp_eq_u32_e64 s[0:1], 11, v12
	s_nop 1
	v_cndmask_b32_e64 v14, v14, v7, s[0:1]
	v_cmp_eq_u32_e64 s[0:1], 12, v12
	s_nop 1
	v_cndmask_b32_e64 v14, v14, v4, s[0:1]
	v_cmp_eq_u32_e64 s[0:1], 13, v12
	s_nop 1
	v_cndmask_b32_e64 v14, v14, v5, s[0:1]
	v_cmp_eq_u32_e64 s[0:1], 14, v12
	s_nop 1
	v_cndmask_b32_e64 v14, v14, v2, s[0:1]
	v_cmp_eq_u32_e64 s[0:1], 15, v12
	s_nop 1
	v_cndmask_b32_e64 v12, v14, v3, s[0:1]
	v_or_b32_e32 v14, 2, v100
	v_cmp_eq_u32_e64 s[0:1], 1, v14
	ds_bpermute_b32 v12, v24, v12
	s_nop 0
	v_cndmask_b32_e64 v21, v0, v23, s[0:1]
	v_cmp_eq_u32_e64 s[0:1], 2, v14
	s_nop 1
	v_cndmask_b32_e64 v18, v21, v18, s[0:1]
	v_cmp_eq_u32_e64 s[0:1], 3, v14
	v_cndmask_b32_e32 v21, v105, v139, vcc
	ds_bpermute_b32 v21, v24, v21
	v_cndmask_b32_e64 v18, v18, v19, s[0:1]
	v_cmp_eq_u32_e64 s[0:1], 4, v14
	s_nop 1
	v_cndmask_b32_e64 v18, v18, v16, s[0:1]
	v_cmp_eq_u32_e64 s[0:1], 5, v14
	s_nop 1
	v_cndmask_b32_e64 v18, v18, v17, s[0:1]
	v_cmp_eq_u32_e64 s[0:1], 6, v14
	s_nop 1
	v_cndmask_b32_e64 v18, v18, v10, s[0:1]
	v_cmp_eq_u32_e64 s[0:1], 7, v14
	s_nop 1
	v_cndmask_b32_e64 v18, v18, v11, s[0:1]
	v_cmp_eq_u32_e64 s[0:1], 8, v14
	s_nop 1
	v_cndmask_b32_e64 v18, v18, v8, s[0:1]
	v_cmp_eq_u32_e64 s[0:1], 9, v14
	s_nop 1
	v_cndmask_b32_e64 v18, v18, v9, s[0:1]
	v_cmp_eq_u32_e64 s[0:1], 10, v14
	s_nop 1
	v_cndmask_b32_e64 v18, v18, v6, s[0:1]
	v_cmp_eq_u32_e64 s[0:1], 11, v14
	s_nop 1
	v_cndmask_b32_e64 v18, v18, v7, s[0:1]
	v_cmp_eq_u32_e64 s[0:1], 12, v14
	s_nop 1
	v_cndmask_b32_e64 v18, v18, v4, s[0:1]
	v_cmp_eq_u32_e64 s[0:1], 13, v14
	s_nop 1
	v_cndmask_b32_e64 v18, v18, v5, s[0:1]
	v_cmp_eq_u32_e64 s[0:1], 14, v14
	s_nop 1
	v_cndmask_b32_e64 v18, v18, v2, s[0:1]
	v_cmp_eq_u32_e64 s[0:1], 15, v14
	s_nop 1
	v_cndmask_b32_e64 v14, v18, v3, s[0:1]
	s_waitcnt lgkmcnt(0)
	v_add_f32_e32 v22, v14, v12
	v_bitop3_b32 v12, v144, 11, 8 bitop3:0x6c
	v_cmp_eq_u32_e64 s[0:1], 1, v12
	v_cndmask_b32_e32 v18, v139, v105, vcc
	v_add_f32_e32 v18, v18, v21
	v_cndmask_b32_e64 v14, v0, v23, s[0:1]
	v_cmp_eq_u32_e64 s[0:1], 2, v12
	s_nop 1
	v_cndmask_b32_e64 v14, v14, v22, s[0:1]
	v_cmp_eq_u32_e64 s[0:1], 3, v12
	s_nop 1
	v_cndmask_b32_e64 v14, v14, v19, s[0:1]
	v_cmp_eq_u32_e64 s[0:1], 4, v12
	s_nop 1
	v_cndmask_b32_e64 v14, v14, v16, s[0:1]
	v_cmp_eq_u32_e64 s[0:1], 5, v12
	s_nop 1
	v_cndmask_b32_e64 v14, v14, v17, s[0:1]
	v_cmp_eq_u32_e64 s[0:1], 6, v12
	s_nop 1
	v_cndmask_b32_e64 v14, v14, v10, s[0:1]
	v_cmp_eq_u32_e64 s[0:1], 7, v12
	s_nop 1
	v_cndmask_b32_e64 v14, v14, v11, s[0:1]
	v_cmp_eq_u32_e64 s[0:1], 8, v12
	s_nop 1
	v_cndmask_b32_e64 v14, v14, v8, s[0:1]
	v_cmp_eq_u32_e64 s[0:1], 9, v12
	s_nop 1
	v_cndmask_b32_e64 v14, v14, v9, s[0:1]
	v_cmp_eq_u32_e64 s[0:1], 10, v12
	s_nop 1
	v_cndmask_b32_e64 v14, v14, v6, s[0:1]
	v_cmp_eq_u32_e64 s[0:1], 11, v12
	s_nop 1
	v_cndmask_b32_e64 v14, v14, v7, s[0:1]
	v_cmp_eq_u32_e64 s[0:1], 12, v12
	s_nop 1
	v_cndmask_b32_e64 v14, v14, v4, s[0:1]
	v_cmp_eq_u32_e64 s[0:1], 13, v12
	s_nop 1
	v_cndmask_b32_e64 v14, v14, v5, s[0:1]
	v_cmp_eq_u32_e64 s[0:1], 14, v12
	s_nop 1
	v_cndmask_b32_e64 v14, v14, v2, s[0:1]
	v_cmp_eq_u32_e64 s[0:1], 15, v12
	s_nop 1
	v_cndmask_b32_e64 v12, v14, v3, s[0:1]
	v_or_b32_e32 v14, 3, v100
	v_cmp_eq_u32_e64 s[0:1], 1, v14
	ds_bpermute_b32 v12, v24, v12
	s_nop 0
	v_cndmask_b32_e64 v21, v0, v23, s[0:1]
	v_cmp_eq_u32_e64 s[0:1], 2, v14
	s_nop 1
	v_cndmask_b32_e64 v21, v21, v22, s[0:1]
	v_cmp_eq_u32_e64 s[0:1], 3, v14
	s_nop 1
	v_cndmask_b32_e64 v19, v21, v19, s[0:1]
	v_cmp_eq_u32_e64 s[0:1], 4, v14
	v_cndmask_b32_e32 v21, v104, v72, vcc
	ds_bpermute_b32 v25, v24, v21
	v_cndmask_b32_e64 v19, v19, v16, s[0:1]
	v_cmp_eq_u32_e64 s[0:1], 5, v14
	s_nop 1
	v_cndmask_b32_e64 v19, v19, v17, s[0:1]
	v_cmp_eq_u32_e64 s[0:1], 6, v14
	s_nop 1
	v_cndmask_b32_e64 v19, v19, v10, s[0:1]
	v_cmp_eq_u32_e64 s[0:1], 7, v14
	s_nop 1
	v_cndmask_b32_e64 v19, v19, v11, s[0:1]
	v_cmp_eq_u32_e64 s[0:1], 8, v14
	s_nop 1
	v_cndmask_b32_e64 v19, v19, v8, s[0:1]
	v_cmp_eq_u32_e64 s[0:1], 9, v14
	s_nop 1
	v_cndmask_b32_e64 v19, v19, v9, s[0:1]
	v_cmp_eq_u32_e64 s[0:1], 10, v14
	s_nop 1
	v_cndmask_b32_e64 v19, v19, v6, s[0:1]
	v_cmp_eq_u32_e64 s[0:1], 11, v14
	s_nop 1
	v_cndmask_b32_e64 v19, v19, v7, s[0:1]
	v_cmp_eq_u32_e64 s[0:1], 12, v14
	s_nop 1
	v_cndmask_b32_e64 v19, v19, v4, s[0:1]
	v_cmp_eq_u32_e64 s[0:1], 13, v14
	s_nop 1
	v_cndmask_b32_e64 v19, v19, v5, s[0:1]
	v_cmp_eq_u32_e64 s[0:1], 14, v14
	s_nop 1
	v_cndmask_b32_e64 v19, v19, v2, s[0:1]
	v_cmp_eq_u32_e64 s[0:1], 15, v14
	s_nop 1
	v_cndmask_b32_e64 v14, v19, v3, s[0:1]
	s_waitcnt lgkmcnt(0)
	v_add_f32_e32 v21, v14, v12
	v_bitop3_b32 v12, v144, 12, 8 bitop3:0x6c
	v_cmp_eq_u32_e64 s[0:1], 1, v12
	v_cndmask_b32_e32 v19, v72, v104, vcc
	v_add_f32_e32 v19, v19, v25
	v_cndmask_b32_e64 v14, v0, v23, s[0:1]
	v_cmp_eq_u32_e64 s[0:1], 2, v12
	s_nop 1
	v_cndmask_b32_e64 v14, v14, v22, s[0:1]
	v_cmp_eq_u32_e64 s[0:1], 3, v12
	s_nop 1
	v_cndmask_b32_e64 v14, v14, v21, s[0:1]
	v_cmp_eq_u32_e64 s[0:1], 4, v12
	s_nop 1
	v_cndmask_b32_e64 v14, v14, v16, s[0:1]
	v_cmp_eq_u32_e64 s[0:1], 5, v12
	s_nop 1
	v_cndmask_b32_e64 v14, v14, v17, s[0:1]
	v_cmp_eq_u32_e64 s[0:1], 6, v12
	s_nop 1
	v_cndmask_b32_e64 v14, v14, v10, s[0:1]
	v_cmp_eq_u32_e64 s[0:1], 7, v12
	s_nop 1
	v_cndmask_b32_e64 v14, v14, v11, s[0:1]
	v_cmp_eq_u32_e64 s[0:1], 8, v12
	s_nop 1
	v_cndmask_b32_e64 v14, v14, v8, s[0:1]
	v_cmp_eq_u32_e64 s[0:1], 9, v12
	s_nop 1
	v_cndmask_b32_e64 v14, v14, v9, s[0:1]
	v_cmp_eq_u32_e64 s[0:1], 10, v12
	s_nop 1
	v_cndmask_b32_e64 v14, v14, v6, s[0:1]
	v_cmp_eq_u32_e64 s[0:1], 11, v12
	s_nop 1
	v_cndmask_b32_e64 v14, v14, v7, s[0:1]
	v_cmp_eq_u32_e64 s[0:1], 12, v12
	s_nop 1
	v_cndmask_b32_e64 v14, v14, v4, s[0:1]
	v_cmp_eq_u32_e64 s[0:1], 13, v12
	s_nop 1
	v_cndmask_b32_e64 v14, v14, v5, s[0:1]
	v_cmp_eq_u32_e64 s[0:1], 14, v12
	s_nop 1
	v_cndmask_b32_e64 v14, v14, v2, s[0:1]
	v_cmp_eq_u32_e64 s[0:1], 15, v12
	s_nop 1
	v_cndmask_b32_e64 v12, v14, v3, s[0:1]
	v_or_b32_e32 v14, 4, v100
	v_cmp_eq_u32_e64 s[0:1], 1, v14
	ds_bpermute_b32 v12, v24, v12
	s_nop 0
	v_cndmask_b32_e64 v25, v0, v23, s[0:1]
	v_cmp_eq_u32_e64 s[0:1], 2, v14
	s_nop 1
	v_cndmask_b32_e64 v25, v25, v22, s[0:1]
	v_cmp_eq_u32_e64 s[0:1], 3, v14
	s_nop 1
	v_cndmask_b32_e64 v25, v25, v21, s[0:1]
	v_cmp_eq_u32_e64 s[0:1], 4, v14
	s_nop 1
	v_cndmask_b32_e64 v16, v25, v16, s[0:1]
	v_cmp_eq_u32_e64 s[0:1], 5, v14
	v_cndmask_b32_e32 v25, v103, v50, vcc
	ds_bpermute_b32 v25, v24, v25
	v_cndmask_b32_e64 v16, v16, v17, s[0:1]
	v_cmp_eq_u32_e64 s[0:1], 6, v14
	s_nop 1
	v_cndmask_b32_e64 v16, v16, v10, s[0:1]
	v_cmp_eq_u32_e64 s[0:1], 7, v14
	s_nop 1
	v_cndmask_b32_e64 v16, v16, v11, s[0:1]
	v_cmp_eq_u32_e64 s[0:1], 8, v14
	s_nop 1
	v_cndmask_b32_e64 v16, v16, v8, s[0:1]
	v_cmp_eq_u32_e64 s[0:1], 9, v14
	s_nop 1
	v_cndmask_b32_e64 v16, v16, v9, s[0:1]
	v_cmp_eq_u32_e64 s[0:1], 10, v14
	s_nop 1
	v_cndmask_b32_e64 v16, v16, v6, s[0:1]
	v_cmp_eq_u32_e64 s[0:1], 11, v14
	s_nop 1
	v_cndmask_b32_e64 v16, v16, v7, s[0:1]
	v_cmp_eq_u32_e64 s[0:1], 12, v14
	s_nop 1
	v_cndmask_b32_e64 v16, v16, v4, s[0:1]
	v_cmp_eq_u32_e64 s[0:1], 13, v14
	s_nop 1
	v_cndmask_b32_e64 v16, v16, v5, s[0:1]
	v_cmp_eq_u32_e64 s[0:1], 14, v14
	s_nop 1
	v_cndmask_b32_e64 v16, v16, v2, s[0:1]
	v_cmp_eq_u32_e64 s[0:1], 15, v14
	s_nop 1
	v_cndmask_b32_e64 v14, v16, v3, s[0:1]
	s_waitcnt lgkmcnt(0)
	v_add_f32_e32 v12, v14, v12
	v_bitop3_b32 v14, v144, 13, 8 bitop3:0x6c
	v_cndmask_b32_e32 v16, v50, v103, vcc
	v_cmp_eq_u32_e64 s[0:1], 1, v14
	v_add_f32_e32 v16, v16, v25
	s_nop 0
	v_cndmask_b32_e64 v25, v0, v23, s[0:1]
	v_cmp_eq_u32_e64 s[0:1], 2, v14
	s_nop 1
	v_cndmask_b32_e64 v25, v25, v22, s[0:1]
	v_cmp_eq_u32_e64 s[0:1], 3, v14
	s_nop 1
	v_cndmask_b32_e64 v25, v25, v21, s[0:1]
	v_cmp_eq_u32_e64 s[0:1], 4, v14
	s_nop 1
	v_cndmask_b32_e64 v25, v25, v12, s[0:1]
	v_cmp_eq_u32_e64 s[0:1], 5, v14
	s_nop 1
	v_cndmask_b32_e64 v25, v25, v17, s[0:1]
	v_cmp_eq_u32_e64 s[0:1], 6, v14
	s_nop 1
	v_cndmask_b32_e64 v25, v25, v10, s[0:1]
	v_cmp_eq_u32_e64 s[0:1], 7, v14
	s_nop 1
	v_cndmask_b32_e64 v25, v25, v11, s[0:1]
	v_cmp_eq_u32_e64 s[0:1], 8, v14
	s_nop 1
	v_cndmask_b32_e64 v25, v25, v8, s[0:1]
	v_cmp_eq_u32_e64 s[0:1], 9, v14
	s_nop 1
	v_cndmask_b32_e64 v25, v25, v9, s[0:1]
	v_cmp_eq_u32_e64 s[0:1], 10, v14
	s_nop 1
	v_cndmask_b32_e64 v25, v25, v6, s[0:1]
	v_cmp_eq_u32_e64 s[0:1], 11, v14
	s_nop 1
	v_cndmask_b32_e64 v25, v25, v7, s[0:1]
	v_cmp_eq_u32_e64 s[0:1], 12, v14
	s_nop 1
	v_cndmask_b32_e64 v25, v25, v4, s[0:1]
	v_cmp_eq_u32_e64 s[0:1], 13, v14
	s_nop 1
	v_cndmask_b32_e64 v25, v25, v5, s[0:1]
	v_cmp_eq_u32_e64 s[0:1], 14, v14
	s_nop 1
	v_cndmask_b32_e64 v25, v25, v2, s[0:1]
	v_cmp_eq_u32_e64 s[0:1], 15, v14
	s_nop 1
	v_cndmask_b32_e64 v14, v25, v3, s[0:1]
	v_or_b32_e32 v25, 5, v100
	v_cmp_eq_u32_e64 s[0:1], 1, v25
	ds_bpermute_b32 v14, v24, v14
	s_nop 0
	v_cndmask_b32_e64 v26, v0, v23, s[0:1]
	v_cmp_eq_u32_e64 s[0:1], 2, v25
	s_nop 1
	v_cndmask_b32_e64 v26, v26, v22, s[0:1]
	v_cmp_eq_u32_e64 s[0:1], 3, v25
	s_nop 1
	v_cndmask_b32_e64 v26, v26, v21, s[0:1]
	v_cmp_eq_u32_e64 s[0:1], 4, v25
	s_nop 1
	v_cndmask_b32_e64 v26, v26, v12, s[0:1]
	v_cmp_eq_u32_e64 s[0:1], 5, v25
	s_nop 1
	v_cndmask_b32_e64 v17, v26, v17, s[0:1]
	v_cmp_eq_u32_e64 s[0:1], 6, v25
	v_cndmask_b32_e32 v26, v102, v43, vcc
	ds_bpermute_b32 v26, v24, v26
	v_cndmask_b32_e64 v17, v17, v10, s[0:1]
	v_cmp_eq_u32_e64 s[0:1], 7, v25
	s_nop 1
	v_cndmask_b32_e64 v17, v17, v11, s[0:1]
	v_cmp_eq_u32_e64 s[0:1], 8, v25
	s_nop 1
	v_cndmask_b32_e64 v17, v17, v8, s[0:1]
	v_cmp_eq_u32_e64 s[0:1], 9, v25
	s_nop 1
	v_cndmask_b32_e64 v17, v17, v9, s[0:1]
	v_cmp_eq_u32_e64 s[0:1], 10, v25
	s_nop 1
	v_cndmask_b32_e64 v17, v17, v6, s[0:1]
	v_cmp_eq_u32_e64 s[0:1], 11, v25
	s_nop 1
	v_cndmask_b32_e64 v17, v17, v7, s[0:1]
	v_cmp_eq_u32_e64 s[0:1], 12, v25
	s_nop 1
	v_cndmask_b32_e64 v17, v17, v4, s[0:1]
	v_cmp_eq_u32_e64 s[0:1], 13, v25
	s_nop 1
	v_cndmask_b32_e64 v17, v17, v5, s[0:1]
	v_cmp_eq_u32_e64 s[0:1], 14, v25
	s_nop 1
	v_cndmask_b32_e64 v17, v17, v2, s[0:1]
	v_cmp_eq_u32_e64 s[0:1], 15, v25
	v_cndmask_b32_e32 v25, v43, v102, vcc
	s_nop 0
	v_cndmask_b32_e64 v17, v17, v3, s[0:1]
	s_waitcnt lgkmcnt(0)
	v_add_f32_e32 v14, v17, v14
	v_add_f32_e32 v17, v25, v26
	v_bitop3_b32 v25, v144, 14, 8 bitop3:0x6c
	v_cmp_eq_u32_e64 s[0:1], 1, v25
	s_nop 1
	v_cndmask_b32_e64 v26, v0, v23, s[0:1]
	v_cmp_eq_u32_e64 s[0:1], 2, v25
	s_nop 1
	v_cndmask_b32_e64 v26, v26, v22, s[0:1]
	v_cmp_eq_u32_e64 s[0:1], 3, v25
	s_nop 1
	v_cndmask_b32_e64 v26, v26, v21, s[0:1]
	v_cmp_eq_u32_e64 s[0:1], 4, v25
	s_nop 1
	v_cndmask_b32_e64 v26, v26, v12, s[0:1]
	v_cmp_eq_u32_e64 s[0:1], 5, v25
	s_nop 1
	v_cndmask_b32_e64 v26, v26, v14, s[0:1]
	v_cmp_eq_u32_e64 s[0:1], 6, v25
	s_nop 1
	v_cndmask_b32_e64 v26, v26, v10, s[0:1]
	v_cmp_eq_u32_e64 s[0:1], 7, v25
	s_nop 1
	v_cndmask_b32_e64 v26, v26, v11, s[0:1]
	v_cmp_eq_u32_e64 s[0:1], 8, v25
	s_nop 1
	v_cndmask_b32_e64 v26, v26, v8, s[0:1]
	v_cmp_eq_u32_e64 s[0:1], 9, v25
	s_nop 1
	v_cndmask_b32_e64 v26, v26, v9, s[0:1]
	v_cmp_eq_u32_e64 s[0:1], 10, v25
	s_nop 1
	v_cndmask_b32_e64 v26, v26, v6, s[0:1]
	v_cmp_eq_u32_e64 s[0:1], 11, v25
	s_nop 1
	v_cndmask_b32_e64 v26, v26, v7, s[0:1]
	v_cmp_eq_u32_e64 s[0:1], 12, v25
	s_nop 1
	v_cndmask_b32_e64 v26, v26, v4, s[0:1]
	v_cmp_eq_u32_e64 s[0:1], 13, v25
	s_nop 1
	v_cndmask_b32_e64 v26, v26, v5, s[0:1]
	v_cmp_eq_u32_e64 s[0:1], 14, v25
	s_nop 1
	v_cndmask_b32_e64 v26, v26, v2, s[0:1]
	v_cmp_eq_u32_e64 s[0:1], 15, v25
	s_nop 1
	v_cndmask_b32_e64 v25, v26, v3, s[0:1]
	v_or_b32_e32 v26, 6, v100
	v_cmp_eq_u32_e64 s[0:1], 1, v26
	ds_bpermute_b32 v25, v24, v25
	s_nop 0
	v_cndmask_b32_e64 v27, v0, v23, s[0:1]
	v_cmp_eq_u32_e64 s[0:1], 2, v26
	s_nop 1
	v_cndmask_b32_e64 v27, v27, v22, s[0:1]
	v_cmp_eq_u32_e64 s[0:1], 3, v26
	s_nop 1
	v_cndmask_b32_e64 v27, v27, v21, s[0:1]
	v_cmp_eq_u32_e64 s[0:1], 4, v26
	s_nop 1
	v_cndmask_b32_e64 v27, v27, v12, s[0:1]
	v_cmp_eq_u32_e64 s[0:1], 5, v26
	s_nop 1
	v_cndmask_b32_e64 v27, v27, v14, s[0:1]
	v_cmp_eq_u32_e64 s[0:1], 6, v26
	s_nop 1
	v_cndmask_b32_e64 v10, v27, v10, s[0:1]
	v_cmp_eq_u32_e64 s[0:1], 7, v26
	v_cndmask_b32_e32 v27, v101, v35, vcc
	ds_bpermute_b32 v27, v24, v27
	v_cndmask_b32_e64 v10, v10, v11, s[0:1]
	v_cmp_eq_u32_e64 s[0:1], 8, v26
	s_nop 1
	v_cndmask_b32_e64 v10, v10, v8, s[0:1]
	v_cmp_eq_u32_e64 s[0:1], 9, v26
	s_nop 1
	v_cndmask_b32_e64 v10, v10, v9, s[0:1]
	v_cmp_eq_u32_e64 s[0:1], 10, v26
	s_nop 1
	v_cndmask_b32_e64 v10, v10, v6, s[0:1]
	v_cmp_eq_u32_e64 s[0:1], 11, v26
	s_nop 1
	v_cndmask_b32_e64 v10, v10, v7, s[0:1]
	v_cmp_eq_u32_e64 s[0:1], 12, v26
	s_nop 1
	v_cndmask_b32_e64 v10, v10, v4, s[0:1]
	v_cmp_eq_u32_e64 s[0:1], 13, v26
	s_nop 1
	v_cndmask_b32_e64 v10, v10, v5, s[0:1]
	v_cmp_eq_u32_e64 s[0:1], 14, v26
	s_nop 1
	v_cndmask_b32_e64 v10, v10, v2, s[0:1]
	v_cmp_eq_u32_e64 s[0:1], 15, v26
	v_cndmask_b32_e32 v26, v35, v101, vcc
	s_nop 0
	v_cndmask_b32_e64 v10, v10, v3, s[0:1]
	s_waitcnt lgkmcnt(0)
	v_add_f32_e32 v10, v10, v25
	v_add_f32_e32 v25, v26, v27
	v_bitop3_b32 v26, v144, 15, 8 bitop3:0x6c
	v_cmp_eq_u32_e64 s[0:1], 1, v26
	s_nop 1
	v_cndmask_b32_e64 v27, v0, v23, s[0:1]
	v_cmp_eq_u32_e64 s[0:1], 2, v26
	s_nop 1
	v_cndmask_b32_e64 v27, v27, v22, s[0:1]
	v_cmp_eq_u32_e64 s[0:1], 3, v26
	s_nop 1
	v_cndmask_b32_e64 v27, v27, v21, s[0:1]
	v_cmp_eq_u32_e64 s[0:1], 4, v26
	s_nop 1
	v_cndmask_b32_e64 v27, v27, v12, s[0:1]
	v_cmp_eq_u32_e64 s[0:1], 5, v26
	s_nop 1
	v_cndmask_b32_e64 v27, v27, v14, s[0:1]
	v_cmp_eq_u32_e64 s[0:1], 6, v26
	s_nop 1
	v_cndmask_b32_e64 v27, v27, v10, s[0:1]
	v_cmp_eq_u32_e64 s[0:1], 7, v26
	s_nop 1
	v_cndmask_b32_e64 v27, v27, v11, s[0:1]
	v_cmp_eq_u32_e64 s[0:1], 8, v26
	s_nop 1
	v_cndmask_b32_e64 v27, v27, v8, s[0:1]
	v_cmp_eq_u32_e64 s[0:1], 9, v26
	s_nop 1
	v_cndmask_b32_e64 v27, v27, v9, s[0:1]
	v_cmp_eq_u32_e64 s[0:1], 10, v26
	s_nop 1
	v_cndmask_b32_e64 v27, v27, v6, s[0:1]
	v_cmp_eq_u32_e64 s[0:1], 11, v26
	s_nop 1
	v_cndmask_b32_e64 v27, v27, v7, s[0:1]
	v_cmp_eq_u32_e64 s[0:1], 12, v26
	s_nop 1
	v_cndmask_b32_e64 v27, v27, v4, s[0:1]
	v_cmp_eq_u32_e64 s[0:1], 13, v26
	s_nop 1
	v_cndmask_b32_e64 v27, v27, v5, s[0:1]
	v_cmp_eq_u32_e64 s[0:1], 14, v26
	s_nop 1
	v_cndmask_b32_e64 v27, v27, v2, s[0:1]
	v_cmp_eq_u32_e64 s[0:1], 15, v26
	s_nop 1
	v_cndmask_b32_e64 v26, v27, v3, s[0:1]
	v_or_b32_e32 v27, 7, v100
	v_cmp_eq_u32_e64 s[0:1], 1, v27
	ds_bpermute_b32 v26, v24, v26
	s_nop 0
	v_cndmask_b32_e64 v28, v0, v23, s[0:1]
	v_cmp_eq_u32_e64 s[0:1], 2, v27
	s_nop 1
	v_cndmask_b32_e64 v28, v28, v22, s[0:1]
	v_cmp_eq_u32_e64 s[0:1], 3, v27
	s_nop 1
	v_cndmask_b32_e64 v28, v28, v21, s[0:1]
	v_cmp_eq_u32_e64 s[0:1], 4, v27
	s_nop 1
	v_cndmask_b32_e64 v28, v28, v12, s[0:1]
	v_cmp_eq_u32_e64 s[0:1], 5, v27
	s_nop 1
	v_cndmask_b32_e64 v28, v28, v14, s[0:1]
	v_cmp_eq_u32_e64 s[0:1], 6, v27
	s_nop 1
	v_cndmask_b32_e64 v28, v28, v10, s[0:1]
	v_cmp_eq_u32_e64 s[0:1], 7, v27
	s_nop 1
	v_cndmask_b32_e64 v11, v28, v11, s[0:1]
	v_cmp_eq_u32_e64 s[0:1], 8, v27
	v_cndmask_b32_e32 v28, v13, v34, vcc
	ds_bpermute_b32 v24, v24, v28
	v_cndmask_b32_e64 v11, v11, v8, s[0:1]
	v_cmp_eq_u32_e64 s[0:1], 9, v27
	v_cndmask_b32_e32 v13, v34, v13, vcc
	v_xor_b32_e32 v28, 4, v199
	v_cndmask_b32_e64 v11, v11, v9, s[0:1]
	v_cmp_eq_u32_e64 s[0:1], 10, v27
	s_nop 1
	v_cndmask_b32_e64 v11, v11, v6, s[0:1]
	v_cmp_eq_u32_e64 s[0:1], 11, v27
	s_nop 1
	v_cndmask_b32_e64 v11, v11, v7, s[0:1]
	v_cmp_eq_u32_e64 s[0:1], 12, v27
	s_nop 1
	v_cndmask_b32_e64 v11, v11, v4, s[0:1]
	v_cmp_eq_u32_e64 s[0:1], 13, v27
	s_nop 1
	v_cndmask_b32_e64 v11, v11, v5, s[0:1]
	v_cmp_eq_u32_e64 s[0:1], 14, v27
	s_nop 1
	v_cndmask_b32_e64 v11, v11, v2, s[0:1]
	v_cmp_eq_u32_e64 s[0:1], 15, v27
	s_nop 1
	v_cndmask_b32_e64 v11, v11, v3, s[0:1]
	s_waitcnt lgkmcnt(0)
	v_add_f32_e32 v26, v11, v26
	v_add_f32_e32 v11, v13, v24
	v_bitop3_b32 v24, v144, 4, v144 bitop3:0xc
	v_cmp_eq_u32_e32 vcc, 1, v24
	v_and_b32_e32 v13, 4, v144
	v_cmp_lt_i32_e64 s[0:1], v28, v1
	v_cndmask_b32_e32 v27, v0, v23, vcc
	v_cmp_eq_u32_e32 vcc, 2, v24
	v_cndmask_b32_e64 v28, v199, v28, s[0:1]
	v_lshlrev_b32_e32 v28, 2, v28
	v_cndmask_b32_e32 v27, v27, v22, vcc
	v_cmp_eq_u32_e32 vcc, 3, v24
	v_cmp_eq_u32_e64 s[0:1], 15, v13
	s_nop 0
	v_cndmask_b32_e32 v27, v27, v21, vcc
	v_cmp_eq_u32_e32 vcc, 4, v24
	s_nop 1
	v_cndmask_b32_e32 v27, v27, v12, vcc
	v_cmp_eq_u32_e32 vcc, 5, v24
	s_nop 1
	v_cndmask_b32_e32 v27, v27, v14, vcc
	v_cmp_eq_u32_e32 vcc, 6, v24
	s_nop 1
	v_cndmask_b32_e32 v27, v27, v10, vcc
	v_cmp_eq_u32_e32 vcc, 7, v24
	s_nop 1
	v_cndmask_b32_e32 v27, v27, v26, vcc
	v_cmp_eq_u32_e32 vcc, 8, v24
	s_nop 1
	v_cndmask_b32_e32 v27, v27, v8, vcc
	v_cmp_eq_u32_e32 vcc, 9, v24
	s_nop 1
	v_cndmask_b32_e32 v27, v27, v9, vcc
	v_cmp_eq_u32_e32 vcc, 10, v24
	s_nop 1
	v_cndmask_b32_e32 v27, v27, v6, vcc
	v_cmp_eq_u32_e32 vcc, 11, v24
	s_nop 1
	v_cndmask_b32_e32 v27, v27, v7, vcc
	v_cmp_eq_u32_e32 vcc, 12, v24
	s_nop 1
	v_cndmask_b32_e32 v27, v27, v4, vcc
	v_cmp_eq_u32_e32 vcc, 13, v24
	s_nop 1
	v_cndmask_b32_e32 v27, v27, v5, vcc
	v_cmp_eq_u32_e32 vcc, 14, v24
	s_nop 1
	v_cndmask_b32_e32 v27, v27, v2, vcc
	v_cmp_eq_u32_e32 vcc, 15, v24
	s_nop 1
	v_cndmask_b32_e32 v24, v27, v3, vcc
	v_cmp_eq_u32_e32 vcc, 1, v13
	ds_bpermute_b32 v24, v28, v24
	s_nop 0
	v_cndmask_b32_e32 v0, v0, v23, vcc
	v_cmp_eq_u32_e32 vcc, 2, v13
	s_nop 1
	v_cndmask_b32_e32 v0, v0, v22, vcc
	v_cmp_eq_u32_e32 vcc, 3, v13
	s_nop 1
	v_cndmask_b32_e32 v0, v0, v21, vcc
	v_cmp_ne_u32_e32 vcc, 0, v13
	s_nop 1
	v_cndmask_b32_e32 v0, v0, v12, vcc
	v_cmp_eq_u32_e32 vcc, 5, v13
	s_nop 1
	v_cndmask_b32_e32 v0, v0, v14, vcc
	v_cmp_eq_u32_e32 vcc, 6, v13
	s_nop 1
	v_cndmask_b32_e32 v0, v0, v10, vcc
	v_cmp_eq_u32_e32 vcc, 7, v13
	s_nop 1
	v_cndmask_b32_e32 v0, v0, v26, vcc
	v_cmp_eq_u32_e32 vcc, 8, v13
	s_nop 1
	v_cndmask_b32_e32 v0, v0, v8, vcc
	v_cmp_eq_u32_e32 vcc, 9, v13
	s_nop 1
	v_cndmask_b32_e32 v0, v0, v9, vcc
	v_cmp_eq_u32_e32 vcc, 10, v13
	s_nop 1
	v_cndmask_b32_e32 v0, v0, v6, vcc
	v_cmp_eq_u32_e32 vcc, 11, v13
	s_nop 1
	v_cndmask_b32_e32 v0, v0, v7, vcc
	v_cmp_eq_u32_e32 vcc, 12, v13
	s_nop 1
	v_cndmask_b32_e32 v0, v0, v4, vcc
	v_cmp_eq_u32_e32 vcc, 13, v13
	s_nop 1
	v_cndmask_b32_e32 v0, v0, v5, vcc
	v_cmp_eq_u32_e32 vcc, 14, v13
	s_nop 1
	v_cndmask_b32_e32 v0, v0, v2, vcc
	v_cmp_eq_u32_e32 vcc, 0, v13
	v_cndmask_b32_e64 v0, v0, v3, s[0:1]
	s_waitcnt lgkmcnt(0)
	v_add_f32_e32 v0, v0, v24
	v_cndmask_b32_e32 v27, v15, v16, vcc
	v_cndmask_b32_e32 v15, v16, v15, vcc
	v_bitop3_b32 v16, v144, 5, 4 bitop3:0x6c
	v_cmp_eq_u32_e64 s[0:1], 1, v16
	ds_bpermute_b32 v27, v28, v27
	s_waitcnt lgkmcnt(0)
	v_add_f32_e32 v15, v15, v27
	v_cndmask_b32_e64 v24, v0, v23, s[0:1]
	v_cmp_eq_u32_e64 s[0:1], 2, v16
	v_cndmask_b32_e32 v27, v20, v17, vcc
	v_cndmask_b32_e32 v17, v17, v20, vcc
	v_cndmask_b32_e64 v24, v24, v22, s[0:1]
	v_cmp_eq_u32_e64 s[0:1], 3, v16
	v_bitop3_b32 v20, v144, 6, 4 bitop3:0x6c
	ds_bpermute_b32 v27, v28, v27
	v_cndmask_b32_e64 v24, v24, v21, s[0:1]
	v_cmp_eq_u32_e64 s[0:1], 4, v16
	s_waitcnt lgkmcnt(0)
	v_add_f32_e32 v17, v17, v27
	v_cndmask_b32_e64 v24, v24, v12, s[0:1]
	v_cmp_eq_u32_e64 s[0:1], 5, v16
	s_nop 1
	v_cndmask_b32_e64 v24, v24, v14, s[0:1]
	v_cmp_eq_u32_e64 s[0:1], 6, v16
	s_nop 1
	v_cndmask_b32_e64 v24, v24, v10, s[0:1]
	v_cmp_eq_u32_e64 s[0:1], 7, v16
	s_nop 1
	v_cndmask_b32_e64 v24, v24, v26, s[0:1]
	v_cmp_eq_u32_e64 s[0:1], 8, v16
	s_nop 1
	v_cndmask_b32_e64 v24, v24, v8, s[0:1]
	v_cmp_eq_u32_e64 s[0:1], 9, v16
	s_nop 1
	v_cndmask_b32_e64 v24, v24, v9, s[0:1]
	v_cmp_eq_u32_e64 s[0:1], 10, v16
	s_nop 1
	v_cndmask_b32_e64 v24, v24, v6, s[0:1]
	v_cmp_eq_u32_e64 s[0:1], 11, v16
	s_nop 1
	v_cndmask_b32_e64 v24, v24, v7, s[0:1]
	v_cmp_eq_u32_e64 s[0:1], 12, v16
	s_nop 1
	v_cndmask_b32_e64 v24, v24, v4, s[0:1]
	v_cmp_eq_u32_e64 s[0:1], 13, v16
	s_nop 1
	v_cndmask_b32_e64 v24, v24, v5, s[0:1]
	v_cmp_eq_u32_e64 s[0:1], 14, v16
	s_nop 1
	v_cndmask_b32_e64 v24, v24, v2, s[0:1]
	v_cmp_eq_u32_e64 s[0:1], 15, v16
	s_nop 1
	v_cndmask_b32_e64 v16, v24, v3, s[0:1]
	v_or_b32_e32 v24, 1, v13
	v_cmp_eq_u32_e64 s[0:1], 1, v24
	ds_bpermute_b32 v16, v28, v16
	s_nop 0
	v_cndmask_b32_e64 v23, v0, v23, s[0:1]
	v_cmp_eq_u32_e64 s[0:1], 2, v24
	s_nop 1
	v_cndmask_b32_e64 v23, v23, v22, s[0:1]
	v_cmp_eq_u32_e64 s[0:1], 3, v24
	s_nop 1
	v_cndmask_b32_e64 v23, v23, v21, s[0:1]
	v_cmp_eq_u32_e64 s[0:1], 4, v24
	s_nop 1
	v_cndmask_b32_e64 v23, v23, v12, s[0:1]
	v_cmp_eq_u32_e64 s[0:1], 5, v24
	s_nop 1
	v_cndmask_b32_e64 v23, v23, v14, s[0:1]
	v_cmp_eq_u32_e64 s[0:1], 6, v24
	s_nop 1
	v_cndmask_b32_e64 v23, v23, v10, s[0:1]
	v_cmp_eq_u32_e64 s[0:1], 7, v24
	s_nop 1
	v_cndmask_b32_e64 v23, v23, v26, s[0:1]
	v_cmp_eq_u32_e64 s[0:1], 8, v24
	s_nop 1
	v_cndmask_b32_e64 v23, v23, v8, s[0:1]
	v_cmp_eq_u32_e64 s[0:1], 9, v24
	s_nop 1
	v_cndmask_b32_e64 v23, v23, v9, s[0:1]
	v_cmp_eq_u32_e64 s[0:1], 10, v24
	s_nop 1
	v_cndmask_b32_e64 v23, v23, v6, s[0:1]
	v_cmp_eq_u32_e64 s[0:1], 11, v24
	s_nop 1
	v_cndmask_b32_e64 v23, v23, v7, s[0:1]
	v_cmp_eq_u32_e64 s[0:1], 12, v24
	s_nop 1
	v_cndmask_b32_e64 v23, v23, v4, s[0:1]
	v_cmp_eq_u32_e64 s[0:1], 13, v24
	s_nop 1
	v_cndmask_b32_e64 v23, v23, v5, s[0:1]
	v_cmp_eq_u32_e64 s[0:1], 14, v24
	s_nop 1
	v_cndmask_b32_e64 v23, v23, v2, s[0:1]
	v_cmp_eq_u32_e64 s[0:1], 15, v24
	s_nop 1
	v_cndmask_b32_e64 v23, v23, v3, s[0:1]
	s_waitcnt lgkmcnt(0)
	v_add_f32_e32 v16, v23, v16
	v_cmp_eq_u32_e64 s[0:1], 1, v20
	s_nop 1
	v_cndmask_b32_e64 v23, v0, v16, s[0:1]
	v_cmp_eq_u32_e64 s[0:1], 2, v20
	s_nop 1
	v_cndmask_b32_e64 v23, v23, v22, s[0:1]
	v_cmp_eq_u32_e64 s[0:1], 3, v20
	s_nop 1
	v_cndmask_b32_e64 v23, v23, v21, s[0:1]
	v_cmp_eq_u32_e64 s[0:1], 4, v20
	s_nop 1
	v_cndmask_b32_e64 v23, v23, v12, s[0:1]
	v_cmp_eq_u32_e64 s[0:1], 5, v20
	s_nop 1
	v_cndmask_b32_e64 v23, v23, v14, s[0:1]
	v_cmp_eq_u32_e64 s[0:1], 6, v20
	s_nop 1
	v_cndmask_b32_e64 v23, v23, v10, s[0:1]
	v_cmp_eq_u32_e64 s[0:1], 7, v20
	s_nop 1
	v_cndmask_b32_e64 v23, v23, v26, s[0:1]
	v_cmp_eq_u32_e64 s[0:1], 8, v20
	s_nop 1
	v_cndmask_b32_e64 v23, v23, v8, s[0:1]
	v_cmp_eq_u32_e64 s[0:1], 9, v20
	s_nop 1
	v_cndmask_b32_e64 v23, v23, v9, s[0:1]
	v_cmp_eq_u32_e64 s[0:1], 10, v20
	s_nop 1
	v_cndmask_b32_e64 v23, v23, v6, s[0:1]
	v_cmp_eq_u32_e64 s[0:1], 11, v20
	s_nop 1
	v_cndmask_b32_e64 v23, v23, v7, s[0:1]
	v_cmp_eq_u32_e64 s[0:1], 12, v20
	s_nop 1
	v_cndmask_b32_e64 v23, v23, v4, s[0:1]
	v_cmp_eq_u32_e64 s[0:1], 13, v20
	s_nop 1
	v_cndmask_b32_e64 v23, v23, v5, s[0:1]
	v_cmp_eq_u32_e64 s[0:1], 14, v20
	s_nop 1
	v_cndmask_b32_e64 v23, v23, v2, s[0:1]
	v_cmp_eq_u32_e64 s[0:1], 15, v20
	s_nop 1
	v_cndmask_b32_e64 v20, v23, v3, s[0:1]
	v_or_b32_e32 v23, 2, v13
	v_cmp_eq_u32_e64 s[0:1], 1, v23
	ds_bpermute_b32 v20, v28, v20
	v_or_b32_e32 v13, 3, v13
	v_cndmask_b32_e64 v24, v0, v16, s[0:1]
	v_cmp_eq_u32_e64 s[0:1], 2, v23
	s_nop 1
	v_cndmask_b32_e64 v22, v24, v22, s[0:1]
	v_cmp_eq_u32_e64 s[0:1], 3, v23
	v_cndmask_b32_e32 v24, v18, v25, vcc
	v_cndmask_b32_e32 v18, v25, v18, vcc
	v_cndmask_b32_e64 v22, v22, v21, s[0:1]
	v_cmp_eq_u32_e64 s[0:1], 4, v23
	ds_bpermute_b32 v24, v28, v24
	s_waitcnt lgkmcnt(0)
	v_add_f32_e32 v18, v18, v24
	v_cndmask_b32_e64 v22, v22, v12, s[0:1]
	v_cmp_eq_u32_e64 s[0:1], 5, v23
	s_nop 1
	v_cndmask_b32_e64 v22, v22, v14, s[0:1]
	v_cmp_eq_u32_e64 s[0:1], 6, v23
	s_nop 1
	v_cndmask_b32_e64 v22, v22, v10, s[0:1]
	v_cmp_eq_u32_e64 s[0:1], 7, v23
	s_nop 1
	v_cndmask_b32_e64 v22, v22, v26, s[0:1]
	v_cmp_eq_u32_e64 s[0:1], 8, v23
	s_nop 1
	v_cndmask_b32_e64 v22, v22, v8, s[0:1]
	v_cmp_eq_u32_e64 s[0:1], 9, v23
	s_nop 1
	v_cndmask_b32_e64 v22, v22, v9, s[0:1]
	v_cmp_eq_u32_e64 s[0:1], 10, v23
	s_nop 1
	v_cndmask_b32_e64 v22, v22, v6, s[0:1]
	v_cmp_eq_u32_e64 s[0:1], 11, v23
	s_nop 1
	v_cndmask_b32_e64 v22, v22, v7, s[0:1]
	v_cmp_eq_u32_e64 s[0:1], 12, v23
	s_nop 1
	v_cndmask_b32_e64 v22, v22, v4, s[0:1]
	v_cmp_eq_u32_e64 s[0:1], 13, v23
	s_nop 1
	v_cndmask_b32_e64 v22, v22, v5, s[0:1]
	v_cmp_eq_u32_e64 s[0:1], 14, v23
	s_nop 1
	v_cndmask_b32_e64 v22, v22, v2, s[0:1]
	v_cmp_eq_u32_e64 s[0:1], 15, v23
	s_nop 1
	v_cndmask_b32_e64 v22, v22, v3, s[0:1]
	v_add_f32_e32 v20, v22, v20
	v_bitop3_b32 v22, v144, 7, 4 bitop3:0x6c
	v_cmp_eq_u32_e64 s[0:1], 1, v22
	s_nop 1
	v_cndmask_b32_e64 v23, v0, v16, s[0:1]
	v_cmp_eq_u32_e64 s[0:1], 2, v22
	s_nop 1
	v_cndmask_b32_e64 v23, v23, v20, s[0:1]
	v_cmp_eq_u32_e64 s[0:1], 3, v22
	s_nop 1
	v_cndmask_b32_e64 v23, v23, v21, s[0:1]
	v_cmp_eq_u32_e64 s[0:1], 4, v22
	s_nop 1
	v_cndmask_b32_e64 v23, v23, v12, s[0:1]
	v_cmp_eq_u32_e64 s[0:1], 5, v22
	s_nop 1
	v_cndmask_b32_e64 v23, v23, v14, s[0:1]
	v_cmp_eq_u32_e64 s[0:1], 6, v22
	s_nop 1
	v_cndmask_b32_e64 v23, v23, v10, s[0:1]
	v_cmp_eq_u32_e64 s[0:1], 7, v22
	s_nop 1
	v_cndmask_b32_e64 v23, v23, v26, s[0:1]
	v_cmp_eq_u32_e64 s[0:1], 8, v22
	s_nop 1
	v_cndmask_b32_e64 v23, v23, v8, s[0:1]
	v_cmp_eq_u32_e64 s[0:1], 9, v22
	s_nop 1
	v_cndmask_b32_e64 v23, v23, v9, s[0:1]
	v_cmp_eq_u32_e64 s[0:1], 10, v22
	s_nop 1
	v_cndmask_b32_e64 v23, v23, v6, s[0:1]
	v_cmp_eq_u32_e64 s[0:1], 11, v22
	s_nop 1
	v_cndmask_b32_e64 v23, v23, v7, s[0:1]
	v_cmp_eq_u32_e64 s[0:1], 12, v22
	s_nop 1
	v_cndmask_b32_e64 v23, v23, v4, s[0:1]
	v_cmp_eq_u32_e64 s[0:1], 13, v22
	s_nop 1
	v_cndmask_b32_e64 v23, v23, v5, s[0:1]
	v_cmp_eq_u32_e64 s[0:1], 14, v22
	s_nop 1
	v_cndmask_b32_e64 v23, v23, v2, s[0:1]
	v_cmp_eq_u32_e64 s[0:1], 15, v22
	s_nop 1
	v_cndmask_b32_e64 v22, v23, v3, s[0:1]
	v_cmp_eq_u32_e64 s[0:1], 1, v13
	ds_bpermute_b32 v22, v28, v22
	s_nop 0
	v_cndmask_b32_e64 v23, v0, v16, s[0:1]
	v_cmp_eq_u32_e64 s[0:1], 2, v13
	s_nop 1
	v_cndmask_b32_e64 v23, v23, v20, s[0:1]
	v_cmp_eq_u32_e64 s[0:1], 3, v13
	s_nop 1
	v_cndmask_b32_e64 v21, v23, v21, s[0:1]
	v_cmp_eq_u32_e64 s[0:1], 4, v13
	v_cndmask_b32_e32 v23, v19, v11, vcc
	v_cndmask_b32_e32 v11, v11, v19, vcc
	v_cndmask_b32_e64 v21, v21, v12, s[0:1]
	v_cmp_eq_u32_e64 s[0:1], 5, v13
	v_and_b32_e32 v19, 2, v144
	ds_bpermute_b32 v23, v28, v23
	v_cndmask_b32_e64 v21, v21, v14, s[0:1]
	v_cmp_eq_u32_e64 s[0:1], 6, v13
	s_waitcnt lgkmcnt(0)
	v_add_f32_e32 v11, v11, v23
	v_cndmask_b32_e64 v21, v21, v10, s[0:1]
	v_cmp_eq_u32_e64 s[0:1], 7, v13
	v_xor_b32_e32 v23, 2, v199
	s_nop 0
	v_cndmask_b32_e64 v21, v21, v26, s[0:1]
	v_cmp_eq_u32_e64 s[0:1], 8, v13
	s_nop 1
	v_cndmask_b32_e64 v21, v21, v8, s[0:1]
	v_cmp_eq_u32_e64 s[0:1], 9, v13
	s_nop 1
	v_cndmask_b32_e64 v21, v21, v9, s[0:1]
	v_cmp_eq_u32_e64 s[0:1], 10, v13
	s_nop 1
	v_cndmask_b32_e64 v21, v21, v6, s[0:1]
	v_cmp_eq_u32_e64 s[0:1], 11, v13
	s_nop 1
	v_cndmask_b32_e64 v21, v21, v7, s[0:1]
	v_cmp_eq_u32_e64 s[0:1], 12, v13
	s_nop 1
	v_cndmask_b32_e64 v21, v21, v4, s[0:1]
	v_cmp_eq_u32_e64 s[0:1], 13, v13
	s_nop 1
	v_cndmask_b32_e64 v21, v21, v5, s[0:1]
	v_cmp_eq_u32_e64 s[0:1], 14, v13
	s_nop 1
	v_cndmask_b32_e64 v21, v21, v2, s[0:1]
	v_cmp_eq_u32_e64 s[0:1], 15, v13
	s_nop 1
	v_cndmask_b32_e64 v13, v21, v3, s[0:1]
	v_bitop3_b32 v21, v144, 2, v144 bitop3:0xc
	v_cmp_eq_u32_e32 vcc, 1, v21
	v_add_f32_e32 v13, v13, v22
	v_cmp_lt_i32_e64 s[0:1], v23, v1
	v_cndmask_b32_e32 v22, v0, v16, vcc
	v_cmp_eq_u32_e32 vcc, 2, v21
	v_cndmask_b32_e64 v23, v199, v23, s[0:1]
	v_lshlrev_b32_e32 v23, 2, v23
	v_cndmask_b32_e32 v22, v22, v20, vcc
	v_cmp_eq_u32_e32 vcc, 3, v21
	v_cmp_eq_u32_e64 s[0:1], 15, v19
	s_nop 0
	v_cndmask_b32_e32 v22, v22, v13, vcc
	v_cmp_eq_u32_e32 vcc, 4, v21
	s_nop 1
	v_cndmask_b32_e32 v22, v22, v12, vcc
	v_cmp_eq_u32_e32 vcc, 5, v21
	s_nop 1
	v_cndmask_b32_e32 v22, v22, v14, vcc
	v_cmp_eq_u32_e32 vcc, 6, v21
	s_nop 1
	v_cndmask_b32_e32 v22, v22, v10, vcc
	v_cmp_eq_u32_e32 vcc, 7, v21
	s_nop 1
	v_cndmask_b32_e32 v22, v22, v26, vcc
	v_cmp_eq_u32_e32 vcc, 8, v21
	s_nop 1
	v_cndmask_b32_e32 v22, v22, v8, vcc
	v_cmp_eq_u32_e32 vcc, 9, v21
	s_nop 1
	v_cndmask_b32_e32 v22, v22, v9, vcc
	v_cmp_eq_u32_e32 vcc, 10, v21
	s_nop 1
	v_cndmask_b32_e32 v22, v22, v6, vcc
	v_cmp_eq_u32_e32 vcc, 11, v21
	s_nop 1
	v_cndmask_b32_e32 v22, v22, v7, vcc
	v_cmp_eq_u32_e32 vcc, 12, v21
	s_nop 1
	v_cndmask_b32_e32 v22, v22, v4, vcc
	v_cmp_eq_u32_e32 vcc, 13, v21
	s_nop 1
	v_cndmask_b32_e32 v22, v22, v5, vcc
	v_cmp_eq_u32_e32 vcc, 14, v21
	s_nop 1
	v_cndmask_b32_e32 v22, v22, v2, vcc
	v_cmp_eq_u32_e32 vcc, 15, v21
	s_nop 1
	v_cndmask_b32_e32 v21, v22, v3, vcc
	v_cmp_eq_u32_e32 vcc, 1, v19
	ds_bpermute_b32 v21, v23, v21
	s_nop 0
	v_cndmask_b32_e32 v0, v0, v16, vcc
	v_cmp_ne_u32_e32 vcc, 0, v19
	s_nop 1
	v_cndmask_b32_e32 v0, v0, v20, vcc
	v_cmp_eq_u32_e32 vcc, 3, v19
	s_nop 1
	v_cndmask_b32_e32 v0, v0, v13, vcc
	v_cmp_eq_u32_e32 vcc, 4, v19
	s_nop 1
	v_cndmask_b32_e32 v0, v0, v12, vcc
	v_cmp_eq_u32_e32 vcc, 5, v19
	s_nop 1
	v_cndmask_b32_e32 v0, v0, v14, vcc
	v_cmp_eq_u32_e32 vcc, 6, v19
	s_nop 1
	v_cndmask_b32_e32 v0, v0, v10, vcc
	v_cmp_eq_u32_e32 vcc, 7, v19
	s_nop 1
	v_cndmask_b32_e32 v0, v0, v26, vcc
	v_cmp_eq_u32_e32 vcc, 8, v19
	s_nop 1
	v_cndmask_b32_e32 v0, v0, v8, vcc
	v_cmp_eq_u32_e32 vcc, 9, v19
	s_nop 1
	v_cndmask_b32_e32 v0, v0, v9, vcc
	v_cmp_eq_u32_e32 vcc, 10, v19
	s_nop 1
	v_cndmask_b32_e32 v0, v0, v6, vcc
	v_cmp_eq_u32_e32 vcc, 11, v19
	s_nop 1
	v_cndmask_b32_e32 v0, v0, v7, vcc
	v_cmp_eq_u32_e32 vcc, 12, v19
	s_nop 1
	v_cndmask_b32_e32 v0, v0, v4, vcc
	v_cmp_eq_u32_e32 vcc, 13, v19
	s_nop 1
	v_cndmask_b32_e32 v0, v0, v5, vcc
	v_cmp_eq_u32_e32 vcc, 14, v19
	s_nop 1
	v_cndmask_b32_e32 v0, v0, v2, vcc
	v_cmp_eq_u32_e32 vcc, 0, v19
	v_cndmask_b32_e64 v0, v0, v3, s[0:1]
	v_or_b32_e32 v19, 1, v19
	v_cndmask_b32_e32 v22, v15, v18, vcc
	v_cndmask_b32_e32 v15, v18, v15, vcc
	s_waitcnt lgkmcnt(0)
	v_add_f32_e32 v18, v0, v21
	v_bitop3_b32 v0, v144, 3, 2 bitop3:0x6c
	v_cmp_eq_u32_e64 s[0:1], 1, v0
	ds_bpermute_b32 v22, v23, v22
	s_waitcnt lgkmcnt(0)
	v_add_f32_e32 v15, v15, v22
	v_cndmask_b32_e64 v21, v18, v16, s[0:1]
	v_cmp_eq_u32_e64 s[0:1], 2, v0
	s_nop 1
	v_cndmask_b32_e64 v21, v21, v20, s[0:1]
	v_cmp_eq_u32_e64 s[0:1], 3, v0
	s_nop 1
	v_cndmask_b32_e64 v21, v21, v13, s[0:1]
	v_cmp_eq_u32_e64 s[0:1], 4, v0
	s_nop 1
	v_cndmask_b32_e64 v21, v21, v12, s[0:1]
	v_cmp_eq_u32_e64 s[0:1], 5, v0
	s_nop 1
	v_cndmask_b32_e64 v21, v21, v14, s[0:1]
	v_cmp_eq_u32_e64 s[0:1], 6, v0
	s_nop 1
	v_cndmask_b32_e64 v21, v21, v10, s[0:1]
	v_cmp_eq_u32_e64 s[0:1], 7, v0
	s_nop 1
	v_cndmask_b32_e64 v21, v21, v26, s[0:1]
	v_cmp_eq_u32_e64 s[0:1], 8, v0
	s_nop 1
	v_cndmask_b32_e64 v21, v21, v8, s[0:1]
	v_cmp_eq_u32_e64 s[0:1], 9, v0
	s_nop 1
	v_cndmask_b32_e64 v21, v21, v9, s[0:1]
	v_cmp_eq_u32_e64 s[0:1], 10, v0
	s_nop 1
	v_cndmask_b32_e64 v21, v21, v6, s[0:1]
	v_cmp_eq_u32_e64 s[0:1], 11, v0
	s_nop 1
	v_cndmask_b32_e64 v21, v21, v7, s[0:1]
	v_cmp_eq_u32_e64 s[0:1], 12, v0
	s_nop 1
	v_cndmask_b32_e64 v21, v21, v4, s[0:1]
	v_cmp_eq_u32_e64 s[0:1], 13, v0
	s_nop 1
	v_cndmask_b32_e64 v21, v21, v5, s[0:1]
	v_cmp_eq_u32_e64 s[0:1], 14, v0
	s_nop 1
	v_cndmask_b32_e64 v21, v21, v2, s[0:1]
	v_cmp_eq_u32_e64 s[0:1], 15, v0
	s_nop 1
	v_cndmask_b32_e64 v0, v21, v3, s[0:1]
	v_cmp_eq_u32_e64 s[0:1], 1, v19
	ds_bpermute_b32 v0, v23, v0
	v_cndmask_b32_e32 v21, v17, v11, vcc
	v_cndmask_b32_e64 v16, v18, v16, s[0:1]
	v_cmp_eq_u32_e64 s[0:1], 2, v19
	v_cndmask_b32_e32 v11, v11, v17, vcc
	v_and_b32_e32 v17, 1, v144
	v_cndmask_b32_e64 v16, v16, v20, s[0:1]
	v_cmp_eq_u32_e64 s[0:1], 3, v19
	v_cmp_eq_u32_e32 vcc, 1, v17
	ds_bpermute_b32 v21, v23, v21
	v_cndmask_b32_e64 v16, v16, v13, s[0:1]
	v_cmp_eq_u32_e64 s[0:1], 4, v19
	s_waitcnt lgkmcnt(0)
	v_add_f32_e32 v11, v11, v21
	v_cndmask_b32_e64 v16, v16, v12, s[0:1]
	v_cmp_eq_u32_e64 s[0:1], 5, v19
	v_xor_b32_e32 v21, 1, v199
	v_cmp_lt_i32_e64 s[4:5], v21, v1
	v_cndmask_b32_e64 v16, v16, v14, s[0:1]
	v_cmp_eq_u32_e64 s[0:1], 6, v19
	v_cndmask_b32_e64 v1, v199, v21, s[4:5]
	v_lshlrev_b32_e32 v1, 2, v1
	v_cndmask_b32_e64 v16, v16, v10, s[0:1]
	v_cmp_eq_u32_e64 s[0:1], 7, v19
	s_mov_b64 s[4:5], s[22:23]
	s_nop 0
	v_cndmask_b32_e64 v16, v16, v26, s[0:1]
	v_cmp_eq_u32_e64 s[0:1], 8, v19
	s_nop 1
	v_cndmask_b32_e64 v16, v16, v8, s[0:1]
	v_cmp_eq_u32_e64 s[0:1], 9, v19
	s_nop 1
	v_cndmask_b32_e64 v16, v16, v9, s[0:1]
	v_cmp_eq_u32_e64 s[0:1], 10, v19
	s_nop 1
	v_cndmask_b32_e64 v16, v16, v6, s[0:1]
	v_cmp_eq_u32_e64 s[0:1], 11, v19
	s_nop 1
	v_cndmask_b32_e64 v16, v16, v7, s[0:1]
	v_cmp_eq_u32_e64 s[0:1], 12, v19
	s_nop 1
	v_cndmask_b32_e64 v16, v16, v4, s[0:1]
	v_cmp_eq_u32_e64 s[0:1], 13, v19
	s_nop 1
	v_cndmask_b32_e64 v16, v16, v5, s[0:1]
	v_cmp_eq_u32_e64 s[0:1], 14, v19
	s_nop 1
	v_cndmask_b32_e64 v16, v16, v2, s[0:1]
	v_cmp_eq_u32_e64 s[0:1], 15, v19
	s_nop 1
	v_cndmask_b32_e64 v16, v16, v3, s[0:1]
	v_add_f32_e32 v16, v16, v0
	v_bitop3_b32 v0, v144, 1, v144 bitop3:0xc
	v_cndmask_b32_e32 v19, v16, v18, vcc
	v_cmp_eq_u32_e64 s[0:1], 2, v0
	s_nop 1
	v_cndmask_b32_e64 v19, v19, v20, s[0:1]
	v_cmp_eq_u32_e64 s[0:1], 3, v0
	s_nop 1
	v_cndmask_b32_e64 v19, v19, v13, s[0:1]
	v_cmp_eq_u32_e64 s[0:1], 4, v0
	s_nop 1
	v_cndmask_b32_e64 v19, v19, v12, s[0:1]
	v_cmp_eq_u32_e64 s[0:1], 5, v0
	s_nop 1
	v_cndmask_b32_e64 v19, v19, v14, s[0:1]
	v_cmp_eq_u32_e64 s[0:1], 6, v0
	s_nop 1
	v_cndmask_b32_e64 v19, v19, v10, s[0:1]
	v_cmp_eq_u32_e64 s[0:1], 7, v0
	s_nop 1
	v_cndmask_b32_e64 v19, v19, v26, s[0:1]
	v_cmp_eq_u32_e64 s[0:1], 8, v0
	s_nop 1
	v_cndmask_b32_e64 v19, v19, v8, s[0:1]
	v_cmp_eq_u32_e64 s[0:1], 9, v0
	s_nop 1
	v_cndmask_b32_e64 v19, v19, v9, s[0:1]
	v_cmp_eq_u32_e64 s[0:1], 10, v0
	s_nop 1
	v_cndmask_b32_e64 v19, v19, v6, s[0:1]
	v_cmp_eq_u32_e64 s[0:1], 11, v0
	s_nop 1
	v_cndmask_b32_e64 v19, v19, v7, s[0:1]
	v_cmp_eq_u32_e64 s[0:1], 12, v0
	s_nop 1
	v_cndmask_b32_e64 v19, v19, v4, s[0:1]
	v_cmp_eq_u32_e64 s[0:1], 13, v0
	s_nop 1
	v_cndmask_b32_e64 v19, v19, v5, s[0:1]
	v_cmp_eq_u32_e64 s[0:1], 14, v0
	s_nop 1
	v_cndmask_b32_e64 v19, v19, v2, s[0:1]
	v_cmp_eq_u32_e64 s[0:1], 15, v0
	s_nop 1
	v_cndmask_b32_e64 v0, v19, v3, s[0:1]
	v_cmp_eq_u32_e64 s[0:1], 0, v17
	ds_bpermute_b32 v0, v1, v0
	s_nop 0
	v_cndmask_b32_e64 v19, v15, v11, s[0:1]
	v_cndmask_b32_e64 v11, v11, v15, s[0:1]
	v_cndmask_b32_e32 v15, v18, v16, vcc
	v_cmp_eq_u32_e32 vcc, 2, v17
	ds_bpermute_b32 v1, v1, v19
	s_lshl_b32 s0, s2, 1
	v_cndmask_b32_e32 v15, v15, v20, vcc
	v_cmp_eq_u32_e32 vcc, 3, v17
	s_ashr_i32 s1, s0, 31
	s_add_u32 s0, s0, s34
	v_cndmask_b32_e32 v13, v15, v13, vcc
	v_cmp_eq_u32_e32 vcc, 4, v17
	s_addc_u32 s1, s1, s43
	s_mov_b32 s2, s16
	v_cndmask_b32_e32 v12, v13, v12, vcc
	v_cmp_eq_u32_e32 vcc, 5, v17
	s_nop 1
	v_cndmask_b32_e32 v12, v12, v14, vcc
	v_cmp_eq_u32_e32 vcc, 6, v17
	s_nop 1
	v_cndmask_b32_e32 v10, v12, v10, vcc
	v_cmp_eq_u32_e32 vcc, 7, v17
	s_nop 1
	v_cndmask_b32_e32 v10, v10, v26, vcc
	v_cmp_eq_u32_e32 vcc, 8, v17
	s_nop 1
	v_cndmask_b32_e32 v8, v10, v8, vcc
	v_cmp_eq_u32_e32 vcc, 9, v17
	s_nop 1
	v_cndmask_b32_e32 v8, v8, v9, vcc
	v_cmp_eq_u32_e32 vcc, 10, v17
	s_nop 1
	v_cndmask_b32_e32 v6, v8, v6, vcc
	v_cmp_eq_u32_e32 vcc, 11, v17
	s_nop 1
	v_cndmask_b32_e32 v6, v6, v7, vcc
	v_cmp_eq_u32_e32 vcc, 12, v17
	s_nop 1
	v_cndmask_b32_e32 v4, v6, v4, vcc
	v_cmp_eq_u32_e32 vcc, 13, v17
	s_nop 1
	v_cndmask_b32_e32 v4, v4, v5, vcc
	v_cmp_eq_u32_e32 vcc, 14, v17
	s_nop 1
	v_cndmask_b32_e32 v2, v4, v2, vcc
	v_cmp_eq_u32_e32 vcc, 15, v17
	s_nop 1
	v_cndmask_b32_e32 v10, v2, v3, vcc
	v_lshlrev_b32_e32 v2, 4, v144
	v_and_b32_e32 v2, 0xffffff80, v2
	v_add_u32_e32 v2, v138, v2
	v_and_or_b32 v2, v144, 7, v2
	v_ashrrev_i32_e32 v3, 31, v2
	v_lshlrev_b64 v[2:3], 8, v[2:3]
	v_lshl_add_u64 v[2:3], s[12:13], 0, v[2:3]
	s_waitcnt lgkmcnt(0)
	v_pk_add_f32 v[0:1], v[10:11], v[0:1]
	v_lshl_add_u64 v[2:3], s[0:1], 3, v[2:3]
	s_and_b64 vcc, exec, s[14:15]
	s_mov_b64 s[0:1], s[20:21]
	global_store_dwordx2 v[2:3], v[0:1], off
	s_cbranch_vccz .LBB0_327
	s_waitcnt vmcnt(0)
	s_cmpk_gt_u32 s30, 0xff
	s_cbranch_scc1 .LBB0_338
	s_barrier
